# hazard margins (extra wait states after MFMA before VALU reads) on the hand-written indexer / gathered-logit paths
# speedup vs baseline: 1.0403x; 1.0017x over previous
.LBB0_532:
	v_mov_b32_e32 v129, v194
	v_readfirstlane_b32 s83, v194
	v_and_b32_e32 v180, 31, v194
	v_bfe_u32 v131, v194, 5, 1
	v_and_b32_e32 v243, 63, v194
	s_ashr_i32 s84, s83, 6
	s_lshl_b32 s0, s84, 5
	v_or_b32_e32 v130, s0, v180
	v_lshlrev_b32_e32 v243, 2, v243
	s_lshl_b32 s0, s2, 17
	s_lshl_b32 s1, s84, 8
	s_add_u32 s0, s0, s1
	s_add_u32 s8, s28, s0
	s_addc_u32 s9, s29, 0
	s_lshl_b32 s21, s84, 12
	s_cmp_lg_u32 s82, 0
	s_cbranch_scc1 .Lix_reload
	v_bfe_u32 v0, v194, 2, 1
	v_lshrrev_b32_e32 v1, 1, v194
	v_and_b32_e32 v1, 12, v1
	v_and_b32_e32 v228, 3, v194
	v_or_b32_e32 v1, v1, v228
	v_add_u32_e32 v0, s34, v0
	v_lshlrev_b32_e32 v0, 11, v0
	v_lshl_add_u32 v0, v1, 7, v0
	v_lshl_add_u32 v0, v131, 4, v0
	v_add_u32_e32 v1, 0x1000, v0
	global_load_dwordx4 v[70:73], v0, s[36:37]
	global_load_dwordx4 v[74:77], v0, s[36:37] offset:32
	global_load_dwordx4 v[78:81], v0, s[36:37] offset:64
	global_load_dwordx4 v[82:85], v0, s[36:37] offset:96
	global_load_dwordx4 v[86:89], v1, s[36:37]
	global_load_dwordx4 v[90:93], v1, s[36:37] offset:32
	global_load_dwordx4 v[94:97], v1, s[36:37] offset:64
	global_load_dwordx4 v[98:101], v1, s[36:37] offset:96
	v_add_u32_e32 v228, s34, v131
	v_lshlrev_b32_e32 v228, 6, v228
	global_load_dwordx4 v[22:25], v228, s[38:39]
	global_load_dwordx4 v[26:29], v228, s[38:39] offset:16
	global_load_dwordx4 v[30:33], v228, s[38:39] offset:32
	global_load_dwordx4 v[34:37], v228, s[38:39] offset:48
	global_load_dwordx2 v[244:245], v228, s[38:39] offset:128
	global_load_dwordx2 v[246:247], v228, s[38:39] offset:136
	global_load_dwordx2 v[248:249], v228, s[38:39] offset:144
	global_load_dwordx2 v[250:251], v228, s[38:39] offset:152
	global_load_dwordx2 v[252:253], v228, s[38:39] offset:160
	global_load_dwordx2 v[254:255], v228, s[38:39] offset:168
	global_load_dwordx2 v[200:201], v228, s[38:39] offset:176
	global_load_dwordx2 v[202:203], v228, s[38:39] offset:184
	v_lshrrev_b32_e32 v0, 2, v243
	v_lshrrev_b32_e32 v1, 3, v0
	v_lshrrev_b32_e32 v228, 4, v0
	v_and_b32_e32 v229, 7, v0
	v_xor_b32_e32 v228, v229, v228
	v_xor_b32_e32 v229, 4, v228
	s_lshl_b32 s0, s84, 12
	v_lshl_add_u32 v1, v1, 7, s0
	v_lshl_add_u32 v102, v228, 4, v1
	v_lshl_add_u32 v110, v229, 4, v1
	v_add_u32_e32 v110, 0x400, v110
	v_add_u32_e32 v112, 0x800, v102
	v_add_u32_e32 v193, 0x800, v110
	v_lshlrev_b32_e32 v0, 7, v130
	v_bfe_u32 v1, v180, 1, 3
	v_or_b32_e32 v228, 0, v131
	v_xor_b32_e32 v228, v228, v1
	v_lshl_add_u32 v5, v228, 4, v0
	v_or_b32_e32 v228, 2, v131
	v_xor_b32_e32 v228, v228, v1
	v_lshl_add_u32 v52, v228, 4, v0
	v_or_b32_e32 v228, 4, v131
	v_xor_b32_e32 v228, v228, v1
	v_lshl_add_u32 v55, v228, 4, v0
	v_or_b32_e32 v228, 6, v131
	v_xor_b32_e32 v228, v228, v1
	v_lshl_add_u32 v56, v228, 4, v0
	s_mov_b32 s6, s14
	s_mov_b32 s7, s15
	s_add_i32 s10, s0, 10496
	s_sub_i32 s11, s35, s84
	s_add_i32 m0, s10, 0
	s_nop 0
	global_load_lds_dwordx4 v102, s[6:7]
	s_add_i32 m0, s10, 1024
	s_nop 0
	global_load_lds_dwordx4 v110, s[6:7]
	s_add_i32 m0, s10, 2048
	s_nop 0
	global_load_lds_dwordx4 v112, s[6:7]
	s_add_i32 m0, s10, 3072
	s_nop 0
	global_load_lds_dwordx4 v193, s[6:7]
	s_add_u32 s6, s6, 0x8000
	s_addc_u32 s7, s7, 0
	s_add_i32 m0, s10, 32768
	s_nop 0
	global_load_lds_dwordx4 v102, s[6:7]
	s_add_i32 m0, s10, 33792
	s_nop 0
	global_load_lds_dwordx4 v110, s[6:7]
	s_add_i32 m0, s10, 34816
	s_nop 0
	global_load_lds_dwordx4 v112, s[6:7]
	s_add_i32 m0, s10, 35840
	s_nop 0
	global_load_lds_dwordx4 v193, s[6:7]
	s_add_u32 s6, s6, 0x8000
	s_addc_u32 s7, s7, 0
	s_add_i32 m0, s10, 65536
	s_nop 0
	global_load_lds_dwordx4 v102, s[6:7]
	s_add_i32 m0, s10, 66560
	s_nop 0
	global_load_lds_dwordx4 v110, s[6:7]
	s_add_i32 m0, s10, 67584
	s_nop 0
	global_load_lds_dwordx4 v112, s[6:7]
	s_add_i32 m0, s10, 68608
	s_nop 0
	global_load_lds_dwordx4 v193, s[6:7]
	s_add_u32 s6, s6, 0x8000
	s_addc_u32 s7, s7, 0
	s_waitcnt vmcnt(8)
	ds_read_b128 v[38:41], v5 offset:10496
	ds_read_b128 v[42:45], v52 offset:10496
	ds_read_b128 v[46:49], v55 offset:10496
	ds_read_b128 v[196:199], v56 offset:10496
	s_waitcnt lgkmcnt(3)
	v_mfma_f32_32x32x16_bf16 v[212:227], v[70:73], v[38:41], 0
	s_add_i32 m0, s10, 98304
	s_nop 0
	global_load_lds_dwordx4 v102, s[6:7]
	s_waitcnt lgkmcnt(2)
	v_mfma_f32_32x32x16_bf16 v[212:227], v[74:77], v[42:45], v[212:227]
	s_add_i32 m0, s10, 99328
	s_nop 0
	global_load_lds_dwordx4 v110, s[6:7]
	s_waitcnt lgkmcnt(1)
	v_mfma_f32_32x32x16_bf16 v[212:227], v[78:81], v[46:49], v[212:227]
	s_add_i32 m0, s10, 100352
	s_nop 0
	global_load_lds_dwordx4 v112, s[6:7]
	s_waitcnt lgkmcnt(0)
	v_mfma_f32_32x32x16_bf16 v[212:227], v[82:85], v[196:199], v[212:227]
	s_add_i32 m0, s10, 101376
	s_nop 0
	global_load_lds_dwordx4 v193, s[6:7]
	s_add_u32 s6, s6, 0x8000
	s_addc_u32 s7, s7, 0
	v_mfma_f32_32x32x16_bf16 v[6:21], v[86:89], v[38:41], 0
	s_nop 7
	s_nop 2
	v_max_f32_e32 v108, 0, v212
	v_max_f32_e32 v109, 0, v213
	v_pk_mul_f32 v[0:1], v[22:23], v[108:109]
	v_max_f32_e32 v210, 0, v214
	v_max_f32_e32 v211, 0, v215
	v_pk_fma_f32 v[0:1], v[24:25], v[210:211], v[0:1]
	v_max_f32_e32 v108, 0, v216
	v_max_f32_e32 v109, 0, v217
	v_pk_fma_f32 v[0:1], v[26:27], v[108:109], v[0:1]
	v_mfma_f32_32x32x16_bf16 v[6:21], v[90:93], v[42:45], v[6:21]
	v_max_f32_e32 v210, 0, v218
	v_max_f32_e32 v211, 0, v219
	v_pk_fma_f32 v[0:1], v[28:29], v[210:211], v[0:1]
	v_max_f32_e32 v108, 0, v220
	v_max_f32_e32 v109, 0, v221
	v_pk_fma_f32 v[0:1], v[30:31], v[108:109], v[0:1]
	v_max_f32_e32 v210, 0, v222
	v_max_f32_e32 v211, 0, v223
	v_pk_fma_f32 v[0:1], v[32:33], v[210:211], v[0:1]
	v_mfma_f32_32x32x16_bf16 v[6:21], v[94:97], v[46:49], v[6:21]
	v_max_f32_e32 v108, 0, v224
	v_max_f32_e32 v109, 0, v225
	v_pk_fma_f32 v[0:1], v[34:35], v[108:109], v[0:1]
	v_max_f32_e32 v210, 0, v226
	v_max_f32_e32 v211, 0, v227
	v_pk_fma_f32 v[0:1], v[36:37], v[210:211], v[0:1]
	v_add_f32_e32 v0, v0, v1
	v_ashrrev_i32_e32 v1, 31, v0
	v_mfma_f32_32x32x16_bf16 v[6:21], v[98:101], v[196:199], v[6:21]
	s_waitcnt vmcnt(8)
	ds_read_b128 v[38:41], v5 offset:43264
	ds_read_b128 v[42:45], v52 offset:43264
	ds_read_b128 v[46:49], v55 offset:43264
	ds_read_b128 v[196:199], v56 offset:43264
	v_or_b32_e32 v1, 0x80000000, v1
	s_cmpk_gt_i32 s11, 0
	s_cselect_b64 vcc, -1, 0
	v_xor_b32_e32 v0, v1, v0
	v_cndmask_b32_e32 v133, v123, v0, vcc
	s_nop 3
	s_waitcnt lgkmcnt(3)
	v_mfma_f32_32x32x16_bf16 v[212:227], v[70:73], v[38:41], 0
	v_max_f32_e32 v108, 0, v6
	v_max_f32_e32 v109, 0, v7
	v_pk_mul_f32 v[50:51], v[244:245], v[108:109]
	v_max_f32_e32 v210, 0, v8
	v_max_f32_e32 v211, 0, v9
	v_pk_fma_f32 v[50:51], v[246:247], v[210:211], v[50:51]
	v_max_f32_e32 v108, 0, v10
	v_max_f32_e32 v109, 0, v11
	v_pk_fma_f32 v[50:51], v[248:249], v[108:109], v[50:51]
	s_waitcnt lgkmcnt(2)
	v_mfma_f32_32x32x16_bf16 v[212:227], v[74:77], v[42:45], v[212:227]
	v_max_f32_e32 v210, 0, v12
	v_max_f32_e32 v211, 0, v13
	v_pk_fma_f32 v[50:51], v[250:251], v[210:211], v[50:51]
	v_max_f32_e32 v108, 0, v14
	v_max_f32_e32 v109, 0, v15
	v_pk_fma_f32 v[50:51], v[252:253], v[108:109], v[50:51]
	v_max_f32_e32 v210, 0, v16
	v_max_f32_e32 v211, 0, v17
	v_pk_fma_f32 v[50:51], v[254:255], v[210:211], v[50:51]
	s_waitcnt lgkmcnt(1)
	v_mfma_f32_32x32x16_bf16 v[212:227], v[78:81], v[46:49], v[212:227]
	v_max_f32_e32 v108, 0, v18
	v_max_f32_e32 v109, 0, v19
	v_pk_fma_f32 v[50:51], v[200:201], v[108:109], v[50:51]
	v_max_f32_e32 v210, 0, v20
	v_max_f32_e32 v211, 0, v21
	v_pk_fma_f32 v[50:51], v[202:203], v[210:211], v[50:51]
	v_add_f32_e32 v50, v50, v51
	v_ashrrev_i32_e32 v51, 31, v50
	s_waitcnt lgkmcnt(0)
	v_mfma_f32_32x32x16_bf16 v[212:227], v[82:85], v[196:199], v[212:227]
	v_or_b32_e32 v51, 0x80000000, v51
	s_cmpk_gt_i32 s11, 0
	s_cselect_b64 vcc, -1, 0
	v_xor_b32_e32 v50, v51, v50
	v_cndmask_b32_e32 v50, v123, v50, vcc
	global_store_dword v243, v50, s[8:9]
	v_mfma_f32_32x32x16_bf16 v[6:21], v[86:89], v[38:41], 0
	s_add_i32 m0, s10, 0
	s_nop 0
	global_load_lds_dwordx4 v102, s[6:7]
	s_add_i32 m0, s10, 1024
	s_nop 0
	global_load_lds_dwordx4 v110, s[6:7]
	s_add_i32 m0, s10, 2048
	s_nop 0
	global_load_lds_dwordx4 v112, s[6:7]
	s_add_i32 m0, s10, 3072
	s_nop 0
	global_load_lds_dwordx4 v193, s[6:7]
	s_add_u32 s6, s6, 0x8000
	s_addc_u32 s7, s7, 0
	v_max_f32_e32 v108, 0, v212
	v_max_f32_e32 v109, 0, v213
	v_pk_mul_f32 v[0:1], v[22:23], v[108:109]
	v_max_f32_e32 v210, 0, v214
	v_max_f32_e32 v211, 0, v215
	v_pk_fma_f32 v[0:1], v[24:25], v[210:211], v[0:1]
	v_max_f32_e32 v108, 0, v216
	v_max_f32_e32 v109, 0, v217
	v_pk_fma_f32 v[0:1], v[26:27], v[108:109], v[0:1]
	v_mfma_f32_32x32x16_bf16 v[6:21], v[90:93], v[42:45], v[6:21]
	v_max_f32_e32 v210, 0, v218
	v_max_f32_e32 v211, 0, v219
	v_pk_fma_f32 v[0:1], v[28:29], v[210:211], v[0:1]
	v_max_f32_e32 v108, 0, v220
	v_max_f32_e32 v109, 0, v221
	v_pk_fma_f32 v[0:1], v[30:31], v[108:109], v[0:1]
	v_max_f32_e32 v210, 0, v222
	v_max_f32_e32 v211, 0, v223
	v_pk_fma_f32 v[0:1], v[32:33], v[210:211], v[0:1]
	v_mfma_f32_32x32x16_bf16 v[6:21], v[94:97], v[46:49], v[6:21]
	v_max_f32_e32 v108, 0, v224
	v_max_f32_e32 v109, 0, v225
	v_pk_fma_f32 v[0:1], v[34:35], v[108:109], v[0:1]
	v_max_f32_e32 v210, 0, v226
	v_max_f32_e32 v211, 0, v227
	v_pk_fma_f32 v[0:1], v[36:37], v[210:211], v[0:1]
	v_add_f32_e32 v0, v0, v1
	v_ashrrev_i32_e32 v1, 31, v0
	v_mfma_f32_32x32x16_bf16 v[6:21], v[98:101], v[196:199], v[6:21]
	s_waitcnt vmcnt(9)
	v_add_u32_e32 v228, 0x10000, v5
	ds_read_b128 v[38:41], v228 offset:10496
	v_add_u32_e32 v228, 0x10000, v52
	ds_read_b128 v[42:45], v228 offset:10496
	v_add_u32_e32 v228, 0x10000, v55
	ds_read_b128 v[46:49], v228 offset:10496
	v_add_u32_e32 v228, 0x10000, v56
	ds_read_b128 v[196:199], v228 offset:10496
	v_or_b32_e32 v1, 0x80000000, v1
	s_cmpk_gt_i32 s11, 8
	s_cselect_b64 vcc, -1, 0
	v_xor_b32_e32 v0, v1, v0
	v_cndmask_b32_e32 v132, v123, v0, vcc
	s_nop 3
	s_waitcnt lgkmcnt(3)
	v_mfma_f32_32x32x16_bf16 v[212:227], v[70:73], v[38:41], 0
	v_max_f32_e32 v108, 0, v6
	v_max_f32_e32 v109, 0, v7
	v_pk_mul_f32 v[50:51], v[244:245], v[108:109]
	v_max_f32_e32 v210, 0, v8
	v_max_f32_e32 v211, 0, v9
	v_pk_fma_f32 v[50:51], v[246:247], v[210:211], v[50:51]
	v_max_f32_e32 v108, 0, v10
	v_max_f32_e32 v109, 0, v11
	v_pk_fma_f32 v[50:51], v[248:249], v[108:109], v[50:51]
	s_waitcnt lgkmcnt(2)
	v_mfma_f32_32x32x16_bf16 v[212:227], v[74:77], v[42:45], v[212:227]
	v_max_f32_e32 v210, 0, v12
	v_max_f32_e32 v211, 0, v13
	v_pk_fma_f32 v[50:51], v[250:251], v[210:211], v[50:51]
	v_max_f32_e32 v108, 0, v14
	v_max_f32_e32 v109, 0, v15
	v_pk_fma_f32 v[50:51], v[252:253], v[108:109], v[50:51]
	v_max_f32_e32 v210, 0, v16
	v_max_f32_e32 v211, 0, v17
	v_pk_fma_f32 v[50:51], v[254:255], v[210:211], v[50:51]
	s_waitcnt lgkmcnt(1)
	v_mfma_f32_32x32x16_bf16 v[212:227], v[78:81], v[46:49], v[212:227]
	v_max_f32_e32 v108, 0, v18
	v_max_f32_e32 v109, 0, v19
	v_pk_fma_f32 v[50:51], v[200:201], v[108:109], v[50:51]
	v_max_f32_e32 v210, 0, v20
	v_max_f32_e32 v211, 0, v21
	v_pk_fma_f32 v[50:51], v[202:203], v[210:211], v[50:51]
	v_add_f32_e32 v50, v50, v51
	v_ashrrev_i32_e32 v51, 31, v50
	s_waitcnt lgkmcnt(0)
	v_mfma_f32_32x32x16_bf16 v[212:227], v[82:85], v[196:199], v[212:227]
	v_or_b32_e32 v51, 0x80000000, v51
	s_cmpk_gt_i32 s11, 8
	s_cselect_b64 vcc, -1, 0
	v_xor_b32_e32 v50, v51, v50
	v_cndmask_b32_e32 v50, v123, v50, vcc
	global_store_dword v243, v50, s[8:9] offset:2048
	s_add_u32 s8, s8, 0x1000
	s_addc_u32 s9, s9, 0
	v_mfma_f32_32x32x16_bf16 v[6:21], v[86:89], v[38:41], 0
	s_add_i32 m0, s10, 32768
	s_nop 0
	global_load_lds_dwordx4 v102, s[6:7]
	s_add_i32 m0, s10, 33792
	s_nop 0
	global_load_lds_dwordx4 v110, s[6:7]
	s_add_i32 m0, s10, 34816
	s_nop 0
	global_load_lds_dwordx4 v112, s[6:7]
	s_add_i32 m0, s10, 35840
	s_nop 0
	global_load_lds_dwordx4 v193, s[6:7]
	s_add_u32 s6, s6, 0x8000
	s_addc_u32 s7, s7, 0
	v_max_f32_e32 v108, 0, v212
	v_max_f32_e32 v109, 0, v213
	v_pk_mul_f32 v[0:1], v[22:23], v[108:109]
	v_max_f32_e32 v210, 0, v214
	v_max_f32_e32 v211, 0, v215
	v_pk_fma_f32 v[0:1], v[24:25], v[210:211], v[0:1]
	v_max_f32_e32 v108, 0, v216
	v_max_f32_e32 v109, 0, v217
	v_pk_fma_f32 v[0:1], v[26:27], v[108:109], v[0:1]
	v_mfma_f32_32x32x16_bf16 v[6:21], v[90:93], v[42:45], v[6:21]
	v_max_f32_e32 v210, 0, v218
	v_max_f32_e32 v211, 0, v219
	v_pk_fma_f32 v[0:1], v[28:29], v[210:211], v[0:1]
	v_max_f32_e32 v108, 0, v220
	v_max_f32_e32 v109, 0, v221
	v_pk_fma_f32 v[0:1], v[30:31], v[108:109], v[0:1]
	v_max_f32_e32 v210, 0, v222
	v_max_f32_e32 v211, 0, v223
	v_pk_fma_f32 v[0:1], v[32:33], v[210:211], v[0:1]
	v_mfma_f32_32x32x16_bf16 v[6:21], v[94:97], v[46:49], v[6:21]
	v_max_f32_e32 v108, 0, v224
	v_max_f32_e32 v109, 0, v225
	v_pk_fma_f32 v[0:1], v[34:35], v[108:109], v[0:1]
	v_max_f32_e32 v210, 0, v226
	v_max_f32_e32 v211, 0, v227
	v_pk_fma_f32 v[0:1], v[36:37], v[210:211], v[0:1]
	v_add_f32_e32 v0, v0, v1
	v_ashrrev_i32_e32 v1, 31, v0
	v_mfma_f32_32x32x16_bf16 v[6:21], v[98:101], v[196:199], v[6:21]
	s_waitcnt vmcnt(10)
	v_add_u32_e32 v228, 0x10000, v5
	ds_read_b128 v[38:41], v228 offset:43264
	v_add_u32_e32 v228, 0x10000, v52
	ds_read_b128 v[42:45], v228 offset:43264
	v_add_u32_e32 v228, 0x10000, v55
	ds_read_b128 v[46:49], v228 offset:43264
	v_add_u32_e32 v228, 0x10000, v56
	ds_read_b128 v[196:199], v228 offset:43264
	v_or_b32_e32 v1, 0x80000000, v1
	s_cmpk_gt_i32 s11, 16
	s_cselect_b64 vcc, -1, 0
	v_xor_b32_e32 v0, v1, v0
	v_cndmask_b32_e32 v135, v123, v0, vcc
	s_nop 3
	s_waitcnt lgkmcnt(3)
	v_mfma_f32_32x32x16_bf16 v[212:227], v[70:73], v[38:41], 0
	v_max_f32_e32 v108, 0, v6
	v_max_f32_e32 v109, 0, v7
	v_pk_mul_f32 v[50:51], v[244:245], v[108:109]
	v_max_f32_e32 v210, 0, v8
	v_max_f32_e32 v211, 0, v9
	v_pk_fma_f32 v[50:51], v[246:247], v[210:211], v[50:51]
	v_max_f32_e32 v108, 0, v10
	v_max_f32_e32 v109, 0, v11
	v_pk_fma_f32 v[50:51], v[248:249], v[108:109], v[50:51]
	s_waitcnt lgkmcnt(2)
	v_mfma_f32_32x32x16_bf16 v[212:227], v[74:77], v[42:45], v[212:227]
	v_max_f32_e32 v210, 0, v12
	v_max_f32_e32 v211, 0, v13
	v_pk_fma_f32 v[50:51], v[250:251], v[210:211], v[50:51]
	v_max_f32_e32 v108, 0, v14
	v_max_f32_e32 v109, 0, v15
	v_pk_fma_f32 v[50:51], v[252:253], v[108:109], v[50:51]
	v_max_f32_e32 v210, 0, v16
	v_max_f32_e32 v211, 0, v17
	v_pk_fma_f32 v[50:51], v[254:255], v[210:211], v[50:51]
	s_waitcnt lgkmcnt(1)
	v_mfma_f32_32x32x16_bf16 v[212:227], v[78:81], v[46:49], v[212:227]
	v_max_f32_e32 v108, 0, v18
	v_max_f32_e32 v109, 0, v19
	v_pk_fma_f32 v[50:51], v[200:201], v[108:109], v[50:51]
	v_max_f32_e32 v210, 0, v20
	v_max_f32_e32 v211, 0, v21
	v_pk_fma_f32 v[50:51], v[202:203], v[210:211], v[50:51]
	v_add_f32_e32 v50, v50, v51
	v_ashrrev_i32_e32 v51, 31, v50
	s_waitcnt lgkmcnt(0)
	v_mfma_f32_32x32x16_bf16 v[212:227], v[82:85], v[196:199], v[212:227]
	v_or_b32_e32 v51, 0x80000000, v51
	s_cmpk_gt_i32 s11, 16
	s_cselect_b64 vcc, -1, 0
	v_xor_b32_e32 v50, v51, v50
	v_cndmask_b32_e32 v50, v123, v50, vcc
	global_store_dword v243, v50, s[8:9]
	v_mfma_f32_32x32x16_bf16 v[6:21], v[86:89], v[38:41], 0
	s_add_i32 m0, s10, 65536
	s_nop 0
	global_load_lds_dwordx4 v102, s[6:7]
	s_add_i32 m0, s10, 66560
	s_nop 0
	global_load_lds_dwordx4 v110, s[6:7]
	s_add_i32 m0, s10, 67584
	s_nop 0
	global_load_lds_dwordx4 v112, s[6:7]
	s_add_i32 m0, s10, 68608
	s_nop 0
	global_load_lds_dwordx4 v193, s[6:7]
	s_add_u32 s6, s6, 0x8000
	s_addc_u32 s7, s7, 0
	v_max_f32_e32 v108, 0, v212
	v_max_f32_e32 v109, 0, v213
	v_pk_mul_f32 v[0:1], v[22:23], v[108:109]
	v_max_f32_e32 v210, 0, v214
	v_max_f32_e32 v211, 0, v215
	v_pk_fma_f32 v[0:1], v[24:25], v[210:211], v[0:1]
	v_max_f32_e32 v108, 0, v216
	v_max_f32_e32 v109, 0, v217
	v_pk_fma_f32 v[0:1], v[26:27], v[108:109], v[0:1]
	v_mfma_f32_32x32x16_bf16 v[6:21], v[90:93], v[42:45], v[6:21]
	v_max_f32_e32 v210, 0, v218
	v_max_f32_e32 v211, 0, v219
	v_pk_fma_f32 v[0:1], v[28:29], v[210:211], v[0:1]
	v_max_f32_e32 v108, 0, v220
	v_max_f32_e32 v109, 0, v221
	v_pk_fma_f32 v[0:1], v[30:31], v[108:109], v[0:1]
	v_max_f32_e32 v210, 0, v222
	v_max_f32_e32 v211, 0, v223
	v_pk_fma_f32 v[0:1], v[32:33], v[210:211], v[0:1]
	v_mfma_f32_32x32x16_bf16 v[6:21], v[94:97], v[46:49], v[6:21]
	v_max_f32_e32 v108, 0, v224
	v_max_f32_e32 v109, 0, v225
	v_pk_fma_f32 v[0:1], v[34:35], v[108:109], v[0:1]
	v_max_f32_e32 v210, 0, v226
	v_max_f32_e32 v211, 0, v227
	v_pk_fma_f32 v[0:1], v[36:37], v[210:211], v[0:1]
	v_add_f32_e32 v0, v0, v1
	v_ashrrev_i32_e32 v1, 31, v0
	v_mfma_f32_32x32x16_bf16 v[6:21], v[98:101], v[196:199], v[6:21]
	s_waitcnt vmcnt(10)
	ds_read_b128 v[38:41], v5 offset:10496
	ds_read_b128 v[42:45], v52 offset:10496
	ds_read_b128 v[46:49], v55 offset:10496
	ds_read_b128 v[196:199], v56 offset:10496
	v_or_b32_e32 v1, 0x80000000, v1
	s_cmpk_gt_i32 s11, 24
	s_cselect_b64 vcc, -1, 0
	v_xor_b32_e32 v0, v1, v0
	v_cndmask_b32_e32 v134, v123, v0, vcc
	s_nop 3
	s_waitcnt lgkmcnt(3)
	v_mfma_f32_32x32x16_bf16 v[212:227], v[70:73], v[38:41], 0
	v_max_f32_e32 v108, 0, v6
	v_max_f32_e32 v109, 0, v7
	v_pk_mul_f32 v[50:51], v[244:245], v[108:109]
	v_max_f32_e32 v210, 0, v8
	v_max_f32_e32 v211, 0, v9
	v_pk_fma_f32 v[50:51], v[246:247], v[210:211], v[50:51]
	v_max_f32_e32 v108, 0, v10
	v_max_f32_e32 v109, 0, v11
	v_pk_fma_f32 v[50:51], v[248:249], v[108:109], v[50:51]
	s_waitcnt lgkmcnt(2)
	v_mfma_f32_32x32x16_bf16 v[212:227], v[74:77], v[42:45], v[212:227]
	v_max_f32_e32 v210, 0, v12
	v_max_f32_e32 v211, 0, v13
	v_pk_fma_f32 v[50:51], v[250:251], v[210:211], v[50:51]
	v_max_f32_e32 v108, 0, v14
	v_max_f32_e32 v109, 0, v15
	v_pk_fma_f32 v[50:51], v[252:253], v[108:109], v[50:51]
	v_max_f32_e32 v210, 0, v16
	v_max_f32_e32 v211, 0, v17
	v_pk_fma_f32 v[50:51], v[254:255], v[210:211], v[50:51]
	s_waitcnt lgkmcnt(1)
	v_mfma_f32_32x32x16_bf16 v[212:227], v[78:81], v[46:49], v[212:227]
	v_max_f32_e32 v108, 0, v18
	v_max_f32_e32 v109, 0, v19
	v_pk_fma_f32 v[50:51], v[200:201], v[108:109], v[50:51]
	v_max_f32_e32 v210, 0, v20
	v_max_f32_e32 v211, 0, v21
	v_pk_fma_f32 v[50:51], v[202:203], v[210:211], v[50:51]
	v_add_f32_e32 v50, v50, v51
	v_ashrrev_i32_e32 v51, 31, v50
	s_waitcnt lgkmcnt(0)
	v_mfma_f32_32x32x16_bf16 v[212:227], v[82:85], v[196:199], v[212:227]
	v_or_b32_e32 v51, 0x80000000, v51
	s_cmpk_gt_i32 s11, 24
	s_cselect_b64 vcc, -1, 0
	v_xor_b32_e32 v50, v51, v50
	v_cndmask_b32_e32 v50, v123, v50, vcc
	global_store_dword v243, v50, s[8:9] offset:2048
	s_add_u32 s8, s8, 0x1000
	s_addc_u32 s9, s9, 0
	v_mfma_f32_32x32x16_bf16 v[6:21], v[86:89], v[38:41], 0
	s_add_i32 m0, s10, 98304
	s_nop 0
	global_load_lds_dwordx4 v102, s[6:7]
	s_add_i32 m0, s10, 99328
	s_nop 0
	global_load_lds_dwordx4 v110, s[6:7]
	s_add_i32 m0, s10, 100352
	s_nop 0
	global_load_lds_dwordx4 v112, s[6:7]
	s_add_i32 m0, s10, 101376
	s_nop 0
	global_load_lds_dwordx4 v193, s[6:7]
	s_add_u32 s6, s6, 0x8000
	s_addc_u32 s7, s7, 0
	v_max_f32_e32 v108, 0, v212
	v_max_f32_e32 v109, 0, v213
	v_pk_mul_f32 v[0:1], v[22:23], v[108:109]
	v_max_f32_e32 v210, 0, v214
	v_max_f32_e32 v211, 0, v215
	v_pk_fma_f32 v[0:1], v[24:25], v[210:211], v[0:1]
	v_max_f32_e32 v108, 0, v216
	v_max_f32_e32 v109, 0, v217
	v_pk_fma_f32 v[0:1], v[26:27], v[108:109], v[0:1]
	v_mfma_f32_32x32x16_bf16 v[6:21], v[90:93], v[42:45], v[6:21]
	v_max_f32_e32 v210, 0, v218
	v_max_f32_e32 v211, 0, v219
	v_pk_fma_f32 v[0:1], v[28:29], v[210:211], v[0:1]
	v_max_f32_e32 v108, 0, v220
	v_max_f32_e32 v109, 0, v221
	v_pk_fma_f32 v[0:1], v[30:31], v[108:109], v[0:1]
	v_max_f32_e32 v210, 0, v222
	v_max_f32_e32 v211, 0, v223
	v_pk_fma_f32 v[0:1], v[32:33], v[210:211], v[0:1]
	v_mfma_f32_32x32x16_bf16 v[6:21], v[94:97], v[46:49], v[6:21]
	v_max_f32_e32 v108, 0, v224
	v_max_f32_e32 v109, 0, v225
	v_pk_fma_f32 v[0:1], v[34:35], v[108:109], v[0:1]
	v_max_f32_e32 v210, 0, v226
	v_max_f32_e32 v211, 0, v227
	v_pk_fma_f32 v[0:1], v[36:37], v[210:211], v[0:1]
	v_add_f32_e32 v0, v0, v1
	v_ashrrev_i32_e32 v1, 31, v0
	v_mfma_f32_32x32x16_bf16 v[6:21], v[98:101], v[196:199], v[6:21]
	s_waitcnt vmcnt(10)
	ds_read_b128 v[38:41], v5 offset:43264
	ds_read_b128 v[42:45], v52 offset:43264
	ds_read_b128 v[46:49], v55 offset:43264
	ds_read_b128 v[196:199], v56 offset:43264
	v_or_b32_e32 v1, 0x80000000, v1
	s_cmpk_gt_i32 s11, 32
	s_cselect_b64 vcc, -1, 0
	v_xor_b32_e32 v0, v1, v0
	v_cndmask_b32_e32 v138, v123, v0, vcc
	s_nop 3
	s_waitcnt lgkmcnt(3)
	v_mfma_f32_32x32x16_bf16 v[212:227], v[70:73], v[38:41], 0
	v_max_f32_e32 v108, 0, v6
	v_max_f32_e32 v109, 0, v7
	v_pk_mul_f32 v[50:51], v[244:245], v[108:109]
	v_max_f32_e32 v210, 0, v8
	v_max_f32_e32 v211, 0, v9
	v_pk_fma_f32 v[50:51], v[246:247], v[210:211], v[50:51]
	v_max_f32_e32 v108, 0, v10
	v_max_f32_e32 v109, 0, v11
	v_pk_fma_f32 v[50:51], v[248:249], v[108:109], v[50:51]
	s_waitcnt lgkmcnt(2)
	v_mfma_f32_32x32x16_bf16 v[212:227], v[74:77], v[42:45], v[212:227]
	v_max_f32_e32 v210, 0, v12
	v_max_f32_e32 v211, 0, v13
	v_pk_fma_f32 v[50:51], v[250:251], v[210:211], v[50:51]
	v_max_f32_e32 v108, 0, v14
	v_max_f32_e32 v109, 0, v15
	v_pk_fma_f32 v[50:51], v[252:253], v[108:109], v[50:51]
	v_max_f32_e32 v210, 0, v16
	v_max_f32_e32 v211, 0, v17
	v_pk_fma_f32 v[50:51], v[254:255], v[210:211], v[50:51]
	s_waitcnt lgkmcnt(1)
	v_mfma_f32_32x32x16_bf16 v[212:227], v[78:81], v[46:49], v[212:227]
	v_max_f32_e32 v108, 0, v18
	v_max_f32_e32 v109, 0, v19
	v_pk_fma_f32 v[50:51], v[200:201], v[108:109], v[50:51]
	v_max_f32_e32 v210, 0, v20
	v_max_f32_e32 v211, 0, v21
	v_pk_fma_f32 v[50:51], v[202:203], v[210:211], v[50:51]
	v_add_f32_e32 v50, v50, v51
	v_ashrrev_i32_e32 v51, 31, v50
	s_waitcnt lgkmcnt(0)
	v_mfma_f32_32x32x16_bf16 v[212:227], v[82:85], v[196:199], v[212:227]
	v_or_b32_e32 v51, 0x80000000, v51
	s_cmpk_gt_i32 s11, 32
	s_cselect_b64 vcc, -1, 0
	v_xor_b32_e32 v50, v51, v50
	v_cndmask_b32_e32 v50, v123, v50, vcc
	global_store_dword v243, v50, s[8:9]
	v_mfma_f32_32x32x16_bf16 v[6:21], v[86:89], v[38:41], 0
	s_add_i32 m0, s10, 0
	s_nop 0
	global_load_lds_dwordx4 v102, s[6:7]
	s_add_i32 m0, s10, 1024
	s_nop 0
	global_load_lds_dwordx4 v110, s[6:7]
	s_add_i32 m0, s10, 2048
	s_nop 0
	global_load_lds_dwordx4 v112, s[6:7]
	s_add_i32 m0, s10, 3072
	s_nop 0
	global_load_lds_dwordx4 v193, s[6:7]
	s_add_u32 s6, s6, 0x8000
	s_addc_u32 s7, s7, 0
	v_max_f32_e32 v108, 0, v212
	v_max_f32_e32 v109, 0, v213
	v_pk_mul_f32 v[0:1], v[22:23], v[108:109]
	v_max_f32_e32 v210, 0, v214
	v_max_f32_e32 v211, 0, v215
	v_pk_fma_f32 v[0:1], v[24:25], v[210:211], v[0:1]
	v_max_f32_e32 v108, 0, v216
	v_max_f32_e32 v109, 0, v217
	v_pk_fma_f32 v[0:1], v[26:27], v[108:109], v[0:1]
	v_mfma_f32_32x32x16_bf16 v[6:21], v[90:93], v[42:45], v[6:21]
	v_max_f32_e32 v210, 0, v218
	v_max_f32_e32 v211, 0, v219
	v_pk_fma_f32 v[0:1], v[28:29], v[210:211], v[0:1]
	v_max_f32_e32 v108, 0, v220
	v_max_f32_e32 v109, 0, v221
	v_pk_fma_f32 v[0:1], v[30:31], v[108:109], v[0:1]
	v_max_f32_e32 v210, 0, v222
	v_max_f32_e32 v211, 0, v223
	v_pk_fma_f32 v[0:1], v[32:33], v[210:211], v[0:1]
	v_mfma_f32_32x32x16_bf16 v[6:21], v[94:97], v[46:49], v[6:21]
	v_max_f32_e32 v108, 0, v224
	v_max_f32_e32 v109, 0, v225
	v_pk_fma_f32 v[0:1], v[34:35], v[108:109], v[0:1]
	v_max_f32_e32 v210, 0, v226
	v_max_f32_e32 v211, 0, v227
	v_pk_fma_f32 v[0:1], v[36:37], v[210:211], v[0:1]
	v_add_f32_e32 v0, v0, v1
	v_ashrrev_i32_e32 v1, 31, v0
	v_mfma_f32_32x32x16_bf16 v[6:21], v[98:101], v[196:199], v[6:21]
	s_waitcnt vmcnt(10)
	v_add_u32_e32 v228, 0x10000, v5
	ds_read_b128 v[38:41], v228 offset:10496
	v_add_u32_e32 v228, 0x10000, v52
	ds_read_b128 v[42:45], v228 offset:10496
	v_add_u32_e32 v228, 0x10000, v55
	ds_read_b128 v[46:49], v228 offset:10496
	v_add_u32_e32 v228, 0x10000, v56
	ds_read_b128 v[196:199], v228 offset:10496
	v_or_b32_e32 v1, 0x80000000, v1
	s_cmpk_gt_i32 s11, 40
	s_cselect_b64 vcc, -1, 0
	v_xor_b32_e32 v0, v1, v0
	v_cndmask_b32_e32 v137, v123, v0, vcc
	s_nop 3
	s_waitcnt lgkmcnt(3)
	v_mfma_f32_32x32x16_bf16 v[212:227], v[70:73], v[38:41], 0
	v_max_f32_e32 v108, 0, v6
	v_max_f32_e32 v109, 0, v7
	v_pk_mul_f32 v[50:51], v[244:245], v[108:109]
	v_max_f32_e32 v210, 0, v8
	v_max_f32_e32 v211, 0, v9
	v_pk_fma_f32 v[50:51], v[246:247], v[210:211], v[50:51]
	v_max_f32_e32 v108, 0, v10
	v_max_f32_e32 v109, 0, v11
	v_pk_fma_f32 v[50:51], v[248:249], v[108:109], v[50:51]
	s_waitcnt lgkmcnt(2)
	v_mfma_f32_32x32x16_bf16 v[212:227], v[74:77], v[42:45], v[212:227]
	v_max_f32_e32 v210, 0, v12
	v_max_f32_e32 v211, 0, v13
	v_pk_fma_f32 v[50:51], v[250:251], v[210:211], v[50:51]
	v_max_f32_e32 v108, 0, v14
	v_max_f32_e32 v109, 0, v15
	v_pk_fma_f32 v[50:51], v[252:253], v[108:109], v[50:51]
	v_max_f32_e32 v210, 0, v16
	v_max_f32_e32 v211, 0, v17
	v_pk_fma_f32 v[50:51], v[254:255], v[210:211], v[50:51]
	s_waitcnt lgkmcnt(1)
	v_mfma_f32_32x32x16_bf16 v[212:227], v[78:81], v[46:49], v[212:227]
	v_max_f32_e32 v108, 0, v18
	v_max_f32_e32 v109, 0, v19
	v_pk_fma_f32 v[50:51], v[200:201], v[108:109], v[50:51]
	v_max_f32_e32 v210, 0, v20
	v_max_f32_e32 v211, 0, v21
	v_pk_fma_f32 v[50:51], v[202:203], v[210:211], v[50:51]
	v_add_f32_e32 v50, v50, v51
	v_ashrrev_i32_e32 v51, 31, v50
	s_waitcnt lgkmcnt(0)
	v_mfma_f32_32x32x16_bf16 v[212:227], v[82:85], v[196:199], v[212:227]
	v_or_b32_e32 v51, 0x80000000, v51
	s_cmpk_gt_i32 s11, 40
	s_cselect_b64 vcc, -1, 0
	v_xor_b32_e32 v50, v51, v50
	v_cndmask_b32_e32 v50, v123, v50, vcc
	global_store_dword v243, v50, s[8:9] offset:2048
	s_add_u32 s8, s8, 0x1000
	s_addc_u32 s9, s9, 0
	v_mfma_f32_32x32x16_bf16 v[6:21], v[86:89], v[38:41], 0
	s_add_i32 m0, s10, 32768
	s_nop 0
	global_load_lds_dwordx4 v102, s[6:7]
	s_add_i32 m0, s10, 33792
	s_nop 0
	global_load_lds_dwordx4 v110, s[6:7]
	s_add_i32 m0, s10, 34816
	s_nop 0
	global_load_lds_dwordx4 v112, s[6:7]
	s_add_i32 m0, s10, 35840
	s_nop 0
	global_load_lds_dwordx4 v193, s[6:7]
	s_add_u32 s6, s6, 0x8000
	s_addc_u32 s7, s7, 0
	v_max_f32_e32 v108, 0, v212
	v_max_f32_e32 v109, 0, v213
	v_pk_mul_f32 v[0:1], v[22:23], v[108:109]
	v_max_f32_e32 v210, 0, v214
	v_max_f32_e32 v211, 0, v215
	v_pk_fma_f32 v[0:1], v[24:25], v[210:211], v[0:1]
	v_max_f32_e32 v108, 0, v216
	v_max_f32_e32 v109, 0, v217
	v_pk_fma_f32 v[0:1], v[26:27], v[108:109], v[0:1]
	v_mfma_f32_32x32x16_bf16 v[6:21], v[90:93], v[42:45], v[6:21]
	v_max_f32_e32 v210, 0, v218
	v_max_f32_e32 v211, 0, v219
	v_pk_fma_f32 v[0:1], v[28:29], v[210:211], v[0:1]
	v_max_f32_e32 v108, 0, v220
	v_max_f32_e32 v109, 0, v221
	v_pk_fma_f32 v[0:1], v[30:31], v[108:109], v[0:1]
	v_max_f32_e32 v210, 0, v222
	v_max_f32_e32 v211, 0, v223
	v_pk_fma_f32 v[0:1], v[32:33], v[210:211], v[0:1]
	v_mfma_f32_32x32x16_bf16 v[6:21], v[94:97], v[46:49], v[6:21]
	v_max_f32_e32 v108, 0, v224
	v_max_f32_e32 v109, 0, v225
	v_pk_fma_f32 v[0:1], v[34:35], v[108:109], v[0:1]
	v_max_f32_e32 v210, 0, v226
	v_max_f32_e32 v211, 0, v227
	v_pk_fma_f32 v[0:1], v[36:37], v[210:211], v[0:1]
	v_add_f32_e32 v0, v0, v1
	v_ashrrev_i32_e32 v1, 31, v0
	v_mfma_f32_32x32x16_bf16 v[6:21], v[98:101], v[196:199], v[6:21]
	s_waitcnt vmcnt(10)
	v_add_u32_e32 v228, 0x10000, v5
	ds_read_b128 v[38:41], v228 offset:43264
	v_add_u32_e32 v228, 0x10000, v52
	ds_read_b128 v[42:45], v228 offset:43264
	v_add_u32_e32 v228, 0x10000, v55
	ds_read_b128 v[46:49], v228 offset:43264
	v_add_u32_e32 v228, 0x10000, v56
	ds_read_b128 v[196:199], v228 offset:43264
	v_or_b32_e32 v1, 0x80000000, v1
	s_cmpk_gt_i32 s11, 48
	s_cselect_b64 vcc, -1, 0
	v_xor_b32_e32 v0, v1, v0
	v_cndmask_b32_e32 v140, v123, v0, vcc
	s_nop 3
	s_waitcnt lgkmcnt(3)
	v_mfma_f32_32x32x16_bf16 v[212:227], v[70:73], v[38:41], 0
	v_max_f32_e32 v108, 0, v6
	v_max_f32_e32 v109, 0, v7
	v_pk_mul_f32 v[50:51], v[244:245], v[108:109]
	v_max_f32_e32 v210, 0, v8
	v_max_f32_e32 v211, 0, v9
	v_pk_fma_f32 v[50:51], v[246:247], v[210:211], v[50:51]
	v_max_f32_e32 v108, 0, v10
	v_max_f32_e32 v109, 0, v11
	v_pk_fma_f32 v[50:51], v[248:249], v[108:109], v[50:51]
	s_waitcnt lgkmcnt(2)
	v_mfma_f32_32x32x16_bf16 v[212:227], v[74:77], v[42:45], v[212:227]
	v_max_f32_e32 v210, 0, v12
	v_max_f32_e32 v211, 0, v13
	v_pk_fma_f32 v[50:51], v[250:251], v[210:211], v[50:51]
	v_max_f32_e32 v108, 0, v14
	v_max_f32_e32 v109, 0, v15
	v_pk_fma_f32 v[50:51], v[252:253], v[108:109], v[50:51]
	v_max_f32_e32 v210, 0, v16
	v_max_f32_e32 v211, 0, v17
	v_pk_fma_f32 v[50:51], v[254:255], v[210:211], v[50:51]
	s_waitcnt lgkmcnt(1)
	v_mfma_f32_32x32x16_bf16 v[212:227], v[78:81], v[46:49], v[212:227]
	v_max_f32_e32 v108, 0, v18
	v_max_f32_e32 v109, 0, v19
	v_pk_fma_f32 v[50:51], v[200:201], v[108:109], v[50:51]
	v_max_f32_e32 v210, 0, v20
	v_max_f32_e32 v211, 0, v21
	v_pk_fma_f32 v[50:51], v[202:203], v[210:211], v[50:51]
	v_add_f32_e32 v50, v50, v51
	v_ashrrev_i32_e32 v51, 31, v50
	s_waitcnt lgkmcnt(0)
	v_mfma_f32_32x32x16_bf16 v[212:227], v[82:85], v[196:199], v[212:227]
	v_or_b32_e32 v51, 0x80000000, v51
	s_cmpk_gt_i32 s11, 48
	s_cselect_b64 vcc, -1, 0
	v_xor_b32_e32 v50, v51, v50
	v_cndmask_b32_e32 v50, v123, v50, vcc
	global_store_dword v243, v50, s[8:9]
	v_mfma_f32_32x32x16_bf16 v[6:21], v[86:89], v[38:41], 0
	s_add_i32 m0, s10, 65536
	s_nop 0
	global_load_lds_dwordx4 v102, s[6:7]
	s_add_i32 m0, s10, 66560
	s_nop 0
	global_load_lds_dwordx4 v110, s[6:7]
	s_add_i32 m0, s10, 67584
	s_nop 0
	global_load_lds_dwordx4 v112, s[6:7]
	s_add_i32 m0, s10, 68608
	s_nop 0
	global_load_lds_dwordx4 v193, s[6:7]
	s_add_u32 s6, s6, 0x8000
	s_addc_u32 s7, s7, 0
	v_max_f32_e32 v108, 0, v212
	v_max_f32_e32 v109, 0, v213
	v_pk_mul_f32 v[0:1], v[22:23], v[108:109]
	v_max_f32_e32 v210, 0, v214
	v_max_f32_e32 v211, 0, v215
	v_pk_fma_f32 v[0:1], v[24:25], v[210:211], v[0:1]
	v_max_f32_e32 v108, 0, v216
	v_max_f32_e32 v109, 0, v217
	v_pk_fma_f32 v[0:1], v[26:27], v[108:109], v[0:1]
	v_mfma_f32_32x32x16_bf16 v[6:21], v[90:93], v[42:45], v[6:21]
	v_max_f32_e32 v210, 0, v218
	v_max_f32_e32 v211, 0, v219
	v_pk_fma_f32 v[0:1], v[28:29], v[210:211], v[0:1]
	v_max_f32_e32 v108, 0, v220
	v_max_f32_e32 v109, 0, v221
	v_pk_fma_f32 v[0:1], v[30:31], v[108:109], v[0:1]
	v_max_f32_e32 v210, 0, v222
	v_max_f32_e32 v211, 0, v223
	v_pk_fma_f32 v[0:1], v[32:33], v[210:211], v[0:1]
	v_mfma_f32_32x32x16_bf16 v[6:21], v[94:97], v[46:49], v[6:21]
	v_max_f32_e32 v108, 0, v224
	v_max_f32_e32 v109, 0, v225
	v_pk_fma_f32 v[0:1], v[34:35], v[108:109], v[0:1]
	v_max_f32_e32 v210, 0, v226
	v_max_f32_e32 v211, 0, v227
	v_pk_fma_f32 v[0:1], v[36:37], v[210:211], v[0:1]
	v_add_f32_e32 v0, v0, v1
	v_ashrrev_i32_e32 v1, 31, v0
	v_mfma_f32_32x32x16_bf16 v[6:21], v[98:101], v[196:199], v[6:21]
	s_waitcnt vmcnt(10)
	ds_read_b128 v[38:41], v5 offset:10496
	ds_read_b128 v[42:45], v52 offset:10496
	ds_read_b128 v[46:49], v55 offset:10496
	ds_read_b128 v[196:199], v56 offset:10496
	v_or_b32_e32 v1, 0x80000000, v1
	s_cmpk_gt_i32 s11, 56
	s_cselect_b64 vcc, -1, 0
	v_xor_b32_e32 v0, v1, v0
	v_cndmask_b32_e32 v139, v123, v0, vcc
	s_nop 3
	v_max_f32_e32 v108, 0, v6
	v_max_f32_e32 v109, 0, v7
	v_pk_mul_f32 v[50:51], v[244:245], v[108:109]
	v_max_f32_e32 v210, 0, v8
	v_max_f32_e32 v211, 0, v9
	v_pk_fma_f32 v[50:51], v[246:247], v[210:211], v[50:51]
	v_max_f32_e32 v108, 0, v10
	v_max_f32_e32 v109, 0, v11
	v_pk_fma_f32 v[50:51], v[248:249], v[108:109], v[50:51]
	v_max_f32_e32 v210, 0, v12
	v_max_f32_e32 v211, 0, v13
	v_pk_fma_f32 v[50:51], v[250:251], v[210:211], v[50:51]
	v_max_f32_e32 v108, 0, v14
	v_max_f32_e32 v109, 0, v15
	v_pk_fma_f32 v[50:51], v[252:253], v[108:109], v[50:51]
	v_max_f32_e32 v210, 0, v16
	v_max_f32_e32 v211, 0, v17
	v_pk_fma_f32 v[50:51], v[254:255], v[210:211], v[50:51]
	v_max_f32_e32 v108, 0, v18
	v_max_f32_e32 v109, 0, v19
	v_pk_fma_f32 v[50:51], v[200:201], v[108:109], v[50:51]
	v_max_f32_e32 v210, 0, v20
	v_max_f32_e32 v211, 0, v21
	v_pk_fma_f32 v[50:51], v[202:203], v[210:211], v[50:51]
	v_add_f32_e32 v50, v50, v51
	v_ashrrev_i32_e32 v51, 31, v50
	v_or_b32_e32 v51, 0x80000000, v51
	s_cmpk_gt_i32 s11, 56
	s_cselect_b64 vcc, -1, 0
	v_xor_b32_e32 v50, v51, v50
	v_cndmask_b32_e32 v50, v123, v50, vcc
	global_store_dword v243, v50, s[8:9] offset:2048
	s_add_u32 s8, s8, 0x1000
	s_addc_u32 s9, s9, 0
	s_cmpk_gt_i32 s81, 8
	s_cbranch_scc0 .Lix_fill_1
	s_waitcnt lgkmcnt(3)
	v_mfma_f32_32x32x16_bf16 v[212:227], v[70:73], v[38:41], 0
	s_add_i32 m0, s10, 98304
	s_nop 0
	global_load_lds_dwordx4 v102, s[6:7]
	s_waitcnt lgkmcnt(2)
	v_mfma_f32_32x32x16_bf16 v[212:227], v[74:77], v[42:45], v[212:227]
	s_add_i32 m0, s10, 99328
	s_nop 0
	global_load_lds_dwordx4 v110, s[6:7]
	s_waitcnt lgkmcnt(1)
	v_mfma_f32_32x32x16_bf16 v[212:227], v[78:81], v[46:49], v[212:227]
	s_add_i32 m0, s10, 100352
	s_nop 0
	global_load_lds_dwordx4 v112, s[6:7]
	s_waitcnt lgkmcnt(0)
	v_mfma_f32_32x32x16_bf16 v[212:227], v[82:85], v[196:199], v[212:227]
	s_add_i32 m0, s10, 101376
	s_nop 0
	global_load_lds_dwordx4 v193, s[6:7]
	s_add_u32 s6, s6, 0x8000
	s_addc_u32 s7, s7, 0
	v_mfma_f32_32x32x16_bf16 v[6:21], v[86:89], v[38:41], 0
	s_nop 7
	s_nop 2
	v_max_f32_e32 v108, 0, v212
	v_max_f32_e32 v109, 0, v213
	v_pk_mul_f32 v[0:1], v[22:23], v[108:109]
	v_max_f32_e32 v210, 0, v214
	v_max_f32_e32 v211, 0, v215
	v_pk_fma_f32 v[0:1], v[24:25], v[210:211], v[0:1]
	v_max_f32_e32 v108, 0, v216
	v_max_f32_e32 v109, 0, v217
	v_pk_fma_f32 v[0:1], v[26:27], v[108:109], v[0:1]
	v_mfma_f32_32x32x16_bf16 v[6:21], v[90:93], v[42:45], v[6:21]
	v_max_f32_e32 v210, 0, v218
	v_max_f32_e32 v211, 0, v219
	v_pk_fma_f32 v[0:1], v[28:29], v[210:211], v[0:1]
	v_max_f32_e32 v108, 0, v220
	v_max_f32_e32 v109, 0, v221
	v_pk_fma_f32 v[0:1], v[30:31], v[108:109], v[0:1]
	v_max_f32_e32 v210, 0, v222
	v_max_f32_e32 v211, 0, v223
	v_pk_fma_f32 v[0:1], v[32:33], v[210:211], v[0:1]
	v_mfma_f32_32x32x16_bf16 v[6:21], v[94:97], v[46:49], v[6:21]
	v_max_f32_e32 v108, 0, v224
	v_max_f32_e32 v109, 0, v225
	v_pk_fma_f32 v[0:1], v[34:35], v[108:109], v[0:1]
	v_max_f32_e32 v210, 0, v226
	v_max_f32_e32 v211, 0, v227
	v_pk_fma_f32 v[0:1], v[36:37], v[210:211], v[0:1]
	v_add_f32_e32 v0, v0, v1
	v_ashrrev_i32_e32 v1, 31, v0
	v_mfma_f32_32x32x16_bf16 v[6:21], v[98:101], v[196:199], v[6:21]
	s_waitcnt vmcnt(10)
	ds_read_b128 v[38:41], v5 offset:43264
	ds_read_b128 v[42:45], v52 offset:43264
	ds_read_b128 v[46:49], v55 offset:43264
	ds_read_b128 v[196:199], v56 offset:43264
	v_or_b32_e32 v1, 0x80000000, v1
	s_cmpk_gt_i32 s11, 64
	s_cselect_b64 vcc, -1, 0
	v_xor_b32_e32 v0, v1, v0
	v_cndmask_b32_e32 v142, v123, v0, vcc
	s_nop 3
	s_waitcnt lgkmcnt(3)
	v_mfma_f32_32x32x16_bf16 v[212:227], v[70:73], v[38:41], 0
	v_max_f32_e32 v108, 0, v6
	v_max_f32_e32 v109, 0, v7
	v_pk_mul_f32 v[50:51], v[244:245], v[108:109]
	v_max_f32_e32 v210, 0, v8
	v_max_f32_e32 v211, 0, v9
	v_pk_fma_f32 v[50:51], v[246:247], v[210:211], v[50:51]
	v_max_f32_e32 v108, 0, v10
	v_max_f32_e32 v109, 0, v11
	v_pk_fma_f32 v[50:51], v[248:249], v[108:109], v[50:51]
	s_waitcnt lgkmcnt(2)
	v_mfma_f32_32x32x16_bf16 v[212:227], v[74:77], v[42:45], v[212:227]
	v_max_f32_e32 v210, 0, v12
	v_max_f32_e32 v211, 0, v13
	v_pk_fma_f32 v[50:51], v[250:251], v[210:211], v[50:51]
	v_max_f32_e32 v108, 0, v14
	v_max_f32_e32 v109, 0, v15
	v_pk_fma_f32 v[50:51], v[252:253], v[108:109], v[50:51]
	v_max_f32_e32 v210, 0, v16
	v_max_f32_e32 v211, 0, v17
	v_pk_fma_f32 v[50:51], v[254:255], v[210:211], v[50:51]
	s_waitcnt lgkmcnt(1)
	v_mfma_f32_32x32x16_bf16 v[212:227], v[78:81], v[46:49], v[212:227]
	v_max_f32_e32 v108, 0, v18
	v_max_f32_e32 v109, 0, v19
	v_pk_fma_f32 v[50:51], v[200:201], v[108:109], v[50:51]
	v_max_f32_e32 v210, 0, v20
	v_max_f32_e32 v211, 0, v21
	v_pk_fma_f32 v[50:51], v[202:203], v[210:211], v[50:51]
	v_add_f32_e32 v50, v50, v51
	v_ashrrev_i32_e32 v51, 31, v50
	s_waitcnt lgkmcnt(0)
	v_mfma_f32_32x32x16_bf16 v[212:227], v[82:85], v[196:199], v[212:227]
	v_or_b32_e32 v51, 0x80000000, v51
	s_cmpk_gt_i32 s11, 64
	s_cselect_b64 vcc, -1, 0
	v_xor_b32_e32 v50, v51, v50
	v_cndmask_b32_e32 v50, v123, v50, vcc
	global_store_dword v243, v50, s[8:9]
	v_mfma_f32_32x32x16_bf16 v[6:21], v[86:89], v[38:41], 0
	s_add_i32 m0, s10, 0
	s_nop 0
	global_load_lds_dwordx4 v102, s[6:7]
	s_add_i32 m0, s10, 1024
	s_nop 0
	global_load_lds_dwordx4 v110, s[6:7]
	s_add_i32 m0, s10, 2048
	s_nop 0
	global_load_lds_dwordx4 v112, s[6:7]
	s_add_i32 m0, s10, 3072
	s_nop 0
	global_load_lds_dwordx4 v193, s[6:7]
	s_add_u32 s6, s6, 0x8000
	s_addc_u32 s7, s7, 0
	v_max_f32_e32 v108, 0, v212
	v_max_f32_e32 v109, 0, v213
	v_pk_mul_f32 v[0:1], v[22:23], v[108:109]
	v_max_f32_e32 v210, 0, v214
	v_max_f32_e32 v211, 0, v215
	v_pk_fma_f32 v[0:1], v[24:25], v[210:211], v[0:1]
	v_max_f32_e32 v108, 0, v216
	v_max_f32_e32 v109, 0, v217
	v_pk_fma_f32 v[0:1], v[26:27], v[108:109], v[0:1]
	v_mfma_f32_32x32x16_bf16 v[6:21], v[90:93], v[42:45], v[6:21]
	v_max_f32_e32 v210, 0, v218
	v_max_f32_e32 v211, 0, v219
	v_pk_fma_f32 v[0:1], v[28:29], v[210:211], v[0:1]
	v_max_f32_e32 v108, 0, v220
	v_max_f32_e32 v109, 0, v221
	v_pk_fma_f32 v[0:1], v[30:31], v[108:109], v[0:1]
	v_max_f32_e32 v210, 0, v222
	v_max_f32_e32 v211, 0, v223
	v_pk_fma_f32 v[0:1], v[32:33], v[210:211], v[0:1]
	v_mfma_f32_32x32x16_bf16 v[6:21], v[94:97], v[46:49], v[6:21]
	v_max_f32_e32 v108, 0, v224
	v_max_f32_e32 v109, 0, v225
	v_pk_fma_f32 v[0:1], v[34:35], v[108:109], v[0:1]
	v_max_f32_e32 v210, 0, v226
	v_max_f32_e32 v211, 0, v227
	v_pk_fma_f32 v[0:1], v[36:37], v[210:211], v[0:1]
	v_add_f32_e32 v0, v0, v1
	v_ashrrev_i32_e32 v1, 31, v0
	v_mfma_f32_32x32x16_bf16 v[6:21], v[98:101], v[196:199], v[6:21]
	s_waitcnt vmcnt(10)
	v_add_u32_e32 v228, 0x10000, v5
	ds_read_b128 v[38:41], v228 offset:10496
	v_add_u32_e32 v228, 0x10000, v52
	ds_read_b128 v[42:45], v228 offset:10496
	v_add_u32_e32 v228, 0x10000, v55
	ds_read_b128 v[46:49], v228 offset:10496
	v_add_u32_e32 v228, 0x10000, v56
	ds_read_b128 v[196:199], v228 offset:10496
	v_or_b32_e32 v1, 0x80000000, v1
	s_cmpk_gt_i32 s11, 72
	s_cselect_b64 vcc, -1, 0
	v_xor_b32_e32 v0, v1, v0
	v_cndmask_b32_e32 v141, v123, v0, vcc
	s_nop 3
	s_waitcnt lgkmcnt(3)
	v_mfma_f32_32x32x16_bf16 v[212:227], v[70:73], v[38:41], 0
	v_max_f32_e32 v108, 0, v6
	v_max_f32_e32 v109, 0, v7
	v_pk_mul_f32 v[50:51], v[244:245], v[108:109]
	v_max_f32_e32 v210, 0, v8
	v_max_f32_e32 v211, 0, v9
	v_pk_fma_f32 v[50:51], v[246:247], v[210:211], v[50:51]
	v_max_f32_e32 v108, 0, v10
	v_max_f32_e32 v109, 0, v11
	v_pk_fma_f32 v[50:51], v[248:249], v[108:109], v[50:51]
	s_waitcnt lgkmcnt(2)
	v_mfma_f32_32x32x16_bf16 v[212:227], v[74:77], v[42:45], v[212:227]
	v_max_f32_e32 v210, 0, v12
	v_max_f32_e32 v211, 0, v13
	v_pk_fma_f32 v[50:51], v[250:251], v[210:211], v[50:51]
	v_max_f32_e32 v108, 0, v14
	v_max_f32_e32 v109, 0, v15
	v_pk_fma_f32 v[50:51], v[252:253], v[108:109], v[50:51]
	v_max_f32_e32 v210, 0, v16
	v_max_f32_e32 v211, 0, v17
	v_pk_fma_f32 v[50:51], v[254:255], v[210:211], v[50:51]
	s_waitcnt lgkmcnt(1)
	v_mfma_f32_32x32x16_bf16 v[212:227], v[78:81], v[46:49], v[212:227]
	v_max_f32_e32 v108, 0, v18
	v_max_f32_e32 v109, 0, v19
	v_pk_fma_f32 v[50:51], v[200:201], v[108:109], v[50:51]
	v_max_f32_e32 v210, 0, v20
	v_max_f32_e32 v211, 0, v21
	v_pk_fma_f32 v[50:51], v[202:203], v[210:211], v[50:51]
	v_add_f32_e32 v50, v50, v51
	v_ashrrev_i32_e32 v51, 31, v50
	s_waitcnt lgkmcnt(0)
	v_mfma_f32_32x32x16_bf16 v[212:227], v[82:85], v[196:199], v[212:227]
	v_or_b32_e32 v51, 0x80000000, v51
	s_cmpk_gt_i32 s11, 72
	s_cselect_b64 vcc, -1, 0
	v_xor_b32_e32 v50, v51, v50
	v_cndmask_b32_e32 v50, v123, v50, vcc
	global_store_dword v243, v50, s[8:9] offset:2048
	s_add_u32 s8, s8, 0x1000
	s_addc_u32 s9, s9, 0
	v_mfma_f32_32x32x16_bf16 v[6:21], v[86:89], v[38:41], 0
	s_add_i32 m0, s10, 32768
	s_nop 0
	global_load_lds_dwordx4 v102, s[6:7]
	s_add_i32 m0, s10, 33792
	s_nop 0
	global_load_lds_dwordx4 v110, s[6:7]
	s_add_i32 m0, s10, 34816
	s_nop 0
	global_load_lds_dwordx4 v112, s[6:7]
	s_add_i32 m0, s10, 35840
	s_nop 0
	global_load_lds_dwordx4 v193, s[6:7]
	s_add_u32 s6, s6, 0x8000
	s_addc_u32 s7, s7, 0
	v_max_f32_e32 v108, 0, v212
	v_max_f32_e32 v109, 0, v213
	v_pk_mul_f32 v[0:1], v[22:23], v[108:109]
	v_max_f32_e32 v210, 0, v214
	v_max_f32_e32 v211, 0, v215
	v_pk_fma_f32 v[0:1], v[24:25], v[210:211], v[0:1]
	v_max_f32_e32 v108, 0, v216
	v_max_f32_e32 v109, 0, v217
	v_pk_fma_f32 v[0:1], v[26:27], v[108:109], v[0:1]
	v_mfma_f32_32x32x16_bf16 v[6:21], v[90:93], v[42:45], v[6:21]
	v_max_f32_e32 v210, 0, v218
	v_max_f32_e32 v211, 0, v219
	v_pk_fma_f32 v[0:1], v[28:29], v[210:211], v[0:1]
	v_max_f32_e32 v108, 0, v220
	v_max_f32_e32 v109, 0, v221
	v_pk_fma_f32 v[0:1], v[30:31], v[108:109], v[0:1]
	v_max_f32_e32 v210, 0, v222
	v_max_f32_e32 v211, 0, v223
	v_pk_fma_f32 v[0:1], v[32:33], v[210:211], v[0:1]
	v_mfma_f32_32x32x16_bf16 v[6:21], v[94:97], v[46:49], v[6:21]
	v_max_f32_e32 v108, 0, v224
	v_max_f32_e32 v109, 0, v225
	v_pk_fma_f32 v[0:1], v[34:35], v[108:109], v[0:1]
	v_max_f32_e32 v210, 0, v226
	v_max_f32_e32 v211, 0, v227
	v_pk_fma_f32 v[0:1], v[36:37], v[210:211], v[0:1]
	v_add_f32_e32 v0, v0, v1
	v_ashrrev_i32_e32 v1, 31, v0
	v_mfma_f32_32x32x16_bf16 v[6:21], v[98:101], v[196:199], v[6:21]
	s_waitcnt vmcnt(10)
	v_add_u32_e32 v228, 0x10000, v5
	ds_read_b128 v[38:41], v228 offset:43264
	v_add_u32_e32 v228, 0x10000, v52
	ds_read_b128 v[42:45], v228 offset:43264
	v_add_u32_e32 v228, 0x10000, v55
	ds_read_b128 v[46:49], v228 offset:43264
	v_add_u32_e32 v228, 0x10000, v56
	ds_read_b128 v[196:199], v228 offset:43264
	v_or_b32_e32 v1, 0x80000000, v1
	s_cmpk_gt_i32 s11, 80
	s_cselect_b64 vcc, -1, 0
	v_xor_b32_e32 v0, v1, v0
	v_cndmask_b32_e32 v144, v123, v0, vcc
	s_nop 3
	s_waitcnt lgkmcnt(3)
	v_mfma_f32_32x32x16_bf16 v[212:227], v[70:73], v[38:41], 0
	v_max_f32_e32 v108, 0, v6
	v_max_f32_e32 v109, 0, v7
	v_pk_mul_f32 v[50:51], v[244:245], v[108:109]
	v_max_f32_e32 v210, 0, v8
	v_max_f32_e32 v211, 0, v9
	v_pk_fma_f32 v[50:51], v[246:247], v[210:211], v[50:51]
	v_max_f32_e32 v108, 0, v10
	v_max_f32_e32 v109, 0, v11
	v_pk_fma_f32 v[50:51], v[248:249], v[108:109], v[50:51]
	s_waitcnt lgkmcnt(2)
	v_mfma_f32_32x32x16_bf16 v[212:227], v[74:77], v[42:45], v[212:227]
	v_max_f32_e32 v210, 0, v12
	v_max_f32_e32 v211, 0, v13
	v_pk_fma_f32 v[50:51], v[250:251], v[210:211], v[50:51]
	v_max_f32_e32 v108, 0, v14
	v_max_f32_e32 v109, 0, v15
	v_pk_fma_f32 v[50:51], v[252:253], v[108:109], v[50:51]
	v_max_f32_e32 v210, 0, v16
	v_max_f32_e32 v211, 0, v17
	v_pk_fma_f32 v[50:51], v[254:255], v[210:211], v[50:51]
	s_waitcnt lgkmcnt(1)
	v_mfma_f32_32x32x16_bf16 v[212:227], v[78:81], v[46:49], v[212:227]
	v_max_f32_e32 v108, 0, v18
	v_max_f32_e32 v109, 0, v19
	v_pk_fma_f32 v[50:51], v[200:201], v[108:109], v[50:51]
	v_max_f32_e32 v210, 0, v20
	v_max_f32_e32 v211, 0, v21
	v_pk_fma_f32 v[50:51], v[202:203], v[210:211], v[50:51]
	v_add_f32_e32 v50, v50, v51
	v_ashrrev_i32_e32 v51, 31, v50
	s_waitcnt lgkmcnt(0)
	v_mfma_f32_32x32x16_bf16 v[212:227], v[82:85], v[196:199], v[212:227]
	v_or_b32_e32 v51, 0x80000000, v51
	s_cmpk_gt_i32 s11, 80
	s_cselect_b64 vcc, -1, 0
	v_xor_b32_e32 v50, v51, v50
	v_cndmask_b32_e32 v50, v123, v50, vcc
	global_store_dword v243, v50, s[8:9]
	v_mfma_f32_32x32x16_bf16 v[6:21], v[86:89], v[38:41], 0
	s_add_i32 m0, s10, 65536
	s_nop 0
	global_load_lds_dwordx4 v102, s[6:7]
	s_add_i32 m0, s10, 66560
	s_nop 0
	global_load_lds_dwordx4 v110, s[6:7]
	s_add_i32 m0, s10, 67584
	s_nop 0
	global_load_lds_dwordx4 v112, s[6:7]
	s_add_i32 m0, s10, 68608
	s_nop 0
	global_load_lds_dwordx4 v193, s[6:7]
	s_add_u32 s6, s6, 0x8000
	s_addc_u32 s7, s7, 0
	v_max_f32_e32 v108, 0, v212
	v_max_f32_e32 v109, 0, v213
	v_pk_mul_f32 v[0:1], v[22:23], v[108:109]
	v_max_f32_e32 v210, 0, v214
	v_max_f32_e32 v211, 0, v215
	v_pk_fma_f32 v[0:1], v[24:25], v[210:211], v[0:1]
	v_max_f32_e32 v108, 0, v216
	v_max_f32_e32 v109, 0, v217
	v_pk_fma_f32 v[0:1], v[26:27], v[108:109], v[0:1]
	v_mfma_f32_32x32x16_bf16 v[6:21], v[90:93], v[42:45], v[6:21]
	v_max_f32_e32 v210, 0, v218
	v_max_f32_e32 v211, 0, v219
	v_pk_fma_f32 v[0:1], v[28:29], v[210:211], v[0:1]
	v_max_f32_e32 v108, 0, v220
	v_max_f32_e32 v109, 0, v221
	v_pk_fma_f32 v[0:1], v[30:31], v[108:109], v[0:1]
	v_max_f32_e32 v210, 0, v222
	v_max_f32_e32 v211, 0, v223
	v_pk_fma_f32 v[0:1], v[32:33], v[210:211], v[0:1]
	v_mfma_f32_32x32x16_bf16 v[6:21], v[94:97], v[46:49], v[6:21]
	v_max_f32_e32 v108, 0, v224
	v_max_f32_e32 v109, 0, v225
	v_pk_fma_f32 v[0:1], v[34:35], v[108:109], v[0:1]
	v_max_f32_e32 v210, 0, v226
	v_max_f32_e32 v211, 0, v227
	v_pk_fma_f32 v[0:1], v[36:37], v[210:211], v[0:1]
	v_add_f32_e32 v0, v0, v1
	v_ashrrev_i32_e32 v1, 31, v0
	v_mfma_f32_32x32x16_bf16 v[6:21], v[98:101], v[196:199], v[6:21]
	s_waitcnt vmcnt(10)
	ds_read_b128 v[38:41], v5 offset:10496
	ds_read_b128 v[42:45], v52 offset:10496
	ds_read_b128 v[46:49], v55 offset:10496
	ds_read_b128 v[196:199], v56 offset:10496
	v_or_b32_e32 v1, 0x80000000, v1
	s_cmpk_gt_i32 s11, 88
	s_cselect_b64 vcc, -1, 0
	v_xor_b32_e32 v0, v1, v0
	v_cndmask_b32_e32 v143, v123, v0, vcc
	s_nop 3
	s_waitcnt lgkmcnt(3)
	v_mfma_f32_32x32x16_bf16 v[212:227], v[70:73], v[38:41], 0
	v_max_f32_e32 v108, 0, v6
	v_max_f32_e32 v109, 0, v7
	v_pk_mul_f32 v[50:51], v[244:245], v[108:109]
	v_max_f32_e32 v210, 0, v8
	v_max_f32_e32 v211, 0, v9
	v_pk_fma_f32 v[50:51], v[246:247], v[210:211], v[50:51]
	v_max_f32_e32 v108, 0, v10
	v_max_f32_e32 v109, 0, v11
	v_pk_fma_f32 v[50:51], v[248:249], v[108:109], v[50:51]
	s_waitcnt lgkmcnt(2)
	v_mfma_f32_32x32x16_bf16 v[212:227], v[74:77], v[42:45], v[212:227]
	v_max_f32_e32 v210, 0, v12
	v_max_f32_e32 v211, 0, v13
	v_pk_fma_f32 v[50:51], v[250:251], v[210:211], v[50:51]
	v_max_f32_e32 v108, 0, v14
	v_max_f32_e32 v109, 0, v15
	v_pk_fma_f32 v[50:51], v[252:253], v[108:109], v[50:51]
	v_max_f32_e32 v210, 0, v16
	v_max_f32_e32 v211, 0, v17
	v_pk_fma_f32 v[50:51], v[254:255], v[210:211], v[50:51]
	s_waitcnt lgkmcnt(1)
	v_mfma_f32_32x32x16_bf16 v[212:227], v[78:81], v[46:49], v[212:227]
	v_max_f32_e32 v108, 0, v18
	v_max_f32_e32 v109, 0, v19
	v_pk_fma_f32 v[50:51], v[200:201], v[108:109], v[50:51]
	v_max_f32_e32 v210, 0, v20
	v_max_f32_e32 v211, 0, v21
	v_pk_fma_f32 v[50:51], v[202:203], v[210:211], v[50:51]
	v_add_f32_e32 v50, v50, v51
	v_ashrrev_i32_e32 v51, 31, v50
	s_waitcnt lgkmcnt(0)
	v_mfma_f32_32x32x16_bf16 v[212:227], v[82:85], v[196:199], v[212:227]
	v_or_b32_e32 v51, 0x80000000, v51
	s_cmpk_gt_i32 s11, 88
	s_cselect_b64 vcc, -1, 0
	v_xor_b32_e32 v50, v51, v50
	v_cndmask_b32_e32 v50, v123, v50, vcc
	global_store_dword v243, v50, s[8:9] offset:2048
	s_add_u32 s8, s8, 0x1000
	s_addc_u32 s9, s9, 0
	v_mfma_f32_32x32x16_bf16 v[6:21], v[86:89], v[38:41], 0
	s_add_i32 m0, s10, 98304
	s_nop 0
	global_load_lds_dwordx4 v102, s[6:7]
	s_add_i32 m0, s10, 99328
	s_nop 0
	global_load_lds_dwordx4 v110, s[6:7]
	s_add_i32 m0, s10, 100352
	s_nop 0
	global_load_lds_dwordx4 v112, s[6:7]
	s_add_i32 m0, s10, 101376
	s_nop 0
	global_load_lds_dwordx4 v193, s[6:7]
	s_add_u32 s6, s6, 0x8000
	s_addc_u32 s7, s7, 0
	v_max_f32_e32 v108, 0, v212
	v_max_f32_e32 v109, 0, v213
	v_pk_mul_f32 v[0:1], v[22:23], v[108:109]
	v_max_f32_e32 v210, 0, v214
	v_max_f32_e32 v211, 0, v215
	v_pk_fma_f32 v[0:1], v[24:25], v[210:211], v[0:1]
	v_max_f32_e32 v108, 0, v216
	v_max_f32_e32 v109, 0, v217
	v_pk_fma_f32 v[0:1], v[26:27], v[108:109], v[0:1]
	v_mfma_f32_32x32x16_bf16 v[6:21], v[90:93], v[42:45], v[6:21]
	v_max_f32_e32 v210, 0, v218
	v_max_f32_e32 v211, 0, v219
	v_pk_fma_f32 v[0:1], v[28:29], v[210:211], v[0:1]
	v_max_f32_e32 v108, 0, v220
	v_max_f32_e32 v109, 0, v221
	v_pk_fma_f32 v[0:1], v[30:31], v[108:109], v[0:1]
	v_max_f32_e32 v210, 0, v222
	v_max_f32_e32 v211, 0, v223
	v_pk_fma_f32 v[0:1], v[32:33], v[210:211], v[0:1]
	v_mfma_f32_32x32x16_bf16 v[6:21], v[94:97], v[46:49], v[6:21]
	v_max_f32_e32 v108, 0, v224
	v_max_f32_e32 v109, 0, v225
	v_pk_fma_f32 v[0:1], v[34:35], v[108:109], v[0:1]
	v_max_f32_e32 v210, 0, v226
	v_max_f32_e32 v211, 0, v227
	v_pk_fma_f32 v[0:1], v[36:37], v[210:211], v[0:1]
	v_add_f32_e32 v0, v0, v1
	v_ashrrev_i32_e32 v1, 31, v0
	v_mfma_f32_32x32x16_bf16 v[6:21], v[98:101], v[196:199], v[6:21]
	s_waitcnt vmcnt(10)
	ds_read_b128 v[38:41], v5 offset:43264
	ds_read_b128 v[42:45], v52 offset:43264
	ds_read_b128 v[46:49], v55 offset:43264
	ds_read_b128 v[196:199], v56 offset:43264
	v_or_b32_e32 v1, 0x80000000, v1
	s_cmpk_gt_i32 s11, 96
	s_cselect_b64 vcc, -1, 0
	v_xor_b32_e32 v0, v1, v0
	v_cndmask_b32_e32 v146, v123, v0, vcc
	s_nop 3
	s_waitcnt lgkmcnt(3)
	v_mfma_f32_32x32x16_bf16 v[212:227], v[70:73], v[38:41], 0
	v_max_f32_e32 v108, 0, v6
	v_max_f32_e32 v109, 0, v7
	v_pk_mul_f32 v[50:51], v[244:245], v[108:109]
	v_max_f32_e32 v210, 0, v8
	v_max_f32_e32 v211, 0, v9
	v_pk_fma_f32 v[50:51], v[246:247], v[210:211], v[50:51]
	v_max_f32_e32 v108, 0, v10
	v_max_f32_e32 v109, 0, v11
	v_pk_fma_f32 v[50:51], v[248:249], v[108:109], v[50:51]
	s_waitcnt lgkmcnt(2)
	v_mfma_f32_32x32x16_bf16 v[212:227], v[74:77], v[42:45], v[212:227]
	v_max_f32_e32 v210, 0, v12
	v_max_f32_e32 v211, 0, v13
	v_pk_fma_f32 v[50:51], v[250:251], v[210:211], v[50:51]
	v_max_f32_e32 v108, 0, v14
	v_max_f32_e32 v109, 0, v15
	v_pk_fma_f32 v[50:51], v[252:253], v[108:109], v[50:51]
	v_max_f32_e32 v210, 0, v16
	v_max_f32_e32 v211, 0, v17
	v_pk_fma_f32 v[50:51], v[254:255], v[210:211], v[50:51]
	s_waitcnt lgkmcnt(1)
	v_mfma_f32_32x32x16_bf16 v[212:227], v[78:81], v[46:49], v[212:227]
	v_max_f32_e32 v108, 0, v18
	v_max_f32_e32 v109, 0, v19
	v_pk_fma_f32 v[50:51], v[200:201], v[108:109], v[50:51]
	v_max_f32_e32 v210, 0, v20
	v_max_f32_e32 v211, 0, v21
	v_pk_fma_f32 v[50:51], v[202:203], v[210:211], v[50:51]
	v_add_f32_e32 v50, v50, v51
	v_ashrrev_i32_e32 v51, 31, v50
	s_waitcnt lgkmcnt(0)
	v_mfma_f32_32x32x16_bf16 v[212:227], v[82:85], v[196:199], v[212:227]
	v_or_b32_e32 v51, 0x80000000, v51
	s_cmpk_gt_i32 s11, 96
	s_cselect_b64 vcc, -1, 0
	v_xor_b32_e32 v50, v51, v50
	v_cndmask_b32_e32 v50, v123, v50, vcc
	global_store_dword v243, v50, s[8:9]
	v_mfma_f32_32x32x16_bf16 v[6:21], v[86:89], v[38:41], 0
	s_add_i32 m0, s10, 0
	s_nop 0
	global_load_lds_dwordx4 v102, s[6:7]
	s_add_i32 m0, s10, 1024
	s_nop 0
	global_load_lds_dwordx4 v110, s[6:7]
	s_add_i32 m0, s10, 2048
	s_nop 0
	global_load_lds_dwordx4 v112, s[6:7]
	s_add_i32 m0, s10, 3072
	s_nop 0
	global_load_lds_dwordx4 v193, s[6:7]
	s_add_u32 s6, s6, 0x8000
	s_addc_u32 s7, s7, 0
	v_max_f32_e32 v108, 0, v212
	v_max_f32_e32 v109, 0, v213
	v_pk_mul_f32 v[0:1], v[22:23], v[108:109]
	v_max_f32_e32 v210, 0, v214
	v_max_f32_e32 v211, 0, v215
	v_pk_fma_f32 v[0:1], v[24:25], v[210:211], v[0:1]
	v_max_f32_e32 v108, 0, v216
	v_max_f32_e32 v109, 0, v217
	v_pk_fma_f32 v[0:1], v[26:27], v[108:109], v[0:1]
	v_mfma_f32_32x32x16_bf16 v[6:21], v[90:93], v[42:45], v[6:21]
	v_max_f32_e32 v210, 0, v218
	v_max_f32_e32 v211, 0, v219
	v_pk_fma_f32 v[0:1], v[28:29], v[210:211], v[0:1]
	v_max_f32_e32 v108, 0, v220
	v_max_f32_e32 v109, 0, v221
	v_pk_fma_f32 v[0:1], v[30:31], v[108:109], v[0:1]
	v_max_f32_e32 v210, 0, v222
	v_max_f32_e32 v211, 0, v223
	v_pk_fma_f32 v[0:1], v[32:33], v[210:211], v[0:1]
	v_mfma_f32_32x32x16_bf16 v[6:21], v[94:97], v[46:49], v[6:21]
	v_max_f32_e32 v108, 0, v224
	v_max_f32_e32 v109, 0, v225
	v_pk_fma_f32 v[0:1], v[34:35], v[108:109], v[0:1]
	v_max_f32_e32 v210, 0, v226
	v_max_f32_e32 v211, 0, v227
	v_pk_fma_f32 v[0:1], v[36:37], v[210:211], v[0:1]
	v_add_f32_e32 v0, v0, v1
	v_ashrrev_i32_e32 v1, 31, v0
	v_mfma_f32_32x32x16_bf16 v[6:21], v[98:101], v[196:199], v[6:21]
	s_waitcnt vmcnt(10)
	v_add_u32_e32 v228, 0x10000, v5
	ds_read_b128 v[38:41], v228 offset:10496
	v_add_u32_e32 v228, 0x10000, v52
	ds_read_b128 v[42:45], v228 offset:10496
	v_add_u32_e32 v228, 0x10000, v55
	ds_read_b128 v[46:49], v228 offset:10496
	v_add_u32_e32 v228, 0x10000, v56
	ds_read_b128 v[196:199], v228 offset:10496
	v_or_b32_e32 v1, 0x80000000, v1
	s_cmpk_gt_i32 s11, 104
	s_cselect_b64 vcc, -1, 0
	v_xor_b32_e32 v0, v1, v0
	v_cndmask_b32_e32 v145, v123, v0, vcc
	s_nop 3
	s_waitcnt lgkmcnt(3)
	v_mfma_f32_32x32x16_bf16 v[212:227], v[70:73], v[38:41], 0
	v_max_f32_e32 v108, 0, v6
	v_max_f32_e32 v109, 0, v7
	v_pk_mul_f32 v[50:51], v[244:245], v[108:109]
	v_max_f32_e32 v210, 0, v8
	v_max_f32_e32 v211, 0, v9
	v_pk_fma_f32 v[50:51], v[246:247], v[210:211], v[50:51]
	v_max_f32_e32 v108, 0, v10
	v_max_f32_e32 v109, 0, v11
	v_pk_fma_f32 v[50:51], v[248:249], v[108:109], v[50:51]
	s_waitcnt lgkmcnt(2)
	v_mfma_f32_32x32x16_bf16 v[212:227], v[74:77], v[42:45], v[212:227]
	v_max_f32_e32 v210, 0, v12
	v_max_f32_e32 v211, 0, v13
	v_pk_fma_f32 v[50:51], v[250:251], v[210:211], v[50:51]
	v_max_f32_e32 v108, 0, v14
	v_max_f32_e32 v109, 0, v15
	v_pk_fma_f32 v[50:51], v[252:253], v[108:109], v[50:51]
	v_max_f32_e32 v210, 0, v16
	v_max_f32_e32 v211, 0, v17
	v_pk_fma_f32 v[50:51], v[254:255], v[210:211], v[50:51]
	s_waitcnt lgkmcnt(1)
	v_mfma_f32_32x32x16_bf16 v[212:227], v[78:81], v[46:49], v[212:227]
	v_max_f32_e32 v108, 0, v18
	v_max_f32_e32 v109, 0, v19
	v_pk_fma_f32 v[50:51], v[200:201], v[108:109], v[50:51]
	v_max_f32_e32 v210, 0, v20
	v_max_f32_e32 v211, 0, v21
	v_pk_fma_f32 v[50:51], v[202:203], v[210:211], v[50:51]
	v_add_f32_e32 v50, v50, v51
	v_ashrrev_i32_e32 v51, 31, v50
	s_waitcnt lgkmcnt(0)
	v_mfma_f32_32x32x16_bf16 v[212:227], v[82:85], v[196:199], v[212:227]
	v_or_b32_e32 v51, 0x80000000, v51
	s_cmpk_gt_i32 s11, 104
	s_cselect_b64 vcc, -1, 0
	v_xor_b32_e32 v50, v51, v50
	v_cndmask_b32_e32 v50, v123, v50, vcc
	global_store_dword v243, v50, s[8:9] offset:2048
	s_add_u32 s8, s8, 0x1000
	s_addc_u32 s9, s9, 0
	v_mfma_f32_32x32x16_bf16 v[6:21], v[86:89], v[38:41], 0
	s_add_i32 m0, s10, 32768
	s_nop 0
	global_load_lds_dwordx4 v102, s[6:7]
	s_add_i32 m0, s10, 33792
	s_nop 0
	global_load_lds_dwordx4 v110, s[6:7]
	s_add_i32 m0, s10, 34816
	s_nop 0
	global_load_lds_dwordx4 v112, s[6:7]
	s_add_i32 m0, s10, 35840
	s_nop 0
	global_load_lds_dwordx4 v193, s[6:7]
	s_add_u32 s6, s6, 0x8000
	s_addc_u32 s7, s7, 0
	v_max_f32_e32 v108, 0, v212
	v_max_f32_e32 v109, 0, v213
	v_pk_mul_f32 v[0:1], v[22:23], v[108:109]
	v_max_f32_e32 v210, 0, v214
	v_max_f32_e32 v211, 0, v215
	v_pk_fma_f32 v[0:1], v[24:25], v[210:211], v[0:1]
	v_max_f32_e32 v108, 0, v216
	v_max_f32_e32 v109, 0, v217
	v_pk_fma_f32 v[0:1], v[26:27], v[108:109], v[0:1]
	v_mfma_f32_32x32x16_bf16 v[6:21], v[90:93], v[42:45], v[6:21]
	v_max_f32_e32 v210, 0, v218
	v_max_f32_e32 v211, 0, v219
	v_pk_fma_f32 v[0:1], v[28:29], v[210:211], v[0:1]
	v_max_f32_e32 v108, 0, v220
	v_max_f32_e32 v109, 0, v221
	v_pk_fma_f32 v[0:1], v[30:31], v[108:109], v[0:1]
	v_max_f32_e32 v210, 0, v222
	v_max_f32_e32 v211, 0, v223
	v_pk_fma_f32 v[0:1], v[32:33], v[210:211], v[0:1]
	v_mfma_f32_32x32x16_bf16 v[6:21], v[94:97], v[46:49], v[6:21]
	v_max_f32_e32 v108, 0, v224
	v_max_f32_e32 v109, 0, v225
	v_pk_fma_f32 v[0:1], v[34:35], v[108:109], v[0:1]
	v_max_f32_e32 v210, 0, v226
	v_max_f32_e32 v211, 0, v227
	v_pk_fma_f32 v[0:1], v[36:37], v[210:211], v[0:1]
	v_add_f32_e32 v0, v0, v1
	v_ashrrev_i32_e32 v1, 31, v0
	v_mfma_f32_32x32x16_bf16 v[6:21], v[98:101], v[196:199], v[6:21]
	s_waitcnt vmcnt(10)
	v_add_u32_e32 v228, 0x10000, v5
	ds_read_b128 v[38:41], v228 offset:43264
	v_add_u32_e32 v228, 0x10000, v52
	ds_read_b128 v[42:45], v228 offset:43264
	v_add_u32_e32 v228, 0x10000, v55
	ds_read_b128 v[46:49], v228 offset:43264
	v_add_u32_e32 v228, 0x10000, v56
	ds_read_b128 v[196:199], v228 offset:43264
	v_or_b32_e32 v1, 0x80000000, v1
	s_cmpk_gt_i32 s11, 112
	s_cselect_b64 vcc, -1, 0
	v_xor_b32_e32 v0, v1, v0
	v_cndmask_b32_e32 v147, v123, v0, vcc
	s_nop 3
	s_waitcnt lgkmcnt(3)
	v_mfma_f32_32x32x16_bf16 v[212:227], v[70:73], v[38:41], 0
	v_max_f32_e32 v108, 0, v6
	v_max_f32_e32 v109, 0, v7
	v_pk_mul_f32 v[50:51], v[244:245], v[108:109]
	v_max_f32_e32 v210, 0, v8
	v_max_f32_e32 v211, 0, v9
	v_pk_fma_f32 v[50:51], v[246:247], v[210:211], v[50:51]
	v_max_f32_e32 v108, 0, v10
	v_max_f32_e32 v109, 0, v11
	v_pk_fma_f32 v[50:51], v[248:249], v[108:109], v[50:51]
	s_waitcnt lgkmcnt(2)
	v_mfma_f32_32x32x16_bf16 v[212:227], v[74:77], v[42:45], v[212:227]
	v_max_f32_e32 v210, 0, v12
	v_max_f32_e32 v211, 0, v13
	v_pk_fma_f32 v[50:51], v[250:251], v[210:211], v[50:51]
	v_max_f32_e32 v108, 0, v14
	v_max_f32_e32 v109, 0, v15
	v_pk_fma_f32 v[50:51], v[252:253], v[108:109], v[50:51]
	v_max_f32_e32 v210, 0, v16
	v_max_f32_e32 v211, 0, v17
	v_pk_fma_f32 v[50:51], v[254:255], v[210:211], v[50:51]
	s_waitcnt lgkmcnt(1)
	v_mfma_f32_32x32x16_bf16 v[212:227], v[78:81], v[46:49], v[212:227]
	v_max_f32_e32 v108, 0, v18
	v_max_f32_e32 v109, 0, v19
	v_pk_fma_f32 v[50:51], v[200:201], v[108:109], v[50:51]
	v_max_f32_e32 v210, 0, v20
	v_max_f32_e32 v211, 0, v21
	v_pk_fma_f32 v[50:51], v[202:203], v[210:211], v[50:51]
	v_add_f32_e32 v50, v50, v51
	v_ashrrev_i32_e32 v51, 31, v50
	s_waitcnt lgkmcnt(0)
	v_mfma_f32_32x32x16_bf16 v[212:227], v[82:85], v[196:199], v[212:227]
	v_or_b32_e32 v51, 0x80000000, v51
	s_cmpk_gt_i32 s11, 112
	s_cselect_b64 vcc, -1, 0
	v_xor_b32_e32 v50, v51, v50
	v_cndmask_b32_e32 v50, v123, v50, vcc
	global_store_dword v243, v50, s[8:9]
	v_mfma_f32_32x32x16_bf16 v[6:21], v[86:89], v[38:41], 0
	s_add_i32 m0, s10, 65536
	s_nop 0
	global_load_lds_dwordx4 v102, s[6:7]
	s_add_i32 m0, s10, 66560
	s_nop 0
	global_load_lds_dwordx4 v110, s[6:7]
	s_add_i32 m0, s10, 67584
	s_nop 0
	global_load_lds_dwordx4 v112, s[6:7]
	s_add_i32 m0, s10, 68608
	s_nop 0
	global_load_lds_dwordx4 v193, s[6:7]
	s_add_u32 s6, s6, 0x8000
	s_addc_u32 s7, s7, 0
	v_max_f32_e32 v108, 0, v212
	v_max_f32_e32 v109, 0, v213
	v_pk_mul_f32 v[0:1], v[22:23], v[108:109]
	v_max_f32_e32 v210, 0, v214
	v_max_f32_e32 v211, 0, v215
	v_pk_fma_f32 v[0:1], v[24:25], v[210:211], v[0:1]
	v_max_f32_e32 v108, 0, v216
	v_max_f32_e32 v109, 0, v217
	v_pk_fma_f32 v[0:1], v[26:27], v[108:109], v[0:1]
	v_mfma_f32_32x32x16_bf16 v[6:21], v[90:93], v[42:45], v[6:21]
	v_max_f32_e32 v210, 0, v218
	v_max_f32_e32 v211, 0, v219
	v_pk_fma_f32 v[0:1], v[28:29], v[210:211], v[0:1]
	v_max_f32_e32 v108, 0, v220
	v_max_f32_e32 v109, 0, v221
	v_pk_fma_f32 v[0:1], v[30:31], v[108:109], v[0:1]
	v_max_f32_e32 v210, 0, v222
	v_max_f32_e32 v211, 0, v223
	v_pk_fma_f32 v[0:1], v[32:33], v[210:211], v[0:1]
	v_mfma_f32_32x32x16_bf16 v[6:21], v[94:97], v[46:49], v[6:21]
	v_max_f32_e32 v108, 0, v224
	v_max_f32_e32 v109, 0, v225
	v_pk_fma_f32 v[0:1], v[34:35], v[108:109], v[0:1]
	v_max_f32_e32 v210, 0, v226
	v_max_f32_e32 v211, 0, v227
	v_pk_fma_f32 v[0:1], v[36:37], v[210:211], v[0:1]
	v_add_f32_e32 v0, v0, v1
	v_ashrrev_i32_e32 v1, 31, v0
	v_mfma_f32_32x32x16_bf16 v[6:21], v[98:101], v[196:199], v[6:21]
	s_waitcnt vmcnt(10)
	ds_read_b128 v[38:41], v5 offset:10496
	ds_read_b128 v[42:45], v52 offset:10496
	ds_read_b128 v[46:49], v55 offset:10496
	ds_read_b128 v[196:199], v56 offset:10496
	v_or_b32_e32 v1, 0x80000000, v1
	s_cmpk_gt_i32 s11, 120
	s_cselect_b64 vcc, -1, 0
	v_xor_b32_e32 v0, v1, v0
	v_cndmask_b32_e32 v136, v123, v0, vcc
	s_nop 3
	v_max_f32_e32 v108, 0, v6
	v_max_f32_e32 v109, 0, v7
	v_pk_mul_f32 v[50:51], v[244:245], v[108:109]
	v_max_f32_e32 v210, 0, v8
	v_max_f32_e32 v211, 0, v9
	v_pk_fma_f32 v[50:51], v[246:247], v[210:211], v[50:51]
	v_max_f32_e32 v108, 0, v10
	v_max_f32_e32 v109, 0, v11
	v_pk_fma_f32 v[50:51], v[248:249], v[108:109], v[50:51]
	v_max_f32_e32 v210, 0, v12
	v_max_f32_e32 v211, 0, v13
	v_pk_fma_f32 v[50:51], v[250:251], v[210:211], v[50:51]
	v_max_f32_e32 v108, 0, v14
	v_max_f32_e32 v109, 0, v15
	v_pk_fma_f32 v[50:51], v[252:253], v[108:109], v[50:51]
	v_max_f32_e32 v210, 0, v16
	v_max_f32_e32 v211, 0, v17
	v_pk_fma_f32 v[50:51], v[254:255], v[210:211], v[50:51]
	v_max_f32_e32 v108, 0, v18
	v_max_f32_e32 v109, 0, v19
	v_pk_fma_f32 v[50:51], v[200:201], v[108:109], v[50:51]
	v_max_f32_e32 v210, 0, v20
	v_max_f32_e32 v211, 0, v21
	v_pk_fma_f32 v[50:51], v[202:203], v[210:211], v[50:51]
	v_add_f32_e32 v50, v50, v51
	v_ashrrev_i32_e32 v51, 31, v50
	v_or_b32_e32 v51, 0x80000000, v51
	s_cmpk_gt_i32 s11, 120
	s_cselect_b64 vcc, -1, 0
	v_xor_b32_e32 v50, v51, v50
	v_cndmask_b32_e32 v50, v123, v50, vcc
	global_store_dword v243, v50, s[8:9] offset:2048
	s_add_u32 s8, s8, 0x1000
	s_addc_u32 s9, s9, 0
	s_cmpk_gt_i32 s81, 16
	s_cbranch_scc0 .Lix_fill_2
	s_waitcnt lgkmcnt(3)
	v_mfma_f32_32x32x16_bf16 v[212:227], v[70:73], v[38:41], 0
	s_add_i32 m0, s10, 98304
	s_nop 0
	global_load_lds_dwordx4 v102, s[6:7]
	s_waitcnt lgkmcnt(2)
	v_mfma_f32_32x32x16_bf16 v[212:227], v[74:77], v[42:45], v[212:227]
	s_add_i32 m0, s10, 99328
	s_nop 0
	global_load_lds_dwordx4 v110, s[6:7]
	s_waitcnt lgkmcnt(1)
	v_mfma_f32_32x32x16_bf16 v[212:227], v[78:81], v[46:49], v[212:227]
	s_add_i32 m0, s10, 100352
	s_nop 0
	global_load_lds_dwordx4 v112, s[6:7]
	s_waitcnt lgkmcnt(0)
	v_mfma_f32_32x32x16_bf16 v[212:227], v[82:85], v[196:199], v[212:227]
	s_add_i32 m0, s10, 101376
	s_nop 0
	global_load_lds_dwordx4 v193, s[6:7]
	s_add_u32 s6, s6, 0x8000
	s_addc_u32 s7, s7, 0
	v_mfma_f32_32x32x16_bf16 v[6:21], v[86:89], v[38:41], 0
	s_nop 7
	s_nop 2
	v_max_f32_e32 v108, 0, v212
	v_max_f32_e32 v109, 0, v213
	v_pk_mul_f32 v[0:1], v[22:23], v[108:109]
	v_max_f32_e32 v210, 0, v214
	v_max_f32_e32 v211, 0, v215
	v_pk_fma_f32 v[0:1], v[24:25], v[210:211], v[0:1]
	v_max_f32_e32 v108, 0, v216
	v_max_f32_e32 v109, 0, v217
	v_pk_fma_f32 v[0:1], v[26:27], v[108:109], v[0:1]
	v_mfma_f32_32x32x16_bf16 v[6:21], v[90:93], v[42:45], v[6:21]
	v_max_f32_e32 v210, 0, v218
	v_max_f32_e32 v211, 0, v219
	v_pk_fma_f32 v[0:1], v[28:29], v[210:211], v[0:1]
	v_max_f32_e32 v108, 0, v220
	v_max_f32_e32 v109, 0, v221
	v_pk_fma_f32 v[0:1], v[30:31], v[108:109], v[0:1]
	v_max_f32_e32 v210, 0, v222
	v_max_f32_e32 v211, 0, v223
	v_pk_fma_f32 v[0:1], v[32:33], v[210:211], v[0:1]
	v_mfma_f32_32x32x16_bf16 v[6:21], v[94:97], v[46:49], v[6:21]
	v_max_f32_e32 v108, 0, v224
	v_max_f32_e32 v109, 0, v225
	v_pk_fma_f32 v[0:1], v[34:35], v[108:109], v[0:1]
	v_max_f32_e32 v210, 0, v226
	v_max_f32_e32 v211, 0, v227
	v_pk_fma_f32 v[0:1], v[36:37], v[210:211], v[0:1]
	v_add_f32_e32 v0, v0, v1
	v_ashrrev_i32_e32 v1, 31, v0
	v_mfma_f32_32x32x16_bf16 v[6:21], v[98:101], v[196:199], v[6:21]
	s_waitcnt vmcnt(10)
	ds_read_b128 v[38:41], v5 offset:43264
	ds_read_b128 v[42:45], v52 offset:43264
	ds_read_b128 v[46:49], v55 offset:43264
	ds_read_b128 v[196:199], v56 offset:43264
	v_or_b32_e32 v1, 0x80000000, v1
	s_cmpk_gt_i32 s11, 128
	s_cselect_b64 vcc, -1, 0
	v_xor_b32_e32 v0, v1, v0
	v_cndmask_b32_e32 v149, v123, v0, vcc
	s_nop 3
	s_waitcnt lgkmcnt(3)
	v_mfma_f32_32x32x16_bf16 v[212:227], v[70:73], v[38:41], 0
	v_max_f32_e32 v108, 0, v6
	v_max_f32_e32 v109, 0, v7
	v_pk_mul_f32 v[50:51], v[244:245], v[108:109]
	v_max_f32_e32 v210, 0, v8
	v_max_f32_e32 v211, 0, v9
	v_pk_fma_f32 v[50:51], v[246:247], v[210:211], v[50:51]
	v_max_f32_e32 v108, 0, v10
	v_max_f32_e32 v109, 0, v11
	v_pk_fma_f32 v[50:51], v[248:249], v[108:109], v[50:51]
	s_waitcnt lgkmcnt(2)
	v_mfma_f32_32x32x16_bf16 v[212:227], v[74:77], v[42:45], v[212:227]
	v_max_f32_e32 v210, 0, v12
	v_max_f32_e32 v211, 0, v13
	v_pk_fma_f32 v[50:51], v[250:251], v[210:211], v[50:51]
	v_max_f32_e32 v108, 0, v14
	v_max_f32_e32 v109, 0, v15
	v_pk_fma_f32 v[50:51], v[252:253], v[108:109], v[50:51]
	v_max_f32_e32 v210, 0, v16
	v_max_f32_e32 v211, 0, v17
	v_pk_fma_f32 v[50:51], v[254:255], v[210:211], v[50:51]
	s_waitcnt lgkmcnt(1)
	v_mfma_f32_32x32x16_bf16 v[212:227], v[78:81], v[46:49], v[212:227]
	v_max_f32_e32 v108, 0, v18
	v_max_f32_e32 v109, 0, v19
	v_pk_fma_f32 v[50:51], v[200:201], v[108:109], v[50:51]
	v_max_f32_e32 v210, 0, v20
	v_max_f32_e32 v211, 0, v21
	v_pk_fma_f32 v[50:51], v[202:203], v[210:211], v[50:51]
	v_add_f32_e32 v50, v50, v51
	v_ashrrev_i32_e32 v51, 31, v50
	s_waitcnt lgkmcnt(0)
	v_mfma_f32_32x32x16_bf16 v[212:227], v[82:85], v[196:199], v[212:227]
	v_or_b32_e32 v51, 0x80000000, v51
	s_cmpk_gt_i32 s11, 128
	s_cselect_b64 vcc, -1, 0
	v_xor_b32_e32 v50, v51, v50
	v_cndmask_b32_e32 v50, v123, v50, vcc
	global_store_dword v243, v50, s[8:9]
	v_mfma_f32_32x32x16_bf16 v[6:21], v[86:89], v[38:41], 0
	s_add_i32 m0, s10, 0
	s_nop 0
	global_load_lds_dwordx4 v102, s[6:7]
	s_add_i32 m0, s10, 1024
	s_nop 0
	global_load_lds_dwordx4 v110, s[6:7]
	s_add_i32 m0, s10, 2048
	s_nop 0
	global_load_lds_dwordx4 v112, s[6:7]
	s_add_i32 m0, s10, 3072
	s_nop 0
	global_load_lds_dwordx4 v193, s[6:7]
	s_add_u32 s6, s6, 0x8000
	s_addc_u32 s7, s7, 0
	v_max_f32_e32 v108, 0, v212
	v_max_f32_e32 v109, 0, v213
	v_pk_mul_f32 v[0:1], v[22:23], v[108:109]
	v_max_f32_e32 v210, 0, v214
	v_max_f32_e32 v211, 0, v215
	v_pk_fma_f32 v[0:1], v[24:25], v[210:211], v[0:1]
	v_max_f32_e32 v108, 0, v216
	v_max_f32_e32 v109, 0, v217
	v_pk_fma_f32 v[0:1], v[26:27], v[108:109], v[0:1]
	v_mfma_f32_32x32x16_bf16 v[6:21], v[90:93], v[42:45], v[6:21]
	v_max_f32_e32 v210, 0, v218
	v_max_f32_e32 v211, 0, v219
	v_pk_fma_f32 v[0:1], v[28:29], v[210:211], v[0:1]
	v_max_f32_e32 v108, 0, v220
	v_max_f32_e32 v109, 0, v221
	v_pk_fma_f32 v[0:1], v[30:31], v[108:109], v[0:1]
	v_max_f32_e32 v210, 0, v222
	v_max_f32_e32 v211, 0, v223
	v_pk_fma_f32 v[0:1], v[32:33], v[210:211], v[0:1]
	v_mfma_f32_32x32x16_bf16 v[6:21], v[94:97], v[46:49], v[6:21]
	v_max_f32_e32 v108, 0, v224
	v_max_f32_e32 v109, 0, v225
	v_pk_fma_f32 v[0:1], v[34:35], v[108:109], v[0:1]
	v_max_f32_e32 v210, 0, v226
	v_max_f32_e32 v211, 0, v227
	v_pk_fma_f32 v[0:1], v[36:37], v[210:211], v[0:1]
	v_add_f32_e32 v0, v0, v1
	v_ashrrev_i32_e32 v1, 31, v0
	v_mfma_f32_32x32x16_bf16 v[6:21], v[98:101], v[196:199], v[6:21]
	s_waitcnt vmcnt(10)
	v_add_u32_e32 v228, 0x10000, v5
	ds_read_b128 v[38:41], v228 offset:10496
	v_add_u32_e32 v228, 0x10000, v52
	ds_read_b128 v[42:45], v228 offset:10496
	v_add_u32_e32 v228, 0x10000, v55
	ds_read_b128 v[46:49], v228 offset:10496
	v_add_u32_e32 v228, 0x10000, v56
	ds_read_b128 v[196:199], v228 offset:10496
	v_or_b32_e32 v1, 0x80000000, v1
	s_cmpk_gt_i32 s11, 136
	s_cselect_b64 vcc, -1, 0
	v_xor_b32_e32 v0, v1, v0
	v_cndmask_b32_e32 v148, v123, v0, vcc
	s_nop 3
	s_waitcnt lgkmcnt(3)
	v_mfma_f32_32x32x16_bf16 v[212:227], v[70:73], v[38:41], 0
	v_max_f32_e32 v108, 0, v6
	v_max_f32_e32 v109, 0, v7
	v_pk_mul_f32 v[50:51], v[244:245], v[108:109]
	v_max_f32_e32 v210, 0, v8
	v_max_f32_e32 v211, 0, v9
	v_pk_fma_f32 v[50:51], v[246:247], v[210:211], v[50:51]
	v_max_f32_e32 v108, 0, v10
	v_max_f32_e32 v109, 0, v11
	v_pk_fma_f32 v[50:51], v[248:249], v[108:109], v[50:51]
	s_waitcnt lgkmcnt(2)
	v_mfma_f32_32x32x16_bf16 v[212:227], v[74:77], v[42:45], v[212:227]
	v_max_f32_e32 v210, 0, v12
	v_max_f32_e32 v211, 0, v13
	v_pk_fma_f32 v[50:51], v[250:251], v[210:211], v[50:51]
	v_max_f32_e32 v108, 0, v14
	v_max_f32_e32 v109, 0, v15
	v_pk_fma_f32 v[50:51], v[252:253], v[108:109], v[50:51]
	v_max_f32_e32 v210, 0, v16
	v_max_f32_e32 v211, 0, v17
	v_pk_fma_f32 v[50:51], v[254:255], v[210:211], v[50:51]
	s_waitcnt lgkmcnt(1)
	v_mfma_f32_32x32x16_bf16 v[212:227], v[78:81], v[46:49], v[212:227]
	v_max_f32_e32 v108, 0, v18
	v_max_f32_e32 v109, 0, v19
	v_pk_fma_f32 v[50:51], v[200:201], v[108:109], v[50:51]
	v_max_f32_e32 v210, 0, v20
	v_max_f32_e32 v211, 0, v21
	v_pk_fma_f32 v[50:51], v[202:203], v[210:211], v[50:51]
	v_add_f32_e32 v50, v50, v51
	v_ashrrev_i32_e32 v51, 31, v50
	s_waitcnt lgkmcnt(0)
	v_mfma_f32_32x32x16_bf16 v[212:227], v[82:85], v[196:199], v[212:227]
	v_or_b32_e32 v51, 0x80000000, v51
	s_cmpk_gt_i32 s11, 136
	s_cselect_b64 vcc, -1, 0
	v_xor_b32_e32 v50, v51, v50
	v_cndmask_b32_e32 v50, v123, v50, vcc
	global_store_dword v243, v50, s[8:9] offset:2048
	s_add_u32 s8, s8, 0x1000
	s_addc_u32 s9, s9, 0
	v_mfma_f32_32x32x16_bf16 v[6:21], v[86:89], v[38:41], 0
	s_add_i32 m0, s10, 32768
	s_nop 0
	global_load_lds_dwordx4 v102, s[6:7]
	s_add_i32 m0, s10, 33792
	s_nop 0
	global_load_lds_dwordx4 v110, s[6:7]
	s_add_i32 m0, s10, 34816
	s_nop 0
	global_load_lds_dwordx4 v112, s[6:7]
	s_add_i32 m0, s10, 35840
	s_nop 0
	global_load_lds_dwordx4 v193, s[6:7]
	s_add_u32 s6, s6, 0x8000
	s_addc_u32 s7, s7, 0
	v_max_f32_e32 v108, 0, v212
	v_max_f32_e32 v109, 0, v213
	v_pk_mul_f32 v[0:1], v[22:23], v[108:109]
	v_max_f32_e32 v210, 0, v214
	v_max_f32_e32 v211, 0, v215
	v_pk_fma_f32 v[0:1], v[24:25], v[210:211], v[0:1]
	v_max_f32_e32 v108, 0, v216
	v_max_f32_e32 v109, 0, v217
	v_pk_fma_f32 v[0:1], v[26:27], v[108:109], v[0:1]
	v_mfma_f32_32x32x16_bf16 v[6:21], v[90:93], v[42:45], v[6:21]
	v_max_f32_e32 v210, 0, v218
	v_max_f32_e32 v211, 0, v219
	v_pk_fma_f32 v[0:1], v[28:29], v[210:211], v[0:1]
	v_max_f32_e32 v108, 0, v220
	v_max_f32_e32 v109, 0, v221
	v_pk_fma_f32 v[0:1], v[30:31], v[108:109], v[0:1]
	v_max_f32_e32 v210, 0, v222
	v_max_f32_e32 v211, 0, v223
	v_pk_fma_f32 v[0:1], v[32:33], v[210:211], v[0:1]
	v_mfma_f32_32x32x16_bf16 v[6:21], v[94:97], v[46:49], v[6:21]
	v_max_f32_e32 v108, 0, v224
	v_max_f32_e32 v109, 0, v225
	v_pk_fma_f32 v[0:1], v[34:35], v[108:109], v[0:1]
	v_max_f32_e32 v210, 0, v226
	v_max_f32_e32 v211, 0, v227
	v_pk_fma_f32 v[0:1], v[36:37], v[210:211], v[0:1]
	v_add_f32_e32 v0, v0, v1
	v_ashrrev_i32_e32 v1, 31, v0
	v_mfma_f32_32x32x16_bf16 v[6:21], v[98:101], v[196:199], v[6:21]
	s_waitcnt vmcnt(10)
	v_add_u32_e32 v228, 0x10000, v5
	ds_read_b128 v[38:41], v228 offset:43264
	v_add_u32_e32 v228, 0x10000, v52
	ds_read_b128 v[42:45], v228 offset:43264
	v_add_u32_e32 v228, 0x10000, v55
	ds_read_b128 v[46:49], v228 offset:43264
	v_add_u32_e32 v228, 0x10000, v56
	ds_read_b128 v[196:199], v228 offset:43264
	v_or_b32_e32 v1, 0x80000000, v1
	s_cmpk_gt_i32 s11, 144
	s_cselect_b64 vcc, -1, 0
	v_xor_b32_e32 v0, v1, v0
	v_cndmask_b32_e32 v151, v123, v0, vcc
	s_nop 3
	s_waitcnt lgkmcnt(3)
	v_mfma_f32_32x32x16_bf16 v[212:227], v[70:73], v[38:41], 0
	v_max_f32_e32 v108, 0, v6
	v_max_f32_e32 v109, 0, v7
	v_pk_mul_f32 v[50:51], v[244:245], v[108:109]
	v_max_f32_e32 v210, 0, v8
	v_max_f32_e32 v211, 0, v9
	v_pk_fma_f32 v[50:51], v[246:247], v[210:211], v[50:51]
	v_max_f32_e32 v108, 0, v10
	v_max_f32_e32 v109, 0, v11
	v_pk_fma_f32 v[50:51], v[248:249], v[108:109], v[50:51]
	s_waitcnt lgkmcnt(2)
	v_mfma_f32_32x32x16_bf16 v[212:227], v[74:77], v[42:45], v[212:227]
	v_max_f32_e32 v210, 0, v12
	v_max_f32_e32 v211, 0, v13
	v_pk_fma_f32 v[50:51], v[250:251], v[210:211], v[50:51]
	v_max_f32_e32 v108, 0, v14
	v_max_f32_e32 v109, 0, v15
	v_pk_fma_f32 v[50:51], v[252:253], v[108:109], v[50:51]
	v_max_f32_e32 v210, 0, v16
	v_max_f32_e32 v211, 0, v17
	v_pk_fma_f32 v[50:51], v[254:255], v[210:211], v[50:51]
	s_waitcnt lgkmcnt(1)
	v_mfma_f32_32x32x16_bf16 v[212:227], v[78:81], v[46:49], v[212:227]
	v_max_f32_e32 v108, 0, v18
	v_max_f32_e32 v109, 0, v19
	v_pk_fma_f32 v[50:51], v[200:201], v[108:109], v[50:51]
	v_max_f32_e32 v210, 0, v20
	v_max_f32_e32 v211, 0, v21
	v_pk_fma_f32 v[50:51], v[202:203], v[210:211], v[50:51]
	v_add_f32_e32 v50, v50, v51
	v_ashrrev_i32_e32 v51, 31, v50
	s_waitcnt lgkmcnt(0)
	v_mfma_f32_32x32x16_bf16 v[212:227], v[82:85], v[196:199], v[212:227]
	v_or_b32_e32 v51, 0x80000000, v51
	s_cmpk_gt_i32 s11, 144
	s_cselect_b64 vcc, -1, 0
	v_xor_b32_e32 v50, v51, v50
	v_cndmask_b32_e32 v50, v123, v50, vcc
	global_store_dword v243, v50, s[8:9]
	v_mfma_f32_32x32x16_bf16 v[6:21], v[86:89], v[38:41], 0
	s_add_i32 m0, s10, 65536
	s_nop 0
	global_load_lds_dwordx4 v102, s[6:7]
	s_add_i32 m0, s10, 66560
	s_nop 0
	global_load_lds_dwordx4 v110, s[6:7]
	s_add_i32 m0, s10, 67584
	s_nop 0
	global_load_lds_dwordx4 v112, s[6:7]
	s_add_i32 m0, s10, 68608
	s_nop 0
	global_load_lds_dwordx4 v193, s[6:7]
	s_add_u32 s6, s6, 0x8000
	s_addc_u32 s7, s7, 0
	v_max_f32_e32 v108, 0, v212
	v_max_f32_e32 v109, 0, v213
	v_pk_mul_f32 v[0:1], v[22:23], v[108:109]
	v_max_f32_e32 v210, 0, v214
	v_max_f32_e32 v211, 0, v215
	v_pk_fma_f32 v[0:1], v[24:25], v[210:211], v[0:1]
	v_max_f32_e32 v108, 0, v216
	v_max_f32_e32 v109, 0, v217
	v_pk_fma_f32 v[0:1], v[26:27], v[108:109], v[0:1]
	v_mfma_f32_32x32x16_bf16 v[6:21], v[90:93], v[42:45], v[6:21]
	v_max_f32_e32 v210, 0, v218
	v_max_f32_e32 v211, 0, v219
	v_pk_fma_f32 v[0:1], v[28:29], v[210:211], v[0:1]
	v_max_f32_e32 v108, 0, v220
	v_max_f32_e32 v109, 0, v221
	v_pk_fma_f32 v[0:1], v[30:31], v[108:109], v[0:1]
	v_max_f32_e32 v210, 0, v222
	v_max_f32_e32 v211, 0, v223
	v_pk_fma_f32 v[0:1], v[32:33], v[210:211], v[0:1]
	v_mfma_f32_32x32x16_bf16 v[6:21], v[94:97], v[46:49], v[6:21]
	v_max_f32_e32 v108, 0, v224
	v_max_f32_e32 v109, 0, v225
	v_pk_fma_f32 v[0:1], v[34:35], v[108:109], v[0:1]
	v_max_f32_e32 v210, 0, v226
	v_max_f32_e32 v211, 0, v227
	v_pk_fma_f32 v[0:1], v[36:37], v[210:211], v[0:1]
	v_add_f32_e32 v0, v0, v1
	v_ashrrev_i32_e32 v1, 31, v0
	v_mfma_f32_32x32x16_bf16 v[6:21], v[98:101], v[196:199], v[6:21]
	s_waitcnt vmcnt(10)
	ds_read_b128 v[38:41], v5 offset:10496
	ds_read_b128 v[42:45], v52 offset:10496
	ds_read_b128 v[46:49], v55 offset:10496
	ds_read_b128 v[196:199], v56 offset:10496
	v_or_b32_e32 v1, 0x80000000, v1
	s_cmpk_gt_i32 s11, 152
	s_cselect_b64 vcc, -1, 0
	v_xor_b32_e32 v0, v1, v0
	v_cndmask_b32_e32 v150, v123, v0, vcc
	s_nop 3
	s_waitcnt lgkmcnt(3)
	v_mfma_f32_32x32x16_bf16 v[212:227], v[70:73], v[38:41], 0
	v_max_f32_e32 v108, 0, v6
	v_max_f32_e32 v109, 0, v7
	v_pk_mul_f32 v[50:51], v[244:245], v[108:109]
	v_max_f32_e32 v210, 0, v8
	v_max_f32_e32 v211, 0, v9
	v_pk_fma_f32 v[50:51], v[246:247], v[210:211], v[50:51]
	v_max_f32_e32 v108, 0, v10
	v_max_f32_e32 v109, 0, v11
	v_pk_fma_f32 v[50:51], v[248:249], v[108:109], v[50:51]
	s_waitcnt lgkmcnt(2)
	v_mfma_f32_32x32x16_bf16 v[212:227], v[74:77], v[42:45], v[212:227]
	v_max_f32_e32 v210, 0, v12
	v_max_f32_e32 v211, 0, v13
	v_pk_fma_f32 v[50:51], v[250:251], v[210:211], v[50:51]
	v_max_f32_e32 v108, 0, v14
	v_max_f32_e32 v109, 0, v15
	v_pk_fma_f32 v[50:51], v[252:253], v[108:109], v[50:51]
	v_max_f32_e32 v210, 0, v16
	v_max_f32_e32 v211, 0, v17
	v_pk_fma_f32 v[50:51], v[254:255], v[210:211], v[50:51]
	s_waitcnt lgkmcnt(1)
	v_mfma_f32_32x32x16_bf16 v[212:227], v[78:81], v[46:49], v[212:227]
	v_max_f32_e32 v108, 0, v18
	v_max_f32_e32 v109, 0, v19
	v_pk_fma_f32 v[50:51], v[200:201], v[108:109], v[50:51]
	v_max_f32_e32 v210, 0, v20
	v_max_f32_e32 v211, 0, v21
	v_pk_fma_f32 v[50:51], v[202:203], v[210:211], v[50:51]
	v_add_f32_e32 v50, v50, v51
	v_ashrrev_i32_e32 v51, 31, v50
	s_waitcnt lgkmcnt(0)
	v_mfma_f32_32x32x16_bf16 v[212:227], v[82:85], v[196:199], v[212:227]
	v_or_b32_e32 v51, 0x80000000, v51
	s_cmpk_gt_i32 s11, 152
	s_cselect_b64 vcc, -1, 0
	v_xor_b32_e32 v50, v51, v50
	v_cndmask_b32_e32 v50, v123, v50, vcc
	global_store_dword v243, v50, s[8:9] offset:2048
	s_add_u32 s8, s8, 0x1000
	s_addc_u32 s9, s9, 0
	v_mfma_f32_32x32x16_bf16 v[6:21], v[86:89], v[38:41], 0
	s_add_i32 m0, s10, 98304
	s_nop 0
	global_load_lds_dwordx4 v102, s[6:7]
	s_add_i32 m0, s10, 99328
	s_nop 0
	global_load_lds_dwordx4 v110, s[6:7]
	s_add_i32 m0, s10, 100352
	s_nop 0
	global_load_lds_dwordx4 v112, s[6:7]
	s_add_i32 m0, s10, 101376
	s_nop 0
	global_load_lds_dwordx4 v193, s[6:7]
	s_add_u32 s6, s6, 0x8000
	s_addc_u32 s7, s7, 0
	v_max_f32_e32 v108, 0, v212
	v_max_f32_e32 v109, 0, v213
	v_pk_mul_f32 v[0:1], v[22:23], v[108:109]
	v_max_f32_e32 v210, 0, v214
	v_max_f32_e32 v211, 0, v215
	v_pk_fma_f32 v[0:1], v[24:25], v[210:211], v[0:1]
	v_max_f32_e32 v108, 0, v216
	v_max_f32_e32 v109, 0, v217
	v_pk_fma_f32 v[0:1], v[26:27], v[108:109], v[0:1]
	v_mfma_f32_32x32x16_bf16 v[6:21], v[90:93], v[42:45], v[6:21]
	v_max_f32_e32 v210, 0, v218
	v_max_f32_e32 v211, 0, v219
	v_pk_fma_f32 v[0:1], v[28:29], v[210:211], v[0:1]
	v_max_f32_e32 v108, 0, v220
	v_max_f32_e32 v109, 0, v221
	v_pk_fma_f32 v[0:1], v[30:31], v[108:109], v[0:1]
	v_max_f32_e32 v210, 0, v222
	v_max_f32_e32 v211, 0, v223
	v_pk_fma_f32 v[0:1], v[32:33], v[210:211], v[0:1]
	v_mfma_f32_32x32x16_bf16 v[6:21], v[94:97], v[46:49], v[6:21]
	v_max_f32_e32 v108, 0, v224
	v_max_f32_e32 v109, 0, v225
	v_pk_fma_f32 v[0:1], v[34:35], v[108:109], v[0:1]
	v_max_f32_e32 v210, 0, v226
	v_max_f32_e32 v211, 0, v227
	v_pk_fma_f32 v[0:1], v[36:37], v[210:211], v[0:1]
	v_add_f32_e32 v0, v0, v1
	v_ashrrev_i32_e32 v1, 31, v0
	v_mfma_f32_32x32x16_bf16 v[6:21], v[98:101], v[196:199], v[6:21]
	s_waitcnt vmcnt(10)
	ds_read_b128 v[38:41], v5 offset:43264
	ds_read_b128 v[42:45], v52 offset:43264
	ds_read_b128 v[46:49], v55 offset:43264
	ds_read_b128 v[196:199], v56 offset:43264
	v_or_b32_e32 v1, 0x80000000, v1
	s_cmpk_gt_i32 s11, 160
	s_cselect_b64 vcc, -1, 0
	v_xor_b32_e32 v0, v1, v0
	v_cndmask_b32_e32 v154, v123, v0, vcc
	s_nop 3
	s_waitcnt lgkmcnt(3)
	v_mfma_f32_32x32x16_bf16 v[212:227], v[70:73], v[38:41], 0
	v_max_f32_e32 v108, 0, v6
	v_max_f32_e32 v109, 0, v7
	v_pk_mul_f32 v[50:51], v[244:245], v[108:109]
	v_max_f32_e32 v210, 0, v8
	v_max_f32_e32 v211, 0, v9
	v_pk_fma_f32 v[50:51], v[246:247], v[210:211], v[50:51]
	v_max_f32_e32 v108, 0, v10
	v_max_f32_e32 v109, 0, v11
	v_pk_fma_f32 v[50:51], v[248:249], v[108:109], v[50:51]
	s_waitcnt lgkmcnt(2)
	v_mfma_f32_32x32x16_bf16 v[212:227], v[74:77], v[42:45], v[212:227]
	v_max_f32_e32 v210, 0, v12
	v_max_f32_e32 v211, 0, v13
	v_pk_fma_f32 v[50:51], v[250:251], v[210:211], v[50:51]
	v_max_f32_e32 v108, 0, v14
	v_max_f32_e32 v109, 0, v15
	v_pk_fma_f32 v[50:51], v[252:253], v[108:109], v[50:51]
	v_max_f32_e32 v210, 0, v16
	v_max_f32_e32 v211, 0, v17
	v_pk_fma_f32 v[50:51], v[254:255], v[210:211], v[50:51]
	s_waitcnt lgkmcnt(1)
	v_mfma_f32_32x32x16_bf16 v[212:227], v[78:81], v[46:49], v[212:227]
	v_max_f32_e32 v108, 0, v18
	v_max_f32_e32 v109, 0, v19
	v_pk_fma_f32 v[50:51], v[200:201], v[108:109], v[50:51]
	v_max_f32_e32 v210, 0, v20
	v_max_f32_e32 v211, 0, v21
	v_pk_fma_f32 v[50:51], v[202:203], v[210:211], v[50:51]
	v_add_f32_e32 v50, v50, v51
	v_ashrrev_i32_e32 v51, 31, v50
	s_waitcnt lgkmcnt(0)
	v_mfma_f32_32x32x16_bf16 v[212:227], v[82:85], v[196:199], v[212:227]
	v_or_b32_e32 v51, 0x80000000, v51
	s_cmpk_gt_i32 s11, 160
	s_cselect_b64 vcc, -1, 0
	v_xor_b32_e32 v50, v51, v50
	v_cndmask_b32_e32 v50, v123, v50, vcc
	global_store_dword v243, v50, s[8:9]
	v_mfma_f32_32x32x16_bf16 v[6:21], v[86:89], v[38:41], 0
	s_add_i32 m0, s10, 0
	s_nop 0
	global_load_lds_dwordx4 v102, s[6:7]
	s_add_i32 m0, s10, 1024
	s_nop 0
	global_load_lds_dwordx4 v110, s[6:7]
	s_add_i32 m0, s10, 2048
	s_nop 0
	global_load_lds_dwordx4 v112, s[6:7]
	s_add_i32 m0, s10, 3072
	s_nop 0
	global_load_lds_dwordx4 v193, s[6:7]
	s_add_u32 s6, s6, 0x8000
	s_addc_u32 s7, s7, 0
	v_max_f32_e32 v108, 0, v212
	v_max_f32_e32 v109, 0, v213
	v_pk_mul_f32 v[0:1], v[22:23], v[108:109]
	v_max_f32_e32 v210, 0, v214
	v_max_f32_e32 v211, 0, v215
	v_pk_fma_f32 v[0:1], v[24:25], v[210:211], v[0:1]
	v_max_f32_e32 v108, 0, v216
	v_max_f32_e32 v109, 0, v217
	v_pk_fma_f32 v[0:1], v[26:27], v[108:109], v[0:1]
	v_mfma_f32_32x32x16_bf16 v[6:21], v[90:93], v[42:45], v[6:21]
	v_max_f32_e32 v210, 0, v218
	v_max_f32_e32 v211, 0, v219
	v_pk_fma_f32 v[0:1], v[28:29], v[210:211], v[0:1]
	v_max_f32_e32 v108, 0, v220
	v_max_f32_e32 v109, 0, v221
	v_pk_fma_f32 v[0:1], v[30:31], v[108:109], v[0:1]
	v_max_f32_e32 v210, 0, v222
	v_max_f32_e32 v211, 0, v223
	v_pk_fma_f32 v[0:1], v[32:33], v[210:211], v[0:1]
	v_mfma_f32_32x32x16_bf16 v[6:21], v[94:97], v[46:49], v[6:21]
	v_max_f32_e32 v108, 0, v224
	v_max_f32_e32 v109, 0, v225
	v_pk_fma_f32 v[0:1], v[34:35], v[108:109], v[0:1]
	v_max_f32_e32 v210, 0, v226
	v_max_f32_e32 v211, 0, v227
	v_pk_fma_f32 v[0:1], v[36:37], v[210:211], v[0:1]
	v_add_f32_e32 v0, v0, v1
	v_ashrrev_i32_e32 v1, 31, v0
	v_mfma_f32_32x32x16_bf16 v[6:21], v[98:101], v[196:199], v[6:21]
	s_waitcnt vmcnt(10)
	v_add_u32_e32 v228, 0x10000, v5
	ds_read_b128 v[38:41], v228 offset:10496
	v_add_u32_e32 v228, 0x10000, v52
	ds_read_b128 v[42:45], v228 offset:10496
	v_add_u32_e32 v228, 0x10000, v55
	ds_read_b128 v[46:49], v228 offset:10496
	v_add_u32_e32 v228, 0x10000, v56
	ds_read_b128 v[196:199], v228 offset:10496
	v_or_b32_e32 v1, 0x80000000, v1
	s_cmpk_gt_i32 s11, 168
	s_cselect_b64 vcc, -1, 0
	v_xor_b32_e32 v0, v1, v0
	v_cndmask_b32_e32 v153, v123, v0, vcc
	s_nop 3
	s_waitcnt lgkmcnt(3)
	v_mfma_f32_32x32x16_bf16 v[212:227], v[70:73], v[38:41], 0
	v_max_f32_e32 v108, 0, v6
	v_max_f32_e32 v109, 0, v7
	v_pk_mul_f32 v[50:51], v[244:245], v[108:109]
	v_max_f32_e32 v210, 0, v8
	v_max_f32_e32 v211, 0, v9
	v_pk_fma_f32 v[50:51], v[246:247], v[210:211], v[50:51]
	v_max_f32_e32 v108, 0, v10
	v_max_f32_e32 v109, 0, v11
	v_pk_fma_f32 v[50:51], v[248:249], v[108:109], v[50:51]
	s_waitcnt lgkmcnt(2)
	v_mfma_f32_32x32x16_bf16 v[212:227], v[74:77], v[42:45], v[212:227]
	v_max_f32_e32 v210, 0, v12
	v_max_f32_e32 v211, 0, v13
	v_pk_fma_f32 v[50:51], v[250:251], v[210:211], v[50:51]
	v_max_f32_e32 v108, 0, v14
	v_max_f32_e32 v109, 0, v15
	v_pk_fma_f32 v[50:51], v[252:253], v[108:109], v[50:51]
	v_max_f32_e32 v210, 0, v16
	v_max_f32_e32 v211, 0, v17
	v_pk_fma_f32 v[50:51], v[254:255], v[210:211], v[50:51]
	s_waitcnt lgkmcnt(1)
	v_mfma_f32_32x32x16_bf16 v[212:227], v[78:81], v[46:49], v[212:227]
	v_max_f32_e32 v108, 0, v18
	v_max_f32_e32 v109, 0, v19
	v_pk_fma_f32 v[50:51], v[200:201], v[108:109], v[50:51]
	v_max_f32_e32 v210, 0, v20
	v_max_f32_e32 v211, 0, v21
	v_pk_fma_f32 v[50:51], v[202:203], v[210:211], v[50:51]
	v_add_f32_e32 v50, v50, v51
	v_ashrrev_i32_e32 v51, 31, v50
	s_waitcnt lgkmcnt(0)
	v_mfma_f32_32x32x16_bf16 v[212:227], v[82:85], v[196:199], v[212:227]
	v_or_b32_e32 v51, 0x80000000, v51
	s_cmpk_gt_i32 s11, 168
	s_cselect_b64 vcc, -1, 0
	v_xor_b32_e32 v50, v51, v50
	v_cndmask_b32_e32 v50, v123, v50, vcc
	global_store_dword v243, v50, s[8:9] offset:2048
	s_add_u32 s8, s8, 0x1000
	s_addc_u32 s9, s9, 0
	v_mfma_f32_32x32x16_bf16 v[6:21], v[86:89], v[38:41], 0
	s_add_i32 m0, s10, 32768
	s_nop 0
	global_load_lds_dwordx4 v102, s[6:7]
	s_add_i32 m0, s10, 33792
	s_nop 0
	global_load_lds_dwordx4 v110, s[6:7]
	s_add_i32 m0, s10, 34816
	s_nop 0
	global_load_lds_dwordx4 v112, s[6:7]
	s_add_i32 m0, s10, 35840
	s_nop 0
	global_load_lds_dwordx4 v193, s[6:7]
	s_add_u32 s6, s6, 0x8000
	s_addc_u32 s7, s7, 0
	v_max_f32_e32 v108, 0, v212
	v_max_f32_e32 v109, 0, v213
	v_pk_mul_f32 v[0:1], v[22:23], v[108:109]
	v_max_f32_e32 v210, 0, v214
	v_max_f32_e32 v211, 0, v215
	v_pk_fma_f32 v[0:1], v[24:25], v[210:211], v[0:1]
	v_max_f32_e32 v108, 0, v216
	v_max_f32_e32 v109, 0, v217
	v_pk_fma_f32 v[0:1], v[26:27], v[108:109], v[0:1]
	v_mfma_f32_32x32x16_bf16 v[6:21], v[90:93], v[42:45], v[6:21]
	v_max_f32_e32 v210, 0, v218
	v_max_f32_e32 v211, 0, v219
	v_pk_fma_f32 v[0:1], v[28:29], v[210:211], v[0:1]
	v_max_f32_e32 v108, 0, v220
	v_max_f32_e32 v109, 0, v221
	v_pk_fma_f32 v[0:1], v[30:31], v[108:109], v[0:1]
	v_max_f32_e32 v210, 0, v222
	v_max_f32_e32 v211, 0, v223
	v_pk_fma_f32 v[0:1], v[32:33], v[210:211], v[0:1]
	v_mfma_f32_32x32x16_bf16 v[6:21], v[94:97], v[46:49], v[6:21]
	v_max_f32_e32 v108, 0, v224
	v_max_f32_e32 v109, 0, v225
	v_pk_fma_f32 v[0:1], v[34:35], v[108:109], v[0:1]
	v_max_f32_e32 v210, 0, v226
	v_max_f32_e32 v211, 0, v227
	v_pk_fma_f32 v[0:1], v[36:37], v[210:211], v[0:1]
	v_add_f32_e32 v0, v0, v1
	v_ashrrev_i32_e32 v1, 31, v0
	v_mfma_f32_32x32x16_bf16 v[6:21], v[98:101], v[196:199], v[6:21]
	s_waitcnt vmcnt(10)
	v_add_u32_e32 v228, 0x10000, v5
	ds_read_b128 v[38:41], v228 offset:43264
	v_add_u32_e32 v228, 0x10000, v52
	ds_read_b128 v[42:45], v228 offset:43264
	v_add_u32_e32 v228, 0x10000, v55
	ds_read_b128 v[46:49], v228 offset:43264
	v_add_u32_e32 v228, 0x10000, v56
	ds_read_b128 v[196:199], v228 offset:43264
	v_or_b32_e32 v1, 0x80000000, v1
	s_cmpk_gt_i32 s11, 176
	s_cselect_b64 vcc, -1, 0
	v_xor_b32_e32 v0, v1, v0
	v_cndmask_b32_e32 v156, v123, v0, vcc
	s_nop 3
	s_waitcnt lgkmcnt(3)
	v_mfma_f32_32x32x16_bf16 v[212:227], v[70:73], v[38:41], 0
	v_max_f32_e32 v108, 0, v6
	v_max_f32_e32 v109, 0, v7
	v_pk_mul_f32 v[50:51], v[244:245], v[108:109]
	v_max_f32_e32 v210, 0, v8
	v_max_f32_e32 v211, 0, v9
	v_pk_fma_f32 v[50:51], v[246:247], v[210:211], v[50:51]
	v_max_f32_e32 v108, 0, v10
	v_max_f32_e32 v109, 0, v11
	v_pk_fma_f32 v[50:51], v[248:249], v[108:109], v[50:51]
	s_waitcnt lgkmcnt(2)
	v_mfma_f32_32x32x16_bf16 v[212:227], v[74:77], v[42:45], v[212:227]
	v_max_f32_e32 v210, 0, v12
	v_max_f32_e32 v211, 0, v13
	v_pk_fma_f32 v[50:51], v[250:251], v[210:211], v[50:51]
	v_max_f32_e32 v108, 0, v14
	v_max_f32_e32 v109, 0, v15
	v_pk_fma_f32 v[50:51], v[252:253], v[108:109], v[50:51]
	v_max_f32_e32 v210, 0, v16
	v_max_f32_e32 v211, 0, v17
	v_pk_fma_f32 v[50:51], v[254:255], v[210:211], v[50:51]
	s_waitcnt lgkmcnt(1)
	v_mfma_f32_32x32x16_bf16 v[212:227], v[78:81], v[46:49], v[212:227]
	v_max_f32_e32 v108, 0, v18
	v_max_f32_e32 v109, 0, v19
	v_pk_fma_f32 v[50:51], v[200:201], v[108:109], v[50:51]
	v_max_f32_e32 v210, 0, v20
	v_max_f32_e32 v211, 0, v21
	v_pk_fma_f32 v[50:51], v[202:203], v[210:211], v[50:51]
	v_add_f32_e32 v50, v50, v51
	v_ashrrev_i32_e32 v51, 31, v50
	s_waitcnt lgkmcnt(0)
	v_mfma_f32_32x32x16_bf16 v[212:227], v[82:85], v[196:199], v[212:227]
	v_or_b32_e32 v51, 0x80000000, v51
	s_cmpk_gt_i32 s11, 176
	s_cselect_b64 vcc, -1, 0
	v_xor_b32_e32 v50, v51, v50
	v_cndmask_b32_e32 v50, v123, v50, vcc
	global_store_dword v243, v50, s[8:9]
	v_mfma_f32_32x32x16_bf16 v[6:21], v[86:89], v[38:41], 0
	s_add_i32 m0, s10, 65536
	s_nop 0
	global_load_lds_dwordx4 v102, s[6:7]
	s_add_i32 m0, s10, 66560
	s_nop 0
	global_load_lds_dwordx4 v110, s[6:7]
	s_add_i32 m0, s10, 67584
	s_nop 0
	global_load_lds_dwordx4 v112, s[6:7]
	s_add_i32 m0, s10, 68608
	s_nop 0
	global_load_lds_dwordx4 v193, s[6:7]
	s_add_u32 s6, s6, 0x8000
	s_addc_u32 s7, s7, 0
	v_max_f32_e32 v108, 0, v212
	v_max_f32_e32 v109, 0, v213
	v_pk_mul_f32 v[0:1], v[22:23], v[108:109]
	v_max_f32_e32 v210, 0, v214
	v_max_f32_e32 v211, 0, v215
	v_pk_fma_f32 v[0:1], v[24:25], v[210:211], v[0:1]
	v_max_f32_e32 v108, 0, v216
	v_max_f32_e32 v109, 0, v217
	v_pk_fma_f32 v[0:1], v[26:27], v[108:109], v[0:1]
	v_mfma_f32_32x32x16_bf16 v[6:21], v[90:93], v[42:45], v[6:21]
	v_max_f32_e32 v210, 0, v218
	v_max_f32_e32 v211, 0, v219
	v_pk_fma_f32 v[0:1], v[28:29], v[210:211], v[0:1]
	v_max_f32_e32 v108, 0, v220
	v_max_f32_e32 v109, 0, v221
	v_pk_fma_f32 v[0:1], v[30:31], v[108:109], v[0:1]
	v_max_f32_e32 v210, 0, v222
	v_max_f32_e32 v211, 0, v223
	v_pk_fma_f32 v[0:1], v[32:33], v[210:211], v[0:1]
	v_mfma_f32_32x32x16_bf16 v[6:21], v[94:97], v[46:49], v[6:21]
	v_max_f32_e32 v108, 0, v224
	v_max_f32_e32 v109, 0, v225
	v_pk_fma_f32 v[0:1], v[34:35], v[108:109], v[0:1]
	v_max_f32_e32 v210, 0, v226
	v_max_f32_e32 v211, 0, v227
	v_pk_fma_f32 v[0:1], v[36:37], v[210:211], v[0:1]
	v_add_f32_e32 v0, v0, v1
	v_ashrrev_i32_e32 v1, 31, v0
	v_mfma_f32_32x32x16_bf16 v[6:21], v[98:101], v[196:199], v[6:21]
	s_waitcnt vmcnt(10)
	ds_read_b128 v[38:41], v5 offset:10496
	ds_read_b128 v[42:45], v52 offset:10496
	ds_read_b128 v[46:49], v55 offset:10496
	ds_read_b128 v[196:199], v56 offset:10496
	v_or_b32_e32 v1, 0x80000000, v1
	s_cmpk_gt_i32 s11, 184
	s_cselect_b64 vcc, -1, 0
	v_xor_b32_e32 v0, v1, v0
	v_cndmask_b32_e32 v155, v123, v0, vcc
	s_nop 3
	v_max_f32_e32 v108, 0, v6
	v_max_f32_e32 v109, 0, v7
	v_pk_mul_f32 v[50:51], v[244:245], v[108:109]
	v_max_f32_e32 v210, 0, v8
	v_max_f32_e32 v211, 0, v9
	v_pk_fma_f32 v[50:51], v[246:247], v[210:211], v[50:51]
	v_max_f32_e32 v108, 0, v10
	v_max_f32_e32 v109, 0, v11
	v_pk_fma_f32 v[50:51], v[248:249], v[108:109], v[50:51]
	v_max_f32_e32 v210, 0, v12
	v_max_f32_e32 v211, 0, v13
	v_pk_fma_f32 v[50:51], v[250:251], v[210:211], v[50:51]
	v_max_f32_e32 v108, 0, v14
	v_max_f32_e32 v109, 0, v15
	v_pk_fma_f32 v[50:51], v[252:253], v[108:109], v[50:51]
	v_max_f32_e32 v210, 0, v16
	v_max_f32_e32 v211, 0, v17
	v_pk_fma_f32 v[50:51], v[254:255], v[210:211], v[50:51]
	v_max_f32_e32 v108, 0, v18
	v_max_f32_e32 v109, 0, v19
	v_pk_fma_f32 v[50:51], v[200:201], v[108:109], v[50:51]
	v_max_f32_e32 v210, 0, v20
	v_max_f32_e32 v211, 0, v21
	v_pk_fma_f32 v[50:51], v[202:203], v[210:211], v[50:51]
	v_add_f32_e32 v50, v50, v51
	v_ashrrev_i32_e32 v51, 31, v50
	v_or_b32_e32 v51, 0x80000000, v51
	s_cmpk_gt_i32 s11, 184
	s_cselect_b64 vcc, -1, 0
	v_xor_b32_e32 v50, v51, v50
	v_cndmask_b32_e32 v50, v123, v50, vcc
	global_store_dword v243, v50, s[8:9] offset:2048
	s_add_u32 s8, s8, 0x1000
	s_addc_u32 s9, s9, 0
	s_cmpk_gt_i32 s81, 24
	s_cbranch_scc0 .Lix_fill_3
	s_waitcnt lgkmcnt(3)
	v_mfma_f32_32x32x16_bf16 v[212:227], v[70:73], v[38:41], 0
	s_add_i32 m0, s10, 98304
	s_nop 0
	global_load_lds_dwordx4 v102, s[6:7]
	s_waitcnt lgkmcnt(2)
	v_mfma_f32_32x32x16_bf16 v[212:227], v[74:77], v[42:45], v[212:227]
	s_add_i32 m0, s10, 99328
	s_nop 0
	global_load_lds_dwordx4 v110, s[6:7]
	s_waitcnt lgkmcnt(1)
	v_mfma_f32_32x32x16_bf16 v[212:227], v[78:81], v[46:49], v[212:227]
	s_add_i32 m0, s10, 100352
	s_nop 0
	global_load_lds_dwordx4 v112, s[6:7]
	s_waitcnt lgkmcnt(0)
	v_mfma_f32_32x32x16_bf16 v[212:227], v[82:85], v[196:199], v[212:227]
	s_add_i32 m0, s10, 101376
	s_nop 0
	global_load_lds_dwordx4 v193, s[6:7]
	s_add_u32 s6, s6, 0x8000
	s_addc_u32 s7, s7, 0
	v_mfma_f32_32x32x16_bf16 v[6:21], v[86:89], v[38:41], 0
	s_nop 7
	s_nop 2
	v_max_f32_e32 v108, 0, v212
	v_max_f32_e32 v109, 0, v213
	v_pk_mul_f32 v[0:1], v[22:23], v[108:109]
	v_max_f32_e32 v210, 0, v214
	v_max_f32_e32 v211, 0, v215
	v_pk_fma_f32 v[0:1], v[24:25], v[210:211], v[0:1]
	v_max_f32_e32 v108, 0, v216
	v_max_f32_e32 v109, 0, v217
	v_pk_fma_f32 v[0:1], v[26:27], v[108:109], v[0:1]
	v_mfma_f32_32x32x16_bf16 v[6:21], v[90:93], v[42:45], v[6:21]
	v_max_f32_e32 v210, 0, v218
	v_max_f32_e32 v211, 0, v219
	v_pk_fma_f32 v[0:1], v[28:29], v[210:211], v[0:1]
	v_max_f32_e32 v108, 0, v220
	v_max_f32_e32 v109, 0, v221
	v_pk_fma_f32 v[0:1], v[30:31], v[108:109], v[0:1]
	v_max_f32_e32 v210, 0, v222
	v_max_f32_e32 v211, 0, v223
	v_pk_fma_f32 v[0:1], v[32:33], v[210:211], v[0:1]
	v_mfma_f32_32x32x16_bf16 v[6:21], v[94:97], v[46:49], v[6:21]
	v_max_f32_e32 v108, 0, v224
	v_max_f32_e32 v109, 0, v225
	v_pk_fma_f32 v[0:1], v[34:35], v[108:109], v[0:1]
	v_max_f32_e32 v210, 0, v226
	v_max_f32_e32 v211, 0, v227
	v_pk_fma_f32 v[0:1], v[36:37], v[210:211], v[0:1]
	v_add_f32_e32 v0, v0, v1
	v_ashrrev_i32_e32 v1, 31, v0
	v_mfma_f32_32x32x16_bf16 v[6:21], v[98:101], v[196:199], v[6:21]
	s_waitcnt vmcnt(10)
	ds_read_b128 v[38:41], v5 offset:43264
	ds_read_b128 v[42:45], v52 offset:43264
	ds_read_b128 v[46:49], v55 offset:43264
	ds_read_b128 v[196:199], v56 offset:43264
	v_or_b32_e32 v1, 0x80000000, v1
	s_cmpk_gt_i32 s11, 192
	s_cselect_b64 vcc, -1, 0
	v_xor_b32_e32 v0, v1, v0
	v_cndmask_b32_e32 v158, v123, v0, vcc
	s_nop 3
	s_waitcnt lgkmcnt(3)
	v_mfma_f32_32x32x16_bf16 v[212:227], v[70:73], v[38:41], 0
	v_max_f32_e32 v108, 0, v6
	v_max_f32_e32 v109, 0, v7
	v_pk_mul_f32 v[50:51], v[244:245], v[108:109]
	v_max_f32_e32 v210, 0, v8
	v_max_f32_e32 v211, 0, v9
	v_pk_fma_f32 v[50:51], v[246:247], v[210:211], v[50:51]
	v_max_f32_e32 v108, 0, v10
	v_max_f32_e32 v109, 0, v11
	v_pk_fma_f32 v[50:51], v[248:249], v[108:109], v[50:51]
	s_waitcnt lgkmcnt(2)
	v_mfma_f32_32x32x16_bf16 v[212:227], v[74:77], v[42:45], v[212:227]
	v_max_f32_e32 v210, 0, v12
	v_max_f32_e32 v211, 0, v13
	v_pk_fma_f32 v[50:51], v[250:251], v[210:211], v[50:51]
	v_max_f32_e32 v108, 0, v14
	v_max_f32_e32 v109, 0, v15
	v_pk_fma_f32 v[50:51], v[252:253], v[108:109], v[50:51]
	v_max_f32_e32 v210, 0, v16
	v_max_f32_e32 v211, 0, v17
	v_pk_fma_f32 v[50:51], v[254:255], v[210:211], v[50:51]
	s_waitcnt lgkmcnt(1)
	v_mfma_f32_32x32x16_bf16 v[212:227], v[78:81], v[46:49], v[212:227]
	v_max_f32_e32 v108, 0, v18
	v_max_f32_e32 v109, 0, v19
	v_pk_fma_f32 v[50:51], v[200:201], v[108:109], v[50:51]
	v_max_f32_e32 v210, 0, v20
	v_max_f32_e32 v211, 0, v21
	v_pk_fma_f32 v[50:51], v[202:203], v[210:211], v[50:51]
	v_add_f32_e32 v50, v50, v51
	v_ashrrev_i32_e32 v51, 31, v50
	s_waitcnt lgkmcnt(0)
	v_mfma_f32_32x32x16_bf16 v[212:227], v[82:85], v[196:199], v[212:227]
	v_or_b32_e32 v51, 0x80000000, v51
	s_cmpk_gt_i32 s11, 192
	s_cselect_b64 vcc, -1, 0
	v_xor_b32_e32 v50, v51, v50
	v_cndmask_b32_e32 v50, v123, v50, vcc
	global_store_dword v243, v50, s[8:9]
	v_mfma_f32_32x32x16_bf16 v[6:21], v[86:89], v[38:41], 0
	s_add_i32 m0, s10, 0
	s_nop 0
	global_load_lds_dwordx4 v102, s[6:7]
	s_add_i32 m0, s10, 1024
	s_nop 0
	global_load_lds_dwordx4 v110, s[6:7]
	s_add_i32 m0, s10, 2048
	s_nop 0
	global_load_lds_dwordx4 v112, s[6:7]
	s_add_i32 m0, s10, 3072
	s_nop 0
	global_load_lds_dwordx4 v193, s[6:7]
	s_add_u32 s6, s6, 0x8000
	s_addc_u32 s7, s7, 0
	v_max_f32_e32 v108, 0, v212
	v_max_f32_e32 v109, 0, v213
	v_pk_mul_f32 v[0:1], v[22:23], v[108:109]
	v_max_f32_e32 v210, 0, v214
	v_max_f32_e32 v211, 0, v215
	v_pk_fma_f32 v[0:1], v[24:25], v[210:211], v[0:1]
	v_max_f32_e32 v108, 0, v216
	v_max_f32_e32 v109, 0, v217
	v_pk_fma_f32 v[0:1], v[26:27], v[108:109], v[0:1]
	v_mfma_f32_32x32x16_bf16 v[6:21], v[90:93], v[42:45], v[6:21]
	v_max_f32_e32 v210, 0, v218
	v_max_f32_e32 v211, 0, v219
	v_pk_fma_f32 v[0:1], v[28:29], v[210:211], v[0:1]
	v_max_f32_e32 v108, 0, v220
	v_max_f32_e32 v109, 0, v221
	v_pk_fma_f32 v[0:1], v[30:31], v[108:109], v[0:1]
	v_max_f32_e32 v210, 0, v222
	v_max_f32_e32 v211, 0, v223
	v_pk_fma_f32 v[0:1], v[32:33], v[210:211], v[0:1]
	v_mfma_f32_32x32x16_bf16 v[6:21], v[94:97], v[46:49], v[6:21]
	v_max_f32_e32 v108, 0, v224
	v_max_f32_e32 v109, 0, v225
	v_pk_fma_f32 v[0:1], v[34:35], v[108:109], v[0:1]
	v_max_f32_e32 v210, 0, v226
	v_max_f32_e32 v211, 0, v227
	v_pk_fma_f32 v[0:1], v[36:37], v[210:211], v[0:1]
	v_add_f32_e32 v0, v0, v1
	v_ashrrev_i32_e32 v1, 31, v0
	v_mfma_f32_32x32x16_bf16 v[6:21], v[98:101], v[196:199], v[6:21]
	s_waitcnt vmcnt(10)
	v_add_u32_e32 v228, 0x10000, v5
	ds_read_b128 v[38:41], v228 offset:10496
	v_add_u32_e32 v228, 0x10000, v52
	ds_read_b128 v[42:45], v228 offset:10496
	v_add_u32_e32 v228, 0x10000, v55
	ds_read_b128 v[46:49], v228 offset:10496
	v_add_u32_e32 v228, 0x10000, v56
	ds_read_b128 v[196:199], v228 offset:10496
	v_or_b32_e32 v1, 0x80000000, v1
	s_cmpk_gt_i32 s11, 200
	s_cselect_b64 vcc, -1, 0
	v_xor_b32_e32 v0, v1, v0
	v_cndmask_b32_e32 v157, v123, v0, vcc
	s_nop 3
	s_waitcnt lgkmcnt(3)
	v_mfma_f32_32x32x16_bf16 v[212:227], v[70:73], v[38:41], 0
	v_max_f32_e32 v108, 0, v6
	v_max_f32_e32 v109, 0, v7
	v_pk_mul_f32 v[50:51], v[244:245], v[108:109]
	v_max_f32_e32 v210, 0, v8
	v_max_f32_e32 v211, 0, v9
	v_pk_fma_f32 v[50:51], v[246:247], v[210:211], v[50:51]
	v_max_f32_e32 v108, 0, v10
	v_max_f32_e32 v109, 0, v11
	v_pk_fma_f32 v[50:51], v[248:249], v[108:109], v[50:51]
	s_waitcnt lgkmcnt(2)
	v_mfma_f32_32x32x16_bf16 v[212:227], v[74:77], v[42:45], v[212:227]
	v_max_f32_e32 v210, 0, v12
	v_max_f32_e32 v211, 0, v13
	v_pk_fma_f32 v[50:51], v[250:251], v[210:211], v[50:51]
	v_max_f32_e32 v108, 0, v14
	v_max_f32_e32 v109, 0, v15
	v_pk_fma_f32 v[50:51], v[252:253], v[108:109], v[50:51]
	v_max_f32_e32 v210, 0, v16
	v_max_f32_e32 v211, 0, v17
	v_pk_fma_f32 v[50:51], v[254:255], v[210:211], v[50:51]
	s_waitcnt lgkmcnt(1)
	v_mfma_f32_32x32x16_bf16 v[212:227], v[78:81], v[46:49], v[212:227]
	v_max_f32_e32 v108, 0, v18
	v_max_f32_e32 v109, 0, v19
	v_pk_fma_f32 v[50:51], v[200:201], v[108:109], v[50:51]
	v_max_f32_e32 v210, 0, v20
	v_max_f32_e32 v211, 0, v21
	v_pk_fma_f32 v[50:51], v[202:203], v[210:211], v[50:51]
	v_add_f32_e32 v50, v50, v51
	v_ashrrev_i32_e32 v51, 31, v50
	s_waitcnt lgkmcnt(0)
	v_mfma_f32_32x32x16_bf16 v[212:227], v[82:85], v[196:199], v[212:227]
	v_or_b32_e32 v51, 0x80000000, v51
	s_cmpk_gt_i32 s11, 200
	s_cselect_b64 vcc, -1, 0
	v_xor_b32_e32 v50, v51, v50
	v_cndmask_b32_e32 v50, v123, v50, vcc
	global_store_dword v243, v50, s[8:9] offset:2048
	s_add_u32 s8, s8, 0x1000
	s_addc_u32 s9, s9, 0
	v_mfma_f32_32x32x16_bf16 v[6:21], v[86:89], v[38:41], 0
	s_add_i32 m0, s10, 32768
	s_nop 0
	global_load_lds_dwordx4 v102, s[6:7]
	s_add_i32 m0, s10, 33792
	s_nop 0
	global_load_lds_dwordx4 v110, s[6:7]
	s_add_i32 m0, s10, 34816
	s_nop 0
	global_load_lds_dwordx4 v112, s[6:7]
	s_add_i32 m0, s10, 35840
	s_nop 0
	global_load_lds_dwordx4 v193, s[6:7]
	s_add_u32 s6, s6, 0x8000
	s_addc_u32 s7, s7, 0
	v_max_f32_e32 v108, 0, v212
	v_max_f32_e32 v109, 0, v213
	v_pk_mul_f32 v[0:1], v[22:23], v[108:109]
	v_max_f32_e32 v210, 0, v214
	v_max_f32_e32 v211, 0, v215
	v_pk_fma_f32 v[0:1], v[24:25], v[210:211], v[0:1]
	v_max_f32_e32 v108, 0, v216
	v_max_f32_e32 v109, 0, v217
	v_pk_fma_f32 v[0:1], v[26:27], v[108:109], v[0:1]
	v_mfma_f32_32x32x16_bf16 v[6:21], v[90:93], v[42:45], v[6:21]
	v_max_f32_e32 v210, 0, v218
	v_max_f32_e32 v211, 0, v219
	v_pk_fma_f32 v[0:1], v[28:29], v[210:211], v[0:1]
	v_max_f32_e32 v108, 0, v220
	v_max_f32_e32 v109, 0, v221
	v_pk_fma_f32 v[0:1], v[30:31], v[108:109], v[0:1]
	v_max_f32_e32 v210, 0, v222
	v_max_f32_e32 v211, 0, v223
	v_pk_fma_f32 v[0:1], v[32:33], v[210:211], v[0:1]
	v_mfma_f32_32x32x16_bf16 v[6:21], v[94:97], v[46:49], v[6:21]
	v_max_f32_e32 v108, 0, v224
	v_max_f32_e32 v109, 0, v225
	v_pk_fma_f32 v[0:1], v[34:35], v[108:109], v[0:1]
	v_max_f32_e32 v210, 0, v226
	v_max_f32_e32 v211, 0, v227
	v_pk_fma_f32 v[0:1], v[36:37], v[210:211], v[0:1]
	v_add_f32_e32 v0, v0, v1
	v_ashrrev_i32_e32 v1, 31, v0
	v_mfma_f32_32x32x16_bf16 v[6:21], v[98:101], v[196:199], v[6:21]
	s_waitcnt vmcnt(10)
	v_add_u32_e32 v228, 0x10000, v5
	ds_read_b128 v[38:41], v228 offset:43264
	v_add_u32_e32 v228, 0x10000, v52
	ds_read_b128 v[42:45], v228 offset:43264
	v_add_u32_e32 v228, 0x10000, v55
	ds_read_b128 v[46:49], v228 offset:43264
	v_add_u32_e32 v228, 0x10000, v56
	ds_read_b128 v[196:199], v228 offset:43264
	v_or_b32_e32 v1, 0x80000000, v1
	s_cmpk_gt_i32 s11, 208
	s_cselect_b64 vcc, -1, 0
	v_xor_b32_e32 v0, v1, v0
	v_cndmask_b32_e32 v160, v123, v0, vcc
	s_nop 3
	s_waitcnt lgkmcnt(3)
	v_mfma_f32_32x32x16_bf16 v[212:227], v[70:73], v[38:41], 0
	v_max_f32_e32 v108, 0, v6
	v_max_f32_e32 v109, 0, v7
	v_pk_mul_f32 v[50:51], v[244:245], v[108:109]
	v_max_f32_e32 v210, 0, v8
	v_max_f32_e32 v211, 0, v9
	v_pk_fma_f32 v[50:51], v[246:247], v[210:211], v[50:51]
	v_max_f32_e32 v108, 0, v10
	v_max_f32_e32 v109, 0, v11
	v_pk_fma_f32 v[50:51], v[248:249], v[108:109], v[50:51]
	s_waitcnt lgkmcnt(2)
	v_mfma_f32_32x32x16_bf16 v[212:227], v[74:77], v[42:45], v[212:227]
	v_max_f32_e32 v210, 0, v12
	v_max_f32_e32 v211, 0, v13
	v_pk_fma_f32 v[50:51], v[250:251], v[210:211], v[50:51]
	v_max_f32_e32 v108, 0, v14
	v_max_f32_e32 v109, 0, v15
	v_pk_fma_f32 v[50:51], v[252:253], v[108:109], v[50:51]
	v_max_f32_e32 v210, 0, v16
	v_max_f32_e32 v211, 0, v17
	v_pk_fma_f32 v[50:51], v[254:255], v[210:211], v[50:51]
	s_waitcnt lgkmcnt(1)
	v_mfma_f32_32x32x16_bf16 v[212:227], v[78:81], v[46:49], v[212:227]
	v_max_f32_e32 v108, 0, v18
	v_max_f32_e32 v109, 0, v19
	v_pk_fma_f32 v[50:51], v[200:201], v[108:109], v[50:51]
	v_max_f32_e32 v210, 0, v20
	v_max_f32_e32 v211, 0, v21
	v_pk_fma_f32 v[50:51], v[202:203], v[210:211], v[50:51]
	v_add_f32_e32 v50, v50, v51
	v_ashrrev_i32_e32 v51, 31, v50
	s_waitcnt lgkmcnt(0)
	v_mfma_f32_32x32x16_bf16 v[212:227], v[82:85], v[196:199], v[212:227]
	v_or_b32_e32 v51, 0x80000000, v51
	s_cmpk_gt_i32 s11, 208
	s_cselect_b64 vcc, -1, 0
	v_xor_b32_e32 v50, v51, v50
	v_cndmask_b32_e32 v50, v123, v50, vcc
	global_store_dword v243, v50, s[8:9]
	v_mfma_f32_32x32x16_bf16 v[6:21], v[86:89], v[38:41], 0
	s_add_i32 m0, s10, 65536
	s_nop 0
	global_load_lds_dwordx4 v102, s[6:7]
	s_add_i32 m0, s10, 66560
	s_nop 0
	global_load_lds_dwordx4 v110, s[6:7]
	s_add_i32 m0, s10, 67584
	s_nop 0
	global_load_lds_dwordx4 v112, s[6:7]
	s_add_i32 m0, s10, 68608
	s_nop 0
	global_load_lds_dwordx4 v193, s[6:7]
	s_add_u32 s6, s6, 0x8000
	s_addc_u32 s7, s7, 0
	v_max_f32_e32 v108, 0, v212
	v_max_f32_e32 v109, 0, v213
	v_pk_mul_f32 v[0:1], v[22:23], v[108:109]
	v_max_f32_e32 v210, 0, v214
	v_max_f32_e32 v211, 0, v215
	v_pk_fma_f32 v[0:1], v[24:25], v[210:211], v[0:1]
	v_max_f32_e32 v108, 0, v216
	v_max_f32_e32 v109, 0, v217
	v_pk_fma_f32 v[0:1], v[26:27], v[108:109], v[0:1]
	v_mfma_f32_32x32x16_bf16 v[6:21], v[90:93], v[42:45], v[6:21]
	v_max_f32_e32 v210, 0, v218
	v_max_f32_e32 v211, 0, v219
	v_pk_fma_f32 v[0:1], v[28:29], v[210:211], v[0:1]
	v_max_f32_e32 v108, 0, v220
	v_max_f32_e32 v109, 0, v221
	v_pk_fma_f32 v[0:1], v[30:31], v[108:109], v[0:1]
	v_max_f32_e32 v210, 0, v222
	v_max_f32_e32 v211, 0, v223
	v_pk_fma_f32 v[0:1], v[32:33], v[210:211], v[0:1]
	v_mfma_f32_32x32x16_bf16 v[6:21], v[94:97], v[46:49], v[6:21]
	v_max_f32_e32 v108, 0, v224
	v_max_f32_e32 v109, 0, v225
	v_pk_fma_f32 v[0:1], v[34:35], v[108:109], v[0:1]
	v_max_f32_e32 v210, 0, v226
	v_max_f32_e32 v211, 0, v227
	v_pk_fma_f32 v[0:1], v[36:37], v[210:211], v[0:1]
	v_add_f32_e32 v0, v0, v1
	v_ashrrev_i32_e32 v1, 31, v0
	v_mfma_f32_32x32x16_bf16 v[6:21], v[98:101], v[196:199], v[6:21]
	s_waitcnt vmcnt(10)
	ds_read_b128 v[38:41], v5 offset:10496
	ds_read_b128 v[42:45], v52 offset:10496
	ds_read_b128 v[46:49], v55 offset:10496
	ds_read_b128 v[196:199], v56 offset:10496
	v_or_b32_e32 v1, 0x80000000, v1
	s_cmpk_gt_i32 s11, 216
	s_cselect_b64 vcc, -1, 0
	v_xor_b32_e32 v0, v1, v0
	v_cndmask_b32_e32 v159, v123, v0, vcc
	s_nop 3
	s_waitcnt lgkmcnt(3)
	v_mfma_f32_32x32x16_bf16 v[212:227], v[70:73], v[38:41], 0
	v_max_f32_e32 v108, 0, v6
	v_max_f32_e32 v109, 0, v7
	v_pk_mul_f32 v[50:51], v[244:245], v[108:109]
	v_max_f32_e32 v210, 0, v8
	v_max_f32_e32 v211, 0, v9
	v_pk_fma_f32 v[50:51], v[246:247], v[210:211], v[50:51]
	v_max_f32_e32 v108, 0, v10
	v_max_f32_e32 v109, 0, v11
	v_pk_fma_f32 v[50:51], v[248:249], v[108:109], v[50:51]
	s_waitcnt lgkmcnt(2)
	v_mfma_f32_32x32x16_bf16 v[212:227], v[74:77], v[42:45], v[212:227]
	v_max_f32_e32 v210, 0, v12
	v_max_f32_e32 v211, 0, v13
	v_pk_fma_f32 v[50:51], v[250:251], v[210:211], v[50:51]
	v_max_f32_e32 v108, 0, v14
	v_max_f32_e32 v109, 0, v15
	v_pk_fma_f32 v[50:51], v[252:253], v[108:109], v[50:51]
	v_max_f32_e32 v210, 0, v16
	v_max_f32_e32 v211, 0, v17
	v_pk_fma_f32 v[50:51], v[254:255], v[210:211], v[50:51]
	s_waitcnt lgkmcnt(1)
	v_mfma_f32_32x32x16_bf16 v[212:227], v[78:81], v[46:49], v[212:227]
	v_max_f32_e32 v108, 0, v18
	v_max_f32_e32 v109, 0, v19
	v_pk_fma_f32 v[50:51], v[200:201], v[108:109], v[50:51]
	v_max_f32_e32 v210, 0, v20
	v_max_f32_e32 v211, 0, v21
	v_pk_fma_f32 v[50:51], v[202:203], v[210:211], v[50:51]
	v_add_f32_e32 v50, v50, v51
	v_ashrrev_i32_e32 v51, 31, v50
	s_waitcnt lgkmcnt(0)
	v_mfma_f32_32x32x16_bf16 v[212:227], v[82:85], v[196:199], v[212:227]
	v_or_b32_e32 v51, 0x80000000, v51
	s_cmpk_gt_i32 s11, 216
	s_cselect_b64 vcc, -1, 0
	v_xor_b32_e32 v50, v51, v50
	v_cndmask_b32_e32 v50, v123, v50, vcc
	global_store_dword v243, v50, s[8:9] offset:2048
	s_add_u32 s8, s8, 0x1000
	s_addc_u32 s9, s9, 0
	v_mfma_f32_32x32x16_bf16 v[6:21], v[86:89], v[38:41], 0
	s_add_i32 m0, s10, 98304
	s_nop 0
	global_load_lds_dwordx4 v102, s[6:7]
	s_add_i32 m0, s10, 99328
	s_nop 0
	global_load_lds_dwordx4 v110, s[6:7]
	s_add_i32 m0, s10, 100352
	s_nop 0
	global_load_lds_dwordx4 v112, s[6:7]
	s_add_i32 m0, s10, 101376
	s_nop 0
	global_load_lds_dwordx4 v193, s[6:7]
	s_add_u32 s6, s6, 0x8000
	s_addc_u32 s7, s7, 0
	v_max_f32_e32 v108, 0, v212
	v_max_f32_e32 v109, 0, v213
	v_pk_mul_f32 v[0:1], v[22:23], v[108:109]
	v_max_f32_e32 v210, 0, v214
	v_max_f32_e32 v211, 0, v215
	v_pk_fma_f32 v[0:1], v[24:25], v[210:211], v[0:1]
	v_max_f32_e32 v108, 0, v216
	v_max_f32_e32 v109, 0, v217
	v_pk_fma_f32 v[0:1], v[26:27], v[108:109], v[0:1]
	v_mfma_f32_32x32x16_bf16 v[6:21], v[90:93], v[42:45], v[6:21]
	v_max_f32_e32 v210, 0, v218
	v_max_f32_e32 v211, 0, v219
	v_pk_fma_f32 v[0:1], v[28:29], v[210:211], v[0:1]
	v_max_f32_e32 v108, 0, v220
	v_max_f32_e32 v109, 0, v221
	v_pk_fma_f32 v[0:1], v[30:31], v[108:109], v[0:1]
	v_max_f32_e32 v210, 0, v222
	v_max_f32_e32 v211, 0, v223
	v_pk_fma_f32 v[0:1], v[32:33], v[210:211], v[0:1]
	v_mfma_f32_32x32x16_bf16 v[6:21], v[94:97], v[46:49], v[6:21]
	v_max_f32_e32 v108, 0, v224
	v_max_f32_e32 v109, 0, v225
	v_pk_fma_f32 v[0:1], v[34:35], v[108:109], v[0:1]
	v_max_f32_e32 v210, 0, v226
	v_max_f32_e32 v211, 0, v227
	v_pk_fma_f32 v[0:1], v[36:37], v[210:211], v[0:1]
	v_add_f32_e32 v0, v0, v1
	v_ashrrev_i32_e32 v1, 31, v0
	v_mfma_f32_32x32x16_bf16 v[6:21], v[98:101], v[196:199], v[6:21]
	s_waitcnt vmcnt(10)
	ds_read_b128 v[38:41], v5 offset:43264
	ds_read_b128 v[42:45], v52 offset:43264
	ds_read_b128 v[46:49], v55 offset:43264
	ds_read_b128 v[196:199], v56 offset:43264
	v_or_b32_e32 v1, 0x80000000, v1
	s_cmpk_gt_i32 s11, 224
	s_cselect_b64 vcc, -1, 0
	v_xor_b32_e32 v0, v1, v0
	v_cndmask_b32_e32 v162, v123, v0, vcc
	s_nop 3
	s_waitcnt lgkmcnt(3)
	v_mfma_f32_32x32x16_bf16 v[212:227], v[70:73], v[38:41], 0
	v_max_f32_e32 v108, 0, v6
	v_max_f32_e32 v109, 0, v7
	v_pk_mul_f32 v[50:51], v[244:245], v[108:109]
	v_max_f32_e32 v210, 0, v8
	v_max_f32_e32 v211, 0, v9
	v_pk_fma_f32 v[50:51], v[246:247], v[210:211], v[50:51]
	v_max_f32_e32 v108, 0, v10
	v_max_f32_e32 v109, 0, v11
	v_pk_fma_f32 v[50:51], v[248:249], v[108:109], v[50:51]
	s_waitcnt lgkmcnt(2)
	v_mfma_f32_32x32x16_bf16 v[212:227], v[74:77], v[42:45], v[212:227]
	v_max_f32_e32 v210, 0, v12
	v_max_f32_e32 v211, 0, v13
	v_pk_fma_f32 v[50:51], v[250:251], v[210:211], v[50:51]
	v_max_f32_e32 v108, 0, v14
	v_max_f32_e32 v109, 0, v15
	v_pk_fma_f32 v[50:51], v[252:253], v[108:109], v[50:51]
	v_max_f32_e32 v210, 0, v16
	v_max_f32_e32 v211, 0, v17
	v_pk_fma_f32 v[50:51], v[254:255], v[210:211], v[50:51]
	s_waitcnt lgkmcnt(1)
	v_mfma_f32_32x32x16_bf16 v[212:227], v[78:81], v[46:49], v[212:227]
	v_max_f32_e32 v108, 0, v18
	v_max_f32_e32 v109, 0, v19
	v_pk_fma_f32 v[50:51], v[200:201], v[108:109], v[50:51]
	v_max_f32_e32 v210, 0, v20
	v_max_f32_e32 v211, 0, v21
	v_pk_fma_f32 v[50:51], v[202:203], v[210:211], v[50:51]
	v_add_f32_e32 v50, v50, v51
	v_ashrrev_i32_e32 v51, 31, v50
	s_waitcnt lgkmcnt(0)
	v_mfma_f32_32x32x16_bf16 v[212:227], v[82:85], v[196:199], v[212:227]
	v_or_b32_e32 v51, 0x80000000, v51
	s_cmpk_gt_i32 s11, 224
	s_cselect_b64 vcc, -1, 0
	v_xor_b32_e32 v50, v51, v50
	v_cndmask_b32_e32 v50, v123, v50, vcc
	global_store_dword v243, v50, s[8:9]
	v_mfma_f32_32x32x16_bf16 v[6:21], v[86:89], v[38:41], 0
	s_add_i32 m0, s10, 0
	s_nop 0
	global_load_lds_dwordx4 v102, s[6:7]
	s_add_i32 m0, s10, 1024
	s_nop 0
	global_load_lds_dwordx4 v110, s[6:7]
	s_add_i32 m0, s10, 2048
	s_nop 0
	global_load_lds_dwordx4 v112, s[6:7]
	s_add_i32 m0, s10, 3072
	s_nop 0
	global_load_lds_dwordx4 v193, s[6:7]
	s_add_u32 s6, s6, 0x8000
	s_addc_u32 s7, s7, 0
	v_max_f32_e32 v108, 0, v212
	v_max_f32_e32 v109, 0, v213
	v_pk_mul_f32 v[0:1], v[22:23], v[108:109]
	v_max_f32_e32 v210, 0, v214
	v_max_f32_e32 v211, 0, v215
	v_pk_fma_f32 v[0:1], v[24:25], v[210:211], v[0:1]
	v_max_f32_e32 v108, 0, v216
	v_max_f32_e32 v109, 0, v217
	v_pk_fma_f32 v[0:1], v[26:27], v[108:109], v[0:1]
	v_mfma_f32_32x32x16_bf16 v[6:21], v[90:93], v[42:45], v[6:21]
	v_max_f32_e32 v210, 0, v218
	v_max_f32_e32 v211, 0, v219
	v_pk_fma_f32 v[0:1], v[28:29], v[210:211], v[0:1]
	v_max_f32_e32 v108, 0, v220
	v_max_f32_e32 v109, 0, v221
	v_pk_fma_f32 v[0:1], v[30:31], v[108:109], v[0:1]
	v_max_f32_e32 v210, 0, v222
	v_max_f32_e32 v211, 0, v223
	v_pk_fma_f32 v[0:1], v[32:33], v[210:211], v[0:1]
	v_mfma_f32_32x32x16_bf16 v[6:21], v[94:97], v[46:49], v[6:21]
	v_max_f32_e32 v108, 0, v224
	v_max_f32_e32 v109, 0, v225
	v_pk_fma_f32 v[0:1], v[34:35], v[108:109], v[0:1]
	v_max_f32_e32 v210, 0, v226
	v_max_f32_e32 v211, 0, v227
	v_pk_fma_f32 v[0:1], v[36:37], v[210:211], v[0:1]
	v_add_f32_e32 v0, v0, v1
	v_ashrrev_i32_e32 v1, 31, v0
	v_mfma_f32_32x32x16_bf16 v[6:21], v[98:101], v[196:199], v[6:21]
	s_waitcnt vmcnt(10)
	v_add_u32_e32 v228, 0x10000, v5
	ds_read_b128 v[38:41], v228 offset:10496
	v_add_u32_e32 v228, 0x10000, v52
	ds_read_b128 v[42:45], v228 offset:10496
	v_add_u32_e32 v228, 0x10000, v55
	ds_read_b128 v[46:49], v228 offset:10496
	v_add_u32_e32 v228, 0x10000, v56
	ds_read_b128 v[196:199], v228 offset:10496
	v_or_b32_e32 v1, 0x80000000, v1
	s_cmpk_gt_i32 s11, 232
	s_cselect_b64 vcc, -1, 0
	v_xor_b32_e32 v0, v1, v0
	v_cndmask_b32_e32 v161, v123, v0, vcc
	s_nop 3
	s_waitcnt lgkmcnt(3)
	v_mfma_f32_32x32x16_bf16 v[212:227], v[70:73], v[38:41], 0
	v_max_f32_e32 v108, 0, v6
	v_max_f32_e32 v109, 0, v7
	v_pk_mul_f32 v[50:51], v[244:245], v[108:109]
	v_max_f32_e32 v210, 0, v8
	v_max_f32_e32 v211, 0, v9
	v_pk_fma_f32 v[50:51], v[246:247], v[210:211], v[50:51]
	v_max_f32_e32 v108, 0, v10
	v_max_f32_e32 v109, 0, v11
	v_pk_fma_f32 v[50:51], v[248:249], v[108:109], v[50:51]
	s_waitcnt lgkmcnt(2)
	v_mfma_f32_32x32x16_bf16 v[212:227], v[74:77], v[42:45], v[212:227]
	v_max_f32_e32 v210, 0, v12
	v_max_f32_e32 v211, 0, v13
	v_pk_fma_f32 v[50:51], v[250:251], v[210:211], v[50:51]
	v_max_f32_e32 v108, 0, v14
	v_max_f32_e32 v109, 0, v15
	v_pk_fma_f32 v[50:51], v[252:253], v[108:109], v[50:51]
	v_max_f32_e32 v210, 0, v16
	v_max_f32_e32 v211, 0, v17
	v_pk_fma_f32 v[50:51], v[254:255], v[210:211], v[50:51]
	s_waitcnt lgkmcnt(1)
	v_mfma_f32_32x32x16_bf16 v[212:227], v[78:81], v[46:49], v[212:227]
	v_max_f32_e32 v108, 0, v18
	v_max_f32_e32 v109, 0, v19
	v_pk_fma_f32 v[50:51], v[200:201], v[108:109], v[50:51]
	v_max_f32_e32 v210, 0, v20
	v_max_f32_e32 v211, 0, v21
	v_pk_fma_f32 v[50:51], v[202:203], v[210:211], v[50:51]
	v_add_f32_e32 v50, v50, v51
	v_ashrrev_i32_e32 v51, 31, v50
	s_waitcnt lgkmcnt(0)
	v_mfma_f32_32x32x16_bf16 v[212:227], v[82:85], v[196:199], v[212:227]
	v_or_b32_e32 v51, 0x80000000, v51
	s_cmpk_gt_i32 s11, 232
	s_cselect_b64 vcc, -1, 0
	v_xor_b32_e32 v50, v51, v50
	v_cndmask_b32_e32 v50, v123, v50, vcc
	global_store_dword v243, v50, s[8:9] offset:2048
	s_add_u32 s8, s8, 0x1000
	s_addc_u32 s9, s9, 0
	v_mfma_f32_32x32x16_bf16 v[6:21], v[86:89], v[38:41], 0
	s_add_i32 m0, s10, 32768
	s_nop 0
	global_load_lds_dwordx4 v102, s[6:7]
	s_add_i32 m0, s10, 33792
	s_nop 0
	global_load_lds_dwordx4 v110, s[6:7]
	s_add_i32 m0, s10, 34816
	s_nop 0
	global_load_lds_dwordx4 v112, s[6:7]
	s_add_i32 m0, s10, 35840
	s_nop 0
	global_load_lds_dwordx4 v193, s[6:7]
	s_add_u32 s6, s6, 0x8000
	s_addc_u32 s7, s7, 0
	v_max_f32_e32 v108, 0, v212
	v_max_f32_e32 v109, 0, v213
	v_pk_mul_f32 v[0:1], v[22:23], v[108:109]
	v_max_f32_e32 v210, 0, v214
	v_max_f32_e32 v211, 0, v215
	v_pk_fma_f32 v[0:1], v[24:25], v[210:211], v[0:1]
	v_max_f32_e32 v108, 0, v216
	v_max_f32_e32 v109, 0, v217
	v_pk_fma_f32 v[0:1], v[26:27], v[108:109], v[0:1]
	v_mfma_f32_32x32x16_bf16 v[6:21], v[90:93], v[42:45], v[6:21]
	v_max_f32_e32 v210, 0, v218
	v_max_f32_e32 v211, 0, v219
	v_pk_fma_f32 v[0:1], v[28:29], v[210:211], v[0:1]
	v_max_f32_e32 v108, 0, v220
	v_max_f32_e32 v109, 0, v221
	v_pk_fma_f32 v[0:1], v[30:31], v[108:109], v[0:1]
	v_max_f32_e32 v210, 0, v222
	v_max_f32_e32 v211, 0, v223
	v_pk_fma_f32 v[0:1], v[32:33], v[210:211], v[0:1]
	v_mfma_f32_32x32x16_bf16 v[6:21], v[94:97], v[46:49], v[6:21]
	v_max_f32_e32 v108, 0, v224
	v_max_f32_e32 v109, 0, v225
	v_pk_fma_f32 v[0:1], v[34:35], v[108:109], v[0:1]
	v_max_f32_e32 v210, 0, v226
	v_max_f32_e32 v211, 0, v227
	v_pk_fma_f32 v[0:1], v[36:37], v[210:211], v[0:1]
	v_add_f32_e32 v0, v0, v1
	v_ashrrev_i32_e32 v1, 31, v0
	v_mfma_f32_32x32x16_bf16 v[6:21], v[98:101], v[196:199], v[6:21]
	s_waitcnt vmcnt(10)
	v_add_u32_e32 v228, 0x10000, v5
	ds_read_b128 v[38:41], v228 offset:43264
	v_add_u32_e32 v228, 0x10000, v52
	ds_read_b128 v[42:45], v228 offset:43264
	v_add_u32_e32 v228, 0x10000, v55
	ds_read_b128 v[46:49], v228 offset:43264
	v_add_u32_e32 v228, 0x10000, v56
	ds_read_b128 v[196:199], v228 offset:43264
	v_or_b32_e32 v1, 0x80000000, v1
	s_cmpk_gt_i32 s11, 240
	s_cselect_b64 vcc, -1, 0
	v_xor_b32_e32 v0, v1, v0
	v_cndmask_b32_e32 v163, v123, v0, vcc
	s_nop 3
	s_waitcnt lgkmcnt(3)
	v_mfma_f32_32x32x16_bf16 v[212:227], v[70:73], v[38:41], 0
	v_max_f32_e32 v108, 0, v6
	v_max_f32_e32 v109, 0, v7
	v_pk_mul_f32 v[50:51], v[244:245], v[108:109]
	v_max_f32_e32 v210, 0, v8
	v_max_f32_e32 v211, 0, v9
	v_pk_fma_f32 v[50:51], v[246:247], v[210:211], v[50:51]
	v_max_f32_e32 v108, 0, v10
	v_max_f32_e32 v109, 0, v11
	v_pk_fma_f32 v[50:51], v[248:249], v[108:109], v[50:51]
	s_waitcnt lgkmcnt(2)
	v_mfma_f32_32x32x16_bf16 v[212:227], v[74:77], v[42:45], v[212:227]
	v_max_f32_e32 v210, 0, v12
	v_max_f32_e32 v211, 0, v13
	v_pk_fma_f32 v[50:51], v[250:251], v[210:211], v[50:51]
	v_max_f32_e32 v108, 0, v14
	v_max_f32_e32 v109, 0, v15
	v_pk_fma_f32 v[50:51], v[252:253], v[108:109], v[50:51]
	v_max_f32_e32 v210, 0, v16
	v_max_f32_e32 v211, 0, v17
	v_pk_fma_f32 v[50:51], v[254:255], v[210:211], v[50:51]
	s_waitcnt lgkmcnt(1)
	v_mfma_f32_32x32x16_bf16 v[212:227], v[78:81], v[46:49], v[212:227]
	v_max_f32_e32 v108, 0, v18
	v_max_f32_e32 v109, 0, v19
	v_pk_fma_f32 v[50:51], v[200:201], v[108:109], v[50:51]
	v_max_f32_e32 v210, 0, v20
	v_max_f32_e32 v211, 0, v21
	v_pk_fma_f32 v[50:51], v[202:203], v[210:211], v[50:51]
	v_add_f32_e32 v50, v50, v51
	v_ashrrev_i32_e32 v51, 31, v50
	s_waitcnt lgkmcnt(0)
	v_mfma_f32_32x32x16_bf16 v[212:227], v[82:85], v[196:199], v[212:227]
	v_or_b32_e32 v51, 0x80000000, v51
	s_cmpk_gt_i32 s11, 240
	s_cselect_b64 vcc, -1, 0
	v_xor_b32_e32 v50, v51, v50
	v_cndmask_b32_e32 v50, v123, v50, vcc
	global_store_dword v243, v50, s[8:9]
	v_mfma_f32_32x32x16_bf16 v[6:21], v[86:89], v[38:41], 0
	s_add_i32 m0, s10, 65536
	s_nop 0
	global_load_lds_dwordx4 v102, s[6:7]
	s_add_i32 m0, s10, 66560
	s_nop 0
	global_load_lds_dwordx4 v110, s[6:7]
	s_add_i32 m0, s10, 67584
	s_nop 0
	global_load_lds_dwordx4 v112, s[6:7]
	s_add_i32 m0, s10, 68608
	s_nop 0
	global_load_lds_dwordx4 v193, s[6:7]
	s_add_u32 s6, s6, 0x8000
	s_addc_u32 s7, s7, 0
	v_max_f32_e32 v108, 0, v212
	v_max_f32_e32 v109, 0, v213
	v_pk_mul_f32 v[0:1], v[22:23], v[108:109]
	v_max_f32_e32 v210, 0, v214
	v_max_f32_e32 v211, 0, v215
	v_pk_fma_f32 v[0:1], v[24:25], v[210:211], v[0:1]
	v_max_f32_e32 v108, 0, v216
	v_max_f32_e32 v109, 0, v217
	v_pk_fma_f32 v[0:1], v[26:27], v[108:109], v[0:1]
	v_mfma_f32_32x32x16_bf16 v[6:21], v[90:93], v[42:45], v[6:21]
	v_max_f32_e32 v210, 0, v218
	v_max_f32_e32 v211, 0, v219
	v_pk_fma_f32 v[0:1], v[28:29], v[210:211], v[0:1]
	v_max_f32_e32 v108, 0, v220
	v_max_f32_e32 v109, 0, v221
	v_pk_fma_f32 v[0:1], v[30:31], v[108:109], v[0:1]
	v_max_f32_e32 v210, 0, v222
	v_max_f32_e32 v211, 0, v223
	v_pk_fma_f32 v[0:1], v[32:33], v[210:211], v[0:1]
	v_mfma_f32_32x32x16_bf16 v[6:21], v[94:97], v[46:49], v[6:21]
	v_max_f32_e32 v108, 0, v224
	v_max_f32_e32 v109, 0, v225
	v_pk_fma_f32 v[0:1], v[34:35], v[108:109], v[0:1]
	v_max_f32_e32 v210, 0, v226
	v_max_f32_e32 v211, 0, v227
	v_pk_fma_f32 v[0:1], v[36:37], v[210:211], v[0:1]
	v_add_f32_e32 v0, v0, v1
	v_ashrrev_i32_e32 v1, 31, v0
	v_mfma_f32_32x32x16_bf16 v[6:21], v[98:101], v[196:199], v[6:21]
	s_waitcnt vmcnt(10)
	ds_read_b128 v[38:41], v5 offset:10496
	ds_read_b128 v[42:45], v52 offset:10496
	ds_read_b128 v[46:49], v55 offset:10496
	ds_read_b128 v[196:199], v56 offset:10496
	v_or_b32_e32 v1, 0x80000000, v1
	s_cmpk_gt_i32 s11, 248
	s_cselect_b64 vcc, -1, 0
	v_xor_b32_e32 v0, v1, v0
	v_cndmask_b32_e32 v152, v123, v0, vcc
	s_nop 3
	v_max_f32_e32 v108, 0, v6
	v_max_f32_e32 v109, 0, v7
	v_pk_mul_f32 v[50:51], v[244:245], v[108:109]
	v_max_f32_e32 v210, 0, v8
	v_max_f32_e32 v211, 0, v9
	v_pk_fma_f32 v[50:51], v[246:247], v[210:211], v[50:51]
	v_max_f32_e32 v108, 0, v10
	v_max_f32_e32 v109, 0, v11
	v_pk_fma_f32 v[50:51], v[248:249], v[108:109], v[50:51]
	v_max_f32_e32 v210, 0, v12
	v_max_f32_e32 v211, 0, v13
	v_pk_fma_f32 v[50:51], v[250:251], v[210:211], v[50:51]
	v_max_f32_e32 v108, 0, v14
	v_max_f32_e32 v109, 0, v15
	v_pk_fma_f32 v[50:51], v[252:253], v[108:109], v[50:51]
	v_max_f32_e32 v210, 0, v16
	v_max_f32_e32 v211, 0, v17
	v_pk_fma_f32 v[50:51], v[254:255], v[210:211], v[50:51]
	v_max_f32_e32 v108, 0, v18
	v_max_f32_e32 v109, 0, v19
	v_pk_fma_f32 v[50:51], v[200:201], v[108:109], v[50:51]
	v_max_f32_e32 v210, 0, v20
	v_max_f32_e32 v211, 0, v21
	v_pk_fma_f32 v[50:51], v[202:203], v[210:211], v[50:51]
	v_add_f32_e32 v50, v50, v51
	v_ashrrev_i32_e32 v51, 31, v50
	v_or_b32_e32 v51, 0x80000000, v51
	s_cmpk_gt_i32 s11, 248
	s_cselect_b64 vcc, -1, 0
	v_xor_b32_e32 v50, v51, v50
	v_cndmask_b32_e32 v50, v123, v50, vcc
	global_store_dword v243, v50, s[8:9] offset:2048
	s_add_u32 s8, s8, 0x1000
	s_addc_u32 s9, s9, 0
	s_cmpk_gt_i32 s81, 32
	s_cbranch_scc0 .Lix_fill_4
	s_waitcnt lgkmcnt(3)
	v_mfma_f32_32x32x16_bf16 v[212:227], v[70:73], v[38:41], 0
	s_add_i32 m0, s10, 98304
	s_nop 0
	global_load_lds_dwordx4 v102, s[6:7]
	s_waitcnt lgkmcnt(2)
	v_mfma_f32_32x32x16_bf16 v[212:227], v[74:77], v[42:45], v[212:227]
	s_add_i32 m0, s10, 99328
	s_nop 0
	global_load_lds_dwordx4 v110, s[6:7]
	s_waitcnt lgkmcnt(1)
	v_mfma_f32_32x32x16_bf16 v[212:227], v[78:81], v[46:49], v[212:227]
	s_add_i32 m0, s10, 100352
	s_nop 0
	global_load_lds_dwordx4 v112, s[6:7]
	s_waitcnt lgkmcnt(0)
	v_mfma_f32_32x32x16_bf16 v[212:227], v[82:85], v[196:199], v[212:227]
	s_add_i32 m0, s10, 101376
	s_nop 0
	global_load_lds_dwordx4 v193, s[6:7]
	s_add_u32 s6, s6, 0x8000
	s_addc_u32 s7, s7, 0
	v_mfma_f32_32x32x16_bf16 v[6:21], v[86:89], v[38:41], 0
	s_nop 7
	s_nop 2
	v_max_f32_e32 v108, 0, v212
	v_max_f32_e32 v109, 0, v213
	v_pk_mul_f32 v[0:1], v[22:23], v[108:109]
	v_max_f32_e32 v210, 0, v214
	v_max_f32_e32 v211, 0, v215
	v_pk_fma_f32 v[0:1], v[24:25], v[210:211], v[0:1]
	v_max_f32_e32 v108, 0, v216
	v_max_f32_e32 v109, 0, v217
	v_pk_fma_f32 v[0:1], v[26:27], v[108:109], v[0:1]
	v_mfma_f32_32x32x16_bf16 v[6:21], v[90:93], v[42:45], v[6:21]
	v_max_f32_e32 v210, 0, v218
	v_max_f32_e32 v211, 0, v219
	v_pk_fma_f32 v[0:1], v[28:29], v[210:211], v[0:1]
	v_max_f32_e32 v108, 0, v220
	v_max_f32_e32 v109, 0, v221
	v_pk_fma_f32 v[0:1], v[30:31], v[108:109], v[0:1]
	v_max_f32_e32 v210, 0, v222
	v_max_f32_e32 v211, 0, v223
	v_pk_fma_f32 v[0:1], v[32:33], v[210:211], v[0:1]
	v_mfma_f32_32x32x16_bf16 v[6:21], v[94:97], v[46:49], v[6:21]
	v_max_f32_e32 v108, 0, v224
	v_max_f32_e32 v109, 0, v225
	v_pk_fma_f32 v[0:1], v[34:35], v[108:109], v[0:1]
	v_max_f32_e32 v210, 0, v226
	v_max_f32_e32 v211, 0, v227
	v_pk_fma_f32 v[0:1], v[36:37], v[210:211], v[0:1]
	v_add_f32_e32 v0, v0, v1
	v_ashrrev_i32_e32 v1, 31, v0
	v_mfma_f32_32x32x16_bf16 v[6:21], v[98:101], v[196:199], v[6:21]
	s_waitcnt vmcnt(10)
	ds_read_b128 v[38:41], v5 offset:43264
	ds_read_b128 v[42:45], v52 offset:43264
	ds_read_b128 v[46:49], v55 offset:43264
	ds_read_b128 v[196:199], v56 offset:43264
	v_or_b32_e32 v1, 0x80000000, v1
	s_cmpk_gt_i32 s11, 256
	s_cselect_b64 vcc, -1, 0
	v_xor_b32_e32 v0, v1, v0
	v_cndmask_b32_e32 v165, v123, v0, vcc
	s_nop 3
	s_waitcnt lgkmcnt(3)
	v_mfma_f32_32x32x16_bf16 v[212:227], v[70:73], v[38:41], 0
	v_max_f32_e32 v108, 0, v6
	v_max_f32_e32 v109, 0, v7
	v_pk_mul_f32 v[50:51], v[244:245], v[108:109]
	v_max_f32_e32 v210, 0, v8
	v_max_f32_e32 v211, 0, v9
	v_pk_fma_f32 v[50:51], v[246:247], v[210:211], v[50:51]
	v_max_f32_e32 v108, 0, v10
	v_max_f32_e32 v109, 0, v11
	v_pk_fma_f32 v[50:51], v[248:249], v[108:109], v[50:51]
	s_waitcnt lgkmcnt(2)
	v_mfma_f32_32x32x16_bf16 v[212:227], v[74:77], v[42:45], v[212:227]
	v_max_f32_e32 v210, 0, v12
	v_max_f32_e32 v211, 0, v13
	v_pk_fma_f32 v[50:51], v[250:251], v[210:211], v[50:51]
	v_max_f32_e32 v108, 0, v14
	v_max_f32_e32 v109, 0, v15
	v_pk_fma_f32 v[50:51], v[252:253], v[108:109], v[50:51]
	v_max_f32_e32 v210, 0, v16
	v_max_f32_e32 v211, 0, v17
	v_pk_fma_f32 v[50:51], v[254:255], v[210:211], v[50:51]
	s_waitcnt lgkmcnt(1)
	v_mfma_f32_32x32x16_bf16 v[212:227], v[78:81], v[46:49], v[212:227]
	v_max_f32_e32 v108, 0, v18
	v_max_f32_e32 v109, 0, v19
	v_pk_fma_f32 v[50:51], v[200:201], v[108:109], v[50:51]
	v_max_f32_e32 v210, 0, v20
	v_max_f32_e32 v211, 0, v21
	v_pk_fma_f32 v[50:51], v[202:203], v[210:211], v[50:51]
	v_add_f32_e32 v50, v50, v51
	v_ashrrev_i32_e32 v51, 31, v50
	s_waitcnt lgkmcnt(0)
	v_mfma_f32_32x32x16_bf16 v[212:227], v[82:85], v[196:199], v[212:227]
	v_or_b32_e32 v51, 0x80000000, v51
	s_cmpk_gt_i32 s11, 256
	s_cselect_b64 vcc, -1, 0
	v_xor_b32_e32 v50, v51, v50
	v_cndmask_b32_e32 v50, v123, v50, vcc
	global_store_dword v243, v50, s[8:9]
	v_mfma_f32_32x32x16_bf16 v[6:21], v[86:89], v[38:41], 0
	s_add_i32 m0, s10, 0
	s_nop 0
	global_load_lds_dwordx4 v102, s[6:7]
	s_add_i32 m0, s10, 1024
	s_nop 0
	global_load_lds_dwordx4 v110, s[6:7]
	s_add_i32 m0, s10, 2048
	s_nop 0
	global_load_lds_dwordx4 v112, s[6:7]
	s_add_i32 m0, s10, 3072
	s_nop 0
	global_load_lds_dwordx4 v193, s[6:7]
	s_add_u32 s6, s6, 0x8000
	s_addc_u32 s7, s7, 0
	v_max_f32_e32 v108, 0, v212
	v_max_f32_e32 v109, 0, v213
	v_pk_mul_f32 v[0:1], v[22:23], v[108:109]
	v_max_f32_e32 v210, 0, v214
	v_max_f32_e32 v211, 0, v215
	v_pk_fma_f32 v[0:1], v[24:25], v[210:211], v[0:1]
	v_max_f32_e32 v108, 0, v216
	v_max_f32_e32 v109, 0, v217
	v_pk_fma_f32 v[0:1], v[26:27], v[108:109], v[0:1]
	v_mfma_f32_32x32x16_bf16 v[6:21], v[90:93], v[42:45], v[6:21]
	v_max_f32_e32 v210, 0, v218
	v_max_f32_e32 v211, 0, v219
	v_pk_fma_f32 v[0:1], v[28:29], v[210:211], v[0:1]
	v_max_f32_e32 v108, 0, v220
	v_max_f32_e32 v109, 0, v221
	v_pk_fma_f32 v[0:1], v[30:31], v[108:109], v[0:1]
	v_max_f32_e32 v210, 0, v222
	v_max_f32_e32 v211, 0, v223
	v_pk_fma_f32 v[0:1], v[32:33], v[210:211], v[0:1]
	v_mfma_f32_32x32x16_bf16 v[6:21], v[94:97], v[46:49], v[6:21]
	v_max_f32_e32 v108, 0, v224
	v_max_f32_e32 v109, 0, v225
	v_pk_fma_f32 v[0:1], v[34:35], v[108:109], v[0:1]
	v_max_f32_e32 v210, 0, v226
	v_max_f32_e32 v211, 0, v227
	v_pk_fma_f32 v[0:1], v[36:37], v[210:211], v[0:1]
	v_add_f32_e32 v0, v0, v1
	v_ashrrev_i32_e32 v1, 31, v0
	v_mfma_f32_32x32x16_bf16 v[6:21], v[98:101], v[196:199], v[6:21]
	s_waitcnt vmcnt(10)
	v_add_u32_e32 v228, 0x10000, v5
	ds_read_b128 v[38:41], v228 offset:10496
	v_add_u32_e32 v228, 0x10000, v52
	ds_read_b128 v[42:45], v228 offset:10496
	v_add_u32_e32 v228, 0x10000, v55
	ds_read_b128 v[46:49], v228 offset:10496
	v_add_u32_e32 v228, 0x10000, v56
	ds_read_b128 v[196:199], v228 offset:10496
	v_or_b32_e32 v1, 0x80000000, v1
	s_cmpk_gt_i32 s11, 264
	s_cselect_b64 vcc, -1, 0
	v_xor_b32_e32 v0, v1, v0
	v_cndmask_b32_e32 v164, v123, v0, vcc
	s_nop 3
	s_waitcnt lgkmcnt(3)
	v_mfma_f32_32x32x16_bf16 v[212:227], v[70:73], v[38:41], 0
	v_max_f32_e32 v108, 0, v6
	v_max_f32_e32 v109, 0, v7
	v_pk_mul_f32 v[50:51], v[244:245], v[108:109]
	v_max_f32_e32 v210, 0, v8
	v_max_f32_e32 v211, 0, v9
	v_pk_fma_f32 v[50:51], v[246:247], v[210:211], v[50:51]
	v_max_f32_e32 v108, 0, v10
	v_max_f32_e32 v109, 0, v11
	v_pk_fma_f32 v[50:51], v[248:249], v[108:109], v[50:51]
	s_waitcnt lgkmcnt(2)
	v_mfma_f32_32x32x16_bf16 v[212:227], v[74:77], v[42:45], v[212:227]
	v_max_f32_e32 v210, 0, v12
	v_max_f32_e32 v211, 0, v13
	v_pk_fma_f32 v[50:51], v[250:251], v[210:211], v[50:51]
	v_max_f32_e32 v108, 0, v14
	v_max_f32_e32 v109, 0, v15
	v_pk_fma_f32 v[50:51], v[252:253], v[108:109], v[50:51]
	v_max_f32_e32 v210, 0, v16
	v_max_f32_e32 v211, 0, v17
	v_pk_fma_f32 v[50:51], v[254:255], v[210:211], v[50:51]
	s_waitcnt lgkmcnt(1)
	v_mfma_f32_32x32x16_bf16 v[212:227], v[78:81], v[46:49], v[212:227]
	v_max_f32_e32 v108, 0, v18
	v_max_f32_e32 v109, 0, v19
	v_pk_fma_f32 v[50:51], v[200:201], v[108:109], v[50:51]
	v_max_f32_e32 v210, 0, v20
	v_max_f32_e32 v211, 0, v21
	v_pk_fma_f32 v[50:51], v[202:203], v[210:211], v[50:51]
	v_add_f32_e32 v50, v50, v51
	v_ashrrev_i32_e32 v51, 31, v50
	s_waitcnt lgkmcnt(0)
	v_mfma_f32_32x32x16_bf16 v[212:227], v[82:85], v[196:199], v[212:227]
	v_or_b32_e32 v51, 0x80000000, v51
	s_cmpk_gt_i32 s11, 264
	s_cselect_b64 vcc, -1, 0
	v_xor_b32_e32 v50, v51, v50
	v_cndmask_b32_e32 v50, v123, v50, vcc
	global_store_dword v243, v50, s[8:9] offset:2048
	s_add_u32 s8, s8, 0x1000
	s_addc_u32 s9, s9, 0
	v_mfma_f32_32x32x16_bf16 v[6:21], v[86:89], v[38:41], 0
	s_add_i32 m0, s10, 32768
	s_nop 0
	global_load_lds_dwordx4 v102, s[6:7]
	s_add_i32 m0, s10, 33792
	s_nop 0
	global_load_lds_dwordx4 v110, s[6:7]
	s_add_i32 m0, s10, 34816
	s_nop 0
	global_load_lds_dwordx4 v112, s[6:7]
	s_add_i32 m0, s10, 35840
	s_nop 0
	global_load_lds_dwordx4 v193, s[6:7]
	s_add_u32 s6, s6, 0x8000
	s_addc_u32 s7, s7, 0
	v_max_f32_e32 v108, 0, v212
	v_max_f32_e32 v109, 0, v213
	v_pk_mul_f32 v[0:1], v[22:23], v[108:109]
	v_max_f32_e32 v210, 0, v214
	v_max_f32_e32 v211, 0, v215
	v_pk_fma_f32 v[0:1], v[24:25], v[210:211], v[0:1]
	v_max_f32_e32 v108, 0, v216
	v_max_f32_e32 v109, 0, v217
	v_pk_fma_f32 v[0:1], v[26:27], v[108:109], v[0:1]
	v_mfma_f32_32x32x16_bf16 v[6:21], v[90:93], v[42:45], v[6:21]
	v_max_f32_e32 v210, 0, v218
	v_max_f32_e32 v211, 0, v219
	v_pk_fma_f32 v[0:1], v[28:29], v[210:211], v[0:1]
	v_max_f32_e32 v108, 0, v220
	v_max_f32_e32 v109, 0, v221
	v_pk_fma_f32 v[0:1], v[30:31], v[108:109], v[0:1]
	v_max_f32_e32 v210, 0, v222
	v_max_f32_e32 v211, 0, v223
	v_pk_fma_f32 v[0:1], v[32:33], v[210:211], v[0:1]
	v_mfma_f32_32x32x16_bf16 v[6:21], v[94:97], v[46:49], v[6:21]
	v_max_f32_e32 v108, 0, v224
	v_max_f32_e32 v109, 0, v225
	v_pk_fma_f32 v[0:1], v[34:35], v[108:109], v[0:1]
	v_max_f32_e32 v210, 0, v226
	v_max_f32_e32 v211, 0, v227
	v_pk_fma_f32 v[0:1], v[36:37], v[210:211], v[0:1]
	v_add_f32_e32 v0, v0, v1
	v_ashrrev_i32_e32 v1, 31, v0
	v_mfma_f32_32x32x16_bf16 v[6:21], v[98:101], v[196:199], v[6:21]
	s_waitcnt vmcnt(10)
	v_add_u32_e32 v228, 0x10000, v5
	ds_read_b128 v[38:41], v228 offset:43264
	v_add_u32_e32 v228, 0x10000, v52
	ds_read_b128 v[42:45], v228 offset:43264
	v_add_u32_e32 v228, 0x10000, v55
	ds_read_b128 v[46:49], v228 offset:43264
	v_add_u32_e32 v228, 0x10000, v56
	ds_read_b128 v[196:199], v228 offset:43264
	v_or_b32_e32 v1, 0x80000000, v1
	s_cmpk_gt_i32 s11, 272
	s_cselect_b64 vcc, -1, 0
	v_xor_b32_e32 v0, v1, v0
	v_cndmask_b32_e32 v167, v123, v0, vcc
	s_nop 3
	s_waitcnt lgkmcnt(3)
	v_mfma_f32_32x32x16_bf16 v[212:227], v[70:73], v[38:41], 0
	v_max_f32_e32 v108, 0, v6
	v_max_f32_e32 v109, 0, v7
	v_pk_mul_f32 v[50:51], v[244:245], v[108:109]
	v_max_f32_e32 v210, 0, v8
	v_max_f32_e32 v211, 0, v9
	v_pk_fma_f32 v[50:51], v[246:247], v[210:211], v[50:51]
	v_max_f32_e32 v108, 0, v10
	v_max_f32_e32 v109, 0, v11
	v_pk_fma_f32 v[50:51], v[248:249], v[108:109], v[50:51]
	s_waitcnt lgkmcnt(2)
	v_mfma_f32_32x32x16_bf16 v[212:227], v[74:77], v[42:45], v[212:227]
	v_max_f32_e32 v210, 0, v12
	v_max_f32_e32 v211, 0, v13
	v_pk_fma_f32 v[50:51], v[250:251], v[210:211], v[50:51]
	v_max_f32_e32 v108, 0, v14
	v_max_f32_e32 v109, 0, v15
	v_pk_fma_f32 v[50:51], v[252:253], v[108:109], v[50:51]
	v_max_f32_e32 v210, 0, v16
	v_max_f32_e32 v211, 0, v17
	v_pk_fma_f32 v[50:51], v[254:255], v[210:211], v[50:51]
	s_waitcnt lgkmcnt(1)
	v_mfma_f32_32x32x16_bf16 v[212:227], v[78:81], v[46:49], v[212:227]
	v_max_f32_e32 v108, 0, v18
	v_max_f32_e32 v109, 0, v19
	v_pk_fma_f32 v[50:51], v[200:201], v[108:109], v[50:51]
	v_max_f32_e32 v210, 0, v20
	v_max_f32_e32 v211, 0, v21
	v_pk_fma_f32 v[50:51], v[202:203], v[210:211], v[50:51]
	v_add_f32_e32 v50, v50, v51
	v_ashrrev_i32_e32 v51, 31, v50
	s_waitcnt lgkmcnt(0)
	v_mfma_f32_32x32x16_bf16 v[212:227], v[82:85], v[196:199], v[212:227]
	v_or_b32_e32 v51, 0x80000000, v51
	s_cmpk_gt_i32 s11, 272
	s_cselect_b64 vcc, -1, 0
	v_xor_b32_e32 v50, v51, v50
	v_cndmask_b32_e32 v50, v123, v50, vcc
	global_store_dword v243, v50, s[8:9]
	v_mfma_f32_32x32x16_bf16 v[6:21], v[86:89], v[38:41], 0
	s_add_i32 m0, s10, 65536
	s_nop 0
	global_load_lds_dwordx4 v102, s[6:7]
	s_add_i32 m0, s10, 66560
	s_nop 0
	global_load_lds_dwordx4 v110, s[6:7]
	s_add_i32 m0, s10, 67584
	s_nop 0
	global_load_lds_dwordx4 v112, s[6:7]
	s_add_i32 m0, s10, 68608
	s_nop 0
	global_load_lds_dwordx4 v193, s[6:7]
	s_add_u32 s6, s6, 0x8000
	s_addc_u32 s7, s7, 0
	v_max_f32_e32 v108, 0, v212
	v_max_f32_e32 v109, 0, v213
	v_pk_mul_f32 v[0:1], v[22:23], v[108:109]
	v_max_f32_e32 v210, 0, v214
	v_max_f32_e32 v211, 0, v215
	v_pk_fma_f32 v[0:1], v[24:25], v[210:211], v[0:1]
	v_max_f32_e32 v108, 0, v216
	v_max_f32_e32 v109, 0, v217
	v_pk_fma_f32 v[0:1], v[26:27], v[108:109], v[0:1]
	v_mfma_f32_32x32x16_bf16 v[6:21], v[90:93], v[42:45], v[6:21]
	v_max_f32_e32 v210, 0, v218
	v_max_f32_e32 v211, 0, v219
	v_pk_fma_f32 v[0:1], v[28:29], v[210:211], v[0:1]
	v_max_f32_e32 v108, 0, v220
	v_max_f32_e32 v109, 0, v221
	v_pk_fma_f32 v[0:1], v[30:31], v[108:109], v[0:1]
	v_max_f32_e32 v210, 0, v222
	v_max_f32_e32 v211, 0, v223
	v_pk_fma_f32 v[0:1], v[32:33], v[210:211], v[0:1]
	v_mfma_f32_32x32x16_bf16 v[6:21], v[94:97], v[46:49], v[6:21]
	v_max_f32_e32 v108, 0, v224
	v_max_f32_e32 v109, 0, v225
	v_pk_fma_f32 v[0:1], v[34:35], v[108:109], v[0:1]
	v_max_f32_e32 v210, 0, v226
	v_max_f32_e32 v211, 0, v227
	v_pk_fma_f32 v[0:1], v[36:37], v[210:211], v[0:1]
	v_add_f32_e32 v0, v0, v1
	v_ashrrev_i32_e32 v1, 31, v0
	v_mfma_f32_32x32x16_bf16 v[6:21], v[98:101], v[196:199], v[6:21]
	s_waitcnt vmcnt(10)
	ds_read_b128 v[38:41], v5 offset:10496
	ds_read_b128 v[42:45], v52 offset:10496
	ds_read_b128 v[46:49], v55 offset:10496
	ds_read_b128 v[196:199], v56 offset:10496
	v_or_b32_e32 v1, 0x80000000, v1
	s_cmpk_gt_i32 s11, 280
	s_cselect_b64 vcc, -1, 0
	v_xor_b32_e32 v0, v1, v0
	v_cndmask_b32_e32 v166, v123, v0, vcc
	s_nop 3
	s_waitcnt lgkmcnt(3)
	v_mfma_f32_32x32x16_bf16 v[212:227], v[70:73], v[38:41], 0
	v_max_f32_e32 v108, 0, v6
	v_max_f32_e32 v109, 0, v7
	v_pk_mul_f32 v[50:51], v[244:245], v[108:109]
	v_max_f32_e32 v210, 0, v8
	v_max_f32_e32 v211, 0, v9
	v_pk_fma_f32 v[50:51], v[246:247], v[210:211], v[50:51]
	v_max_f32_e32 v108, 0, v10
	v_max_f32_e32 v109, 0, v11
	v_pk_fma_f32 v[50:51], v[248:249], v[108:109], v[50:51]
	s_waitcnt lgkmcnt(2)
	v_mfma_f32_32x32x16_bf16 v[212:227], v[74:77], v[42:45], v[212:227]
	v_max_f32_e32 v210, 0, v12
	v_max_f32_e32 v211, 0, v13
	v_pk_fma_f32 v[50:51], v[250:251], v[210:211], v[50:51]
	v_max_f32_e32 v108, 0, v14
	v_max_f32_e32 v109, 0, v15
	v_pk_fma_f32 v[50:51], v[252:253], v[108:109], v[50:51]
	v_max_f32_e32 v210, 0, v16
	v_max_f32_e32 v211, 0, v17
	v_pk_fma_f32 v[50:51], v[254:255], v[210:211], v[50:51]
	s_waitcnt lgkmcnt(1)
	v_mfma_f32_32x32x16_bf16 v[212:227], v[78:81], v[46:49], v[212:227]
	v_max_f32_e32 v108, 0, v18
	v_max_f32_e32 v109, 0, v19
	v_pk_fma_f32 v[50:51], v[200:201], v[108:109], v[50:51]
	v_max_f32_e32 v210, 0, v20
	v_max_f32_e32 v211, 0, v21
	v_pk_fma_f32 v[50:51], v[202:203], v[210:211], v[50:51]
	v_add_f32_e32 v50, v50, v51
	v_ashrrev_i32_e32 v51, 31, v50
	s_waitcnt lgkmcnt(0)
	v_mfma_f32_32x32x16_bf16 v[212:227], v[82:85], v[196:199], v[212:227]
	v_or_b32_e32 v51, 0x80000000, v51
	s_cmpk_gt_i32 s11, 280
	s_cselect_b64 vcc, -1, 0
	v_xor_b32_e32 v50, v51, v50
	v_cndmask_b32_e32 v50, v123, v50, vcc
	global_store_dword v243, v50, s[8:9] offset:2048
	s_add_u32 s8, s8, 0x1000
	s_addc_u32 s9, s9, 0
	v_mfma_f32_32x32x16_bf16 v[6:21], v[86:89], v[38:41], 0
	s_add_i32 m0, s10, 98304
	s_nop 0
	global_load_lds_dwordx4 v102, s[6:7]
	s_add_i32 m0, s10, 99328
	s_nop 0
	global_load_lds_dwordx4 v110, s[6:7]
	s_add_i32 m0, s10, 100352
	s_nop 0
	global_load_lds_dwordx4 v112, s[6:7]
	s_add_i32 m0, s10, 101376
	s_nop 0
	global_load_lds_dwordx4 v193, s[6:7]
	s_add_u32 s6, s6, 0x8000
	s_addc_u32 s7, s7, 0
	v_max_f32_e32 v108, 0, v212
	v_max_f32_e32 v109, 0, v213
	v_pk_mul_f32 v[0:1], v[22:23], v[108:109]
	v_max_f32_e32 v210, 0, v214
	v_max_f32_e32 v211, 0, v215
	v_pk_fma_f32 v[0:1], v[24:25], v[210:211], v[0:1]
	v_max_f32_e32 v108, 0, v216
	v_max_f32_e32 v109, 0, v217
	v_pk_fma_f32 v[0:1], v[26:27], v[108:109], v[0:1]
	v_mfma_f32_32x32x16_bf16 v[6:21], v[90:93], v[42:45], v[6:21]
	v_max_f32_e32 v210, 0, v218
	v_max_f32_e32 v211, 0, v219
	v_pk_fma_f32 v[0:1], v[28:29], v[210:211], v[0:1]
	v_max_f32_e32 v108, 0, v220
	v_max_f32_e32 v109, 0, v221
	v_pk_fma_f32 v[0:1], v[30:31], v[108:109], v[0:1]
	v_max_f32_e32 v210, 0, v222
	v_max_f32_e32 v211, 0, v223
	v_pk_fma_f32 v[0:1], v[32:33], v[210:211], v[0:1]
	v_mfma_f32_32x32x16_bf16 v[6:21], v[94:97], v[46:49], v[6:21]
	v_max_f32_e32 v108, 0, v224
	v_max_f32_e32 v109, 0, v225
	v_pk_fma_f32 v[0:1], v[34:35], v[108:109], v[0:1]
	v_max_f32_e32 v210, 0, v226
	v_max_f32_e32 v211, 0, v227
	v_pk_fma_f32 v[0:1], v[36:37], v[210:211], v[0:1]
	v_add_f32_e32 v0, v0, v1
	v_ashrrev_i32_e32 v1, 31, v0
	v_mfma_f32_32x32x16_bf16 v[6:21], v[98:101], v[196:199], v[6:21]
	s_waitcnt vmcnt(10)
	ds_read_b128 v[38:41], v5 offset:43264
	ds_read_b128 v[42:45], v52 offset:43264
	ds_read_b128 v[46:49], v55 offset:43264
	ds_read_b128 v[196:199], v56 offset:43264
	v_or_b32_e32 v1, 0x80000000, v1
	s_cmpk_gt_i32 s11, 288
	s_cselect_b64 vcc, -1, 0
	v_xor_b32_e32 v0, v1, v0
	v_cndmask_b32_e32 v170, v123, v0, vcc
	s_nop 3
	s_waitcnt lgkmcnt(3)
	v_mfma_f32_32x32x16_bf16 v[212:227], v[70:73], v[38:41], 0
	v_max_f32_e32 v108, 0, v6
	v_max_f32_e32 v109, 0, v7
	v_pk_mul_f32 v[50:51], v[244:245], v[108:109]
	v_max_f32_e32 v210, 0, v8
	v_max_f32_e32 v211, 0, v9
	v_pk_fma_f32 v[50:51], v[246:247], v[210:211], v[50:51]
	v_max_f32_e32 v108, 0, v10
	v_max_f32_e32 v109, 0, v11
	v_pk_fma_f32 v[50:51], v[248:249], v[108:109], v[50:51]
	s_waitcnt lgkmcnt(2)
	v_mfma_f32_32x32x16_bf16 v[212:227], v[74:77], v[42:45], v[212:227]
	v_max_f32_e32 v210, 0, v12
	v_max_f32_e32 v211, 0, v13
	v_pk_fma_f32 v[50:51], v[250:251], v[210:211], v[50:51]
	v_max_f32_e32 v108, 0, v14
	v_max_f32_e32 v109, 0, v15
	v_pk_fma_f32 v[50:51], v[252:253], v[108:109], v[50:51]
	v_max_f32_e32 v210, 0, v16
	v_max_f32_e32 v211, 0, v17
	v_pk_fma_f32 v[50:51], v[254:255], v[210:211], v[50:51]
	s_waitcnt lgkmcnt(1)
	v_mfma_f32_32x32x16_bf16 v[212:227], v[78:81], v[46:49], v[212:227]
	v_max_f32_e32 v108, 0, v18
	v_max_f32_e32 v109, 0, v19
	v_pk_fma_f32 v[50:51], v[200:201], v[108:109], v[50:51]
	v_max_f32_e32 v210, 0, v20
	v_max_f32_e32 v211, 0, v21
	v_pk_fma_f32 v[50:51], v[202:203], v[210:211], v[50:51]
	v_add_f32_e32 v50, v50, v51
	v_ashrrev_i32_e32 v51, 31, v50
	s_waitcnt lgkmcnt(0)
	v_mfma_f32_32x32x16_bf16 v[212:227], v[82:85], v[196:199], v[212:227]
	v_or_b32_e32 v51, 0x80000000, v51
	s_cmpk_gt_i32 s11, 288
	s_cselect_b64 vcc, -1, 0
	v_xor_b32_e32 v50, v51, v50
	v_cndmask_b32_e32 v50, v123, v50, vcc
	global_store_dword v243, v50, s[8:9]
	v_mfma_f32_32x32x16_bf16 v[6:21], v[86:89], v[38:41], 0
	s_add_i32 m0, s10, 0
	s_nop 0
	global_load_lds_dwordx4 v102, s[6:7]
	s_add_i32 m0, s10, 1024
	s_nop 0
	global_load_lds_dwordx4 v110, s[6:7]
	s_add_i32 m0, s10, 2048
	s_nop 0
	global_load_lds_dwordx4 v112, s[6:7]
	s_add_i32 m0, s10, 3072
	s_nop 0
	global_load_lds_dwordx4 v193, s[6:7]
	s_add_u32 s6, s6, 0x8000
	s_addc_u32 s7, s7, 0
	v_max_f32_e32 v108, 0, v212
	v_max_f32_e32 v109, 0, v213
	v_pk_mul_f32 v[0:1], v[22:23], v[108:109]
	v_max_f32_e32 v210, 0, v214
	v_max_f32_e32 v211, 0, v215
	v_pk_fma_f32 v[0:1], v[24:25], v[210:211], v[0:1]
	v_max_f32_e32 v108, 0, v216
	v_max_f32_e32 v109, 0, v217
	v_pk_fma_f32 v[0:1], v[26:27], v[108:109], v[0:1]
	v_mfma_f32_32x32x16_bf16 v[6:21], v[90:93], v[42:45], v[6:21]
	v_max_f32_e32 v210, 0, v218
	v_max_f32_e32 v211, 0, v219
	v_pk_fma_f32 v[0:1], v[28:29], v[210:211], v[0:1]
	v_max_f32_e32 v108, 0, v220
	v_max_f32_e32 v109, 0, v221
	v_pk_fma_f32 v[0:1], v[30:31], v[108:109], v[0:1]
	v_max_f32_e32 v210, 0, v222
	v_max_f32_e32 v211, 0, v223
	v_pk_fma_f32 v[0:1], v[32:33], v[210:211], v[0:1]
	v_mfma_f32_32x32x16_bf16 v[6:21], v[94:97], v[46:49], v[6:21]
	v_max_f32_e32 v108, 0, v224
	v_max_f32_e32 v109, 0, v225
	v_pk_fma_f32 v[0:1], v[34:35], v[108:109], v[0:1]
	v_max_f32_e32 v210, 0, v226
	v_max_f32_e32 v211, 0, v227
	v_pk_fma_f32 v[0:1], v[36:37], v[210:211], v[0:1]
	v_add_f32_e32 v0, v0, v1
	v_ashrrev_i32_e32 v1, 31, v0
	v_mfma_f32_32x32x16_bf16 v[6:21], v[98:101], v[196:199], v[6:21]
	s_waitcnt vmcnt(10)
	v_add_u32_e32 v228, 0x10000, v5
	ds_read_b128 v[38:41], v228 offset:10496
	v_add_u32_e32 v228, 0x10000, v52
	ds_read_b128 v[42:45], v228 offset:10496
	v_add_u32_e32 v228, 0x10000, v55
	ds_read_b128 v[46:49], v228 offset:10496
	v_add_u32_e32 v228, 0x10000, v56
	ds_read_b128 v[196:199], v228 offset:10496
	v_or_b32_e32 v1, 0x80000000, v1
	s_cmpk_gt_i32 s11, 296
	s_cselect_b64 vcc, -1, 0
	v_xor_b32_e32 v0, v1, v0
	v_cndmask_b32_e32 v169, v123, v0, vcc
	s_nop 3
	s_waitcnt lgkmcnt(3)
	v_mfma_f32_32x32x16_bf16 v[212:227], v[70:73], v[38:41], 0
	v_max_f32_e32 v108, 0, v6
	v_max_f32_e32 v109, 0, v7
	v_pk_mul_f32 v[50:51], v[244:245], v[108:109]
	v_max_f32_e32 v210, 0, v8
	v_max_f32_e32 v211, 0, v9
	v_pk_fma_f32 v[50:51], v[246:247], v[210:211], v[50:51]
	v_max_f32_e32 v108, 0, v10
	v_max_f32_e32 v109, 0, v11
	v_pk_fma_f32 v[50:51], v[248:249], v[108:109], v[50:51]
	s_waitcnt lgkmcnt(2)
	v_mfma_f32_32x32x16_bf16 v[212:227], v[74:77], v[42:45], v[212:227]
	v_max_f32_e32 v210, 0, v12
	v_max_f32_e32 v211, 0, v13
	v_pk_fma_f32 v[50:51], v[250:251], v[210:211], v[50:51]
	v_max_f32_e32 v108, 0, v14
	v_max_f32_e32 v109, 0, v15
	v_pk_fma_f32 v[50:51], v[252:253], v[108:109], v[50:51]
	v_max_f32_e32 v210, 0, v16
	v_max_f32_e32 v211, 0, v17
	v_pk_fma_f32 v[50:51], v[254:255], v[210:211], v[50:51]
	s_waitcnt lgkmcnt(1)
	v_mfma_f32_32x32x16_bf16 v[212:227], v[78:81], v[46:49], v[212:227]
	v_max_f32_e32 v108, 0, v18
	v_max_f32_e32 v109, 0, v19
	v_pk_fma_f32 v[50:51], v[200:201], v[108:109], v[50:51]
	v_max_f32_e32 v210, 0, v20
	v_max_f32_e32 v211, 0, v21
	v_pk_fma_f32 v[50:51], v[202:203], v[210:211], v[50:51]
	v_add_f32_e32 v50, v50, v51
	v_ashrrev_i32_e32 v51, 31, v50
	s_waitcnt lgkmcnt(0)
	v_mfma_f32_32x32x16_bf16 v[212:227], v[82:85], v[196:199], v[212:227]
	v_or_b32_e32 v51, 0x80000000, v51
	s_cmpk_gt_i32 s11, 296
	s_cselect_b64 vcc, -1, 0
	v_xor_b32_e32 v50, v51, v50
	v_cndmask_b32_e32 v50, v123, v50, vcc
	global_store_dword v243, v50, s[8:9] offset:2048
	s_add_u32 s8, s8, 0x1000
	s_addc_u32 s9, s9, 0
	v_mfma_f32_32x32x16_bf16 v[6:21], v[86:89], v[38:41], 0
	s_add_i32 m0, s10, 32768
	s_nop 0
	global_load_lds_dwordx4 v102, s[6:7]
	s_add_i32 m0, s10, 33792
	s_nop 0
	global_load_lds_dwordx4 v110, s[6:7]
	s_add_i32 m0, s10, 34816
	s_nop 0
	global_load_lds_dwordx4 v112, s[6:7]
	s_add_i32 m0, s10, 35840
	s_nop 0
	global_load_lds_dwordx4 v193, s[6:7]
	s_add_u32 s6, s6, 0x8000
	s_addc_u32 s7, s7, 0
	v_max_f32_e32 v108, 0, v212
	v_max_f32_e32 v109, 0, v213
	v_pk_mul_f32 v[0:1], v[22:23], v[108:109]
	v_max_f32_e32 v210, 0, v214
	v_max_f32_e32 v211, 0, v215
	v_pk_fma_f32 v[0:1], v[24:25], v[210:211], v[0:1]
	v_max_f32_e32 v108, 0, v216
	v_max_f32_e32 v109, 0, v217
	v_pk_fma_f32 v[0:1], v[26:27], v[108:109], v[0:1]
	v_mfma_f32_32x32x16_bf16 v[6:21], v[90:93], v[42:45], v[6:21]
	v_max_f32_e32 v210, 0, v218
	v_max_f32_e32 v211, 0, v219
	v_pk_fma_f32 v[0:1], v[28:29], v[210:211], v[0:1]
	v_max_f32_e32 v108, 0, v220
	v_max_f32_e32 v109, 0, v221
	v_pk_fma_f32 v[0:1], v[30:31], v[108:109], v[0:1]
	v_max_f32_e32 v210, 0, v222
	v_max_f32_e32 v211, 0, v223
	v_pk_fma_f32 v[0:1], v[32:33], v[210:211], v[0:1]
	v_mfma_f32_32x32x16_bf16 v[6:21], v[94:97], v[46:49], v[6:21]
	v_max_f32_e32 v108, 0, v224
	v_max_f32_e32 v109, 0, v225
	v_pk_fma_f32 v[0:1], v[34:35], v[108:109], v[0:1]
	v_max_f32_e32 v210, 0, v226
	v_max_f32_e32 v211, 0, v227
	v_pk_fma_f32 v[0:1], v[36:37], v[210:211], v[0:1]
	v_add_f32_e32 v0, v0, v1
	v_ashrrev_i32_e32 v1, 31, v0
	v_mfma_f32_32x32x16_bf16 v[6:21], v[98:101], v[196:199], v[6:21]
	s_waitcnt vmcnt(10)
	v_add_u32_e32 v228, 0x10000, v5
	ds_read_b128 v[38:41], v228 offset:43264
	v_add_u32_e32 v228, 0x10000, v52
	ds_read_b128 v[42:45], v228 offset:43264
	v_add_u32_e32 v228, 0x10000, v55
	ds_read_b128 v[46:49], v228 offset:43264
	v_add_u32_e32 v228, 0x10000, v56
	ds_read_b128 v[196:199], v228 offset:43264
	v_or_b32_e32 v1, 0x80000000, v1
	s_cmpk_gt_i32 s11, 304
	s_cselect_b64 vcc, -1, 0
	v_xor_b32_e32 v0, v1, v0
	v_cndmask_b32_e32 v172, v123, v0, vcc
	s_nop 3
	s_waitcnt lgkmcnt(3)
	v_mfma_f32_32x32x16_bf16 v[212:227], v[70:73], v[38:41], 0
	v_max_f32_e32 v108, 0, v6
	v_max_f32_e32 v109, 0, v7
	v_pk_mul_f32 v[50:51], v[244:245], v[108:109]
	v_max_f32_e32 v210, 0, v8
	v_max_f32_e32 v211, 0, v9
	v_pk_fma_f32 v[50:51], v[246:247], v[210:211], v[50:51]
	v_max_f32_e32 v108, 0, v10
	v_max_f32_e32 v109, 0, v11
	v_pk_fma_f32 v[50:51], v[248:249], v[108:109], v[50:51]
	s_waitcnt lgkmcnt(2)
	v_mfma_f32_32x32x16_bf16 v[212:227], v[74:77], v[42:45], v[212:227]
	v_max_f32_e32 v210, 0, v12
	v_max_f32_e32 v211, 0, v13
	v_pk_fma_f32 v[50:51], v[250:251], v[210:211], v[50:51]
	v_max_f32_e32 v108, 0, v14
	v_max_f32_e32 v109, 0, v15
	v_pk_fma_f32 v[50:51], v[252:253], v[108:109], v[50:51]
	v_max_f32_e32 v210, 0, v16
	v_max_f32_e32 v211, 0, v17
	v_pk_fma_f32 v[50:51], v[254:255], v[210:211], v[50:51]
	s_waitcnt lgkmcnt(1)
	v_mfma_f32_32x32x16_bf16 v[212:227], v[78:81], v[46:49], v[212:227]
	v_max_f32_e32 v108, 0, v18
	v_max_f32_e32 v109, 0, v19
	v_pk_fma_f32 v[50:51], v[200:201], v[108:109], v[50:51]
	v_max_f32_e32 v210, 0, v20
	v_max_f32_e32 v211, 0, v21
	v_pk_fma_f32 v[50:51], v[202:203], v[210:211], v[50:51]
	v_add_f32_e32 v50, v50, v51
	v_ashrrev_i32_e32 v51, 31, v50
	s_waitcnt lgkmcnt(0)
	v_mfma_f32_32x32x16_bf16 v[212:227], v[82:85], v[196:199], v[212:227]
	v_or_b32_e32 v51, 0x80000000, v51
	s_cmpk_gt_i32 s11, 304
	s_cselect_b64 vcc, -1, 0
	v_xor_b32_e32 v50, v51, v50
	v_cndmask_b32_e32 v50, v123, v50, vcc
	global_store_dword v243, v50, s[8:9]
	v_mfma_f32_32x32x16_bf16 v[6:21], v[86:89], v[38:41], 0
	s_add_i32 m0, s10, 65536
	s_nop 0
	global_load_lds_dwordx4 v102, s[6:7]
	s_add_i32 m0, s10, 66560
	s_nop 0
	global_load_lds_dwordx4 v110, s[6:7]
	s_add_i32 m0, s10, 67584
	s_nop 0
	global_load_lds_dwordx4 v112, s[6:7]
	s_add_i32 m0, s10, 68608
	s_nop 0
	global_load_lds_dwordx4 v193, s[6:7]
	s_add_u32 s6, s6, 0x8000
	s_addc_u32 s7, s7, 0
	v_max_f32_e32 v108, 0, v212
	v_max_f32_e32 v109, 0, v213
	v_pk_mul_f32 v[0:1], v[22:23], v[108:109]
	v_max_f32_e32 v210, 0, v214
	v_max_f32_e32 v211, 0, v215
	v_pk_fma_f32 v[0:1], v[24:25], v[210:211], v[0:1]
	v_max_f32_e32 v108, 0, v216
	v_max_f32_e32 v109, 0, v217
	v_pk_fma_f32 v[0:1], v[26:27], v[108:109], v[0:1]
	v_mfma_f32_32x32x16_bf16 v[6:21], v[90:93], v[42:45], v[6:21]
	v_max_f32_e32 v210, 0, v218
	v_max_f32_e32 v211, 0, v219
	v_pk_fma_f32 v[0:1], v[28:29], v[210:211], v[0:1]
	v_max_f32_e32 v108, 0, v220
	v_max_f32_e32 v109, 0, v221
	v_pk_fma_f32 v[0:1], v[30:31], v[108:109], v[0:1]
	v_max_f32_e32 v210, 0, v222
	v_max_f32_e32 v211, 0, v223
	v_pk_fma_f32 v[0:1], v[32:33], v[210:211], v[0:1]
	v_mfma_f32_32x32x16_bf16 v[6:21], v[94:97], v[46:49], v[6:21]
	v_max_f32_e32 v108, 0, v224
	v_max_f32_e32 v109, 0, v225
	v_pk_fma_f32 v[0:1], v[34:35], v[108:109], v[0:1]
	v_max_f32_e32 v210, 0, v226
	v_max_f32_e32 v211, 0, v227
	v_pk_fma_f32 v[0:1], v[36:37], v[210:211], v[0:1]
	v_add_f32_e32 v0, v0, v1
	v_ashrrev_i32_e32 v1, 31, v0
	v_mfma_f32_32x32x16_bf16 v[6:21], v[98:101], v[196:199], v[6:21]
	s_waitcnt vmcnt(10)
	ds_read_b128 v[38:41], v5 offset:10496
	ds_read_b128 v[42:45], v52 offset:10496
	ds_read_b128 v[46:49], v55 offset:10496
	ds_read_b128 v[196:199], v56 offset:10496
	v_or_b32_e32 v1, 0x80000000, v1
	s_cmpk_gt_i32 s11, 312
	s_cselect_b64 vcc, -1, 0
	v_xor_b32_e32 v0, v1, v0
	v_cndmask_b32_e32 v171, v123, v0, vcc
	s_nop 3
	v_max_f32_e32 v108, 0, v6
	v_max_f32_e32 v109, 0, v7
	v_pk_mul_f32 v[50:51], v[244:245], v[108:109]
	v_max_f32_e32 v210, 0, v8
	v_max_f32_e32 v211, 0, v9
	v_pk_fma_f32 v[50:51], v[246:247], v[210:211], v[50:51]
	v_max_f32_e32 v108, 0, v10
	v_max_f32_e32 v109, 0, v11
	v_pk_fma_f32 v[50:51], v[248:249], v[108:109], v[50:51]
	v_max_f32_e32 v210, 0, v12
	v_max_f32_e32 v211, 0, v13
	v_pk_fma_f32 v[50:51], v[250:251], v[210:211], v[50:51]
	v_max_f32_e32 v108, 0, v14
	v_max_f32_e32 v109, 0, v15
	v_pk_fma_f32 v[50:51], v[252:253], v[108:109], v[50:51]
	v_max_f32_e32 v210, 0, v16
	v_max_f32_e32 v211, 0, v17
	v_pk_fma_f32 v[50:51], v[254:255], v[210:211], v[50:51]
	v_max_f32_e32 v108, 0, v18
	v_max_f32_e32 v109, 0, v19
	v_pk_fma_f32 v[50:51], v[200:201], v[108:109], v[50:51]
	v_max_f32_e32 v210, 0, v20
	v_max_f32_e32 v211, 0, v21
	v_pk_fma_f32 v[50:51], v[202:203], v[210:211], v[50:51]
	v_add_f32_e32 v50, v50, v51
	v_ashrrev_i32_e32 v51, 31, v50
	v_or_b32_e32 v51, 0x80000000, v51
	s_cmpk_gt_i32 s11, 312
	s_cselect_b64 vcc, -1, 0
	v_xor_b32_e32 v50, v51, v50
	v_cndmask_b32_e32 v50, v123, v50, vcc
	global_store_dword v243, v50, s[8:9] offset:2048
	s_add_u32 s8, s8, 0x1000
	s_addc_u32 s9, s9, 0
	s_cmpk_gt_i32 s81, 40
	s_cbranch_scc0 .Lix_fill_5
	s_waitcnt lgkmcnt(3)
	v_mfma_f32_32x32x16_bf16 v[212:227], v[70:73], v[38:41], 0
	s_add_i32 m0, s10, 98304
	s_nop 0
	global_load_lds_dwordx4 v102, s[6:7]
	s_waitcnt lgkmcnt(2)
	v_mfma_f32_32x32x16_bf16 v[212:227], v[74:77], v[42:45], v[212:227]
	s_add_i32 m0, s10, 99328
	s_nop 0
	global_load_lds_dwordx4 v110, s[6:7]
	s_waitcnt lgkmcnt(1)
	v_mfma_f32_32x32x16_bf16 v[212:227], v[78:81], v[46:49], v[212:227]
	s_add_i32 m0, s10, 100352
	s_nop 0
	global_load_lds_dwordx4 v112, s[6:7]
	s_waitcnt lgkmcnt(0)
	v_mfma_f32_32x32x16_bf16 v[212:227], v[82:85], v[196:199], v[212:227]
	s_add_i32 m0, s10, 101376
	s_nop 0
	global_load_lds_dwordx4 v193, s[6:7]
	s_add_u32 s6, s6, 0x8000
	s_addc_u32 s7, s7, 0
	v_mfma_f32_32x32x16_bf16 v[6:21], v[86:89], v[38:41], 0
	s_nop 7
	s_nop 2
	v_max_f32_e32 v108, 0, v212
	v_max_f32_e32 v109, 0, v213
	v_pk_mul_f32 v[0:1], v[22:23], v[108:109]
	v_max_f32_e32 v210, 0, v214
	v_max_f32_e32 v211, 0, v215
	v_pk_fma_f32 v[0:1], v[24:25], v[210:211], v[0:1]
	v_max_f32_e32 v108, 0, v216
	v_max_f32_e32 v109, 0, v217
	v_pk_fma_f32 v[0:1], v[26:27], v[108:109], v[0:1]
	v_mfma_f32_32x32x16_bf16 v[6:21], v[90:93], v[42:45], v[6:21]
	v_max_f32_e32 v210, 0, v218
	v_max_f32_e32 v211, 0, v219
	v_pk_fma_f32 v[0:1], v[28:29], v[210:211], v[0:1]
	v_max_f32_e32 v108, 0, v220
	v_max_f32_e32 v109, 0, v221
	v_pk_fma_f32 v[0:1], v[30:31], v[108:109], v[0:1]
	v_max_f32_e32 v210, 0, v222
	v_max_f32_e32 v211, 0, v223
	v_pk_fma_f32 v[0:1], v[32:33], v[210:211], v[0:1]
	v_mfma_f32_32x32x16_bf16 v[6:21], v[94:97], v[46:49], v[6:21]
	v_max_f32_e32 v108, 0, v224
	v_max_f32_e32 v109, 0, v225
	v_pk_fma_f32 v[0:1], v[34:35], v[108:109], v[0:1]
	v_max_f32_e32 v210, 0, v226
	v_max_f32_e32 v211, 0, v227
	v_pk_fma_f32 v[0:1], v[36:37], v[210:211], v[0:1]
	v_add_f32_e32 v0, v0, v1
	v_ashrrev_i32_e32 v1, 31, v0
	v_mfma_f32_32x32x16_bf16 v[6:21], v[98:101], v[196:199], v[6:21]
	s_waitcnt vmcnt(10)
	ds_read_b128 v[38:41], v5 offset:43264
	ds_read_b128 v[42:45], v52 offset:43264
	ds_read_b128 v[46:49], v55 offset:43264
	ds_read_b128 v[196:199], v56 offset:43264
	v_or_b32_e32 v1, 0x80000000, v1
	s_cmpk_gt_i32 s11, 320
	s_cselect_b64 vcc, -1, 0
	v_xor_b32_e32 v0, v1, v0
	v_cndmask_b32_e32 v174, v123, v0, vcc
	s_nop 3
	s_waitcnt lgkmcnt(3)
	v_mfma_f32_32x32x16_bf16 v[212:227], v[70:73], v[38:41], 0
	v_max_f32_e32 v108, 0, v6
	v_max_f32_e32 v109, 0, v7
	v_pk_mul_f32 v[50:51], v[244:245], v[108:109]
	v_max_f32_e32 v210, 0, v8
	v_max_f32_e32 v211, 0, v9
	v_pk_fma_f32 v[50:51], v[246:247], v[210:211], v[50:51]
	v_max_f32_e32 v108, 0, v10
	v_max_f32_e32 v109, 0, v11
	v_pk_fma_f32 v[50:51], v[248:249], v[108:109], v[50:51]
	s_waitcnt lgkmcnt(2)
	v_mfma_f32_32x32x16_bf16 v[212:227], v[74:77], v[42:45], v[212:227]
	v_max_f32_e32 v210, 0, v12
	v_max_f32_e32 v211, 0, v13
	v_pk_fma_f32 v[50:51], v[250:251], v[210:211], v[50:51]
	v_max_f32_e32 v108, 0, v14
	v_max_f32_e32 v109, 0, v15
	v_pk_fma_f32 v[50:51], v[252:253], v[108:109], v[50:51]
	v_max_f32_e32 v210, 0, v16
	v_max_f32_e32 v211, 0, v17
	v_pk_fma_f32 v[50:51], v[254:255], v[210:211], v[50:51]
	s_waitcnt lgkmcnt(1)
	v_mfma_f32_32x32x16_bf16 v[212:227], v[78:81], v[46:49], v[212:227]
	v_max_f32_e32 v108, 0, v18
	v_max_f32_e32 v109, 0, v19
	v_pk_fma_f32 v[50:51], v[200:201], v[108:109], v[50:51]
	v_max_f32_e32 v210, 0, v20
	v_max_f32_e32 v211, 0, v21
	v_pk_fma_f32 v[50:51], v[202:203], v[210:211], v[50:51]
	v_add_f32_e32 v50, v50, v51
	v_ashrrev_i32_e32 v51, 31, v50
	s_waitcnt lgkmcnt(0)
	v_mfma_f32_32x32x16_bf16 v[212:227], v[82:85], v[196:199], v[212:227]
	v_or_b32_e32 v51, 0x80000000, v51
	s_cmpk_gt_i32 s11, 320
	s_cselect_b64 vcc, -1, 0
	v_xor_b32_e32 v50, v51, v50
	v_cndmask_b32_e32 v50, v123, v50, vcc
	global_store_dword v243, v50, s[8:9]
	v_mfma_f32_32x32x16_bf16 v[6:21], v[86:89], v[38:41], 0
	s_add_i32 m0, s10, 0
	s_nop 0
	global_load_lds_dwordx4 v102, s[6:7]
	s_add_i32 m0, s10, 1024
	s_nop 0
	global_load_lds_dwordx4 v110, s[6:7]
	s_add_i32 m0, s10, 2048
	s_nop 0
	global_load_lds_dwordx4 v112, s[6:7]
	s_add_i32 m0, s10, 3072
	s_nop 0
	global_load_lds_dwordx4 v193, s[6:7]
	s_add_u32 s6, s6, 0x8000
	s_addc_u32 s7, s7, 0
	v_max_f32_e32 v108, 0, v212
	v_max_f32_e32 v109, 0, v213
	v_pk_mul_f32 v[0:1], v[22:23], v[108:109]
	v_max_f32_e32 v210, 0, v214
	v_max_f32_e32 v211, 0, v215
	v_pk_fma_f32 v[0:1], v[24:25], v[210:211], v[0:1]
	v_max_f32_e32 v108, 0, v216
	v_max_f32_e32 v109, 0, v217
	v_pk_fma_f32 v[0:1], v[26:27], v[108:109], v[0:1]
	v_mfma_f32_32x32x16_bf16 v[6:21], v[90:93], v[42:45], v[6:21]
	v_max_f32_e32 v210, 0, v218
	v_max_f32_e32 v211, 0, v219
	v_pk_fma_f32 v[0:1], v[28:29], v[210:211], v[0:1]
	v_max_f32_e32 v108, 0, v220
	v_max_f32_e32 v109, 0, v221
	v_pk_fma_f32 v[0:1], v[30:31], v[108:109], v[0:1]
	v_max_f32_e32 v210, 0, v222
	v_max_f32_e32 v211, 0, v223
	v_pk_fma_f32 v[0:1], v[32:33], v[210:211], v[0:1]
	v_mfma_f32_32x32x16_bf16 v[6:21], v[94:97], v[46:49], v[6:21]
	v_max_f32_e32 v108, 0, v224
	v_max_f32_e32 v109, 0, v225
	v_pk_fma_f32 v[0:1], v[34:35], v[108:109], v[0:1]
	v_max_f32_e32 v210, 0, v226
	v_max_f32_e32 v211, 0, v227
	v_pk_fma_f32 v[0:1], v[36:37], v[210:211], v[0:1]
	v_add_f32_e32 v0, v0, v1
	v_ashrrev_i32_e32 v1, 31, v0
	v_mfma_f32_32x32x16_bf16 v[6:21], v[98:101], v[196:199], v[6:21]
	s_waitcnt vmcnt(10)
	v_add_u32_e32 v228, 0x10000, v5
	ds_read_b128 v[38:41], v228 offset:10496
	v_add_u32_e32 v228, 0x10000, v52
	ds_read_b128 v[42:45], v228 offset:10496
	v_add_u32_e32 v228, 0x10000, v55
	ds_read_b128 v[46:49], v228 offset:10496
	v_add_u32_e32 v228, 0x10000, v56
	ds_read_b128 v[196:199], v228 offset:10496
	v_or_b32_e32 v1, 0x80000000, v1
	s_cmpk_gt_i32 s11, 328
	s_cselect_b64 vcc, -1, 0
	v_xor_b32_e32 v0, v1, v0
	v_cndmask_b32_e32 v173, v123, v0, vcc
	s_nop 3
	s_waitcnt lgkmcnt(3)
	v_mfma_f32_32x32x16_bf16 v[212:227], v[70:73], v[38:41], 0
	v_max_f32_e32 v108, 0, v6
	v_max_f32_e32 v109, 0, v7
	v_pk_mul_f32 v[50:51], v[244:245], v[108:109]
	v_max_f32_e32 v210, 0, v8
	v_max_f32_e32 v211, 0, v9
	v_pk_fma_f32 v[50:51], v[246:247], v[210:211], v[50:51]
	v_max_f32_e32 v108, 0, v10
	v_max_f32_e32 v109, 0, v11
	v_pk_fma_f32 v[50:51], v[248:249], v[108:109], v[50:51]
	s_waitcnt lgkmcnt(2)
	v_mfma_f32_32x32x16_bf16 v[212:227], v[74:77], v[42:45], v[212:227]
	v_max_f32_e32 v210, 0, v12
	v_max_f32_e32 v211, 0, v13
	v_pk_fma_f32 v[50:51], v[250:251], v[210:211], v[50:51]
	v_max_f32_e32 v108, 0, v14
	v_max_f32_e32 v109, 0, v15
	v_pk_fma_f32 v[50:51], v[252:253], v[108:109], v[50:51]
	v_max_f32_e32 v210, 0, v16
	v_max_f32_e32 v211, 0, v17
	v_pk_fma_f32 v[50:51], v[254:255], v[210:211], v[50:51]
	s_waitcnt lgkmcnt(1)
	v_mfma_f32_32x32x16_bf16 v[212:227], v[78:81], v[46:49], v[212:227]
	v_max_f32_e32 v108, 0, v18
	v_max_f32_e32 v109, 0, v19
	v_pk_fma_f32 v[50:51], v[200:201], v[108:109], v[50:51]
	v_max_f32_e32 v210, 0, v20
	v_max_f32_e32 v211, 0, v21
	v_pk_fma_f32 v[50:51], v[202:203], v[210:211], v[50:51]
	v_add_f32_e32 v50, v50, v51
	v_ashrrev_i32_e32 v51, 31, v50
	s_waitcnt lgkmcnt(0)
	v_mfma_f32_32x32x16_bf16 v[212:227], v[82:85], v[196:199], v[212:227]
	v_or_b32_e32 v51, 0x80000000, v51
	s_cmpk_gt_i32 s11, 328
	s_cselect_b64 vcc, -1, 0
	v_xor_b32_e32 v50, v51, v50
	v_cndmask_b32_e32 v50, v123, v50, vcc
	global_store_dword v243, v50, s[8:9] offset:2048
	s_add_u32 s8, s8, 0x1000
	s_addc_u32 s9, s9, 0
	v_mfma_f32_32x32x16_bf16 v[6:21], v[86:89], v[38:41], 0
	s_add_i32 m0, s10, 32768
	s_nop 0
	global_load_lds_dwordx4 v102, s[6:7]
	s_add_i32 m0, s10, 33792
	s_nop 0
	global_load_lds_dwordx4 v110, s[6:7]
	s_add_i32 m0, s10, 34816
	s_nop 0
	global_load_lds_dwordx4 v112, s[6:7]
	s_add_i32 m0, s10, 35840
	s_nop 0
	global_load_lds_dwordx4 v193, s[6:7]
	s_add_u32 s6, s6, 0x8000
	s_addc_u32 s7, s7, 0
	v_max_f32_e32 v108, 0, v212
	v_max_f32_e32 v109, 0, v213
	v_pk_mul_f32 v[0:1], v[22:23], v[108:109]
	v_max_f32_e32 v210, 0, v214
	v_max_f32_e32 v211, 0, v215
	v_pk_fma_f32 v[0:1], v[24:25], v[210:211], v[0:1]
	v_max_f32_e32 v108, 0, v216
	v_max_f32_e32 v109, 0, v217
	v_pk_fma_f32 v[0:1], v[26:27], v[108:109], v[0:1]
	v_mfma_f32_32x32x16_bf16 v[6:21], v[90:93], v[42:45], v[6:21]
	v_max_f32_e32 v210, 0, v218
	v_max_f32_e32 v211, 0, v219
	v_pk_fma_f32 v[0:1], v[28:29], v[210:211], v[0:1]
	v_max_f32_e32 v108, 0, v220
	v_max_f32_e32 v109, 0, v221
	v_pk_fma_f32 v[0:1], v[30:31], v[108:109], v[0:1]
	v_max_f32_e32 v210, 0, v222
	v_max_f32_e32 v211, 0, v223
	v_pk_fma_f32 v[0:1], v[32:33], v[210:211], v[0:1]
	v_mfma_f32_32x32x16_bf16 v[6:21], v[94:97], v[46:49], v[6:21]
	v_max_f32_e32 v108, 0, v224
	v_max_f32_e32 v109, 0, v225
	v_pk_fma_f32 v[0:1], v[34:35], v[108:109], v[0:1]
	v_max_f32_e32 v210, 0, v226
	v_max_f32_e32 v211, 0, v227
	v_pk_fma_f32 v[0:1], v[36:37], v[210:211], v[0:1]
	v_add_f32_e32 v0, v0, v1
	v_ashrrev_i32_e32 v1, 31, v0
	v_mfma_f32_32x32x16_bf16 v[6:21], v[98:101], v[196:199], v[6:21]
	s_waitcnt vmcnt(10)
	v_add_u32_e32 v228, 0x10000, v5
	ds_read_b128 v[38:41], v228 offset:43264
	v_add_u32_e32 v228, 0x10000, v52
	ds_read_b128 v[42:45], v228 offset:43264
	v_add_u32_e32 v228, 0x10000, v55
	ds_read_b128 v[46:49], v228 offset:43264
	v_add_u32_e32 v228, 0x10000, v56
	ds_read_b128 v[196:199], v228 offset:43264
	v_or_b32_e32 v1, 0x80000000, v1
	s_cmpk_gt_i32 s11, 336
	s_cselect_b64 vcc, -1, 0
	v_xor_b32_e32 v0, v1, v0
	v_cndmask_b32_e32 v176, v123, v0, vcc
	s_nop 3
	s_waitcnt lgkmcnt(3)
	v_mfma_f32_32x32x16_bf16 v[212:227], v[70:73], v[38:41], 0
	v_max_f32_e32 v108, 0, v6
	v_max_f32_e32 v109, 0, v7
	v_pk_mul_f32 v[50:51], v[244:245], v[108:109]
	v_max_f32_e32 v210, 0, v8
	v_max_f32_e32 v211, 0, v9
	v_pk_fma_f32 v[50:51], v[246:247], v[210:211], v[50:51]
	v_max_f32_e32 v108, 0, v10
	v_max_f32_e32 v109, 0, v11
	v_pk_fma_f32 v[50:51], v[248:249], v[108:109], v[50:51]
	s_waitcnt lgkmcnt(2)
	v_mfma_f32_32x32x16_bf16 v[212:227], v[74:77], v[42:45], v[212:227]
	v_max_f32_e32 v210, 0, v12
	v_max_f32_e32 v211, 0, v13
	v_pk_fma_f32 v[50:51], v[250:251], v[210:211], v[50:51]
	v_max_f32_e32 v108, 0, v14
	v_max_f32_e32 v109, 0, v15
	v_pk_fma_f32 v[50:51], v[252:253], v[108:109], v[50:51]
	v_max_f32_e32 v210, 0, v16
	v_max_f32_e32 v211, 0, v17
	v_pk_fma_f32 v[50:51], v[254:255], v[210:211], v[50:51]
	s_waitcnt lgkmcnt(1)
	v_mfma_f32_32x32x16_bf16 v[212:227], v[78:81], v[46:49], v[212:227]
	v_max_f32_e32 v108, 0, v18
	v_max_f32_e32 v109, 0, v19
	v_pk_fma_f32 v[50:51], v[200:201], v[108:109], v[50:51]
	v_max_f32_e32 v210, 0, v20
	v_max_f32_e32 v211, 0, v21
	v_pk_fma_f32 v[50:51], v[202:203], v[210:211], v[50:51]
	v_add_f32_e32 v50, v50, v51
	v_ashrrev_i32_e32 v51, 31, v50
	s_waitcnt lgkmcnt(0)
	v_mfma_f32_32x32x16_bf16 v[212:227], v[82:85], v[196:199], v[212:227]
	v_or_b32_e32 v51, 0x80000000, v51
	s_cmpk_gt_i32 s11, 336
	s_cselect_b64 vcc, -1, 0
	v_xor_b32_e32 v50, v51, v50
	v_cndmask_b32_e32 v50, v123, v50, vcc
	global_store_dword v243, v50, s[8:9]
	v_mfma_f32_32x32x16_bf16 v[6:21], v[86:89], v[38:41], 0
	s_add_i32 m0, s10, 65536
	s_nop 0
	global_load_lds_dwordx4 v102, s[6:7]
	s_add_i32 m0, s10, 66560
	s_nop 0
	global_load_lds_dwordx4 v110, s[6:7]
	s_add_i32 m0, s10, 67584
	s_nop 0
	global_load_lds_dwordx4 v112, s[6:7]
	s_add_i32 m0, s10, 68608
	s_nop 0
	global_load_lds_dwordx4 v193, s[6:7]
	s_add_u32 s6, s6, 0x8000
	s_addc_u32 s7, s7, 0
	v_max_f32_e32 v108, 0, v212
	v_max_f32_e32 v109, 0, v213
	v_pk_mul_f32 v[0:1], v[22:23], v[108:109]
	v_max_f32_e32 v210, 0, v214
	v_max_f32_e32 v211, 0, v215
	v_pk_fma_f32 v[0:1], v[24:25], v[210:211], v[0:1]
	v_max_f32_e32 v108, 0, v216
	v_max_f32_e32 v109, 0, v217
	v_pk_fma_f32 v[0:1], v[26:27], v[108:109], v[0:1]
	v_mfma_f32_32x32x16_bf16 v[6:21], v[90:93], v[42:45], v[6:21]
	v_max_f32_e32 v210, 0, v218
	v_max_f32_e32 v211, 0, v219
	v_pk_fma_f32 v[0:1], v[28:29], v[210:211], v[0:1]
	v_max_f32_e32 v108, 0, v220
	v_max_f32_e32 v109, 0, v221
	v_pk_fma_f32 v[0:1], v[30:31], v[108:109], v[0:1]
	v_max_f32_e32 v210, 0, v222
	v_max_f32_e32 v211, 0, v223
	v_pk_fma_f32 v[0:1], v[32:33], v[210:211], v[0:1]
	v_mfma_f32_32x32x16_bf16 v[6:21], v[94:97], v[46:49], v[6:21]
	v_max_f32_e32 v108, 0, v224
	v_max_f32_e32 v109, 0, v225
	v_pk_fma_f32 v[0:1], v[34:35], v[108:109], v[0:1]
	v_max_f32_e32 v210, 0, v226
	v_max_f32_e32 v211, 0, v227
	v_pk_fma_f32 v[0:1], v[36:37], v[210:211], v[0:1]
	v_add_f32_e32 v0, v0, v1
	v_ashrrev_i32_e32 v1, 31, v0
	v_mfma_f32_32x32x16_bf16 v[6:21], v[98:101], v[196:199], v[6:21]
	s_waitcnt vmcnt(10)
	ds_read_b128 v[38:41], v5 offset:10496
	ds_read_b128 v[42:45], v52 offset:10496
	ds_read_b128 v[46:49], v55 offset:10496
	ds_read_b128 v[196:199], v56 offset:10496
	v_or_b32_e32 v1, 0x80000000, v1
	s_cmpk_gt_i32 s11, 344
	s_cselect_b64 vcc, -1, 0
	v_xor_b32_e32 v0, v1, v0
	v_cndmask_b32_e32 v175, v123, v0, vcc
	s_nop 3
	s_waitcnt lgkmcnt(3)
	v_mfma_f32_32x32x16_bf16 v[212:227], v[70:73], v[38:41], 0
	v_max_f32_e32 v108, 0, v6
	v_max_f32_e32 v109, 0, v7
	v_pk_mul_f32 v[50:51], v[244:245], v[108:109]
	v_max_f32_e32 v210, 0, v8
	v_max_f32_e32 v211, 0, v9
	v_pk_fma_f32 v[50:51], v[246:247], v[210:211], v[50:51]
	v_max_f32_e32 v108, 0, v10
	v_max_f32_e32 v109, 0, v11
	v_pk_fma_f32 v[50:51], v[248:249], v[108:109], v[50:51]
	s_waitcnt lgkmcnt(2)
	v_mfma_f32_32x32x16_bf16 v[212:227], v[74:77], v[42:45], v[212:227]
	v_max_f32_e32 v210, 0, v12
	v_max_f32_e32 v211, 0, v13
	v_pk_fma_f32 v[50:51], v[250:251], v[210:211], v[50:51]
	v_max_f32_e32 v108, 0, v14
	v_max_f32_e32 v109, 0, v15
	v_pk_fma_f32 v[50:51], v[252:253], v[108:109], v[50:51]
	v_max_f32_e32 v210, 0, v16
	v_max_f32_e32 v211, 0, v17
	v_pk_fma_f32 v[50:51], v[254:255], v[210:211], v[50:51]
	s_waitcnt lgkmcnt(1)
	v_mfma_f32_32x32x16_bf16 v[212:227], v[78:81], v[46:49], v[212:227]
	v_max_f32_e32 v108, 0, v18
	v_max_f32_e32 v109, 0, v19
	v_pk_fma_f32 v[50:51], v[200:201], v[108:109], v[50:51]
	v_max_f32_e32 v210, 0, v20
	v_max_f32_e32 v211, 0, v21
	v_pk_fma_f32 v[50:51], v[202:203], v[210:211], v[50:51]
	v_add_f32_e32 v50, v50, v51
	v_ashrrev_i32_e32 v51, 31, v50
	s_waitcnt lgkmcnt(0)
	v_mfma_f32_32x32x16_bf16 v[212:227], v[82:85], v[196:199], v[212:227]
	v_or_b32_e32 v51, 0x80000000, v51
	s_cmpk_gt_i32 s11, 344
	s_cselect_b64 vcc, -1, 0
	v_xor_b32_e32 v50, v51, v50
	v_cndmask_b32_e32 v50, v123, v50, vcc
	global_store_dword v243, v50, s[8:9] offset:2048
	s_add_u32 s8, s8, 0x1000
	s_addc_u32 s9, s9, 0
	v_mfma_f32_32x32x16_bf16 v[6:21], v[86:89], v[38:41], 0
	s_add_i32 m0, s10, 98304
	s_nop 0
	global_load_lds_dwordx4 v102, s[6:7]
	s_add_i32 m0, s10, 99328
	s_nop 0
	global_load_lds_dwordx4 v110, s[6:7]
	s_add_i32 m0, s10, 100352
	s_nop 0
	global_load_lds_dwordx4 v112, s[6:7]
	s_add_i32 m0, s10, 101376
	s_nop 0
	global_load_lds_dwordx4 v193, s[6:7]
	s_add_u32 s6, s6, 0x8000
	s_addc_u32 s7, s7, 0
	v_max_f32_e32 v108, 0, v212
	v_max_f32_e32 v109, 0, v213
	v_pk_mul_f32 v[0:1], v[22:23], v[108:109]
	v_max_f32_e32 v210, 0, v214
	v_max_f32_e32 v211, 0, v215
	v_pk_fma_f32 v[0:1], v[24:25], v[210:211], v[0:1]
	v_max_f32_e32 v108, 0, v216
	v_max_f32_e32 v109, 0, v217
	v_pk_fma_f32 v[0:1], v[26:27], v[108:109], v[0:1]
	v_mfma_f32_32x32x16_bf16 v[6:21], v[90:93], v[42:45], v[6:21]
	v_max_f32_e32 v210, 0, v218
	v_max_f32_e32 v211, 0, v219
	v_pk_fma_f32 v[0:1], v[28:29], v[210:211], v[0:1]
	v_max_f32_e32 v108, 0, v220
	v_max_f32_e32 v109, 0, v221
	v_pk_fma_f32 v[0:1], v[30:31], v[108:109], v[0:1]
	v_max_f32_e32 v210, 0, v222
	v_max_f32_e32 v211, 0, v223
	v_pk_fma_f32 v[0:1], v[32:33], v[210:211], v[0:1]
	v_mfma_f32_32x32x16_bf16 v[6:21], v[94:97], v[46:49], v[6:21]
	v_max_f32_e32 v108, 0, v224
	v_max_f32_e32 v109, 0, v225
	v_pk_fma_f32 v[0:1], v[34:35], v[108:109], v[0:1]
	v_max_f32_e32 v210, 0, v226
	v_max_f32_e32 v211, 0, v227
	v_pk_fma_f32 v[0:1], v[36:37], v[210:211], v[0:1]
	v_add_f32_e32 v0, v0, v1
	v_ashrrev_i32_e32 v1, 31, v0
	v_mfma_f32_32x32x16_bf16 v[6:21], v[98:101], v[196:199], v[6:21]
	s_waitcnt vmcnt(10)
	ds_read_b128 v[38:41], v5 offset:43264
	ds_read_b128 v[42:45], v52 offset:43264
	ds_read_b128 v[46:49], v55 offset:43264
	ds_read_b128 v[196:199], v56 offset:43264
	v_or_b32_e32 v1, 0x80000000, v1
	s_cmpk_gt_i32 s11, 352
	s_cselect_b64 vcc, -1, 0
	v_xor_b32_e32 v0, v1, v0
	v_cndmask_b32_e32 v178, v123, v0, vcc
	s_nop 3
	s_waitcnt lgkmcnt(3)
	v_mfma_f32_32x32x16_bf16 v[212:227], v[70:73], v[38:41], 0
	v_max_f32_e32 v108, 0, v6
	v_max_f32_e32 v109, 0, v7
	v_pk_mul_f32 v[50:51], v[244:245], v[108:109]
	v_max_f32_e32 v210, 0, v8
	v_max_f32_e32 v211, 0, v9
	v_pk_fma_f32 v[50:51], v[246:247], v[210:211], v[50:51]
	v_max_f32_e32 v108, 0, v10
	v_max_f32_e32 v109, 0, v11
	v_pk_fma_f32 v[50:51], v[248:249], v[108:109], v[50:51]
	s_waitcnt lgkmcnt(2)
	v_mfma_f32_32x32x16_bf16 v[212:227], v[74:77], v[42:45], v[212:227]
	v_max_f32_e32 v210, 0, v12
	v_max_f32_e32 v211, 0, v13
	v_pk_fma_f32 v[50:51], v[250:251], v[210:211], v[50:51]
	v_max_f32_e32 v108, 0, v14
	v_max_f32_e32 v109, 0, v15
	v_pk_fma_f32 v[50:51], v[252:253], v[108:109], v[50:51]
	v_max_f32_e32 v210, 0, v16
	v_max_f32_e32 v211, 0, v17
	v_pk_fma_f32 v[50:51], v[254:255], v[210:211], v[50:51]
	s_waitcnt lgkmcnt(1)
	v_mfma_f32_32x32x16_bf16 v[212:227], v[78:81], v[46:49], v[212:227]
	v_max_f32_e32 v108, 0, v18
	v_max_f32_e32 v109, 0, v19
	v_pk_fma_f32 v[50:51], v[200:201], v[108:109], v[50:51]
	v_max_f32_e32 v210, 0, v20
	v_max_f32_e32 v211, 0, v21
	v_pk_fma_f32 v[50:51], v[202:203], v[210:211], v[50:51]
	v_add_f32_e32 v50, v50, v51
	v_ashrrev_i32_e32 v51, 31, v50
	s_waitcnt lgkmcnt(0)
	v_mfma_f32_32x32x16_bf16 v[212:227], v[82:85], v[196:199], v[212:227]
	v_or_b32_e32 v51, 0x80000000, v51
	s_cmpk_gt_i32 s11, 352
	s_cselect_b64 vcc, -1, 0
	v_xor_b32_e32 v50, v51, v50
	v_cndmask_b32_e32 v50, v123, v50, vcc
	global_store_dword v243, v50, s[8:9]
	v_mfma_f32_32x32x16_bf16 v[6:21], v[86:89], v[38:41], 0
	s_add_i32 m0, s10, 0
	s_nop 0
	global_load_lds_dwordx4 v102, s[6:7]
	s_add_i32 m0, s10, 1024
	s_nop 0
	global_load_lds_dwordx4 v110, s[6:7]
	s_add_i32 m0, s10, 2048
	s_nop 0
	global_load_lds_dwordx4 v112, s[6:7]
	s_add_i32 m0, s10, 3072
	s_nop 0
	global_load_lds_dwordx4 v193, s[6:7]
	s_add_u32 s6, s6, 0x8000
	s_addc_u32 s7, s7, 0
	v_max_f32_e32 v108, 0, v212
	v_max_f32_e32 v109, 0, v213
	v_pk_mul_f32 v[0:1], v[22:23], v[108:109]
	v_max_f32_e32 v210, 0, v214
	v_max_f32_e32 v211, 0, v215
	v_pk_fma_f32 v[0:1], v[24:25], v[210:211], v[0:1]
	v_max_f32_e32 v108, 0, v216
	v_max_f32_e32 v109, 0, v217
	v_pk_fma_f32 v[0:1], v[26:27], v[108:109], v[0:1]
	v_mfma_f32_32x32x16_bf16 v[6:21], v[90:93], v[42:45], v[6:21]
	v_max_f32_e32 v210, 0, v218
	v_max_f32_e32 v211, 0, v219
	v_pk_fma_f32 v[0:1], v[28:29], v[210:211], v[0:1]
	v_max_f32_e32 v108, 0, v220
	v_max_f32_e32 v109, 0, v221
	v_pk_fma_f32 v[0:1], v[30:31], v[108:109], v[0:1]
	v_max_f32_e32 v210, 0, v222
	v_max_f32_e32 v211, 0, v223
	v_pk_fma_f32 v[0:1], v[32:33], v[210:211], v[0:1]
	v_mfma_f32_32x32x16_bf16 v[6:21], v[94:97], v[46:49], v[6:21]
	v_max_f32_e32 v108, 0, v224
	v_max_f32_e32 v109, 0, v225
	v_pk_fma_f32 v[0:1], v[34:35], v[108:109], v[0:1]
	v_max_f32_e32 v210, 0, v226
	v_max_f32_e32 v211, 0, v227
	v_pk_fma_f32 v[0:1], v[36:37], v[210:211], v[0:1]
	v_add_f32_e32 v0, v0, v1
	v_ashrrev_i32_e32 v1, 31, v0
	v_mfma_f32_32x32x16_bf16 v[6:21], v[98:101], v[196:199], v[6:21]
	s_waitcnt vmcnt(10)
	v_add_u32_e32 v228, 0x10000, v5
	ds_read_b128 v[38:41], v228 offset:10496
	v_add_u32_e32 v228, 0x10000, v52
	ds_read_b128 v[42:45], v228 offset:10496
	v_add_u32_e32 v228, 0x10000, v55
	ds_read_b128 v[46:49], v228 offset:10496
	v_add_u32_e32 v228, 0x10000, v56
	ds_read_b128 v[196:199], v228 offset:10496
	v_or_b32_e32 v1, 0x80000000, v1
	s_cmpk_gt_i32 s11, 360
	s_cselect_b64 vcc, -1, 0
	v_xor_b32_e32 v0, v1, v0
	v_cndmask_b32_e32 v177, v123, v0, vcc
	s_nop 3
	s_waitcnt lgkmcnt(3)
	v_mfma_f32_32x32x16_bf16 v[212:227], v[70:73], v[38:41], 0
	v_max_f32_e32 v108, 0, v6
	v_max_f32_e32 v109, 0, v7
	v_pk_mul_f32 v[50:51], v[244:245], v[108:109]
	v_max_f32_e32 v210, 0, v8
	v_max_f32_e32 v211, 0, v9
	v_pk_fma_f32 v[50:51], v[246:247], v[210:211], v[50:51]
	v_max_f32_e32 v108, 0, v10
	v_max_f32_e32 v109, 0, v11
	v_pk_fma_f32 v[50:51], v[248:249], v[108:109], v[50:51]
	s_waitcnt lgkmcnt(2)
	v_mfma_f32_32x32x16_bf16 v[212:227], v[74:77], v[42:45], v[212:227]
	v_max_f32_e32 v210, 0, v12
	v_max_f32_e32 v211, 0, v13
	v_pk_fma_f32 v[50:51], v[250:251], v[210:211], v[50:51]
	v_max_f32_e32 v108, 0, v14
	v_max_f32_e32 v109, 0, v15
	v_pk_fma_f32 v[50:51], v[252:253], v[108:109], v[50:51]
	v_max_f32_e32 v210, 0, v16
	v_max_f32_e32 v211, 0, v17
	v_pk_fma_f32 v[50:51], v[254:255], v[210:211], v[50:51]
	s_waitcnt lgkmcnt(1)
	v_mfma_f32_32x32x16_bf16 v[212:227], v[78:81], v[46:49], v[212:227]
	v_max_f32_e32 v108, 0, v18
	v_max_f32_e32 v109, 0, v19
	v_pk_fma_f32 v[50:51], v[200:201], v[108:109], v[50:51]
	v_max_f32_e32 v210, 0, v20
	v_max_f32_e32 v211, 0, v21
	v_pk_fma_f32 v[50:51], v[202:203], v[210:211], v[50:51]
	v_add_f32_e32 v50, v50, v51
	v_ashrrev_i32_e32 v51, 31, v50
	s_waitcnt lgkmcnt(0)
	v_mfma_f32_32x32x16_bf16 v[212:227], v[82:85], v[196:199], v[212:227]
	v_or_b32_e32 v51, 0x80000000, v51
	s_cmpk_gt_i32 s11, 360
	s_cselect_b64 vcc, -1, 0
	v_xor_b32_e32 v50, v51, v50
	v_cndmask_b32_e32 v50, v123, v50, vcc
	global_store_dword v243, v50, s[8:9] offset:2048
	s_add_u32 s8, s8, 0x1000
	s_addc_u32 s9, s9, 0
	v_mfma_f32_32x32x16_bf16 v[6:21], v[86:89], v[38:41], 0
	s_add_i32 m0, s10, 32768
	s_nop 0
	global_load_lds_dwordx4 v102, s[6:7]
	s_add_i32 m0, s10, 33792
	s_nop 0
	global_load_lds_dwordx4 v110, s[6:7]
	s_add_i32 m0, s10, 34816
	s_nop 0
	global_load_lds_dwordx4 v112, s[6:7]
	s_add_i32 m0, s10, 35840
	s_nop 0
	global_load_lds_dwordx4 v193, s[6:7]
	s_add_u32 s6, s6, 0x8000
	s_addc_u32 s7, s7, 0
	v_max_f32_e32 v108, 0, v212
	v_max_f32_e32 v109, 0, v213
	v_pk_mul_f32 v[0:1], v[22:23], v[108:109]
	v_max_f32_e32 v210, 0, v214
	v_max_f32_e32 v211, 0, v215
	v_pk_fma_f32 v[0:1], v[24:25], v[210:211], v[0:1]
	v_max_f32_e32 v108, 0, v216
	v_max_f32_e32 v109, 0, v217
	v_pk_fma_f32 v[0:1], v[26:27], v[108:109], v[0:1]
	v_mfma_f32_32x32x16_bf16 v[6:21], v[90:93], v[42:45], v[6:21]
	v_max_f32_e32 v210, 0, v218
	v_max_f32_e32 v211, 0, v219
	v_pk_fma_f32 v[0:1], v[28:29], v[210:211], v[0:1]
	v_max_f32_e32 v108, 0, v220
	v_max_f32_e32 v109, 0, v221
	v_pk_fma_f32 v[0:1], v[30:31], v[108:109], v[0:1]
	v_max_f32_e32 v210, 0, v222
	v_max_f32_e32 v211, 0, v223
	v_pk_fma_f32 v[0:1], v[32:33], v[210:211], v[0:1]
	v_mfma_f32_32x32x16_bf16 v[6:21], v[94:97], v[46:49], v[6:21]
	v_max_f32_e32 v108, 0, v224
	v_max_f32_e32 v109, 0, v225
	v_pk_fma_f32 v[0:1], v[34:35], v[108:109], v[0:1]
	v_max_f32_e32 v210, 0, v226
	v_max_f32_e32 v211, 0, v227
	v_pk_fma_f32 v[0:1], v[36:37], v[210:211], v[0:1]
	v_add_f32_e32 v0, v0, v1
	v_ashrrev_i32_e32 v1, 31, v0
	v_mfma_f32_32x32x16_bf16 v[6:21], v[98:101], v[196:199], v[6:21]
	s_waitcnt vmcnt(10)
	v_add_u32_e32 v228, 0x10000, v5
	ds_read_b128 v[38:41], v228 offset:43264
	v_add_u32_e32 v228, 0x10000, v52
	ds_read_b128 v[42:45], v228 offset:43264
	v_add_u32_e32 v228, 0x10000, v55
	ds_read_b128 v[46:49], v228 offset:43264
	v_add_u32_e32 v228, 0x10000, v56
	ds_read_b128 v[196:199], v228 offset:43264
	v_or_b32_e32 v1, 0x80000000, v1
	s_cmpk_gt_i32 s11, 368
	s_cselect_b64 vcc, -1, 0
	v_xor_b32_e32 v0, v1, v0
	v_cndmask_b32_e32 v179, v123, v0, vcc
	s_nop 3
	s_waitcnt lgkmcnt(3)
	v_mfma_f32_32x32x16_bf16 v[212:227], v[70:73], v[38:41], 0
	v_max_f32_e32 v108, 0, v6
	v_max_f32_e32 v109, 0, v7
	v_pk_mul_f32 v[50:51], v[244:245], v[108:109]
	v_max_f32_e32 v210, 0, v8
	v_max_f32_e32 v211, 0, v9
	v_pk_fma_f32 v[50:51], v[246:247], v[210:211], v[50:51]
	v_max_f32_e32 v108, 0, v10
	v_max_f32_e32 v109, 0, v11
	v_pk_fma_f32 v[50:51], v[248:249], v[108:109], v[50:51]
	s_waitcnt lgkmcnt(2)
	v_mfma_f32_32x32x16_bf16 v[212:227], v[74:77], v[42:45], v[212:227]
	v_max_f32_e32 v210, 0, v12
	v_max_f32_e32 v211, 0, v13
	v_pk_fma_f32 v[50:51], v[250:251], v[210:211], v[50:51]
	v_max_f32_e32 v108, 0, v14
	v_max_f32_e32 v109, 0, v15
	v_pk_fma_f32 v[50:51], v[252:253], v[108:109], v[50:51]
	v_max_f32_e32 v210, 0, v16
	v_max_f32_e32 v211, 0, v17
	v_pk_fma_f32 v[50:51], v[254:255], v[210:211], v[50:51]
	s_waitcnt lgkmcnt(1)
	v_mfma_f32_32x32x16_bf16 v[212:227], v[78:81], v[46:49], v[212:227]
	v_max_f32_e32 v108, 0, v18
	v_max_f32_e32 v109, 0, v19
	v_pk_fma_f32 v[50:51], v[200:201], v[108:109], v[50:51]
	v_max_f32_e32 v210, 0, v20
	v_max_f32_e32 v211, 0, v21
	v_pk_fma_f32 v[50:51], v[202:203], v[210:211], v[50:51]
	v_add_f32_e32 v50, v50, v51
	v_ashrrev_i32_e32 v51, 31, v50
	s_waitcnt lgkmcnt(0)
	v_mfma_f32_32x32x16_bf16 v[212:227], v[82:85], v[196:199], v[212:227]
	v_or_b32_e32 v51, 0x80000000, v51
	s_cmpk_gt_i32 s11, 368
	s_cselect_b64 vcc, -1, 0
	v_xor_b32_e32 v50, v51, v50
	v_cndmask_b32_e32 v50, v123, v50, vcc
	global_store_dword v243, v50, s[8:9]
	v_mfma_f32_32x32x16_bf16 v[6:21], v[86:89], v[38:41], 0
	s_add_i32 m0, s10, 65536
	s_nop 0
	global_load_lds_dwordx4 v102, s[6:7]
	s_add_i32 m0, s10, 66560
	s_nop 0
	global_load_lds_dwordx4 v110, s[6:7]
	s_add_i32 m0, s10, 67584
	s_nop 0
	global_load_lds_dwordx4 v112, s[6:7]
	s_add_i32 m0, s10, 68608
	s_nop 0
	global_load_lds_dwordx4 v193, s[6:7]
	s_add_u32 s6, s6, 0x8000
	s_addc_u32 s7, s7, 0
	v_max_f32_e32 v108, 0, v212
	v_max_f32_e32 v109, 0, v213
	v_pk_mul_f32 v[0:1], v[22:23], v[108:109]
	v_max_f32_e32 v210, 0, v214
	v_max_f32_e32 v211, 0, v215
	v_pk_fma_f32 v[0:1], v[24:25], v[210:211], v[0:1]
	v_max_f32_e32 v108, 0, v216
	v_max_f32_e32 v109, 0, v217
	v_pk_fma_f32 v[0:1], v[26:27], v[108:109], v[0:1]
	v_mfma_f32_32x32x16_bf16 v[6:21], v[90:93], v[42:45], v[6:21]
	v_max_f32_e32 v210, 0, v218
	v_max_f32_e32 v211, 0, v219
	v_pk_fma_f32 v[0:1], v[28:29], v[210:211], v[0:1]
	v_max_f32_e32 v108, 0, v220
	v_max_f32_e32 v109, 0, v221
	v_pk_fma_f32 v[0:1], v[30:31], v[108:109], v[0:1]
	v_max_f32_e32 v210, 0, v222
	v_max_f32_e32 v211, 0, v223
	v_pk_fma_f32 v[0:1], v[32:33], v[210:211], v[0:1]
	v_mfma_f32_32x32x16_bf16 v[6:21], v[94:97], v[46:49], v[6:21]
	v_max_f32_e32 v108, 0, v224
	v_max_f32_e32 v109, 0, v225
	v_pk_fma_f32 v[0:1], v[34:35], v[108:109], v[0:1]
	v_max_f32_e32 v210, 0, v226
	v_max_f32_e32 v211, 0, v227
	v_pk_fma_f32 v[0:1], v[36:37], v[210:211], v[0:1]
	v_add_f32_e32 v0, v0, v1
	v_ashrrev_i32_e32 v1, 31, v0
	v_mfma_f32_32x32x16_bf16 v[6:21], v[98:101], v[196:199], v[6:21]
	s_waitcnt vmcnt(10)
	ds_read_b128 v[38:41], v5 offset:10496
	ds_read_b128 v[42:45], v52 offset:10496
	ds_read_b128 v[46:49], v55 offset:10496
	ds_read_b128 v[196:199], v56 offset:10496
	v_or_b32_e32 v1, 0x80000000, v1
	s_cmpk_gt_i32 s11, 376
	s_cselect_b64 vcc, -1, 0
	v_xor_b32_e32 v0, v1, v0
	v_cndmask_b32_e32 v168, v123, v0, vcc
	s_nop 3
	v_max_f32_e32 v108, 0, v6
	v_max_f32_e32 v109, 0, v7
	v_pk_mul_f32 v[50:51], v[244:245], v[108:109]
	v_max_f32_e32 v210, 0, v8
	v_max_f32_e32 v211, 0, v9
	v_pk_fma_f32 v[50:51], v[246:247], v[210:211], v[50:51]
	v_max_f32_e32 v108, 0, v10
	v_max_f32_e32 v109, 0, v11
	v_pk_fma_f32 v[50:51], v[248:249], v[108:109], v[50:51]
	v_max_f32_e32 v210, 0, v12
	v_max_f32_e32 v211, 0, v13
	v_pk_fma_f32 v[50:51], v[250:251], v[210:211], v[50:51]
	v_max_f32_e32 v108, 0, v14
	v_max_f32_e32 v109, 0, v15
	v_pk_fma_f32 v[50:51], v[252:253], v[108:109], v[50:51]
	v_max_f32_e32 v210, 0, v16
	v_max_f32_e32 v211, 0, v17
	v_pk_fma_f32 v[50:51], v[254:255], v[210:211], v[50:51]
	v_max_f32_e32 v108, 0, v18
	v_max_f32_e32 v109, 0, v19
	v_pk_fma_f32 v[50:51], v[200:201], v[108:109], v[50:51]
	v_max_f32_e32 v210, 0, v20
	v_max_f32_e32 v211, 0, v21
	v_pk_fma_f32 v[50:51], v[202:203], v[210:211], v[50:51]
	v_add_f32_e32 v50, v50, v51
	v_ashrrev_i32_e32 v51, 31, v50
	v_or_b32_e32 v51, 0x80000000, v51
	s_cmpk_gt_i32 s11, 376
	s_cselect_b64 vcc, -1, 0
	v_xor_b32_e32 v50, v51, v50
	v_cndmask_b32_e32 v50, v123, v50, vcc
	global_store_dword v243, v50, s[8:9] offset:2048
	s_add_u32 s8, s8, 0x1000
	s_addc_u32 s9, s9, 0
	s_cmpk_gt_i32 s81, 48
	s_cbranch_scc0 .Lix_fill_6
	s_waitcnt lgkmcnt(3)
	v_mfma_f32_32x32x16_bf16 v[212:227], v[70:73], v[38:41], 0
	s_add_i32 m0, s10, 98304
	s_nop 0
	global_load_lds_dwordx4 v102, s[6:7]
	s_waitcnt lgkmcnt(2)
	v_mfma_f32_32x32x16_bf16 v[212:227], v[74:77], v[42:45], v[212:227]
	s_add_i32 m0, s10, 99328
	s_nop 0
	global_load_lds_dwordx4 v110, s[6:7]
	s_waitcnt lgkmcnt(1)
	v_mfma_f32_32x32x16_bf16 v[212:227], v[78:81], v[46:49], v[212:227]
	s_add_i32 m0, s10, 100352
	s_nop 0
	global_load_lds_dwordx4 v112, s[6:7]
	s_waitcnt lgkmcnt(0)
	v_mfma_f32_32x32x16_bf16 v[212:227], v[82:85], v[196:199], v[212:227]
	s_add_i32 m0, s10, 101376
	s_nop 0
	global_load_lds_dwordx4 v193, s[6:7]
	s_add_u32 s6, s6, 0x8000
	s_addc_u32 s7, s7, 0
	v_mfma_f32_32x32x16_bf16 v[6:21], v[86:89], v[38:41], 0
	s_nop 7
	s_nop 2
	v_max_f32_e32 v108, 0, v212
	v_max_f32_e32 v109, 0, v213
	v_pk_mul_f32 v[0:1], v[22:23], v[108:109]
	v_max_f32_e32 v210, 0, v214
	v_max_f32_e32 v211, 0, v215
	v_pk_fma_f32 v[0:1], v[24:25], v[210:211], v[0:1]
	v_max_f32_e32 v108, 0, v216
	v_max_f32_e32 v109, 0, v217
	v_pk_fma_f32 v[0:1], v[26:27], v[108:109], v[0:1]
	v_mfma_f32_32x32x16_bf16 v[6:21], v[90:93], v[42:45], v[6:21]
	v_max_f32_e32 v210, 0, v218
	v_max_f32_e32 v211, 0, v219
	v_pk_fma_f32 v[0:1], v[28:29], v[210:211], v[0:1]
	v_max_f32_e32 v108, 0, v220
	v_max_f32_e32 v109, 0, v221
	v_pk_fma_f32 v[0:1], v[30:31], v[108:109], v[0:1]
	v_max_f32_e32 v210, 0, v222
	v_max_f32_e32 v211, 0, v223
	v_pk_fma_f32 v[0:1], v[32:33], v[210:211], v[0:1]
	v_mfma_f32_32x32x16_bf16 v[6:21], v[94:97], v[46:49], v[6:21]
	v_max_f32_e32 v108, 0, v224
	v_max_f32_e32 v109, 0, v225
	v_pk_fma_f32 v[0:1], v[34:35], v[108:109], v[0:1]
	v_max_f32_e32 v210, 0, v226
	v_max_f32_e32 v211, 0, v227
	v_pk_fma_f32 v[0:1], v[36:37], v[210:211], v[0:1]
	v_add_f32_e32 v0, v0, v1
	v_ashrrev_i32_e32 v1, 31, v0
	v_mfma_f32_32x32x16_bf16 v[6:21], v[98:101], v[196:199], v[6:21]
	s_waitcnt vmcnt(10)
	ds_read_b128 v[38:41], v5 offset:43264
	ds_read_b128 v[42:45], v52 offset:43264
	ds_read_b128 v[46:49], v55 offset:43264
	ds_read_b128 v[196:199], v56 offset:43264
	v_or_b32_e32 v1, 0x80000000, v1
	s_cmpk_gt_i32 s11, 384
	s_cselect_b64 vcc, -1, 0
	v_xor_b32_e32 v0, v1, v0
	v_cndmask_b32_e32 v182, v123, v0, vcc
	s_nop 3
	s_waitcnt lgkmcnt(3)
	v_mfma_f32_32x32x16_bf16 v[212:227], v[70:73], v[38:41], 0
	v_max_f32_e32 v108, 0, v6
	v_max_f32_e32 v109, 0, v7
	v_pk_mul_f32 v[50:51], v[244:245], v[108:109]
	v_max_f32_e32 v210, 0, v8
	v_max_f32_e32 v211, 0, v9
	v_pk_fma_f32 v[50:51], v[246:247], v[210:211], v[50:51]
	v_max_f32_e32 v108, 0, v10
	v_max_f32_e32 v109, 0, v11
	v_pk_fma_f32 v[50:51], v[248:249], v[108:109], v[50:51]
	s_waitcnt lgkmcnt(2)
	v_mfma_f32_32x32x16_bf16 v[212:227], v[74:77], v[42:45], v[212:227]
	v_max_f32_e32 v210, 0, v12
	v_max_f32_e32 v211, 0, v13
	v_pk_fma_f32 v[50:51], v[250:251], v[210:211], v[50:51]
	v_max_f32_e32 v108, 0, v14
	v_max_f32_e32 v109, 0, v15
	v_pk_fma_f32 v[50:51], v[252:253], v[108:109], v[50:51]
	v_max_f32_e32 v210, 0, v16
	v_max_f32_e32 v211, 0, v17
	v_pk_fma_f32 v[50:51], v[254:255], v[210:211], v[50:51]
	s_waitcnt lgkmcnt(1)
	v_mfma_f32_32x32x16_bf16 v[212:227], v[78:81], v[46:49], v[212:227]
	v_max_f32_e32 v108, 0, v18
	v_max_f32_e32 v109, 0, v19
	v_pk_fma_f32 v[50:51], v[200:201], v[108:109], v[50:51]
	v_max_f32_e32 v210, 0, v20
	v_max_f32_e32 v211, 0, v21
	v_pk_fma_f32 v[50:51], v[202:203], v[210:211], v[50:51]
	v_add_f32_e32 v50, v50, v51
	v_ashrrev_i32_e32 v51, 31, v50
	s_waitcnt lgkmcnt(0)
	v_mfma_f32_32x32x16_bf16 v[212:227], v[82:85], v[196:199], v[212:227]
	v_or_b32_e32 v51, 0x80000000, v51
	s_cmpk_gt_i32 s11, 384
	s_cselect_b64 vcc, -1, 0
	v_xor_b32_e32 v50, v51, v50
	v_cndmask_b32_e32 v50, v123, v50, vcc
	global_store_dword v243, v50, s[8:9]
	v_mfma_f32_32x32x16_bf16 v[6:21], v[86:89], v[38:41], 0
	s_add_i32 m0, s10, 0
	s_nop 0
	global_load_lds_dwordx4 v102, s[6:7]
	s_add_i32 m0, s10, 1024
	s_nop 0
	global_load_lds_dwordx4 v110, s[6:7]
	s_add_i32 m0, s10, 2048
	s_nop 0
	global_load_lds_dwordx4 v112, s[6:7]
	s_add_i32 m0, s10, 3072
	s_nop 0
	global_load_lds_dwordx4 v193, s[6:7]
	s_add_u32 s6, s6, 0x8000
	s_addc_u32 s7, s7, 0
	v_max_f32_e32 v108, 0, v212
	v_max_f32_e32 v109, 0, v213
	v_pk_mul_f32 v[0:1], v[22:23], v[108:109]
	v_max_f32_e32 v210, 0, v214
	v_max_f32_e32 v211, 0, v215
	v_pk_fma_f32 v[0:1], v[24:25], v[210:211], v[0:1]
	v_max_f32_e32 v108, 0, v216
	v_max_f32_e32 v109, 0, v217
	v_pk_fma_f32 v[0:1], v[26:27], v[108:109], v[0:1]
	v_mfma_f32_32x32x16_bf16 v[6:21], v[90:93], v[42:45], v[6:21]
	v_max_f32_e32 v210, 0, v218
	v_max_f32_e32 v211, 0, v219
	v_pk_fma_f32 v[0:1], v[28:29], v[210:211], v[0:1]
	v_max_f32_e32 v108, 0, v220
	v_max_f32_e32 v109, 0, v221
	v_pk_fma_f32 v[0:1], v[30:31], v[108:109], v[0:1]
	v_max_f32_e32 v210, 0, v222
	v_max_f32_e32 v211, 0, v223
	v_pk_fma_f32 v[0:1], v[32:33], v[210:211], v[0:1]
	v_mfma_f32_32x32x16_bf16 v[6:21], v[94:97], v[46:49], v[6:21]
	v_max_f32_e32 v108, 0, v224
	v_max_f32_e32 v109, 0, v225
	v_pk_fma_f32 v[0:1], v[34:35], v[108:109], v[0:1]
	v_max_f32_e32 v210, 0, v226
	v_max_f32_e32 v211, 0, v227
	v_pk_fma_f32 v[0:1], v[36:37], v[210:211], v[0:1]
	v_add_f32_e32 v0, v0, v1
	v_ashrrev_i32_e32 v1, 31, v0
	v_mfma_f32_32x32x16_bf16 v[6:21], v[98:101], v[196:199], v[6:21]
	s_waitcnt vmcnt(10)
	v_add_u32_e32 v228, 0x10000, v5
	ds_read_b128 v[38:41], v228 offset:10496
	v_add_u32_e32 v228, 0x10000, v52
	ds_read_b128 v[42:45], v228 offset:10496
	v_add_u32_e32 v228, 0x10000, v55
	ds_read_b128 v[46:49], v228 offset:10496
	v_add_u32_e32 v228, 0x10000, v56
	ds_read_b128 v[196:199], v228 offset:10496
	v_or_b32_e32 v1, 0x80000000, v1
	s_cmpk_gt_i32 s11, 392
	s_cselect_b64 vcc, -1, 0
	v_xor_b32_e32 v0, v1, v0
	v_cndmask_b32_e32 v181, v123, v0, vcc
	s_nop 3
	s_waitcnt lgkmcnt(3)
	v_mfma_f32_32x32x16_bf16 v[212:227], v[70:73], v[38:41], 0
	v_max_f32_e32 v108, 0, v6
	v_max_f32_e32 v109, 0, v7
	v_pk_mul_f32 v[50:51], v[244:245], v[108:109]
	v_max_f32_e32 v210, 0, v8
	v_max_f32_e32 v211, 0, v9
	v_pk_fma_f32 v[50:51], v[246:247], v[210:211], v[50:51]
	v_max_f32_e32 v108, 0, v10
	v_max_f32_e32 v109, 0, v11
	v_pk_fma_f32 v[50:51], v[248:249], v[108:109], v[50:51]
	s_waitcnt lgkmcnt(2)
	v_mfma_f32_32x32x16_bf16 v[212:227], v[74:77], v[42:45], v[212:227]
	v_max_f32_e32 v210, 0, v12
	v_max_f32_e32 v211, 0, v13
	v_pk_fma_f32 v[50:51], v[250:251], v[210:211], v[50:51]
	v_max_f32_e32 v108, 0, v14
	v_max_f32_e32 v109, 0, v15
	v_pk_fma_f32 v[50:51], v[252:253], v[108:109], v[50:51]
	v_max_f32_e32 v210, 0, v16
	v_max_f32_e32 v211, 0, v17
	v_pk_fma_f32 v[50:51], v[254:255], v[210:211], v[50:51]
	s_waitcnt lgkmcnt(1)
	v_mfma_f32_32x32x16_bf16 v[212:227], v[78:81], v[46:49], v[212:227]
	v_max_f32_e32 v108, 0, v18
	v_max_f32_e32 v109, 0, v19
	v_pk_fma_f32 v[50:51], v[200:201], v[108:109], v[50:51]
	v_max_f32_e32 v210, 0, v20
	v_max_f32_e32 v211, 0, v21
	v_pk_fma_f32 v[50:51], v[202:203], v[210:211], v[50:51]
	v_add_f32_e32 v50, v50, v51
	v_ashrrev_i32_e32 v51, 31, v50
	s_waitcnt lgkmcnt(0)
	v_mfma_f32_32x32x16_bf16 v[212:227], v[82:85], v[196:199], v[212:227]
	v_or_b32_e32 v51, 0x80000000, v51
	s_cmpk_gt_i32 s11, 392
	s_cselect_b64 vcc, -1, 0
	v_xor_b32_e32 v50, v51, v50
	v_cndmask_b32_e32 v50, v123, v50, vcc
	global_store_dword v243, v50, s[8:9] offset:2048
	s_add_u32 s8, s8, 0x1000
	s_addc_u32 s9, s9, 0
	v_mfma_f32_32x32x16_bf16 v[6:21], v[86:89], v[38:41], 0
	s_add_i32 m0, s10, 32768
	s_nop 0
	global_load_lds_dwordx4 v102, s[6:7]
	s_add_i32 m0, s10, 33792
	s_nop 0
	global_load_lds_dwordx4 v110, s[6:7]
	s_add_i32 m0, s10, 34816
	s_nop 0
	global_load_lds_dwordx4 v112, s[6:7]
	s_add_i32 m0, s10, 35840
	s_nop 0
	global_load_lds_dwordx4 v193, s[6:7]
	s_add_u32 s6, s6, 0x8000
	s_addc_u32 s7, s7, 0
	v_max_f32_e32 v108, 0, v212
	v_max_f32_e32 v109, 0, v213
	v_pk_mul_f32 v[0:1], v[22:23], v[108:109]
	v_max_f32_e32 v210, 0, v214
	v_max_f32_e32 v211, 0, v215
	v_pk_fma_f32 v[0:1], v[24:25], v[210:211], v[0:1]
	v_max_f32_e32 v108, 0, v216
	v_max_f32_e32 v109, 0, v217
	v_pk_fma_f32 v[0:1], v[26:27], v[108:109], v[0:1]
	v_mfma_f32_32x32x16_bf16 v[6:21], v[90:93], v[42:45], v[6:21]
	v_max_f32_e32 v210, 0, v218
	v_max_f32_e32 v211, 0, v219
	v_pk_fma_f32 v[0:1], v[28:29], v[210:211], v[0:1]
	v_max_f32_e32 v108, 0, v220
	v_max_f32_e32 v109, 0, v221
	v_pk_fma_f32 v[0:1], v[30:31], v[108:109], v[0:1]
	v_max_f32_e32 v210, 0, v222
	v_max_f32_e32 v211, 0, v223
	v_pk_fma_f32 v[0:1], v[32:33], v[210:211], v[0:1]
	v_mfma_f32_32x32x16_bf16 v[6:21], v[94:97], v[46:49], v[6:21]
	v_max_f32_e32 v108, 0, v224
	v_max_f32_e32 v109, 0, v225
	v_pk_fma_f32 v[0:1], v[34:35], v[108:109], v[0:1]
	v_max_f32_e32 v210, 0, v226
	v_max_f32_e32 v211, 0, v227
	v_pk_fma_f32 v[0:1], v[36:37], v[210:211], v[0:1]
	v_add_f32_e32 v0, v0, v1
	v_ashrrev_i32_e32 v1, 31, v0
	v_mfma_f32_32x32x16_bf16 v[6:21], v[98:101], v[196:199], v[6:21]
	s_waitcnt vmcnt(10)
	v_add_u32_e32 v228, 0x10000, v5
	ds_read_b128 v[38:41], v228 offset:43264
	v_add_u32_e32 v228, 0x10000, v52
	ds_read_b128 v[42:45], v228 offset:43264
	v_add_u32_e32 v228, 0x10000, v55
	ds_read_b128 v[46:49], v228 offset:43264
	v_add_u32_e32 v228, 0x10000, v56
	ds_read_b128 v[196:199], v228 offset:43264
	v_or_b32_e32 v1, 0x80000000, v1
	s_cmpk_gt_i32 s11, 400
	s_cselect_b64 vcc, -1, 0
	v_xor_b32_e32 v0, v1, v0
	v_cndmask_b32_e32 v184, v123, v0, vcc
	s_nop 3
	s_waitcnt lgkmcnt(3)
	v_mfma_f32_32x32x16_bf16 v[212:227], v[70:73], v[38:41], 0
	v_max_f32_e32 v108, 0, v6
	v_max_f32_e32 v109, 0, v7
	v_pk_mul_f32 v[50:51], v[244:245], v[108:109]
	v_max_f32_e32 v210, 0, v8
	v_max_f32_e32 v211, 0, v9
	v_pk_fma_f32 v[50:51], v[246:247], v[210:211], v[50:51]
	v_max_f32_e32 v108, 0, v10
	v_max_f32_e32 v109, 0, v11
	v_pk_fma_f32 v[50:51], v[248:249], v[108:109], v[50:51]
	s_waitcnt lgkmcnt(2)
	v_mfma_f32_32x32x16_bf16 v[212:227], v[74:77], v[42:45], v[212:227]
	v_max_f32_e32 v210, 0, v12
	v_max_f32_e32 v211, 0, v13
	v_pk_fma_f32 v[50:51], v[250:251], v[210:211], v[50:51]
	v_max_f32_e32 v108, 0, v14
	v_max_f32_e32 v109, 0, v15
	v_pk_fma_f32 v[50:51], v[252:253], v[108:109], v[50:51]
	v_max_f32_e32 v210, 0, v16
	v_max_f32_e32 v211, 0, v17
	v_pk_fma_f32 v[50:51], v[254:255], v[210:211], v[50:51]
	s_waitcnt lgkmcnt(1)
	v_mfma_f32_32x32x16_bf16 v[212:227], v[78:81], v[46:49], v[212:227]
	v_max_f32_e32 v108, 0, v18
	v_max_f32_e32 v109, 0, v19
	v_pk_fma_f32 v[50:51], v[200:201], v[108:109], v[50:51]
	v_max_f32_e32 v210, 0, v20
	v_max_f32_e32 v211, 0, v21
	v_pk_fma_f32 v[50:51], v[202:203], v[210:211], v[50:51]
	v_add_f32_e32 v50, v50, v51
	v_ashrrev_i32_e32 v51, 31, v50
	s_waitcnt lgkmcnt(0)
	v_mfma_f32_32x32x16_bf16 v[212:227], v[82:85], v[196:199], v[212:227]
	v_or_b32_e32 v51, 0x80000000, v51
	s_cmpk_gt_i32 s11, 400
	s_cselect_b64 vcc, -1, 0
	v_xor_b32_e32 v50, v51, v50
	v_cndmask_b32_e32 v50, v123, v50, vcc
	global_store_dword v243, v50, s[8:9]
	v_mfma_f32_32x32x16_bf16 v[6:21], v[86:89], v[38:41], 0
	s_add_i32 m0, s10, 65536
	s_nop 0
	global_load_lds_dwordx4 v102, s[6:7]
	s_add_i32 m0, s10, 66560
	s_nop 0
	global_load_lds_dwordx4 v110, s[6:7]
	s_add_i32 m0, s10, 67584
	s_nop 0
	global_load_lds_dwordx4 v112, s[6:7]
	s_add_i32 m0, s10, 68608
	s_nop 0
	global_load_lds_dwordx4 v193, s[6:7]
	s_add_u32 s6, s6, 0x8000
	s_addc_u32 s7, s7, 0
	v_max_f32_e32 v108, 0, v212
	v_max_f32_e32 v109, 0, v213
	v_pk_mul_f32 v[0:1], v[22:23], v[108:109]
	v_max_f32_e32 v210, 0, v214
	v_max_f32_e32 v211, 0, v215
	v_pk_fma_f32 v[0:1], v[24:25], v[210:211], v[0:1]
	v_max_f32_e32 v108, 0, v216
	v_max_f32_e32 v109, 0, v217
	v_pk_fma_f32 v[0:1], v[26:27], v[108:109], v[0:1]
	v_mfma_f32_32x32x16_bf16 v[6:21], v[90:93], v[42:45], v[6:21]
	v_max_f32_e32 v210, 0, v218
	v_max_f32_e32 v211, 0, v219
	v_pk_fma_f32 v[0:1], v[28:29], v[210:211], v[0:1]
	v_max_f32_e32 v108, 0, v220
	v_max_f32_e32 v109, 0, v221
	v_pk_fma_f32 v[0:1], v[30:31], v[108:109], v[0:1]
	v_max_f32_e32 v210, 0, v222
	v_max_f32_e32 v211, 0, v223
	v_pk_fma_f32 v[0:1], v[32:33], v[210:211], v[0:1]
	v_mfma_f32_32x32x16_bf16 v[6:21], v[94:97], v[46:49], v[6:21]
	v_max_f32_e32 v108, 0, v224
	v_max_f32_e32 v109, 0, v225
	v_pk_fma_f32 v[0:1], v[34:35], v[108:109], v[0:1]
	v_max_f32_e32 v210, 0, v226
	v_max_f32_e32 v211, 0, v227
	v_pk_fma_f32 v[0:1], v[36:37], v[210:211], v[0:1]
	v_add_f32_e32 v0, v0, v1
	v_ashrrev_i32_e32 v1, 31, v0
	v_mfma_f32_32x32x16_bf16 v[6:21], v[98:101], v[196:199], v[6:21]
	s_waitcnt vmcnt(10)
	ds_read_b128 v[38:41], v5 offset:10496
	ds_read_b128 v[42:45], v52 offset:10496
	ds_read_b128 v[46:49], v55 offset:10496
	ds_read_b128 v[196:199], v56 offset:10496
	v_or_b32_e32 v1, 0x80000000, v1
	s_cmpk_gt_i32 s11, 408
	s_cselect_b64 vcc, -1, 0
	v_xor_b32_e32 v0, v1, v0
	v_cndmask_b32_e32 v183, v123, v0, vcc
	s_nop 3
	s_waitcnt lgkmcnt(3)
	v_mfma_f32_32x32x16_bf16 v[212:227], v[70:73], v[38:41], 0
	v_max_f32_e32 v108, 0, v6
	v_max_f32_e32 v109, 0, v7
	v_pk_mul_f32 v[50:51], v[244:245], v[108:109]
	v_max_f32_e32 v210, 0, v8
	v_max_f32_e32 v211, 0, v9
	v_pk_fma_f32 v[50:51], v[246:247], v[210:211], v[50:51]
	v_max_f32_e32 v108, 0, v10
	v_max_f32_e32 v109, 0, v11
	v_pk_fma_f32 v[50:51], v[248:249], v[108:109], v[50:51]
	s_waitcnt lgkmcnt(2)
	v_mfma_f32_32x32x16_bf16 v[212:227], v[74:77], v[42:45], v[212:227]
	v_max_f32_e32 v210, 0, v12
	v_max_f32_e32 v211, 0, v13
	v_pk_fma_f32 v[50:51], v[250:251], v[210:211], v[50:51]
	v_max_f32_e32 v108, 0, v14
	v_max_f32_e32 v109, 0, v15
	v_pk_fma_f32 v[50:51], v[252:253], v[108:109], v[50:51]
	v_max_f32_e32 v210, 0, v16
	v_max_f32_e32 v211, 0, v17
	v_pk_fma_f32 v[50:51], v[254:255], v[210:211], v[50:51]
	s_waitcnt lgkmcnt(1)
	v_mfma_f32_32x32x16_bf16 v[212:227], v[78:81], v[46:49], v[212:227]
	v_max_f32_e32 v108, 0, v18
	v_max_f32_e32 v109, 0, v19
	v_pk_fma_f32 v[50:51], v[200:201], v[108:109], v[50:51]
	v_max_f32_e32 v210, 0, v20
	v_max_f32_e32 v211, 0, v21
	v_pk_fma_f32 v[50:51], v[202:203], v[210:211], v[50:51]
	v_add_f32_e32 v50, v50, v51
	v_ashrrev_i32_e32 v51, 31, v50
	s_waitcnt lgkmcnt(0)
	v_mfma_f32_32x32x16_bf16 v[212:227], v[82:85], v[196:199], v[212:227]
	v_or_b32_e32 v51, 0x80000000, v51
	s_cmpk_gt_i32 s11, 408
	s_cselect_b64 vcc, -1, 0
	v_xor_b32_e32 v50, v51, v50
	v_cndmask_b32_e32 v50, v123, v50, vcc
	global_store_dword v243, v50, s[8:9] offset:2048
	s_add_u32 s8, s8, 0x1000
	s_addc_u32 s9, s9, 0
	v_mfma_f32_32x32x16_bf16 v[6:21], v[86:89], v[38:41], 0
	s_add_i32 m0, s10, 98304
	s_nop 0
	global_load_lds_dwordx4 v102, s[6:7]
	s_add_i32 m0, s10, 99328
	s_nop 0
	global_load_lds_dwordx4 v110, s[6:7]
	s_add_i32 m0, s10, 100352
	s_nop 0
	global_load_lds_dwordx4 v112, s[6:7]
	s_add_i32 m0, s10, 101376
	s_nop 0
	global_load_lds_dwordx4 v193, s[6:7]
	s_add_u32 s6, s6, 0x8000
	s_addc_u32 s7, s7, 0
	v_max_f32_e32 v108, 0, v212
	v_max_f32_e32 v109, 0, v213
	v_pk_mul_f32 v[0:1], v[22:23], v[108:109]
	v_max_f32_e32 v210, 0, v214
	v_max_f32_e32 v211, 0, v215
	v_pk_fma_f32 v[0:1], v[24:25], v[210:211], v[0:1]
	v_max_f32_e32 v108, 0, v216
	v_max_f32_e32 v109, 0, v217
	v_pk_fma_f32 v[0:1], v[26:27], v[108:109], v[0:1]
	v_mfma_f32_32x32x16_bf16 v[6:21], v[90:93], v[42:45], v[6:21]
	v_max_f32_e32 v210, 0, v218
	v_max_f32_e32 v211, 0, v219
	v_pk_fma_f32 v[0:1], v[28:29], v[210:211], v[0:1]
	v_max_f32_e32 v108, 0, v220
	v_max_f32_e32 v109, 0, v221
	v_pk_fma_f32 v[0:1], v[30:31], v[108:109], v[0:1]
	v_max_f32_e32 v210, 0, v222
	v_max_f32_e32 v211, 0, v223
	v_pk_fma_f32 v[0:1], v[32:33], v[210:211], v[0:1]
	v_mfma_f32_32x32x16_bf16 v[6:21], v[94:97], v[46:49], v[6:21]
	v_max_f32_e32 v108, 0, v224
	v_max_f32_e32 v109, 0, v225
	v_pk_fma_f32 v[0:1], v[34:35], v[108:109], v[0:1]
	v_max_f32_e32 v210, 0, v226
	v_max_f32_e32 v211, 0, v227
	v_pk_fma_f32 v[0:1], v[36:37], v[210:211], v[0:1]
	v_add_f32_e32 v0, v0, v1
	v_ashrrev_i32_e32 v1, 31, v0
	v_mfma_f32_32x32x16_bf16 v[6:21], v[98:101], v[196:199], v[6:21]
	s_waitcnt vmcnt(10)
	ds_read_b128 v[38:41], v5 offset:43264
	ds_read_b128 v[42:45], v52 offset:43264
	ds_read_b128 v[46:49], v55 offset:43264
	ds_read_b128 v[196:199], v56 offset:43264
	v_or_b32_e32 v1, 0x80000000, v1
	s_cmpk_gt_i32 s11, 416
	s_cselect_b64 vcc, -1, 0
	v_xor_b32_e32 v0, v1, v0
	v_cndmask_b32_e32 v187, v123, v0, vcc
	s_nop 3
	s_waitcnt lgkmcnt(3)
	v_mfma_f32_32x32x16_bf16 v[212:227], v[70:73], v[38:41], 0
	v_max_f32_e32 v108, 0, v6
	v_max_f32_e32 v109, 0, v7
	v_pk_mul_f32 v[50:51], v[244:245], v[108:109]
	v_max_f32_e32 v210, 0, v8
	v_max_f32_e32 v211, 0, v9
	v_pk_fma_f32 v[50:51], v[246:247], v[210:211], v[50:51]
	v_max_f32_e32 v108, 0, v10
	v_max_f32_e32 v109, 0, v11
	v_pk_fma_f32 v[50:51], v[248:249], v[108:109], v[50:51]
	s_waitcnt lgkmcnt(2)
	v_mfma_f32_32x32x16_bf16 v[212:227], v[74:77], v[42:45], v[212:227]
	v_max_f32_e32 v210, 0, v12
	v_max_f32_e32 v211, 0, v13
	v_pk_fma_f32 v[50:51], v[250:251], v[210:211], v[50:51]
	v_max_f32_e32 v108, 0, v14
	v_max_f32_e32 v109, 0, v15
	v_pk_fma_f32 v[50:51], v[252:253], v[108:109], v[50:51]
	v_max_f32_e32 v210, 0, v16
	v_max_f32_e32 v211, 0, v17
	v_pk_fma_f32 v[50:51], v[254:255], v[210:211], v[50:51]
	s_waitcnt lgkmcnt(1)
	v_mfma_f32_32x32x16_bf16 v[212:227], v[78:81], v[46:49], v[212:227]
	v_max_f32_e32 v108, 0, v18
	v_max_f32_e32 v109, 0, v19
	v_pk_fma_f32 v[50:51], v[200:201], v[108:109], v[50:51]
	v_max_f32_e32 v210, 0, v20
	v_max_f32_e32 v211, 0, v21
	v_pk_fma_f32 v[50:51], v[202:203], v[210:211], v[50:51]
	v_add_f32_e32 v50, v50, v51
	v_ashrrev_i32_e32 v51, 31, v50
	s_waitcnt lgkmcnt(0)
	v_mfma_f32_32x32x16_bf16 v[212:227], v[82:85], v[196:199], v[212:227]
	v_or_b32_e32 v51, 0x80000000, v51
	s_cmpk_gt_i32 s11, 416
	s_cselect_b64 vcc, -1, 0
	v_xor_b32_e32 v50, v51, v50
	v_cndmask_b32_e32 v50, v123, v50, vcc
	global_store_dword v243, v50, s[8:9]
	v_mfma_f32_32x32x16_bf16 v[6:21], v[86:89], v[38:41], 0
	s_add_i32 m0, s10, 0
	s_nop 0
	global_load_lds_dwordx4 v102, s[6:7]
	s_add_i32 m0, s10, 1024
	s_nop 0
	global_load_lds_dwordx4 v110, s[6:7]
	s_add_i32 m0, s10, 2048
	s_nop 0
	global_load_lds_dwordx4 v112, s[6:7]
	s_add_i32 m0, s10, 3072
	s_nop 0
	global_load_lds_dwordx4 v193, s[6:7]
	s_add_u32 s6, s6, 0x8000
	s_addc_u32 s7, s7, 0
	v_max_f32_e32 v108, 0, v212
	v_max_f32_e32 v109, 0, v213
	v_pk_mul_f32 v[0:1], v[22:23], v[108:109]
	v_max_f32_e32 v210, 0, v214
	v_max_f32_e32 v211, 0, v215
	v_pk_fma_f32 v[0:1], v[24:25], v[210:211], v[0:1]
	v_max_f32_e32 v108, 0, v216
	v_max_f32_e32 v109, 0, v217
	v_pk_fma_f32 v[0:1], v[26:27], v[108:109], v[0:1]
	v_mfma_f32_32x32x16_bf16 v[6:21], v[90:93], v[42:45], v[6:21]
	v_max_f32_e32 v210, 0, v218
	v_max_f32_e32 v211, 0, v219
	v_pk_fma_f32 v[0:1], v[28:29], v[210:211], v[0:1]
	v_max_f32_e32 v108, 0, v220
	v_max_f32_e32 v109, 0, v221
	v_pk_fma_f32 v[0:1], v[30:31], v[108:109], v[0:1]
	v_max_f32_e32 v210, 0, v222
	v_max_f32_e32 v211, 0, v223
	v_pk_fma_f32 v[0:1], v[32:33], v[210:211], v[0:1]
	v_mfma_f32_32x32x16_bf16 v[6:21], v[94:97], v[46:49], v[6:21]
	v_max_f32_e32 v108, 0, v224
	v_max_f32_e32 v109, 0, v225
	v_pk_fma_f32 v[0:1], v[34:35], v[108:109], v[0:1]
	v_max_f32_e32 v210, 0, v226
	v_max_f32_e32 v211, 0, v227
	v_pk_fma_f32 v[0:1], v[36:37], v[210:211], v[0:1]
	v_add_f32_e32 v0, v0, v1
	v_ashrrev_i32_e32 v1, 31, v0
	v_mfma_f32_32x32x16_bf16 v[6:21], v[98:101], v[196:199], v[6:21]
	s_waitcnt vmcnt(10)
	v_add_u32_e32 v228, 0x10000, v5
	ds_read_b128 v[38:41], v228 offset:10496
	v_add_u32_e32 v228, 0x10000, v52
	ds_read_b128 v[42:45], v228 offset:10496
	v_add_u32_e32 v228, 0x10000, v55
	ds_read_b128 v[46:49], v228 offset:10496
	v_add_u32_e32 v228, 0x10000, v56
	ds_read_b128 v[196:199], v228 offset:10496
	v_or_b32_e32 v1, 0x80000000, v1
	s_cmpk_gt_i32 s11, 424
	s_cselect_b64 vcc, -1, 0
	v_xor_b32_e32 v0, v1, v0
	v_cndmask_b32_e32 v186, v123, v0, vcc
	s_nop 3
	s_waitcnt lgkmcnt(3)
	v_mfma_f32_32x32x16_bf16 v[212:227], v[70:73], v[38:41], 0
	v_max_f32_e32 v108, 0, v6
	v_max_f32_e32 v109, 0, v7
	v_pk_mul_f32 v[50:51], v[244:245], v[108:109]
	v_max_f32_e32 v210, 0, v8
	v_max_f32_e32 v211, 0, v9
	v_pk_fma_f32 v[50:51], v[246:247], v[210:211], v[50:51]
	v_max_f32_e32 v108, 0, v10
	v_max_f32_e32 v109, 0, v11
	v_pk_fma_f32 v[50:51], v[248:249], v[108:109], v[50:51]
	s_waitcnt lgkmcnt(2)
	v_mfma_f32_32x32x16_bf16 v[212:227], v[74:77], v[42:45], v[212:227]
	v_max_f32_e32 v210, 0, v12
	v_max_f32_e32 v211, 0, v13
	v_pk_fma_f32 v[50:51], v[250:251], v[210:211], v[50:51]
	v_max_f32_e32 v108, 0, v14
	v_max_f32_e32 v109, 0, v15
	v_pk_fma_f32 v[50:51], v[252:253], v[108:109], v[50:51]
	v_max_f32_e32 v210, 0, v16
	v_max_f32_e32 v211, 0, v17
	v_pk_fma_f32 v[50:51], v[254:255], v[210:211], v[50:51]
	s_waitcnt lgkmcnt(1)
	v_mfma_f32_32x32x16_bf16 v[212:227], v[78:81], v[46:49], v[212:227]
	v_max_f32_e32 v108, 0, v18
	v_max_f32_e32 v109, 0, v19
	v_pk_fma_f32 v[50:51], v[200:201], v[108:109], v[50:51]
	v_max_f32_e32 v210, 0, v20
	v_max_f32_e32 v211, 0, v21
	v_pk_fma_f32 v[50:51], v[202:203], v[210:211], v[50:51]
	v_add_f32_e32 v50, v50, v51
	v_ashrrev_i32_e32 v51, 31, v50
	s_waitcnt lgkmcnt(0)
	v_mfma_f32_32x32x16_bf16 v[212:227], v[82:85], v[196:199], v[212:227]
	v_or_b32_e32 v51, 0x80000000, v51
	s_cmpk_gt_i32 s11, 424
	s_cselect_b64 vcc, -1, 0
	v_xor_b32_e32 v50, v51, v50
	v_cndmask_b32_e32 v50, v123, v50, vcc
	global_store_dword v243, v50, s[8:9] offset:2048
	s_add_u32 s8, s8, 0x1000
	s_addc_u32 s9, s9, 0
	v_mfma_f32_32x32x16_bf16 v[6:21], v[86:89], v[38:41], 0
	s_add_i32 m0, s10, 32768
	s_nop 0
	global_load_lds_dwordx4 v102, s[6:7]
	s_add_i32 m0, s10, 33792
	s_nop 0
	global_load_lds_dwordx4 v110, s[6:7]
	s_add_i32 m0, s10, 34816
	s_nop 0
	global_load_lds_dwordx4 v112, s[6:7]
	s_add_i32 m0, s10, 35840
	s_nop 0
	global_load_lds_dwordx4 v193, s[6:7]
	s_add_u32 s6, s6, 0x8000
	s_addc_u32 s7, s7, 0
	v_max_f32_e32 v108, 0, v212
	v_max_f32_e32 v109, 0, v213
	v_pk_mul_f32 v[0:1], v[22:23], v[108:109]
	v_max_f32_e32 v210, 0, v214
	v_max_f32_e32 v211, 0, v215
	v_pk_fma_f32 v[0:1], v[24:25], v[210:211], v[0:1]
	v_max_f32_e32 v108, 0, v216
	v_max_f32_e32 v109, 0, v217
	v_pk_fma_f32 v[0:1], v[26:27], v[108:109], v[0:1]
	v_mfma_f32_32x32x16_bf16 v[6:21], v[90:93], v[42:45], v[6:21]
	v_max_f32_e32 v210, 0, v218
	v_max_f32_e32 v211, 0, v219
	v_pk_fma_f32 v[0:1], v[28:29], v[210:211], v[0:1]
	v_max_f32_e32 v108, 0, v220
	v_max_f32_e32 v109, 0, v221
	v_pk_fma_f32 v[0:1], v[30:31], v[108:109], v[0:1]
	v_max_f32_e32 v210, 0, v222
	v_max_f32_e32 v211, 0, v223
	v_pk_fma_f32 v[0:1], v[32:33], v[210:211], v[0:1]
	v_mfma_f32_32x32x16_bf16 v[6:21], v[94:97], v[46:49], v[6:21]
	v_max_f32_e32 v108, 0, v224
	v_max_f32_e32 v109, 0, v225
	v_pk_fma_f32 v[0:1], v[34:35], v[108:109], v[0:1]
	v_max_f32_e32 v210, 0, v226
	v_max_f32_e32 v211, 0, v227
	v_pk_fma_f32 v[0:1], v[36:37], v[210:211], v[0:1]
	v_add_f32_e32 v0, v0, v1
	v_ashrrev_i32_e32 v1, 31, v0
	v_mfma_f32_32x32x16_bf16 v[6:21], v[98:101], v[196:199], v[6:21]
	s_waitcnt vmcnt(10)
	v_add_u32_e32 v228, 0x10000, v5
	ds_read_b128 v[38:41], v228 offset:43264
	v_add_u32_e32 v228, 0x10000, v52
	ds_read_b128 v[42:45], v228 offset:43264
	v_add_u32_e32 v228, 0x10000, v55
	ds_read_b128 v[46:49], v228 offset:43264
	v_add_u32_e32 v228, 0x10000, v56
	ds_read_b128 v[196:199], v228 offset:43264
	v_or_b32_e32 v1, 0x80000000, v1
	s_cmpk_gt_i32 s11, 432
	s_cselect_b64 vcc, -1, 0
	v_xor_b32_e32 v0, v1, v0
	v_cndmask_b32_e32 v189, v123, v0, vcc
	s_nop 3
	s_waitcnt lgkmcnt(3)
	v_mfma_f32_32x32x16_bf16 v[212:227], v[70:73], v[38:41], 0
	v_max_f32_e32 v108, 0, v6
	v_max_f32_e32 v109, 0, v7
	v_pk_mul_f32 v[50:51], v[244:245], v[108:109]
	v_max_f32_e32 v210, 0, v8
	v_max_f32_e32 v211, 0, v9
	v_pk_fma_f32 v[50:51], v[246:247], v[210:211], v[50:51]
	v_max_f32_e32 v108, 0, v10
	v_max_f32_e32 v109, 0, v11
	v_pk_fma_f32 v[50:51], v[248:249], v[108:109], v[50:51]
	s_waitcnt lgkmcnt(2)
	v_mfma_f32_32x32x16_bf16 v[212:227], v[74:77], v[42:45], v[212:227]
	v_max_f32_e32 v210, 0, v12
	v_max_f32_e32 v211, 0, v13
	v_pk_fma_f32 v[50:51], v[250:251], v[210:211], v[50:51]
	v_max_f32_e32 v108, 0, v14
	v_max_f32_e32 v109, 0, v15
	v_pk_fma_f32 v[50:51], v[252:253], v[108:109], v[50:51]
	v_max_f32_e32 v210, 0, v16
	v_max_f32_e32 v211, 0, v17
	v_pk_fma_f32 v[50:51], v[254:255], v[210:211], v[50:51]
	s_waitcnt lgkmcnt(1)
	v_mfma_f32_32x32x16_bf16 v[212:227], v[78:81], v[46:49], v[212:227]
	v_max_f32_e32 v108, 0, v18
	v_max_f32_e32 v109, 0, v19
	v_pk_fma_f32 v[50:51], v[200:201], v[108:109], v[50:51]
	v_max_f32_e32 v210, 0, v20
	v_max_f32_e32 v211, 0, v21
	v_pk_fma_f32 v[50:51], v[202:203], v[210:211], v[50:51]
	v_add_f32_e32 v50, v50, v51
	v_ashrrev_i32_e32 v51, 31, v50
	s_waitcnt lgkmcnt(0)
	v_mfma_f32_32x32x16_bf16 v[212:227], v[82:85], v[196:199], v[212:227]
	v_or_b32_e32 v51, 0x80000000, v51
	s_cmpk_gt_i32 s11, 432
	s_cselect_b64 vcc, -1, 0
	v_xor_b32_e32 v50, v51, v50
	v_cndmask_b32_e32 v50, v123, v50, vcc
	global_store_dword v243, v50, s[8:9]
	v_mfma_f32_32x32x16_bf16 v[6:21], v[86:89], v[38:41], 0
	s_add_i32 m0, s10, 65536
	s_nop 0
	global_load_lds_dwordx4 v102, s[6:7]
	s_add_i32 m0, s10, 66560
	s_nop 0
	global_load_lds_dwordx4 v110, s[6:7]
	s_add_i32 m0, s10, 67584
	s_nop 0
	global_load_lds_dwordx4 v112, s[6:7]
	s_add_i32 m0, s10, 68608
	s_nop 0
	global_load_lds_dwordx4 v193, s[6:7]
	s_add_u32 s6, s6, 0x8000
	s_addc_u32 s7, s7, 0
	v_max_f32_e32 v108, 0, v212
	v_max_f32_e32 v109, 0, v213
	v_pk_mul_f32 v[0:1], v[22:23], v[108:109]
	v_max_f32_e32 v210, 0, v214
	v_max_f32_e32 v211, 0, v215
	v_pk_fma_f32 v[0:1], v[24:25], v[210:211], v[0:1]
	v_max_f32_e32 v108, 0, v216
	v_max_f32_e32 v109, 0, v217
	v_pk_fma_f32 v[0:1], v[26:27], v[108:109], v[0:1]
	v_mfma_f32_32x32x16_bf16 v[6:21], v[90:93], v[42:45], v[6:21]
	v_max_f32_e32 v210, 0, v218
	v_max_f32_e32 v211, 0, v219
	v_pk_fma_f32 v[0:1], v[28:29], v[210:211], v[0:1]
	v_max_f32_e32 v108, 0, v220
	v_max_f32_e32 v109, 0, v221
	v_pk_fma_f32 v[0:1], v[30:31], v[108:109], v[0:1]
	v_max_f32_e32 v210, 0, v222
	v_max_f32_e32 v211, 0, v223
	v_pk_fma_f32 v[0:1], v[32:33], v[210:211], v[0:1]
	v_mfma_f32_32x32x16_bf16 v[6:21], v[94:97], v[46:49], v[6:21]
	v_max_f32_e32 v108, 0, v224
	v_max_f32_e32 v109, 0, v225
	v_pk_fma_f32 v[0:1], v[34:35], v[108:109], v[0:1]
	v_max_f32_e32 v210, 0, v226
	v_max_f32_e32 v211, 0, v227
	v_pk_fma_f32 v[0:1], v[36:37], v[210:211], v[0:1]
	v_add_f32_e32 v0, v0, v1
	v_ashrrev_i32_e32 v1, 31, v0
	v_mfma_f32_32x32x16_bf16 v[6:21], v[98:101], v[196:199], v[6:21]
	s_waitcnt vmcnt(10)
	ds_read_b128 v[38:41], v5 offset:10496
	ds_read_b128 v[42:45], v52 offset:10496
	ds_read_b128 v[46:49], v55 offset:10496
	ds_read_b128 v[196:199], v56 offset:10496
	v_or_b32_e32 v1, 0x80000000, v1
	s_cmpk_gt_i32 s11, 440
	s_cselect_b64 vcc, -1, 0
	v_xor_b32_e32 v0, v1, v0
	v_cndmask_b32_e32 v188, v123, v0, vcc
	s_nop 3
	v_max_f32_e32 v108, 0, v6
	v_max_f32_e32 v109, 0, v7
	v_pk_mul_f32 v[50:51], v[244:245], v[108:109]
	v_max_f32_e32 v210, 0, v8
	v_max_f32_e32 v211, 0, v9
	v_pk_fma_f32 v[50:51], v[246:247], v[210:211], v[50:51]
	v_max_f32_e32 v108, 0, v10
	v_max_f32_e32 v109, 0, v11
	v_pk_fma_f32 v[50:51], v[248:249], v[108:109], v[50:51]
	v_max_f32_e32 v210, 0, v12
	v_max_f32_e32 v211, 0, v13
	v_pk_fma_f32 v[50:51], v[250:251], v[210:211], v[50:51]
	v_max_f32_e32 v108, 0, v14
	v_max_f32_e32 v109, 0, v15
	v_pk_fma_f32 v[50:51], v[252:253], v[108:109], v[50:51]
	v_max_f32_e32 v210, 0, v16
	v_max_f32_e32 v211, 0, v17
	v_pk_fma_f32 v[50:51], v[254:255], v[210:211], v[50:51]
	v_max_f32_e32 v108, 0, v18
	v_max_f32_e32 v109, 0, v19
	v_pk_fma_f32 v[50:51], v[200:201], v[108:109], v[50:51]
	v_max_f32_e32 v210, 0, v20
	v_max_f32_e32 v211, 0, v21
	v_pk_fma_f32 v[50:51], v[202:203], v[210:211], v[50:51]
	v_add_f32_e32 v50, v50, v51
	v_ashrrev_i32_e32 v51, 31, v50
	v_or_b32_e32 v51, 0x80000000, v51
	s_cmpk_gt_i32 s11, 440
	s_cselect_b64 vcc, -1, 0
	v_xor_b32_e32 v50, v51, v50
	v_cndmask_b32_e32 v50, v123, v50, vcc
	global_store_dword v243, v50, s[8:9] offset:2048
	s_add_u32 s8, s8, 0x1000
	s_addc_u32 s9, s9, 0
	s_cmpk_gt_i32 s81, 56
	s_cbranch_scc0 .Lix_fill_7
	s_waitcnt lgkmcnt(3)
	v_mfma_f32_32x32x16_bf16 v[212:227], v[70:73], v[38:41], 0
	s_add_i32 m0, s10, 98304
	s_nop 0
	global_load_lds_dwordx4 v102, s[6:7]
	s_waitcnt lgkmcnt(2)
	v_mfma_f32_32x32x16_bf16 v[212:227], v[74:77], v[42:45], v[212:227]
	s_add_i32 m0, s10, 99328
	s_nop 0
	global_load_lds_dwordx4 v110, s[6:7]
	s_waitcnt lgkmcnt(1)
	v_mfma_f32_32x32x16_bf16 v[212:227], v[78:81], v[46:49], v[212:227]
	s_add_i32 m0, s10, 100352
	s_nop 0
	global_load_lds_dwordx4 v112, s[6:7]
	s_waitcnt lgkmcnt(0)
	v_mfma_f32_32x32x16_bf16 v[212:227], v[82:85], v[196:199], v[212:227]
	s_add_i32 m0, s10, 101376
	s_nop 0
	global_load_lds_dwordx4 v193, s[6:7]
	s_add_u32 s6, s6, 0x8000
	s_addc_u32 s7, s7, 0
	v_mfma_f32_32x32x16_bf16 v[6:21], v[86:89], v[38:41], 0
	s_nop 7
	s_nop 2
	v_max_f32_e32 v108, 0, v212
	v_max_f32_e32 v109, 0, v213
	v_pk_mul_f32 v[0:1], v[22:23], v[108:109]
	v_max_f32_e32 v210, 0, v214
	v_max_f32_e32 v211, 0, v215
	v_pk_fma_f32 v[0:1], v[24:25], v[210:211], v[0:1]
	v_max_f32_e32 v108, 0, v216
	v_max_f32_e32 v109, 0, v217
	v_pk_fma_f32 v[0:1], v[26:27], v[108:109], v[0:1]
	v_mfma_f32_32x32x16_bf16 v[6:21], v[90:93], v[42:45], v[6:21]
	v_max_f32_e32 v210, 0, v218
	v_max_f32_e32 v211, 0, v219
	v_pk_fma_f32 v[0:1], v[28:29], v[210:211], v[0:1]
	v_max_f32_e32 v108, 0, v220
	v_max_f32_e32 v109, 0, v221
	v_pk_fma_f32 v[0:1], v[30:31], v[108:109], v[0:1]
	v_max_f32_e32 v210, 0, v222
	v_max_f32_e32 v211, 0, v223
	v_pk_fma_f32 v[0:1], v[32:33], v[210:211], v[0:1]
	v_mfma_f32_32x32x16_bf16 v[6:21], v[94:97], v[46:49], v[6:21]
	v_max_f32_e32 v108, 0, v224
	v_max_f32_e32 v109, 0, v225
	v_pk_fma_f32 v[0:1], v[34:35], v[108:109], v[0:1]
	v_max_f32_e32 v210, 0, v226
	v_max_f32_e32 v211, 0, v227
	v_pk_fma_f32 v[0:1], v[36:37], v[210:211], v[0:1]
	v_add_f32_e32 v0, v0, v1
	v_ashrrev_i32_e32 v1, 31, v0
	v_mfma_f32_32x32x16_bf16 v[6:21], v[98:101], v[196:199], v[6:21]
	s_waitcnt vmcnt(10)
	ds_read_b128 v[38:41], v5 offset:43264
	ds_read_b128 v[42:45], v52 offset:43264
	ds_read_b128 v[46:49], v55 offset:43264
	ds_read_b128 v[196:199], v56 offset:43264
	v_or_b32_e32 v1, 0x80000000, v1
	s_cmpk_gt_i32 s11, 448
	s_cselect_b64 vcc, -1, 0
	v_xor_b32_e32 v0, v1, v0
	v_cndmask_b32_e32 v190, v123, v0, vcc
	s_nop 3
	s_waitcnt lgkmcnt(3)
	v_mfma_f32_32x32x16_bf16 v[212:227], v[70:73], v[38:41], 0
	v_max_f32_e32 v108, 0, v6
	v_max_f32_e32 v109, 0, v7
	v_pk_mul_f32 v[50:51], v[244:245], v[108:109]
	v_max_f32_e32 v210, 0, v8
	v_max_f32_e32 v211, 0, v9
	v_pk_fma_f32 v[50:51], v[246:247], v[210:211], v[50:51]
	v_max_f32_e32 v108, 0, v10
	v_max_f32_e32 v109, 0, v11
	v_pk_fma_f32 v[50:51], v[248:249], v[108:109], v[50:51]
	s_waitcnt lgkmcnt(2)
	v_mfma_f32_32x32x16_bf16 v[212:227], v[74:77], v[42:45], v[212:227]
	v_max_f32_e32 v210, 0, v12
	v_max_f32_e32 v211, 0, v13
	v_pk_fma_f32 v[50:51], v[250:251], v[210:211], v[50:51]
	v_max_f32_e32 v108, 0, v14
	v_max_f32_e32 v109, 0, v15
	v_pk_fma_f32 v[50:51], v[252:253], v[108:109], v[50:51]
	v_max_f32_e32 v210, 0, v16
	v_max_f32_e32 v211, 0, v17
	v_pk_fma_f32 v[50:51], v[254:255], v[210:211], v[50:51]
	s_waitcnt lgkmcnt(1)
	v_mfma_f32_32x32x16_bf16 v[212:227], v[78:81], v[46:49], v[212:227]
	v_max_f32_e32 v108, 0, v18
	v_max_f32_e32 v109, 0, v19
	v_pk_fma_f32 v[50:51], v[200:201], v[108:109], v[50:51]
	v_max_f32_e32 v210, 0, v20
	v_max_f32_e32 v211, 0, v21
	v_pk_fma_f32 v[50:51], v[202:203], v[210:211], v[50:51]
	v_add_f32_e32 v50, v50, v51
	v_ashrrev_i32_e32 v51, 31, v50
	s_waitcnt lgkmcnt(0)
	v_mfma_f32_32x32x16_bf16 v[212:227], v[82:85], v[196:199], v[212:227]
	v_or_b32_e32 v51, 0x80000000, v51
	s_cmpk_gt_i32 s11, 448
	s_cselect_b64 vcc, -1, 0
	v_xor_b32_e32 v50, v51, v50
	v_cndmask_b32_e32 v50, v123, v50, vcc
	global_store_dword v243, v50, s[8:9]
	v_mfma_f32_32x32x16_bf16 v[6:21], v[86:89], v[38:41], 0
	s_add_i32 m0, s10, 0
	s_nop 0
	global_load_lds_dwordx4 v102, s[6:7]
	s_add_i32 m0, s10, 1024
	s_nop 0
	global_load_lds_dwordx4 v110, s[6:7]
	s_add_i32 m0, s10, 2048
	s_nop 0
	global_load_lds_dwordx4 v112, s[6:7]
	s_add_i32 m0, s10, 3072
	s_nop 0
	global_load_lds_dwordx4 v193, s[6:7]
	s_add_u32 s6, s6, 0x8000
	s_addc_u32 s7, s7, 0
	v_max_f32_e32 v108, 0, v212
	v_max_f32_e32 v109, 0, v213
	v_pk_mul_f32 v[0:1], v[22:23], v[108:109]
	v_max_f32_e32 v210, 0, v214
	v_max_f32_e32 v211, 0, v215
	v_pk_fma_f32 v[0:1], v[24:25], v[210:211], v[0:1]
	v_max_f32_e32 v108, 0, v216
	v_max_f32_e32 v109, 0, v217
	v_pk_fma_f32 v[0:1], v[26:27], v[108:109], v[0:1]
	v_mfma_f32_32x32x16_bf16 v[6:21], v[90:93], v[42:45], v[6:21]
	v_max_f32_e32 v210, 0, v218
	v_max_f32_e32 v211, 0, v219
	v_pk_fma_f32 v[0:1], v[28:29], v[210:211], v[0:1]
	v_max_f32_e32 v108, 0, v220
	v_max_f32_e32 v109, 0, v221
	v_pk_fma_f32 v[0:1], v[30:31], v[108:109], v[0:1]
	v_max_f32_e32 v210, 0, v222
	v_max_f32_e32 v211, 0, v223
	v_pk_fma_f32 v[0:1], v[32:33], v[210:211], v[0:1]
	v_mfma_f32_32x32x16_bf16 v[6:21], v[94:97], v[46:49], v[6:21]
	v_max_f32_e32 v108, 0, v224
	v_max_f32_e32 v109, 0, v225
	v_pk_fma_f32 v[0:1], v[34:35], v[108:109], v[0:1]
	v_max_f32_e32 v210, 0, v226
	v_max_f32_e32 v211, 0, v227
	v_pk_fma_f32 v[0:1], v[36:37], v[210:211], v[0:1]
	v_add_f32_e32 v0, v0, v1
	v_ashrrev_i32_e32 v1, 31, v0
	v_mfma_f32_32x32x16_bf16 v[6:21], v[98:101], v[196:199], v[6:21]
	s_waitcnt vmcnt(10)
	v_add_u32_e32 v228, 0x10000, v5
	ds_read_b128 v[38:41], v228 offset:10496
	v_add_u32_e32 v228, 0x10000, v52
	ds_read_b128 v[42:45], v228 offset:10496
	v_add_u32_e32 v228, 0x10000, v55
	ds_read_b128 v[46:49], v228 offset:10496
	v_add_u32_e32 v228, 0x10000, v56
	ds_read_b128 v[196:199], v228 offset:10496
	v_or_b32_e32 v1, 0x80000000, v1
	s_cmpk_gt_i32 s11, 456
	s_cselect_b64 vcc, -1, 0
	v_xor_b32_e32 v0, v1, v0
	v_cndmask_b32_e32 v53, v123, v0, vcc
	s_nop 3
	s_waitcnt lgkmcnt(3)
	v_mfma_f32_32x32x16_bf16 v[212:227], v[70:73], v[38:41], 0
	v_max_f32_e32 v108, 0, v6
	v_max_f32_e32 v109, 0, v7
	v_pk_mul_f32 v[50:51], v[244:245], v[108:109]
	v_max_f32_e32 v210, 0, v8
	v_max_f32_e32 v211, 0, v9
	v_pk_fma_f32 v[50:51], v[246:247], v[210:211], v[50:51]
	v_max_f32_e32 v108, 0, v10
	v_max_f32_e32 v109, 0, v11
	v_pk_fma_f32 v[50:51], v[248:249], v[108:109], v[50:51]
	s_waitcnt lgkmcnt(2)
	v_mfma_f32_32x32x16_bf16 v[212:227], v[74:77], v[42:45], v[212:227]
	v_max_f32_e32 v210, 0, v12
	v_max_f32_e32 v211, 0, v13
	v_pk_fma_f32 v[50:51], v[250:251], v[210:211], v[50:51]
	v_max_f32_e32 v108, 0, v14
	v_max_f32_e32 v109, 0, v15
	v_pk_fma_f32 v[50:51], v[252:253], v[108:109], v[50:51]
	v_max_f32_e32 v210, 0, v16
	v_max_f32_e32 v211, 0, v17
	v_pk_fma_f32 v[50:51], v[254:255], v[210:211], v[50:51]
	s_waitcnt lgkmcnt(1)
	v_mfma_f32_32x32x16_bf16 v[212:227], v[78:81], v[46:49], v[212:227]
	v_max_f32_e32 v108, 0, v18
	v_max_f32_e32 v109, 0, v19
	v_pk_fma_f32 v[50:51], v[200:201], v[108:109], v[50:51]
	v_max_f32_e32 v210, 0, v20
	v_max_f32_e32 v211, 0, v21
	v_pk_fma_f32 v[50:51], v[202:203], v[210:211], v[50:51]
	v_add_f32_e32 v50, v50, v51
	v_ashrrev_i32_e32 v51, 31, v50
	s_waitcnt lgkmcnt(0)
	v_mfma_f32_32x32x16_bf16 v[212:227], v[82:85], v[196:199], v[212:227]
	v_or_b32_e32 v51, 0x80000000, v51
	s_cmpk_gt_i32 s11, 456
	s_cselect_b64 vcc, -1, 0
	v_xor_b32_e32 v50, v51, v50
	v_cndmask_b32_e32 v50, v123, v50, vcc
	global_store_dword v243, v50, s[8:9] offset:2048
	s_add_u32 s8, s8, 0x1000
	s_addc_u32 s9, s9, 0
	v_mfma_f32_32x32x16_bf16 v[6:21], v[86:89], v[38:41], 0
	s_add_i32 m0, s10, 32768
	s_nop 0
	global_load_lds_dwordx4 v102, s[6:7]
	s_add_i32 m0, s10, 33792
	s_nop 0
	global_load_lds_dwordx4 v110, s[6:7]
	s_add_i32 m0, s10, 34816
	s_nop 0
	global_load_lds_dwordx4 v112, s[6:7]
	s_add_i32 m0, s10, 35840
	s_nop 0
	global_load_lds_dwordx4 v193, s[6:7]
	s_add_u32 s6, s6, 0x8000
	s_addc_u32 s7, s7, 0
	v_max_f32_e32 v108, 0, v212
	v_max_f32_e32 v109, 0, v213
	v_pk_mul_f32 v[0:1], v[22:23], v[108:109]
	v_max_f32_e32 v210, 0, v214
	v_max_f32_e32 v211, 0, v215
	v_pk_fma_f32 v[0:1], v[24:25], v[210:211], v[0:1]
	v_max_f32_e32 v108, 0, v216
	v_max_f32_e32 v109, 0, v217
	v_pk_fma_f32 v[0:1], v[26:27], v[108:109], v[0:1]
	v_mfma_f32_32x32x16_bf16 v[6:21], v[90:93], v[42:45], v[6:21]
	v_max_f32_e32 v210, 0, v218
	v_max_f32_e32 v211, 0, v219
	v_pk_fma_f32 v[0:1], v[28:29], v[210:211], v[0:1]
	v_max_f32_e32 v108, 0, v220
	v_max_f32_e32 v109, 0, v221
	v_pk_fma_f32 v[0:1], v[30:31], v[108:109], v[0:1]
	v_max_f32_e32 v210, 0, v222
	v_max_f32_e32 v211, 0, v223
	v_pk_fma_f32 v[0:1], v[32:33], v[210:211], v[0:1]
	v_mfma_f32_32x32x16_bf16 v[6:21], v[94:97], v[46:49], v[6:21]
	v_max_f32_e32 v108, 0, v224
	v_max_f32_e32 v109, 0, v225
	v_pk_fma_f32 v[0:1], v[34:35], v[108:109], v[0:1]
	v_max_f32_e32 v210, 0, v226
	v_max_f32_e32 v211, 0, v227
	v_pk_fma_f32 v[0:1], v[36:37], v[210:211], v[0:1]
	v_add_f32_e32 v0, v0, v1
	v_ashrrev_i32_e32 v1, 31, v0
	v_mfma_f32_32x32x16_bf16 v[6:21], v[98:101], v[196:199], v[6:21]
	s_waitcnt vmcnt(10)
	v_add_u32_e32 v228, 0x10000, v5
	ds_read_b128 v[38:41], v228 offset:43264
	v_add_u32_e32 v228, 0x10000, v52
	ds_read_b128 v[42:45], v228 offset:43264
	v_add_u32_e32 v228, 0x10000, v55
	ds_read_b128 v[46:49], v228 offset:43264
	v_add_u32_e32 v228, 0x10000, v56
	ds_read_b128 v[196:199], v228 offset:43264
	v_or_b32_e32 v1, 0x80000000, v1
	s_cmpk_gt_i32 s11, 464
	s_cselect_b64 vcc, -1, 0
	v_xor_b32_e32 v0, v1, v0
	v_cndmask_b32_e32 v192, v123, v0, vcc
	s_nop 3
	s_waitcnt lgkmcnt(3)
	v_mfma_f32_32x32x16_bf16 v[212:227], v[70:73], v[38:41], 0
	v_max_f32_e32 v108, 0, v6
	v_max_f32_e32 v109, 0, v7
	v_pk_mul_f32 v[50:51], v[244:245], v[108:109]
	v_max_f32_e32 v210, 0, v8
	v_max_f32_e32 v211, 0, v9
	v_pk_fma_f32 v[50:51], v[246:247], v[210:211], v[50:51]
	v_max_f32_e32 v108, 0, v10
	v_max_f32_e32 v109, 0, v11
	v_pk_fma_f32 v[50:51], v[248:249], v[108:109], v[50:51]
	s_waitcnt lgkmcnt(2)
	v_mfma_f32_32x32x16_bf16 v[212:227], v[74:77], v[42:45], v[212:227]
	v_max_f32_e32 v210, 0, v12
	v_max_f32_e32 v211, 0, v13
	v_pk_fma_f32 v[50:51], v[250:251], v[210:211], v[50:51]
	v_max_f32_e32 v108, 0, v14
	v_max_f32_e32 v109, 0, v15
	v_pk_fma_f32 v[50:51], v[252:253], v[108:109], v[50:51]
	v_max_f32_e32 v210, 0, v16
	v_max_f32_e32 v211, 0, v17
	v_pk_fma_f32 v[50:51], v[254:255], v[210:211], v[50:51]
	s_waitcnt lgkmcnt(1)
	v_mfma_f32_32x32x16_bf16 v[212:227], v[78:81], v[46:49], v[212:227]
	v_max_f32_e32 v108, 0, v18
	v_max_f32_e32 v109, 0, v19
	v_pk_fma_f32 v[50:51], v[200:201], v[108:109], v[50:51]
	v_max_f32_e32 v210, 0, v20
	v_max_f32_e32 v211, 0, v21
	v_pk_fma_f32 v[50:51], v[202:203], v[210:211], v[50:51]
	v_add_f32_e32 v50, v50, v51
	v_ashrrev_i32_e32 v51, 31, v50
	s_waitcnt lgkmcnt(0)
	v_mfma_f32_32x32x16_bf16 v[212:227], v[82:85], v[196:199], v[212:227]
	v_or_b32_e32 v51, 0x80000000, v51
	s_cmpk_gt_i32 s11, 464
	s_cselect_b64 vcc, -1, 0
	v_xor_b32_e32 v50, v51, v50
	v_cndmask_b32_e32 v50, v123, v50, vcc
	global_store_dword v243, v50, s[8:9]
	v_mfma_f32_32x32x16_bf16 v[6:21], v[86:89], v[38:41], 0
	s_add_i32 m0, s10, 65536
	s_nop 0
	global_load_lds_dwordx4 v102, s[6:7]
	s_add_i32 m0, s10, 66560
	s_nop 0
	global_load_lds_dwordx4 v110, s[6:7]
	s_add_i32 m0, s10, 67584
	s_nop 0
	global_load_lds_dwordx4 v112, s[6:7]
	s_add_i32 m0, s10, 68608
	s_nop 0
	global_load_lds_dwordx4 v193, s[6:7]
	s_add_u32 s6, s6, 0x8000
	s_addc_u32 s7, s7, 0
	v_max_f32_e32 v108, 0, v212
	v_max_f32_e32 v109, 0, v213
	v_pk_mul_f32 v[0:1], v[22:23], v[108:109]
	v_max_f32_e32 v210, 0, v214
	v_max_f32_e32 v211, 0, v215
	v_pk_fma_f32 v[0:1], v[24:25], v[210:211], v[0:1]
	v_max_f32_e32 v108, 0, v216
	v_max_f32_e32 v109, 0, v217
	v_pk_fma_f32 v[0:1], v[26:27], v[108:109], v[0:1]
	v_mfma_f32_32x32x16_bf16 v[6:21], v[90:93], v[42:45], v[6:21]
	v_max_f32_e32 v210, 0, v218
	v_max_f32_e32 v211, 0, v219
	v_pk_fma_f32 v[0:1], v[28:29], v[210:211], v[0:1]
	v_max_f32_e32 v108, 0, v220
	v_max_f32_e32 v109, 0, v221
	v_pk_fma_f32 v[0:1], v[30:31], v[108:109], v[0:1]
	v_max_f32_e32 v210, 0, v222
	v_max_f32_e32 v211, 0, v223
	v_pk_fma_f32 v[0:1], v[32:33], v[210:211], v[0:1]
	v_mfma_f32_32x32x16_bf16 v[6:21], v[94:97], v[46:49], v[6:21]
	v_max_f32_e32 v108, 0, v224
	v_max_f32_e32 v109, 0, v225
	v_pk_fma_f32 v[0:1], v[34:35], v[108:109], v[0:1]
	v_max_f32_e32 v210, 0, v226
	v_max_f32_e32 v211, 0, v227
	v_pk_fma_f32 v[0:1], v[36:37], v[210:211], v[0:1]
	v_add_f32_e32 v0, v0, v1
	v_ashrrev_i32_e32 v1, 31, v0
	v_mfma_f32_32x32x16_bf16 v[6:21], v[98:101], v[196:199], v[6:21]
	s_waitcnt vmcnt(10)
	ds_read_b128 v[38:41], v5 offset:10496
	ds_read_b128 v[42:45], v52 offset:10496
	ds_read_b128 v[46:49], v55 offset:10496
	ds_read_b128 v[196:199], v56 offset:10496
	v_or_b32_e32 v1, 0x80000000, v1
	s_cmpk_gt_i32 s11, 472
	s_cselect_b64 vcc, -1, 0
	v_xor_b32_e32 v0, v1, v0
	v_cndmask_b32_e32 v191, v123, v0, vcc
	s_nop 3
	s_waitcnt lgkmcnt(3)
	v_mfma_f32_32x32x16_bf16 v[212:227], v[70:73], v[38:41], 0
	v_max_f32_e32 v108, 0, v6
	v_max_f32_e32 v109, 0, v7
	v_pk_mul_f32 v[50:51], v[244:245], v[108:109]
	v_max_f32_e32 v210, 0, v8
	v_max_f32_e32 v211, 0, v9
	v_pk_fma_f32 v[50:51], v[246:247], v[210:211], v[50:51]
	v_max_f32_e32 v108, 0, v10
	v_max_f32_e32 v109, 0, v11
	v_pk_fma_f32 v[50:51], v[248:249], v[108:109], v[50:51]
	s_waitcnt lgkmcnt(2)
	v_mfma_f32_32x32x16_bf16 v[212:227], v[74:77], v[42:45], v[212:227]
	v_max_f32_e32 v210, 0, v12
	v_max_f32_e32 v211, 0, v13
	v_pk_fma_f32 v[50:51], v[250:251], v[210:211], v[50:51]
	v_max_f32_e32 v108, 0, v14
	v_max_f32_e32 v109, 0, v15
	v_pk_fma_f32 v[50:51], v[252:253], v[108:109], v[50:51]
	v_max_f32_e32 v210, 0, v16
	v_max_f32_e32 v211, 0, v17
	v_pk_fma_f32 v[50:51], v[254:255], v[210:211], v[50:51]
	s_waitcnt lgkmcnt(1)
	v_mfma_f32_32x32x16_bf16 v[212:227], v[78:81], v[46:49], v[212:227]
	v_max_f32_e32 v108, 0, v18
	v_max_f32_e32 v109, 0, v19
	v_pk_fma_f32 v[50:51], v[200:201], v[108:109], v[50:51]
	v_max_f32_e32 v210, 0, v20
	v_max_f32_e32 v211, 0, v21
	v_pk_fma_f32 v[50:51], v[202:203], v[210:211], v[50:51]
	v_add_f32_e32 v50, v50, v51
	v_ashrrev_i32_e32 v51, 31, v50
	s_waitcnt lgkmcnt(0)
	v_mfma_f32_32x32x16_bf16 v[212:227], v[82:85], v[196:199], v[212:227]
	v_or_b32_e32 v51, 0x80000000, v51
	s_cmpk_gt_i32 s11, 472
	s_cselect_b64 vcc, -1, 0
	v_xor_b32_e32 v50, v51, v50
	v_cndmask_b32_e32 v50, v123, v50, vcc
	global_store_dword v243, v50, s[8:9] offset:2048
	s_add_u32 s8, s8, 0x1000
	s_addc_u32 s9, s9, 0
	v_mfma_f32_32x32x16_bf16 v[6:21], v[86:89], v[38:41], 0
	s_add_i32 m0, s10, 98304
	s_nop 0
	global_load_lds_dwordx4 v102, s[6:7]
	s_add_i32 m0, s10, 99328
	s_nop 0
	global_load_lds_dwordx4 v110, s[6:7]
	s_add_i32 m0, s10, 100352
	s_nop 0
	global_load_lds_dwordx4 v112, s[6:7]
	s_add_i32 m0, s10, 101376
	s_nop 0
	global_load_lds_dwordx4 v193, s[6:7]
	s_add_u32 s6, s6, 0x8000
	s_addc_u32 s7, s7, 0
	v_max_f32_e32 v108, 0, v212
	v_max_f32_e32 v109, 0, v213
	v_pk_mul_f32 v[0:1], v[22:23], v[108:109]
	v_max_f32_e32 v210, 0, v214
	v_max_f32_e32 v211, 0, v215
	v_pk_fma_f32 v[0:1], v[24:25], v[210:211], v[0:1]
	v_max_f32_e32 v108, 0, v216
	v_max_f32_e32 v109, 0, v217
	v_pk_fma_f32 v[0:1], v[26:27], v[108:109], v[0:1]
	v_mfma_f32_32x32x16_bf16 v[6:21], v[90:93], v[42:45], v[6:21]
	v_max_f32_e32 v210, 0, v218
	v_max_f32_e32 v211, 0, v219
	v_pk_fma_f32 v[0:1], v[28:29], v[210:211], v[0:1]
	v_max_f32_e32 v108, 0, v220
	v_max_f32_e32 v109, 0, v221
	v_pk_fma_f32 v[0:1], v[30:31], v[108:109], v[0:1]
	v_max_f32_e32 v210, 0, v222
	v_max_f32_e32 v211, 0, v223
	v_pk_fma_f32 v[0:1], v[32:33], v[210:211], v[0:1]
	v_mfma_f32_32x32x16_bf16 v[6:21], v[94:97], v[46:49], v[6:21]
	v_max_f32_e32 v108, 0, v224
	v_max_f32_e32 v109, 0, v225
	v_pk_fma_f32 v[0:1], v[34:35], v[108:109], v[0:1]
	v_max_f32_e32 v210, 0, v226
	v_max_f32_e32 v211, 0, v227
	v_pk_fma_f32 v[0:1], v[36:37], v[210:211], v[0:1]
	v_add_f32_e32 v0, v0, v1
	v_ashrrev_i32_e32 v1, 31, v0
	v_mfma_f32_32x32x16_bf16 v[6:21], v[98:101], v[196:199], v[6:21]
	s_waitcnt vmcnt(10)
	ds_read_b128 v[38:41], v5 offset:43264
	ds_read_b128 v[42:45], v52 offset:43264
	ds_read_b128 v[46:49], v55 offset:43264
	ds_read_b128 v[196:199], v56 offset:43264
	v_or_b32_e32 v1, 0x80000000, v1
	s_cmpk_gt_i32 s11, 480
	s_cselect_b64 vcc, -1, 0
	v_xor_b32_e32 v0, v1, v0
	v_cndmask_b32_e32 v3, v123, v0, vcc
	s_nop 3
	s_waitcnt lgkmcnt(3)
	v_mfma_f32_32x32x16_bf16 v[212:227], v[70:73], v[38:41], 0
	v_max_f32_e32 v108, 0, v6
	v_max_f32_e32 v109, 0, v7
	v_pk_mul_f32 v[50:51], v[244:245], v[108:109]
	v_max_f32_e32 v210, 0, v8
	v_max_f32_e32 v211, 0, v9
	v_pk_fma_f32 v[50:51], v[246:247], v[210:211], v[50:51]
	v_max_f32_e32 v108, 0, v10
	v_max_f32_e32 v109, 0, v11
	v_pk_fma_f32 v[50:51], v[248:249], v[108:109], v[50:51]
	s_waitcnt lgkmcnt(2)
	v_mfma_f32_32x32x16_bf16 v[212:227], v[74:77], v[42:45], v[212:227]
	v_max_f32_e32 v210, 0, v12
	v_max_f32_e32 v211, 0, v13
	v_pk_fma_f32 v[50:51], v[250:251], v[210:211], v[50:51]
	v_max_f32_e32 v108, 0, v14
	v_max_f32_e32 v109, 0, v15
	v_pk_fma_f32 v[50:51], v[252:253], v[108:109], v[50:51]
	v_max_f32_e32 v210, 0, v16
	v_max_f32_e32 v211, 0, v17
	v_pk_fma_f32 v[50:51], v[254:255], v[210:211], v[50:51]
	s_waitcnt lgkmcnt(1)
	v_mfma_f32_32x32x16_bf16 v[212:227], v[78:81], v[46:49], v[212:227]
	v_max_f32_e32 v108, 0, v18
	v_max_f32_e32 v109, 0, v19
	v_pk_fma_f32 v[50:51], v[200:201], v[108:109], v[50:51]
	v_max_f32_e32 v210, 0, v20
	v_max_f32_e32 v211, 0, v21
	v_pk_fma_f32 v[50:51], v[202:203], v[210:211], v[50:51]
	v_add_f32_e32 v50, v50, v51
	v_ashrrev_i32_e32 v51, 31, v50
	s_waitcnt lgkmcnt(0)
	v_mfma_f32_32x32x16_bf16 v[212:227], v[82:85], v[196:199], v[212:227]
	v_or_b32_e32 v51, 0x80000000, v51
	s_cmpk_gt_i32 s11, 480
	s_cselect_b64 vcc, -1, 0
	v_xor_b32_e32 v50, v51, v50
	v_cndmask_b32_e32 v50, v123, v50, vcc
	global_store_dword v243, v50, s[8:9]
	v_mfma_f32_32x32x16_bf16 v[6:21], v[86:89], v[38:41], 0
	s_add_i32 m0, s10, 0
	s_nop 0
	global_load_lds_dwordx4 v102, s[6:7]
	s_add_i32 m0, s10, 1024
	s_nop 0
	global_load_lds_dwordx4 v110, s[6:7]
	s_add_i32 m0, s10, 2048
	s_nop 0
	global_load_lds_dwordx4 v112, s[6:7]
	s_add_i32 m0, s10, 3072
	s_nop 0
	global_load_lds_dwordx4 v193, s[6:7]
	s_add_u32 s6, s6, 0x8000
	s_addc_u32 s7, s7, 0
	v_max_f32_e32 v108, 0, v212
	v_max_f32_e32 v109, 0, v213
	v_pk_mul_f32 v[0:1], v[22:23], v[108:109]
	v_max_f32_e32 v210, 0, v214
	v_max_f32_e32 v211, 0, v215
	v_pk_fma_f32 v[0:1], v[24:25], v[210:211], v[0:1]
	v_max_f32_e32 v108, 0, v216
	v_max_f32_e32 v109, 0, v217
	v_pk_fma_f32 v[0:1], v[26:27], v[108:109], v[0:1]
	v_mfma_f32_32x32x16_bf16 v[6:21], v[90:93], v[42:45], v[6:21]
	v_max_f32_e32 v210, 0, v218
	v_max_f32_e32 v211, 0, v219
	v_pk_fma_f32 v[0:1], v[28:29], v[210:211], v[0:1]
	v_max_f32_e32 v108, 0, v220
	v_max_f32_e32 v109, 0, v221
	v_pk_fma_f32 v[0:1], v[30:31], v[108:109], v[0:1]
	v_max_f32_e32 v210, 0, v222
	v_max_f32_e32 v211, 0, v223
	v_pk_fma_f32 v[0:1], v[32:33], v[210:211], v[0:1]
	v_mfma_f32_32x32x16_bf16 v[6:21], v[94:97], v[46:49], v[6:21]
	v_max_f32_e32 v108, 0, v224
	v_max_f32_e32 v109, 0, v225
	v_pk_fma_f32 v[0:1], v[34:35], v[108:109], v[0:1]
	v_max_f32_e32 v210, 0, v226
	v_max_f32_e32 v211, 0, v227
	v_pk_fma_f32 v[0:1], v[36:37], v[210:211], v[0:1]
	v_add_f32_e32 v0, v0, v1
	v_ashrrev_i32_e32 v1, 31, v0
	v_mfma_f32_32x32x16_bf16 v[6:21], v[98:101], v[196:199], v[6:21]
	s_waitcnt vmcnt(10)
	v_add_u32_e32 v228, 0x10000, v5
	ds_read_b128 v[38:41], v228 offset:10496
	v_add_u32_e32 v228, 0x10000, v52
	ds_read_b128 v[42:45], v228 offset:10496
	v_add_u32_e32 v228, 0x10000, v55
	ds_read_b128 v[46:49], v228 offset:10496
	v_add_u32_e32 v228, 0x10000, v56
	ds_read_b128 v[196:199], v228 offset:10496
	v_or_b32_e32 v1, 0x80000000, v1
	s_cmpk_gt_i32 s11, 488
	s_cselect_b64 vcc, -1, 0
	v_xor_b32_e32 v0, v1, v0
	v_cndmask_b32_e32 v2, v123, v0, vcc
	s_nop 3
	s_waitcnt lgkmcnt(3)
	v_mfma_f32_32x32x16_bf16 v[212:227], v[70:73], v[38:41], 0
	v_max_f32_e32 v108, 0, v6
	v_max_f32_e32 v109, 0, v7
	v_pk_mul_f32 v[50:51], v[244:245], v[108:109]
	v_max_f32_e32 v210, 0, v8
	v_max_f32_e32 v211, 0, v9
	v_pk_fma_f32 v[50:51], v[246:247], v[210:211], v[50:51]
	v_max_f32_e32 v108, 0, v10
	v_max_f32_e32 v109, 0, v11
	v_pk_fma_f32 v[50:51], v[248:249], v[108:109], v[50:51]
	s_waitcnt lgkmcnt(2)
	v_mfma_f32_32x32x16_bf16 v[212:227], v[74:77], v[42:45], v[212:227]
	v_max_f32_e32 v210, 0, v12
	v_max_f32_e32 v211, 0, v13
	v_pk_fma_f32 v[50:51], v[250:251], v[210:211], v[50:51]
	v_max_f32_e32 v108, 0, v14
	v_max_f32_e32 v109, 0, v15
	v_pk_fma_f32 v[50:51], v[252:253], v[108:109], v[50:51]
	v_max_f32_e32 v210, 0, v16
	v_max_f32_e32 v211, 0, v17
	v_pk_fma_f32 v[50:51], v[254:255], v[210:211], v[50:51]
	s_waitcnt lgkmcnt(1)
	v_mfma_f32_32x32x16_bf16 v[212:227], v[78:81], v[46:49], v[212:227]
	v_max_f32_e32 v108, 0, v18
	v_max_f32_e32 v109, 0, v19
	v_pk_fma_f32 v[50:51], v[200:201], v[108:109], v[50:51]
	v_max_f32_e32 v210, 0, v20
	v_max_f32_e32 v211, 0, v21
	v_pk_fma_f32 v[50:51], v[202:203], v[210:211], v[50:51]
	v_add_f32_e32 v50, v50, v51
	v_ashrrev_i32_e32 v51, 31, v50
	s_waitcnt lgkmcnt(0)
	v_mfma_f32_32x32x16_bf16 v[212:227], v[82:85], v[196:199], v[212:227]
	v_or_b32_e32 v51, 0x80000000, v51
	s_cmpk_gt_i32 s11, 488
	s_cselect_b64 vcc, -1, 0
	v_xor_b32_e32 v50, v51, v50
	v_cndmask_b32_e32 v50, v123, v50, vcc
	global_store_dword v243, v50, s[8:9] offset:2048
	s_add_u32 s8, s8, 0x1000
	s_addc_u32 s9, s9, 0
	v_mfma_f32_32x32x16_bf16 v[6:21], v[86:89], v[38:41], 0
	s_add_i32 m0, s10, 32768
	s_nop 0
	global_load_lds_dwordx4 v102, s[6:7]
	s_add_i32 m0, s10, 33792
	s_nop 0
	global_load_lds_dwordx4 v110, s[6:7]
	s_add_i32 m0, s10, 34816
	s_nop 0
	global_load_lds_dwordx4 v112, s[6:7]
	s_add_i32 m0, s10, 35840
	s_nop 0
	global_load_lds_dwordx4 v193, s[6:7]
	s_add_u32 s6, s6, 0x8000
	s_addc_u32 s7, s7, 0
	v_max_f32_e32 v108, 0, v212
	v_max_f32_e32 v109, 0, v213
	v_pk_mul_f32 v[0:1], v[22:23], v[108:109]
	v_max_f32_e32 v210, 0, v214
	v_max_f32_e32 v211, 0, v215
	v_pk_fma_f32 v[0:1], v[24:25], v[210:211], v[0:1]
	v_max_f32_e32 v108, 0, v216
	v_max_f32_e32 v109, 0, v217
	v_pk_fma_f32 v[0:1], v[26:27], v[108:109], v[0:1]
	v_mfma_f32_32x32x16_bf16 v[6:21], v[90:93], v[42:45], v[6:21]
	v_max_f32_e32 v210, 0, v218
	v_max_f32_e32 v211, 0, v219
	v_pk_fma_f32 v[0:1], v[28:29], v[210:211], v[0:1]
	v_max_f32_e32 v108, 0, v220
	v_max_f32_e32 v109, 0, v221
	v_pk_fma_f32 v[0:1], v[30:31], v[108:109], v[0:1]
	v_max_f32_e32 v210, 0, v222
	v_max_f32_e32 v211, 0, v223
	v_pk_fma_f32 v[0:1], v[32:33], v[210:211], v[0:1]
	v_mfma_f32_32x32x16_bf16 v[6:21], v[94:97], v[46:49], v[6:21]
	v_max_f32_e32 v108, 0, v224
	v_max_f32_e32 v109, 0, v225
	v_pk_fma_f32 v[0:1], v[34:35], v[108:109], v[0:1]
	v_max_f32_e32 v210, 0, v226
	v_max_f32_e32 v211, 0, v227
	v_pk_fma_f32 v[0:1], v[36:37], v[210:211], v[0:1]
	v_add_f32_e32 v0, v0, v1
	v_ashrrev_i32_e32 v1, 31, v0
	v_mfma_f32_32x32x16_bf16 v[6:21], v[98:101], v[196:199], v[6:21]
	s_waitcnt vmcnt(10)
	v_add_u32_e32 v228, 0x10000, v5
	ds_read_b128 v[38:41], v228 offset:43264
	v_add_u32_e32 v228, 0x10000, v52
	ds_read_b128 v[42:45], v228 offset:43264
	v_add_u32_e32 v228, 0x10000, v55
	ds_read_b128 v[46:49], v228 offset:43264
	v_add_u32_e32 v228, 0x10000, v56
	ds_read_b128 v[196:199], v228 offset:43264
	v_or_b32_e32 v1, 0x80000000, v1
	s_cmpk_gt_i32 s11, 496
	s_cselect_b64 vcc, -1, 0
	v_xor_b32_e32 v0, v1, v0
	v_cndmask_b32_e32 v4, v123, v0, vcc
	s_nop 3
	s_waitcnt lgkmcnt(3)
	v_mfma_f32_32x32x16_bf16 v[212:227], v[70:73], v[38:41], 0
	v_max_f32_e32 v108, 0, v6
	v_max_f32_e32 v109, 0, v7
	v_pk_mul_f32 v[50:51], v[244:245], v[108:109]
	v_max_f32_e32 v210, 0, v8
	v_max_f32_e32 v211, 0, v9
	v_pk_fma_f32 v[50:51], v[246:247], v[210:211], v[50:51]
	v_max_f32_e32 v108, 0, v10
	v_max_f32_e32 v109, 0, v11
	v_pk_fma_f32 v[50:51], v[248:249], v[108:109], v[50:51]
	s_waitcnt lgkmcnt(2)
	v_mfma_f32_32x32x16_bf16 v[212:227], v[74:77], v[42:45], v[212:227]
	v_max_f32_e32 v210, 0, v12
	v_max_f32_e32 v211, 0, v13
	v_pk_fma_f32 v[50:51], v[250:251], v[210:211], v[50:51]
	v_max_f32_e32 v108, 0, v14
	v_max_f32_e32 v109, 0, v15
	v_pk_fma_f32 v[50:51], v[252:253], v[108:109], v[50:51]
	v_max_f32_e32 v210, 0, v16
	v_max_f32_e32 v211, 0, v17
	v_pk_fma_f32 v[50:51], v[254:255], v[210:211], v[50:51]
	s_waitcnt lgkmcnt(1)
	v_mfma_f32_32x32x16_bf16 v[212:227], v[78:81], v[46:49], v[212:227]
	v_max_f32_e32 v108, 0, v18
	v_max_f32_e32 v109, 0, v19
	v_pk_fma_f32 v[50:51], v[200:201], v[108:109], v[50:51]
	v_max_f32_e32 v210, 0, v20
	v_max_f32_e32 v211, 0, v21
	v_pk_fma_f32 v[50:51], v[202:203], v[210:211], v[50:51]
	v_add_f32_e32 v50, v50, v51
	v_ashrrev_i32_e32 v51, 31, v50
	s_waitcnt lgkmcnt(0)
	v_mfma_f32_32x32x16_bf16 v[212:227], v[82:85], v[196:199], v[212:227]
	v_or_b32_e32 v51, 0x80000000, v51
	s_cmpk_gt_i32 s11, 496
	s_cselect_b64 vcc, -1, 0
	v_xor_b32_e32 v50, v51, v50
	v_cndmask_b32_e32 v50, v123, v50, vcc
	global_store_dword v243, v50, s[8:9]
	v_mfma_f32_32x32x16_bf16 v[6:21], v[86:89], v[38:41], 0
	s_add_i32 m0, s10, 65536
	s_nop 0
	global_load_lds_dwordx4 v102, s[6:7]
	s_add_i32 m0, s10, 66560
	s_nop 0
	global_load_lds_dwordx4 v110, s[6:7]
	s_add_i32 m0, s10, 67584
	s_nop 0
	global_load_lds_dwordx4 v112, s[6:7]
	s_add_i32 m0, s10, 68608
	s_nop 0
	global_load_lds_dwordx4 v193, s[6:7]
	s_add_u32 s6, s6, 0x8000
	s_addc_u32 s7, s7, 0
	v_max_f32_e32 v108, 0, v212
	v_max_f32_e32 v109, 0, v213
	v_pk_mul_f32 v[0:1], v[22:23], v[108:109]
	v_max_f32_e32 v210, 0, v214
	v_max_f32_e32 v211, 0, v215
	v_pk_fma_f32 v[0:1], v[24:25], v[210:211], v[0:1]
	v_max_f32_e32 v108, 0, v216
	v_max_f32_e32 v109, 0, v217
	v_pk_fma_f32 v[0:1], v[26:27], v[108:109], v[0:1]
	v_mfma_f32_32x32x16_bf16 v[6:21], v[90:93], v[42:45], v[6:21]
	v_max_f32_e32 v210, 0, v218
	v_max_f32_e32 v211, 0, v219
	v_pk_fma_f32 v[0:1], v[28:29], v[210:211], v[0:1]
	v_max_f32_e32 v108, 0, v220
	v_max_f32_e32 v109, 0, v221
	v_pk_fma_f32 v[0:1], v[30:31], v[108:109], v[0:1]
	v_max_f32_e32 v210, 0, v222
	v_max_f32_e32 v211, 0, v223
	v_pk_fma_f32 v[0:1], v[32:33], v[210:211], v[0:1]
	v_mfma_f32_32x32x16_bf16 v[6:21], v[94:97], v[46:49], v[6:21]
	v_max_f32_e32 v108, 0, v224
	v_max_f32_e32 v109, 0, v225
	v_pk_fma_f32 v[0:1], v[34:35], v[108:109], v[0:1]
	v_max_f32_e32 v210, 0, v226
	v_max_f32_e32 v211, 0, v227
	v_pk_fma_f32 v[0:1], v[36:37], v[210:211], v[0:1]
	v_add_f32_e32 v0, v0, v1
	v_ashrrev_i32_e32 v1, 31, v0
	v_mfma_f32_32x32x16_bf16 v[6:21], v[98:101], v[196:199], v[6:21]
	s_waitcnt vmcnt(10)
	ds_read_b128 v[38:41], v5 offset:10496
	ds_read_b128 v[42:45], v52 offset:10496
	ds_read_b128 v[46:49], v55 offset:10496
	ds_read_b128 v[196:199], v56 offset:10496
	v_or_b32_e32 v1, 0x80000000, v1
	s_cmpk_gt_i32 s11, 504
	s_cselect_b64 vcc, -1, 0
	v_xor_b32_e32 v0, v1, v0
	v_cndmask_b32_e32 v185, v123, v0, vcc
	s_nop 3
	v_max_f32_e32 v108, 0, v6
	v_max_f32_e32 v109, 0, v7
	v_pk_mul_f32 v[50:51], v[244:245], v[108:109]
	v_max_f32_e32 v210, 0, v8
	v_max_f32_e32 v211, 0, v9
	v_pk_fma_f32 v[50:51], v[246:247], v[210:211], v[50:51]
	v_max_f32_e32 v108, 0, v10
	v_max_f32_e32 v109, 0, v11
	v_pk_fma_f32 v[50:51], v[248:249], v[108:109], v[50:51]
	v_max_f32_e32 v210, 0, v12
	v_max_f32_e32 v211, 0, v13
	v_pk_fma_f32 v[50:51], v[250:251], v[210:211], v[50:51]
	v_max_f32_e32 v108, 0, v14
	v_max_f32_e32 v109, 0, v15
	v_pk_fma_f32 v[50:51], v[252:253], v[108:109], v[50:51]
	v_max_f32_e32 v210, 0, v16
	v_max_f32_e32 v211, 0, v17
	v_pk_fma_f32 v[50:51], v[254:255], v[210:211], v[50:51]
	v_max_f32_e32 v108, 0, v18
	v_max_f32_e32 v109, 0, v19
	v_pk_fma_f32 v[50:51], v[200:201], v[108:109], v[50:51]
	v_max_f32_e32 v210, 0, v20
	v_max_f32_e32 v211, 0, v21
	v_pk_fma_f32 v[50:51], v[202:203], v[210:211], v[50:51]
	v_add_f32_e32 v50, v50, v51
	v_ashrrev_i32_e32 v51, 31, v50
	v_or_b32_e32 v51, 0x80000000, v51
	s_cmpk_gt_i32 s11, 504
	s_cselect_b64 vcc, -1, 0
	v_xor_b32_e32 v50, v51, v50
	v_cndmask_b32_e32 v50, v123, v50, vcc
	global_store_dword v243, v50, s[8:9] offset:2048
	s_add_u32 s8, s8, 0x1000
	s_addc_u32 s9, s9, 0
	s_branch .Lix_done

.Lqk_fast:
	v_lshlrev_b32_e32 v24, 4, v55
	v_lshl_add_u32 v25, v56, 2, s66
	ds_read_b32 v16, v25 offset:6400
	ds_read_b32 v17, v25 offset:6464
	ds_read_b32 v18, v25 offset:6528
	ds_read_b32 v19, v25 offset:6592
	s_waitcnt lgkmcnt(3)
	v_add_u32_e32 v26, s42, v16
	v_lshl_add_u32 v26, v26, 9, v24
	global_load_dwordx4 v[130:133], v26, s[44:45]
	global_load_dwordx4 v[134:137], v26, s[44:45] offset:64
	global_load_dwordx4 v[138:141], v26, s[44:45] offset:128
	global_load_dwordx4 v[142:145], v26, s[44:45] offset:192
	s_waitcnt lgkmcnt(2)
	v_add_u32_e32 v27, s42, v17
	v_lshl_add_u32 v27, v27, 9, v24
	global_load_dwordx4 v[146:149], v27, s[44:45]
	global_load_dwordx4 v[150:153], v27, s[44:45] offset:64
	global_load_dwordx4 v[154:157], v27, s[44:45] offset:128
	global_load_dwordx4 v[158:161], v27, s[44:45] offset:192
	s_waitcnt lgkmcnt(1)
	v_add_u32_e32 v28, s42, v18
	v_lshl_add_u32 v28, v28, 9, v24
	global_load_dwordx4 v[162:165], v28, s[44:45]
	global_load_dwordx4 v[166:169], v28, s[44:45] offset:64
	global_load_dwordx4 v[170:173], v28, s[44:45] offset:128
	global_load_dwordx4 v[174:177], v28, s[44:45] offset:192
	s_waitcnt lgkmcnt(0)
	v_add_u32_e32 v29, s42, v19
	v_lshl_add_u32 v29, v29, 9, v24
	global_load_dwordx4 v[178:181], v29, s[44:45]
	global_load_dwordx4 v[182:185], v29, s[44:45] offset:64
	global_load_dwordx4 v[186:189], v29, s[44:45] offset:128
	global_load_dwordx4 v[190:193], v29, s[44:45] offset:192
	ds_read_b32 v20, v25 offset:6656
	ds_read_b32 v21, v25 offset:6720
	ds_read_b32 v22, v25 offset:6784
	ds_read_b32 v23, v25 offset:6848
	s_waitcnt lgkmcnt(3)
	v_add_u32_e32 v26, s42, v20
	v_lshl_add_u32 v26, v26, 9, v24
	global_load_dwordx4 v[210:213], v26, s[44:45]
	global_load_dwordx4 v[214:217], v26, s[44:45] offset:64
	global_load_dwordx4 v[218:221], v26, s[44:45] offset:128
	global_load_dwordx4 v[222:225], v26, s[44:45] offset:192
	s_waitcnt lgkmcnt(2)
	v_add_u32_e32 v27, s42, v21
	v_lshl_add_u32 v27, v27, 9, v24
	global_load_dwordx4 v[226:229], v27, s[44:45]
	global_load_dwordx4 v[230:233], v27, s[44:45] offset:64
	global_load_dwordx4 v[234:237], v27, s[44:45] offset:128
	global_load_dwordx4 v[238:241], v27, s[44:45] offset:192
	s_waitcnt lgkmcnt(1)
	v_add_u32_e32 v28, s42, v22
	v_lshl_add_u32 v28, v28, 9, v24
	global_load_dwordx4 v[70:73], v28, s[44:45]
	global_load_dwordx4 v[74:77], v28, s[44:45] offset:64
	global_load_dwordx4 v[78:81], v28, s[44:45] offset:128
	global_load_dwordx4 v[82:85], v28, s[44:45] offset:192
	s_waitcnt lgkmcnt(0)
	v_add_u32_e32 v29, s42, v23
	v_lshl_add_u32 v29, v29, 9, v24
	global_load_dwordx4 v[196:199], v29, s[44:45]
	global_load_dwordx4 v[200:203], v29, s[44:45] offset:64
	global_load_dwordx4 v[244:247], v29, s[44:45] offset:128
	global_load_dwordx4 v[248:251], v29, s[44:45] offset:192
	v_subrev_u32_e32 v30, s80, v16
	v_max_i32_e32 v30, 0xffffff80, v30
	v_lshl_add_u32 v30, v30, 2, s72
	ds_read2st64_b32 v[40:41], v30 offset0:2 offset1:5
	ds_read2st64_b32 v[42:43], v30 offset0:8 offset1:11
	s_waitcnt vmcnt(31)
	v_mfma_f32_16x16x32_bf16 v[32:35], v[4:7], v[130:133], 0
	s_waitcnt vmcnt(30)
	v_mfma_f32_16x16x32_bf16 v[32:35], v[0:3], v[134:137], v[32:35]
	s_waitcnt vmcnt(29)
	v_mfma_f32_16x16x32_bf16 v[32:35], v[12:15], v[138:141], v[32:35]
	s_waitcnt vmcnt(28)
	v_mfma_f32_16x16x32_bf16 v[32:35], v[8:11], v[142:145], v[32:35]
	v_add_u32_e32 v30, 0, v87
	s_waitcnt lgkmcnt(0)
	s_nop 7
	v_fmamk_f32 v32, v32, 0x3db504f3, v40
	v_fmac_f32_e32 v41, 0x3db504f3, v33
	v_fmamk_f32 v34, v34, 0x3db504f3, v42
	v_fmac_f32_e32 v43, 0x3db504f3, v35
	v_mov_b32_e32 v33, v41
	v_mov_b32_e32 v35, v43
	s_mov_b64 exec, s[6:7]
	ds_write_b128 v30, v[32:35]
	s_mov_b64 exec, -1
	v_subrev_u32_e32 v30, s80, v17
	v_max_i32_e32 v30, 0xffffff80, v30
	v_lshl_add_u32 v30, v30, 2, s72
	ds_read2st64_b32 v[44:45], v30 offset0:2 offset1:5
	ds_read2st64_b32 v[46:47], v30 offset0:8 offset1:11
	s_waitcnt vmcnt(27)
	v_mfma_f32_16x16x32_bf16 v[36:39], v[4:7], v[146:149], 0
	s_waitcnt vmcnt(26)
	v_mfma_f32_16x16x32_bf16 v[36:39], v[0:3], v[150:153], v[36:39]
	s_waitcnt vmcnt(25)
	v_mfma_f32_16x16x32_bf16 v[36:39], v[12:15], v[154:157], v[36:39]
	s_waitcnt vmcnt(24)
	v_mfma_f32_16x16x32_bf16 v[36:39], v[8:11], v[158:161], v[36:39]
	v_add_u32_e32 v30, 256, v87
	s_waitcnt lgkmcnt(0)
	s_nop 7
	v_fmamk_f32 v36, v36, 0x3db504f3, v44
	v_fmac_f32_e32 v45, 0x3db504f3, v37
	v_fmamk_f32 v38, v38, 0x3db504f3, v46
	v_fmac_f32_e32 v47, 0x3db504f3, v39
	v_mov_b32_e32 v37, v45
	v_mov_b32_e32 v39, v47
	s_mov_b64 exec, s[6:7]
	ds_write_b128 v30, v[36:39]
	s_mov_b64 exec, -1
	v_subrev_u32_e32 v30, s80, v18
	v_max_i32_e32 v30, 0xffffff80, v30
	v_lshl_add_u32 v30, v30, 2, s72
	ds_read2st64_b32 v[40:41], v30 offset0:2 offset1:5
	ds_read2st64_b32 v[42:43], v30 offset0:8 offset1:11
	s_waitcnt vmcnt(23)
	v_mfma_f32_16x16x32_bf16 v[32:35], v[4:7], v[162:165], 0
	s_waitcnt vmcnt(22)
	v_mfma_f32_16x16x32_bf16 v[32:35], v[0:3], v[166:169], v[32:35]
	s_waitcnt vmcnt(21)
	v_mfma_f32_16x16x32_bf16 v[32:35], v[12:15], v[170:173], v[32:35]
	s_waitcnt vmcnt(20)
	v_mfma_f32_16x16x32_bf16 v[32:35], v[8:11], v[174:177], v[32:35]
	v_add_u32_e32 v30, 512, v87
	s_waitcnt lgkmcnt(0)
	s_nop 7
	v_fmamk_f32 v32, v32, 0x3db504f3, v40
	v_fmac_f32_e32 v41, 0x3db504f3, v33
	v_fmamk_f32 v34, v34, 0x3db504f3, v42
	v_fmac_f32_e32 v43, 0x3db504f3, v35
	v_mov_b32_e32 v33, v41
	v_mov_b32_e32 v35, v43
	s_mov_b64 exec, s[6:7]
	ds_write_b128 v30, v[32:35]
	s_mov_b64 exec, -1
	v_subrev_u32_e32 v30, s80, v19
	v_max_i32_e32 v30, 0xffffff80, v30
	v_lshl_add_u32 v30, v30, 2, s72
	ds_read2st64_b32 v[44:45], v30 offset0:2 offset1:5
	ds_read2st64_b32 v[46:47], v30 offset0:8 offset1:11
	s_waitcnt vmcnt(19)
	v_mfma_f32_16x16x32_bf16 v[36:39], v[4:7], v[178:181], 0
	s_waitcnt vmcnt(18)
	v_mfma_f32_16x16x32_bf16 v[36:39], v[0:3], v[182:185], v[36:39]
	s_waitcnt vmcnt(17)
	v_mfma_f32_16x16x32_bf16 v[36:39], v[12:15], v[186:189], v[36:39]
	s_waitcnt vmcnt(16)
	v_mfma_f32_16x16x32_bf16 v[36:39], v[8:11], v[190:193], v[36:39]
	v_add_u32_e32 v30, 768, v87
	s_waitcnt lgkmcnt(0)
	s_nop 7
	v_fmamk_f32 v36, v36, 0x3db504f3, v44
	v_fmac_f32_e32 v45, 0x3db504f3, v37
	v_fmamk_f32 v38, v38, 0x3db504f3, v46
	v_fmac_f32_e32 v47, 0x3db504f3, v39
	v_mov_b32_e32 v37, v45
	v_mov_b32_e32 v39, v47
	s_mov_b64 exec, s[6:7]
	ds_write_b128 v30, v[36:39]
	s_mov_b64 exec, -1
	ds_read_b32 v16, v25 offset:6912
	ds_read_b32 v17, v25 offset:6976
	ds_read_b32 v18, v25 offset:7040
	ds_read_b32 v19, v25 offset:7104
	s_waitcnt lgkmcnt(3)
	v_add_u32_e32 v26, s42, v16
	v_lshl_add_u32 v26, v26, 9, v24
	global_load_dwordx4 v[130:133], v26, s[44:45]
	global_load_dwordx4 v[134:137], v26, s[44:45] offset:64
	global_load_dwordx4 v[138:141], v26, s[44:45] offset:128
	global_load_dwordx4 v[142:145], v26, s[44:45] offset:192
	s_waitcnt lgkmcnt(2)
	v_add_u32_e32 v27, s42, v17
	v_lshl_add_u32 v27, v27, 9, v24
	global_load_dwordx4 v[146:149], v27, s[44:45]
	global_load_dwordx4 v[150:153], v27, s[44:45] offset:64
	global_load_dwordx4 v[154:157], v27, s[44:45] offset:128
	global_load_dwordx4 v[158:161], v27, s[44:45] offset:192
	s_waitcnt lgkmcnt(1)
	v_add_u32_e32 v28, s42, v18
	v_lshl_add_u32 v28, v28, 9, v24
	global_load_dwordx4 v[162:165], v28, s[44:45]
	global_load_dwordx4 v[166:169], v28, s[44:45] offset:64
	global_load_dwordx4 v[170:173], v28, s[44:45] offset:128
	global_load_dwordx4 v[174:177], v28, s[44:45] offset:192
	s_waitcnt lgkmcnt(0)
	v_add_u32_e32 v29, s42, v19
	v_lshl_add_u32 v29, v29, 9, v24
	global_load_dwordx4 v[178:181], v29, s[44:45]
	global_load_dwordx4 v[182:185], v29, s[44:45] offset:64
	global_load_dwordx4 v[186:189], v29, s[44:45] offset:128
	global_load_dwordx4 v[190:193], v29, s[44:45] offset:192
	v_subrev_u32_e32 v30, s80, v20
	v_max_i32_e32 v30, 0xffffff80, v30
	v_lshl_add_u32 v30, v30, 2, s72
	ds_read2st64_b32 v[40:41], v30 offset0:2 offset1:5
	ds_read2st64_b32 v[42:43], v30 offset0:8 offset1:11
	s_waitcnt vmcnt(31)
	v_mfma_f32_16x16x32_bf16 v[32:35], v[4:7], v[210:213], 0
	s_waitcnt vmcnt(30)
	v_mfma_f32_16x16x32_bf16 v[32:35], v[0:3], v[214:217], v[32:35]
	s_waitcnt vmcnt(29)
	v_mfma_f32_16x16x32_bf16 v[32:35], v[12:15], v[218:221], v[32:35]
	s_waitcnt vmcnt(28)
	v_mfma_f32_16x16x32_bf16 v[32:35], v[8:11], v[222:225], v[32:35]
	v_add_u32_e32 v30, 1024, v87
	s_waitcnt lgkmcnt(0)
	s_nop 7
	v_fmamk_f32 v32, v32, 0x3db504f3, v40
	v_fmac_f32_e32 v41, 0x3db504f3, v33
	v_fmamk_f32 v34, v34, 0x3db504f3, v42
	v_fmac_f32_e32 v43, 0x3db504f3, v35
	v_mov_b32_e32 v33, v41
	v_mov_b32_e32 v35, v43
	s_mov_b64 exec, s[6:7]
	ds_write_b128 v30, v[32:35]
	s_mov_b64 exec, -1
	v_subrev_u32_e32 v30, s80, v21
	v_max_i32_e32 v30, 0xffffff80, v30
	v_lshl_add_u32 v30, v30, 2, s72
	ds_read2st64_b32 v[44:45], v30 offset0:2 offset1:5
	ds_read2st64_b32 v[46:47], v30 offset0:8 offset1:11
	s_waitcnt vmcnt(27)
	v_mfma_f32_16x16x32_bf16 v[36:39], v[4:7], v[226:229], 0
	s_waitcnt vmcnt(26)
	v_mfma_f32_16x16x32_bf16 v[36:39], v[0:3], v[230:233], v[36:39]
	s_waitcnt vmcnt(25)
	v_mfma_f32_16x16x32_bf16 v[36:39], v[12:15], v[234:237], v[36:39]
	s_waitcnt vmcnt(24)
	v_mfma_f32_16x16x32_bf16 v[36:39], v[8:11], v[238:241], v[36:39]
	v_add_u32_e32 v30, 1280, v87
	s_waitcnt lgkmcnt(0)
	s_nop 7
	v_fmamk_f32 v36, v36, 0x3db504f3, v44
	v_fmac_f32_e32 v45, 0x3db504f3, v37
	v_fmamk_f32 v38, v38, 0x3db504f3, v46
	v_fmac_f32_e32 v47, 0x3db504f3, v39
	v_mov_b32_e32 v37, v45
	v_mov_b32_e32 v39, v47
	s_mov_b64 exec, s[6:7]
	ds_write_b128 v30, v[36:39]
	s_mov_b64 exec, -1
	v_subrev_u32_e32 v30, s80, v22
	v_max_i32_e32 v30, 0xffffff80, v30
	v_lshl_add_u32 v30, v30, 2, s72
	ds_read2st64_b32 v[40:41], v30 offset0:2 offset1:5
	ds_read2st64_b32 v[42:43], v30 offset0:8 offset1:11
	s_waitcnt vmcnt(23)
	v_mfma_f32_16x16x32_bf16 v[32:35], v[4:7], v[70:73], 0
	s_waitcnt vmcnt(22)
	v_mfma_f32_16x16x32_bf16 v[32:35], v[0:3], v[74:77], v[32:35]
	s_waitcnt vmcnt(21)
	v_mfma_f32_16x16x32_bf16 v[32:35], v[12:15], v[78:81], v[32:35]
	s_waitcnt vmcnt(20)
	v_mfma_f32_16x16x32_bf16 v[32:35], v[8:11], v[82:85], v[32:35]
	v_add_u32_e32 v30, 1536, v87
	s_waitcnt lgkmcnt(0)
	s_nop 7
	v_fmamk_f32 v32, v32, 0x3db504f3, v40
	v_fmac_f32_e32 v41, 0x3db504f3, v33
	v_fmamk_f32 v34, v34, 0x3db504f3, v42
	v_fmac_f32_e32 v43, 0x3db504f3, v35
	v_mov_b32_e32 v33, v41
	v_mov_b32_e32 v35, v43
	s_mov_b64 exec, s[6:7]
	ds_write_b128 v30, v[32:35]
	s_mov_b64 exec, -1
	v_subrev_u32_e32 v30, s80, v23
	v_max_i32_e32 v30, 0xffffff80, v30
	v_lshl_add_u32 v30, v30, 2, s72
	ds_read2st64_b32 v[44:45], v30 offset0:2 offset1:5
	ds_read2st64_b32 v[46:47], v30 offset0:8 offset1:11
	s_waitcnt vmcnt(19)
	v_mfma_f32_16x16x32_bf16 v[36:39], v[4:7], v[196:199], 0
	s_waitcnt vmcnt(18)
	v_mfma_f32_16x16x32_bf16 v[36:39], v[0:3], v[200:203], v[36:39]
	s_waitcnt vmcnt(17)
	v_mfma_f32_16x16x32_bf16 v[36:39], v[12:15], v[244:247], v[36:39]
	s_waitcnt vmcnt(16)
	v_mfma_f32_16x16x32_bf16 v[36:39], v[8:11], v[248:251], v[36:39]
	v_add_u32_e32 v30, 1792, v87
	s_waitcnt lgkmcnt(0)
	s_nop 7
	v_fmamk_f32 v36, v36, 0x3db504f3, v44
	v_fmac_f32_e32 v45, 0x3db504f3, v37
	v_fmamk_f32 v38, v38, 0x3db504f3, v46
	v_fmac_f32_e32 v47, 0x3db504f3, v39
	v_mov_b32_e32 v37, v45
	v_mov_b32_e32 v39, v47
	s_mov_b64 exec, s[6:7]
	ds_write_b128 v30, v[36:39]
	s_mov_b64 exec, -1
	ds_read_b32 v20, v25 offset:7168
	ds_read_b32 v21, v25 offset:7232
	ds_read_b32 v22, v25 offset:7296
	ds_read_b32 v23, v25 offset:7360
	s_waitcnt lgkmcnt(3)
	v_add_u32_e32 v26, s42, v20
	v_lshl_add_u32 v26, v26, 9, v24
	global_load_dwordx4 v[210:213], v26, s[44:45]
	global_load_dwordx4 v[214:217], v26, s[44:45] offset:64
	global_load_dwordx4 v[218:221], v26, s[44:45] offset:128
	global_load_dwordx4 v[222:225], v26, s[44:45] offset:192
	s_waitcnt lgkmcnt(2)
	v_add_u32_e32 v27, s42, v21
	v_lshl_add_u32 v27, v27, 9, v24
	global_load_dwordx4 v[226:229], v27, s[44:45]
	global_load_dwordx4 v[230:233], v27, s[44:45] offset:64
	global_load_dwordx4 v[234:237], v27, s[44:45] offset:128
	global_load_dwordx4 v[238:241], v27, s[44:45] offset:192
	s_waitcnt lgkmcnt(1)
	v_add_u32_e32 v28, s42, v22
	v_lshl_add_u32 v28, v28, 9, v24
	global_load_dwordx4 v[70:73], v28, s[44:45]
	global_load_dwordx4 v[74:77], v28, s[44:45] offset:64
	global_load_dwordx4 v[78:81], v28, s[44:45] offset:128
	global_load_dwordx4 v[82:85], v28, s[44:45] offset:192
	s_waitcnt lgkmcnt(0)
	v_add_u32_e32 v29, s42, v23
	v_lshl_add_u32 v29, v29, 9, v24
	global_load_dwordx4 v[196:199], v29, s[44:45]
	global_load_dwordx4 v[200:203], v29, s[44:45] offset:64
	global_load_dwordx4 v[244:247], v29, s[44:45] offset:128
	global_load_dwordx4 v[248:251], v29, s[44:45] offset:192
	v_subrev_u32_e32 v30, s80, v16
	v_max_i32_e32 v30, 0xffffff80, v30
	v_lshl_add_u32 v30, v30, 2, s72
	ds_read2st64_b32 v[40:41], v30 offset0:2 offset1:5
	ds_read2st64_b32 v[42:43], v30 offset0:8 offset1:11
	s_waitcnt vmcnt(31)
	v_mfma_f32_16x16x32_bf16 v[32:35], v[4:7], v[130:133], 0
	s_waitcnt vmcnt(30)
	v_mfma_f32_16x16x32_bf16 v[32:35], v[0:3], v[134:137], v[32:35]
	s_waitcnt vmcnt(29)
	v_mfma_f32_16x16x32_bf16 v[32:35], v[12:15], v[138:141], v[32:35]
	s_waitcnt vmcnt(28)
	v_mfma_f32_16x16x32_bf16 v[32:35], v[8:11], v[142:145], v[32:35]
	v_add_u32_e32 v30, 2048, v87
	s_waitcnt lgkmcnt(0)
	s_nop 7
	v_fmamk_f32 v32, v32, 0x3db504f3, v40
	v_fmac_f32_e32 v41, 0x3db504f3, v33
	v_fmamk_f32 v34, v34, 0x3db504f3, v42
	v_fmac_f32_e32 v43, 0x3db504f3, v35
	v_mov_b32_e32 v33, v41
	v_mov_b32_e32 v35, v43
	s_mov_b64 exec, s[6:7]
	ds_write_b128 v30, v[32:35]
	s_mov_b64 exec, -1
	v_subrev_u32_e32 v30, s80, v17
	v_max_i32_e32 v30, 0xffffff80, v30
	v_lshl_add_u32 v30, v30, 2, s72
	ds_read2st64_b32 v[44:45], v30 offset0:2 offset1:5
	ds_read2st64_b32 v[46:47], v30 offset0:8 offset1:11
	s_waitcnt vmcnt(27)
	v_mfma_f32_16x16x32_bf16 v[36:39], v[4:7], v[146:149], 0
	s_waitcnt vmcnt(26)
	v_mfma_f32_16x16x32_bf16 v[36:39], v[0:3], v[150:153], v[36:39]
	s_waitcnt vmcnt(25)
	v_mfma_f32_16x16x32_bf16 v[36:39], v[12:15], v[154:157], v[36:39]
	s_waitcnt vmcnt(24)
	v_mfma_f32_16x16x32_bf16 v[36:39], v[8:11], v[158:161], v[36:39]
	v_add_u32_e32 v30, 2304, v87
	s_waitcnt lgkmcnt(0)
	s_nop 7
	v_fmamk_f32 v36, v36, 0x3db504f3, v44
	v_fmac_f32_e32 v45, 0x3db504f3, v37
	v_fmamk_f32 v38, v38, 0x3db504f3, v46
	v_fmac_f32_e32 v47, 0x3db504f3, v39
	v_mov_b32_e32 v37, v45
	v_mov_b32_e32 v39, v47
	s_mov_b64 exec, s[6:7]
	ds_write_b128 v30, v[36:39]
	s_mov_b64 exec, -1
	v_subrev_u32_e32 v30, s80, v18
	v_max_i32_e32 v30, 0xffffff80, v30
	v_lshl_add_u32 v30, v30, 2, s72
	ds_read2st64_b32 v[40:41], v30 offset0:2 offset1:5
	ds_read2st64_b32 v[42:43], v30 offset0:8 offset1:11
	s_waitcnt vmcnt(23)
	v_mfma_f32_16x16x32_bf16 v[32:35], v[4:7], v[162:165], 0
	s_waitcnt vmcnt(22)
	v_mfma_f32_16x16x32_bf16 v[32:35], v[0:3], v[166:169], v[32:35]
	s_waitcnt vmcnt(21)
	v_mfma_f32_16x16x32_bf16 v[32:35], v[12:15], v[170:173], v[32:35]
	s_waitcnt vmcnt(20)
	v_mfma_f32_16x16x32_bf16 v[32:35], v[8:11], v[174:177], v[32:35]
	v_add_u32_e32 v30, 2560, v87
	s_waitcnt lgkmcnt(0)
	s_nop 7
	v_fmamk_f32 v32, v32, 0x3db504f3, v40
	v_fmac_f32_e32 v41, 0x3db504f3, v33
	v_fmamk_f32 v34, v34, 0x3db504f3, v42
	v_fmac_f32_e32 v43, 0x3db504f3, v35
	v_mov_b32_e32 v33, v41
	v_mov_b32_e32 v35, v43
	s_mov_b64 exec, s[6:7]
	ds_write_b128 v30, v[32:35]
	s_mov_b64 exec, -1
	v_subrev_u32_e32 v30, s80, v19
	v_max_i32_e32 v30, 0xffffff80, v30
	v_lshl_add_u32 v30, v30, 2, s72
	ds_read2st64_b32 v[44:45], v30 offset0:2 offset1:5
	ds_read2st64_b32 v[46:47], v30 offset0:8 offset1:11
	s_waitcnt vmcnt(19)
	v_mfma_f32_16x16x32_bf16 v[36:39], v[4:7], v[178:181], 0
	s_waitcnt vmcnt(18)
	v_mfma_f32_16x16x32_bf16 v[36:39], v[0:3], v[182:185], v[36:39]
	s_waitcnt vmcnt(17)
	v_mfma_f32_16x16x32_bf16 v[36:39], v[12:15], v[186:189], v[36:39]
	s_waitcnt vmcnt(16)
	v_mfma_f32_16x16x32_bf16 v[36:39], v[8:11], v[190:193], v[36:39]
	v_add_u32_e32 v30, 2816, v87
	s_waitcnt lgkmcnt(0)
	s_nop 7
	v_fmamk_f32 v36, v36, 0x3db504f3, v44
	v_fmac_f32_e32 v45, 0x3db504f3, v37
	v_fmamk_f32 v38, v38, 0x3db504f3, v46
	v_fmac_f32_e32 v47, 0x3db504f3, v39
	v_mov_b32_e32 v37, v45
	v_mov_b32_e32 v39, v47
	s_mov_b64 exec, s[6:7]
	ds_write_b128 v30, v[36:39]
	s_mov_b64 exec, -1
	v_subrev_u32_e32 v30, s80, v20
	v_max_i32_e32 v30, 0xffffff80, v30
	v_lshl_add_u32 v30, v30, 2, s72
	ds_read2st64_b32 v[40:41], v30 offset0:2 offset1:5
	ds_read2st64_b32 v[42:43], v30 offset0:8 offset1:11
	s_waitcnt vmcnt(15)
	v_mfma_f32_16x16x32_bf16 v[32:35], v[4:7], v[210:213], 0
	s_waitcnt vmcnt(14)
	v_mfma_f32_16x16x32_bf16 v[32:35], v[0:3], v[214:217], v[32:35]
	s_waitcnt vmcnt(13)
	v_mfma_f32_16x16x32_bf16 v[32:35], v[12:15], v[218:221], v[32:35]
	s_waitcnt vmcnt(12)
	v_mfma_f32_16x16x32_bf16 v[32:35], v[8:11], v[222:225], v[32:35]
	v_add_u32_e32 v30, 3072, v87
	s_waitcnt lgkmcnt(0)
	s_nop 7
	v_fmamk_f32 v32, v32, 0x3db504f3, v40
	v_fmac_f32_e32 v41, 0x3db504f3, v33
	v_fmamk_f32 v34, v34, 0x3db504f3, v42
	v_fmac_f32_e32 v43, 0x3db504f3, v35
	v_mov_b32_e32 v33, v41
	v_mov_b32_e32 v35, v43
	s_mov_b64 exec, s[6:7]
	ds_write_b128 v30, v[32:35]
	s_mov_b64 exec, -1
	v_subrev_u32_e32 v30, s80, v21
	v_max_i32_e32 v30, 0xffffff80, v30
	v_lshl_add_u32 v30, v30, 2, s72
	ds_read2st64_b32 v[44:45], v30 offset0:2 offset1:5
	ds_read2st64_b32 v[46:47], v30 offset0:8 offset1:11
	s_waitcnt vmcnt(11)
	v_mfma_f32_16x16x32_bf16 v[36:39], v[4:7], v[226:229], 0
	s_waitcnt vmcnt(10)
	v_mfma_f32_16x16x32_bf16 v[36:39], v[0:3], v[230:233], v[36:39]
	s_waitcnt vmcnt(9)
	v_mfma_f32_16x16x32_bf16 v[36:39], v[12:15], v[234:237], v[36:39]
	s_waitcnt vmcnt(8)
	v_mfma_f32_16x16x32_bf16 v[36:39], v[8:11], v[238:241], v[36:39]
	v_add_u32_e32 v30, 3328, v87
	s_waitcnt lgkmcnt(0)
	s_nop 7
	v_fmamk_f32 v36, v36, 0x3db504f3, v44
	v_fmac_f32_e32 v45, 0x3db504f3, v37
	v_fmamk_f32 v38, v38, 0x3db504f3, v46
	v_fmac_f32_e32 v47, 0x3db504f3, v39
	v_mov_b32_e32 v37, v45
	v_mov_b32_e32 v39, v47
	s_mov_b64 exec, s[6:7]
	ds_write_b128 v30, v[36:39]
	s_mov_b64 exec, -1
	v_subrev_u32_e32 v30, s80, v22
	v_max_i32_e32 v30, 0xffffff80, v30
	v_lshl_add_u32 v30, v30, 2, s72
	ds_read2st64_b32 v[40:41], v30 offset0:2 offset1:5
	ds_read2st64_b32 v[42:43], v30 offset0:8 offset1:11
	s_waitcnt vmcnt(7)
	v_mfma_f32_16x16x32_bf16 v[32:35], v[4:7], v[70:73], 0
	s_waitcnt vmcnt(6)
	v_mfma_f32_16x16x32_bf16 v[32:35], v[0:3], v[74:77], v[32:35]
	s_waitcnt vmcnt(5)
	v_mfma_f32_16x16x32_bf16 v[32:35], v[12:15], v[78:81], v[32:35]
	s_waitcnt vmcnt(4)
	v_mfma_f32_16x16x32_bf16 v[32:35], v[8:11], v[82:85], v[32:35]
	v_add_u32_e32 v30, 3584, v87
	s_waitcnt lgkmcnt(0)
	s_nop 7
	v_fmamk_f32 v32, v32, 0x3db504f3, v40
	v_fmac_f32_e32 v41, 0x3db504f3, v33
	v_fmamk_f32 v34, v34, 0x3db504f3, v42
	v_fmac_f32_e32 v43, 0x3db504f3, v35
	v_mov_b32_e32 v33, v41
	v_mov_b32_e32 v35, v43
	s_mov_b64 exec, s[6:7]
	ds_write_b128 v30, v[32:35]
	s_mov_b64 exec, -1
	v_subrev_u32_e32 v30, s80, v23
	v_max_i32_e32 v30, 0xffffff80, v30
	v_lshl_add_u32 v30, v30, 2, s72
	ds_read2st64_b32 v[44:45], v30 offset0:2 offset1:5
	ds_read2st64_b32 v[46:47], v30 offset0:8 offset1:11
	s_waitcnt vmcnt(3)
	v_mfma_f32_16x16x32_bf16 v[36:39], v[4:7], v[196:199], 0
	s_waitcnt vmcnt(2)
	v_mfma_f32_16x16x32_bf16 v[36:39], v[0:3], v[200:203], v[36:39]
	s_waitcnt vmcnt(1)
	v_mfma_f32_16x16x32_bf16 v[36:39], v[12:15], v[244:247], v[36:39]
	s_waitcnt vmcnt(0)
	v_mfma_f32_16x16x32_bf16 v[36:39], v[8:11], v[248:251], v[36:39]
	v_add_u32_e32 v30, 3840, v87
	s_waitcnt lgkmcnt(0)
	s_nop 7
	v_fmamk_f32 v36, v36, 0x3db504f3, v44
	v_fmac_f32_e32 v45, 0x3db504f3, v37
	v_fmamk_f32 v38, v38, 0x3db504f3, v46
	v_fmac_f32_e32 v47, 0x3db504f3, v39
	v_mov_b32_e32 v37, v45
	v_mov_b32_e32 v39, v47
	s_mov_b64 exec, s[6:7]
	ds_write_b128 v30, v[36:39]
	s_mov_b64 exec, -1
	s_branch .LBB0_1532
